# GEMM k-loops: MFMA-shadow interleave also in the first unit of each k-step (LDS wait counts re-derived)
# baseline (speedup 1.0000x reference)
; template <int MODE>
; __device__ __forceinline__ void gemm_tile(const Params& P, int tm, int tn, unsigned char* smem) {
;     ...
;     const int srow = tid >> 3, sc = tid & 7;
;     constexpr unsigned LDA = (MODE == 2 ? NZ : 1024) * 2u;
;     unsigned aoff, boff; int soff0;
;     {
;         int ar = m0 + srow;
;         if (MODE == 2) { const int b = ar >> 11, t = ar & 2047; ar = b * L + NMETA + t; }
;         aoff = (unsigned)ar * LDA + (unsigned)sc * 16u;
;         boff = (unsigned)(n0 + srow) * 2048u + (unsigned)sc * 16u;
;         soff0 = srow * 128 + ((sc ^ (srow & 7)) << 4);
;     }
;     const unsigned char* Ab = (const unsigned char*)A; const unsigned char* Bb = (const unsigned char*)Bt;
;     float4 ssp0, ssp1, ssp2, ssp3;
;     if (MODE == 3) {
;         const float* ssq = (const float*)(P.ws + WS_SSQ) + (size_t)(m0 + wr * 64 + lr) * 16 + 4 * g;
;         ssp0 = *(const float4*)(ssq); ssp1 = *(const float4*)(ssq + 16 * 16); ssp2 = *(const float4*)(ssq + 32 * 16); ssp3 = *(const float4*)(ssq + 48 * 16);
;     }
;     f32x4 acc[4][4];
; #pragma unroll
;     for (int i = 0; i < 4; ++i)
; #pragma unroll
;         for (int j = 0; j < 4; ++j) acc[i][j] = (f32x4){0.f, 0.f, 0.f, 0.f};
;     uint4 ra0, ra1, ra2, ra3, rb0, rb1, rb2, rb3;
;     ...
;     unsigned char* sA0 = smem; unsigned char* sB0 = smem + 16384; unsigned char* sA1 = smem + 32768; unsigned char* sB1 = smem + 49152;
;     G_LOAD(0)
;     G_WRITE(sA0, sB0)
;     __syncthreads();
;     const int arow_off = (wr * 64 + lr) * 128, brow_off = (wc * 64 + lr) * 128, sw = lr & 7;
;     G_LOAD(1)
;     for (int kt = 0; kt < 16; ++kt) {
;         unsigned char* sA = (kt & 1) ? sA1 : sA0; unsigned char* sB = (kt & 1) ? sB1 : sB0;
;         unsigned char* nA = (kt & 1) ? sA0 : sA1; unsigned char* nB = (kt & 1) ? sB0 : sB1;
;         bf16x8 fa[4], fb[4], ga[4], gb[4];
;         const int ch0 = ((g ^ sw) << 4), ch1 = (((4 + g) ^ sw) << 4);
;         const unsigned ko = (unsigned)(kt + 2) * 128u;
;         const unsigned koa = ko + ((MODE == 2 && kt + 2 >= 8) ? (unsigned)(ZC_FQ - 512) * 2u : 0u);
;         const bool wr_ok = kt < 15, ld_ok = kt < 14;
; #pragma unroll
;         for (int i = 0; i < 4; ++i) { fa[i] = *(const bf16x8*)(sA + arow_off + i * 2048 + ch0); fb[i] = *(const bf16x8*)(sB + brow_off + i * 2048 + ch0); }
;         __builtin_amdgcn_sched_barrier(0);
;         __builtin_amdgcn_s_setprio(2);
.LBB0_182:
	s_mul_hi_i32 s0, s35, 0x92492493
	s_add_i32 s0, s0, s35
	s_lshr_b32 s1, s0, 31
	s_ashr_i32 s0, s0, 7
	s_add_i32 s1, s0, s1
	s_mul_i32 s0, s1, 0xffffff20
	s_lshl_b32 s10, s1, 3
	s_add_i32 s0, s35, s0
	s_sub_i32 s10, 0x81, s10
	s_cmpk_gt_i32 s35, 0xdff
	s_cselect_b32 s10, s10, 8
	s_abs_i32 s11, s10
	v_cvt_f32_u32_e32 v2, s11
	s_ashr_i32 s0, s0, 31
	s_mul_i32 s13, s1, 0xe0
	s_sub_i32 s13, s0, s13
	v_rcp_iflag_f32_e32 v2, v2
	s_ashr_i32 s12, s10, 31
	s_add_i32 s13, s35, s13
	s_xor_b32 s12, s0, s12
	v_mul_f32_e32 v2, 0x4f7ffffe, v2
	v_cvt_u32_f32_e32 v2, v2
	s_xor_b32 s0, s13, s0
	s_sub_i32 s13, 0, s11
	s_mulk_i32 s1, 0xd8
	v_readfirstlane_b32 s42, v2
	s_mul_i32 s13, s13, s42
	s_mul_hi_u32 s13, s42, s13
	s_add_i32 s42, s42, s13
	s_mul_hi_u32 s13, s0, s42
	s_mul_i32 s42, s13, s11
	s_sub_i32 s0, s0, s42
	s_add_i32 s42, s13, 1
	s_sub_i32 s43, s0, s11
	s_cmp_ge_u32 s0, s11
	s_cselect_b32 s13, s42, s13
	s_cselect_b32 s0, s43, s0
	s_add_i32 s42, s13, 1
	s_cmp_ge_u32 s0, s11
	s_cselect_b32 s0, s42, s13
	s_xor_b32 s0, s0, s12
	s_sub_i32 s0, s0, s12
	s_mul_i32 s10, s10, s0
	s_add_i32 s10, s10, s1
	s_sub_i32 s1, s35, s10
	v_mov_b32_e32 v79, v0
	s_lshl_b32 s42, s1, 7
	v_ashrrev_i32_e32 v2, 3, v79
	v_lshlrev_b32_e32 v4, 4, v79
	s_lshl_b32 s10, s0, 7
	v_add_u32_e32 v3, s42, v2
	v_and_b32_e32 v4, 0x70, v4
	v_add_u32_e32 v5, s10, v2
	v_lshl_or_b32 v8, v3, 11, v4
	v_lshl_or_b32 v5, v5, 11, v4
	v_add_u32_e32 v3, 0x10000, v8
	v_add_u32_e32 v4, 0x20000, v8
	global_load_dwordx4 v[10:13], v3, s[36:37]
	global_load_dwordx4 v[14:17], v4, s[36:37]
	v_add_u32_e32 v3, 0x20000, v5
	v_add_u32_e32 v4, 0x30000, v5
	global_load_dwordx4 v[18:21], v3, s[4:5]
	global_load_dwordx4 v[22:25], v4, s[4:5]
	global_load_dwordx4 v[26:29], v8, s[36:37]
	global_load_dwordx4 v[30:33], v5, s[4:5]
	v_add_u32_e32 v3, 0x30000, v8
	v_add_u32_e32 v4, 0x10000, v5
	global_load_dwordx4 v[34:37], v3, s[36:37]
	global_load_dwordx4 v[38:41], v4, s[4:5]
	v_xor_b32_e32 v3, v2, v79
	v_lshlrev_b32_e32 v2, 7, v2
	v_lshlrev_b32_e32 v3, 4, v3
	v_and_or_b32 v2, v3, s20, v2
	v_add_u32_e32 v2, 0, v2
	v_or_b32_e32 v9, 0x80, v8
	v_or_b32_e32 v3, 0x80, v5
	v_add_u32_e32 v4, 0x10080, v5
	v_add_u32_e32 v6, 0x20080, v5
	v_add_u32_e32 v7, 0x30080, v5
	v_add_u32_e32 v42, 0x10080, v8
	v_add_u32_e32 v43, 0x20080, v8
	v_add_u32_e32 v44, 0x30080, v8
	v_and_b32_e32 v80, 15, v79
	v_ashrrev_i32_e32 v81, 7, v79
	v_bfe_u32 v82, v79, 6, 1
	v_bfe_u32 v83, v79, 4, 2
	s_waitcnt vmcnt(5)
	ds_write_b128 v2, v[18:21] offset:24576
	s_waitcnt vmcnt(4)
	ds_write_b128 v2, v[22:25] offset:28672
	s_waitcnt vmcnt(3)
	ds_write_b128 v2, v[26:29]
	s_waitcnt vmcnt(2)
	ds_write_b128 v2, v[30:33] offset:16384
	ds_write_b128 v2, v[10:13] offset:4096
	ds_write_b128 v2, v[14:17] offset:8192
	s_waitcnt vmcnt(1)
	ds_write_b128 v2, v[34:37] offset:12288
	s_waitcnt vmcnt(0)
	ds_write_b128 v2, v[38:41] offset:20480
	s_waitcnt lgkmcnt(0)
	s_barrier
	global_load_dwordx4 v[10:13], v9, s[36:37]
	global_load_dwordx4 v[14:17], v42, s[36:37]
	global_load_dwordx4 v[18:21], v43, s[36:37]
	global_load_dwordx4 v[22:25], v44, s[36:37]
	global_load_dwordx4 v[26:29], v3, s[4:5]
	global_load_dwordx4 v[30:33], v4, s[4:5]
	global_load_dwordx4 v[34:37], v6, s[4:5]
	global_load_dwordx4 v[38:41], v7, s[4:5]
	v_lshrrev_b32_e32 v3, 4, v79
	v_lshlrev_b32_e32 v4, 7, v80
	v_and_b32_e32 v9, 7, v79
	v_lshl_or_b32 v6, v81, 13, v4
	v_bitop3_b32 v3, v3, v9, 3 bitop3:0x6c
	v_lshl_or_b32 v4, v82, 13, v4
	v_lshlrev_b32_e32 v3, 4, v3
	v_add_u32_e32 v66, 0, v6
	v_add_u32_e32 v6, v66, v3
	v_add_u32_e32 v4, 0, v4
	v_add_u32_e32 v7, v4, v3
	ds_read_b128 v[42:45], v6
	ds_read_b128 v[46:49], v6 offset:2048
	ds_read_b128 v[50:53], v7 offset:16384
	ds_read_b128 v[54:57], v7 offset:18432
	ds_read_b128 v[58:61], v6 offset:4096
	ds_read_b128 v[62:65], v6 offset:6144
	ds_read_b128 v[84:87], v7 offset:20480
	ds_read_b128 v[88:91], v7 offset:22528
	v_bitop3_b32 v3, v83, v9, 4 bitop3:0x36
	v_lshlrev_b32_e32 v9, 4, v3
	s_setprio 2
	global_load_dwordx4 v[92:95], v8, s[36:37] offset:256
	s_waitcnt vmcnt(8)
	ds_write_b128 v2, v[10:13] offset:32768
	v_add_u32_e32 v3, v66, v9
	v_add_u32_e32 v4, v4, v9
	ds_read_b128 v[10:13], v3
	ds_read_b128 v[96:99], v4 offset:16384
	s_waitcnt lgkmcnt(8)
	v_mfma_f32_16x16x32_bf16 v[100:103], v[50:53], v[42:45], 0
	s_waitcnt lgkmcnt(7)
	v_mfma_f32_16x16x32_bf16 v[104:107], v[54:57], v[42:45], 0
	s_waitcnt lgkmcnt(4)
	v_mfma_f32_16x16x32_bf16 v[108:111], v[84:87], v[42:45], 0
	s_waitcnt lgkmcnt(3)
	v_mfma_f32_16x16x32_bf16 v[42:45], v[88:91], v[42:45], 0
	v_add_u32_e32 v216, 0x10000, v8
	global_load_dwordx4 v[112:115], v216, s[36:37] offset:256
	s_waitcnt vmcnt(8)
	ds_write_b128 v2, v[14:17] offset:36864
	ds_read_b128 v[14:17], v3 offset:2048
	ds_read_b128 v[116:119], v4 offset:18432
	v_mfma_f32_16x16x32_bf16 v[120:123], v[50:53], v[46:49], 0
	v_mfma_f32_16x16x32_bf16 v[124:127], v[54:57], v[46:49], 0
	v_mfma_f32_16x16x32_bf16 v[132:135], v[84:87], v[46:49], 0
	v_mfma_f32_16x16x32_bf16 v[46:49], v[88:91], v[46:49], 0
	v_add_u32_e32 v217, 0x20000, v8
	global_load_dwordx4 v[146:149], v217, s[36:37] offset:256
	s_waitcnt vmcnt(8)
	ds_write_b128 v2, v[18:21] offset:40960
	ds_read_b128 v[18:21], v3 offset:4096
	ds_read_b128 v[150:153], v4 offset:20480
	v_mfma_f32_16x16x32_bf16 v[154:157], v[50:53], v[58:61], 0
	v_mfma_f32_16x16x32_bf16 v[158:161], v[54:57], v[58:61], 0
	v_mfma_f32_16x16x32_bf16 v[162:165], v[84:87], v[58:61], 0
	v_mfma_f32_16x16x32_bf16 v[58:61], v[88:91], v[58:61], 0
	v_add_u32_e32 v218, 0x30000, v8
	global_load_dwordx4 v[166:169], v218, s[36:37] offset:256
	s_waitcnt vmcnt(8)
; template <int MODE>
; __device__ __forceinline__ void gemm_tile(const Params& P, int tm, int tn, unsigned char* smem) {
;     ...
;     for (int kt = 0; kt < 16; ++kt) {
;         unsigned char* sA = (kt & 1) ? sA1 : sA0; unsigned char* sB = (kt & 1) ? sB1 : sB0;
;         unsigned char* nA = (kt & 1) ? sA0 : sA1; unsigned char* nB = (kt & 1) ? sB0 : sB1;
;         bf16x8 fa[4], fb[4], ga[4], gb[4];
;         const int ch0 = ((g ^ sw) << 4), ch1 = (((4 + g) ^ sw) << 4);
;         const unsigned ko = (unsigned)(kt + 2) * 128u;
;         const unsigned koa = ko + ((MODE == 2 && kt + 2 >= 8) ? (unsigned)(ZC_FQ - 512) * 2u : 0u);
;         const bool wr_ok = kt < 15, ld_ok = kt < 14;
; #pragma unroll
;         for (int i = 0; i < 4; ++i) { fa[i] = *(const bf16x8*)(sA + arow_off + i * 2048 + ch0); fb[i] = *(const bf16x8*)(sB + brow_off + i * 2048 + ch0); }
;         __builtin_amdgcn_sched_barrier(0);
;         __builtin_amdgcn_s_setprio(2);
;         if (wr_ok) *(uint4*)(nA + soff0) = ra0;
;         if (ld_ok) ra0 = *(const uint4*)(Ab + (aoff + 0u * LDA + koa));
;         ga[0] = *(const bf16x8*)(sA + arow_off + 0 * 2048 + ch1); gb[0] = *(const bf16x8*)(sB + brow_off + 0 * 2048 + ch1);
;         __builtin_amdgcn_sched_barrier(0);
; #pragma unroll
;         for (int j = 0; j < 4; ++j) acc[0][j] = __builtin_amdgcn_mfma_f32_16x16x32_bf16(fb[j], fa[0], acc[0][j], 0, 0, 0);
;         __builtin_amdgcn_sched_barrier(0);
;         if (wr_ok) *(uint4*)(nA + soff0 + 4096) = ra1;
;         if (ld_ok) ra1 = *(const uint4*)(Ab + (aoff + 32u * LDA + koa));
;         ga[1] = *(const bf16x8*)(sA + arow_off + 1 * 2048 + ch1); gb[1] = *(const bf16x8*)(sB + brow_off + 1 * 2048 + ch1);
;         __builtin_amdgcn_sched_barrier(0);
; #pragma unroll
;         for (int j = 0; j < 4; ++j) acc[1][j] = __builtin_amdgcn_mfma_f32_16x16x32_bf16(fb[j], fa[1], acc[1][j], 0, 0, 0);
;         __builtin_amdgcn_sched_barrier(0);
;         if (wr_ok) *(uint4*)(nA + soff0 + 8192) = ra2;
;         if (ld_ok) ra2 = *(const uint4*)(Ab + (aoff + 64u * LDA + koa));
;         ga[2] = *(const bf16x8*)(sA + arow_off + 2 * 2048 + ch1); gb[2] = *(const bf16x8*)(sB + brow_off + 2 * 2048 + ch1);
;         __builtin_amdgcn_sched_barrier(0);
; #pragma unroll
;         for (int j = 0; j < 4; ++j) acc[2][j] = __builtin_amdgcn_mfma_f32_16x16x32_bf16(fb[j], fa[2], acc[2][j], 0, 0, 0);
	ds_write_b128 v2, v[22:25] offset:45056
	ds_read_b128 v[22:25], v3 offset:6144
	ds_read_b128 v[170:173], v4 offset:22528
	v_mfma_f32_16x16x32_bf16 v[50:53], v[50:53], v[62:65], 0
	v_mfma_f32_16x16x32_bf16 v[54:57], v[54:57], v[62:65], 0
	v_mfma_f32_16x16x32_bf16 v[84:87], v[84:87], v[62:65], 0
	v_mfma_f32_16x16x32_bf16 v[62:65], v[88:91], v[62:65], 0
	global_load_dwordx4 v[88:91], v5, s[4:5] offset:256
	s_waitcnt vmcnt(8)
	ds_write_b128 v2, v[26:29] offset:49152
	s_waitcnt lgkmcnt(10)
	v_mfma_f32_16x16x32_bf16 v[26:29], v[96:99], v[10:13], v[100:103]
	s_waitcnt lgkmcnt(7)
	v_mfma_f32_16x16x32_bf16 v[100:103], v[116:119], v[10:13], v[104:107]
	s_waitcnt lgkmcnt(4)
	v_mfma_f32_16x16x32_bf16 v[104:107], v[150:153], v[10:13], v[108:111]
	s_waitcnt lgkmcnt(1)
	v_mfma_f32_16x16x32_bf16 v[10:13], v[170:173], v[10:13], v[42:45]
	v_add_u32_e32 v219, 0x10000, v5
	global_load_dwordx4 v[42:45], v219, s[4:5] offset:256
	s_waitcnt vmcnt(8)
	ds_write_b128 v2, v[30:33] offset:53248
	v_mfma_f32_16x16x32_bf16 v[30:33], v[96:99], v[14:17], v[120:123]
	v_mfma_f32_16x16x32_bf16 v[108:111], v[116:119], v[14:17], v[124:127]
	v_mfma_f32_16x16x32_bf16 v[120:123], v[150:153], v[14:17], v[132:135]
	v_mfma_f32_16x16x32_bf16 v[14:17], v[170:173], v[14:17], v[46:49]
	v_add_u32_e32 v220, 0x20000, v5
	global_load_dwordx4 v[46:49], v220, s[4:5] offset:256
	s_waitcnt vmcnt(8)
	ds_write_b128 v2, v[34:37] offset:57344
	v_mfma_f32_16x16x32_bf16 v[34:37], v[96:99], v[18:21], v[154:157]
	v_mfma_f32_16x16x32_bf16 v[124:127], v[116:119], v[18:21], v[158:161]
	v_mfma_f32_16x16x32_bf16 v[132:135], v[150:153], v[18:21], v[162:165]
	v_mfma_f32_16x16x32_bf16 v[18:21], v[170:173], v[18:21], v[58:61]
	v_add_u32_e32 v221, 0x30000, v5
	global_load_dwordx4 v[58:61], v221, s[4:5] offset:256
	s_waitcnt vmcnt(8)
	ds_write_b128 v2, v[38:41] offset:61440
	v_mfma_f32_16x16x32_bf16 v[38:41], v[96:99], v[22:25], v[50:53]
	v_mfma_f32_16x16x32_bf16 v[50:53], v[116:119], v[22:25], v[54:57]
	v_mfma_f32_16x16x32_bf16 v[54:57], v[150:153], v[22:25], v[84:87]
	v_mfma_f32_16x16x32_bf16 v[22:25], v[170:173], v[22:25], v[62:65]
	s_setprio 0
	s_waitcnt lgkmcnt(0)
	s_barrier
	ds_read_b128 v[62:65], v6 offset:32768
	ds_read_b128 v[84:87], v6 offset:34816
	ds_read_b128 v[96:99], v7 offset:49152
	ds_read_b128 v[116:119], v7 offset:51200
	ds_read_b128 v[150:153], v6 offset:36864
	ds_read_b128 v[154:157], v6 offset:38912
	ds_read_b128 v[158:161], v7 offset:53248
	ds_read_b128 v[162:165], v7 offset:55296
	s_setprio 2
	s_waitcnt lgkmcnt(5)
	v_mfma_f32_16x16x32_bf16 v[26:29], v[96:99], v[62:65], v[26:29]
	global_load_dwordx4 v[170:173], v8, s[36:37] offset:384
	s_waitcnt lgkmcnt(0)
	v_mfma_f32_16x16x32_bf16 v[10:13], v[162:165], v[62:65], v[10:13]
	s_waitcnt vmcnt(8)
	ds_write_b128 v2, v[92:95]
	v_mfma_f32_16x16x32_bf16 v[100:103], v[116:119], v[62:65], v[100:103]
	ds_read_b128 v[92:95], v3 offset:32768
	v_mfma_f32_16x16x32_bf16 v[104:107], v[158:161], v[62:65], v[104:107]
	ds_read_b128 v[174:177], v4 offset:49152
	global_load_dwordx4 v[62:65], v216, s[36:37] offset:384
	v_mfma_f32_16x16x32_bf16 v[30:33], v[96:99], v[84:87], v[30:33]
	s_waitcnt vmcnt(8)
	ds_write_b128 v2, v[112:115] offset:4096
	v_mfma_f32_16x16x32_bf16 v[14:17], v[162:165], v[84:87], v[14:17]
	ds_read_b128 v[112:115], v3 offset:34816
	v_mfma_f32_16x16x32_bf16 v[108:111], v[116:119], v[84:87], v[108:111]
	ds_read_b128 v[178:181], v4 offset:51200
	v_mfma_f32_16x16x32_bf16 v[120:123], v[158:161], v[84:87], v[120:123]
	global_load_dwordx4 v[84:87], v217, s[36:37] offset:384
	v_mfma_f32_16x16x32_bf16 v[34:37], v[96:99], v[150:153], v[34:37]
	s_waitcnt vmcnt(8)
	ds_write_b128 v2, v[146:149] offset:8192
	v_mfma_f32_16x16x32_bf16 v[18:21], v[162:165], v[150:153], v[18:21]
	ds_read_b128 v[146:149], v3 offset:36864
	v_mfma_f32_16x16x32_bf16 v[124:127], v[116:119], v[150:153], v[124:127]
	ds_read_b128 v[182:185], v4 offset:53248
	v_mfma_f32_16x16x32_bf16 v[132:135], v[158:161], v[150:153], v[132:135]
	global_load_dwordx4 v[150:153], v218, s[36:37] offset:384
	v_mfma_f32_16x16x32_bf16 v[38:41], v[96:99], v[154:157], v[38:41]
	s_waitcnt vmcnt(8)
	ds_write_b128 v2, v[166:169] offset:12288
	v_mfma_f32_16x16x32_bf16 v[50:53], v[116:119], v[154:157], v[50:53]
	ds_read_b128 v[166:169], v3 offset:38912
	v_mfma_f32_16x16x32_bf16 v[54:57], v[158:161], v[154:157], v[54:57]
	ds_read_b128 v[186:189], v4 offset:55296
	v_mfma_f32_16x16x32_bf16 v[22:25], v[162:165], v[154:157], v[22:25]
	global_load_dwordx4 v[96:99], v5, s[4:5] offset:384
	s_waitcnt vmcnt(8)
	ds_write_b128 v2, v[88:91] offset:16384
	s_waitcnt lgkmcnt(10)
	v_mfma_f32_16x16x32_bf16 v[26:29], v[174:177], v[92:95], v[26:29]
	s_waitcnt lgkmcnt(1)
	v_mfma_f32_16x16x32_bf16 v[10:13], v[186:189], v[92:95], v[10:13]
	v_mfma_f32_16x16x32_bf16 v[88:91], v[178:181], v[92:95], v[100:103]
	v_mfma_f32_16x16x32_bf16 v[100:103], v[182:185], v[92:95], v[104:107]
	global_load_dwordx4 v[92:95], v219, s[4:5] offset:384
	s_waitcnt vmcnt(8)
	ds_write_b128 v2, v[42:45] offset:20480
	v_mfma_f32_16x16x32_bf16 v[30:33], v[174:177], v[112:115], v[30:33]
	v_mfma_f32_16x16x32_bf16 v[42:45], v[178:181], v[112:115], v[108:111]
	v_mfma_f32_16x16x32_bf16 v[14:17], v[186:189], v[112:115], v[14:17]
	v_mfma_f32_16x16x32_bf16 v[104:107], v[182:185], v[112:115], v[120:123]
	global_load_dwordx4 v[108:111], v220, s[4:5] offset:384
	s_waitcnt vmcnt(8)
	ds_write_b128 v2, v[46:49] offset:24576
	v_mfma_f32_16x16x32_bf16 v[34:37], v[174:177], v[146:149], v[34:37]
	v_mfma_f32_16x16x32_bf16 v[46:49], v[178:181], v[146:149], v[124:127]
	v_mfma_f32_16x16x32_bf16 v[18:21], v[186:189], v[146:149], v[18:21]
	v_mfma_f32_16x16x32_bf16 v[112:115], v[182:185], v[146:149], v[132:135]
	global_load_dwordx4 v[116:119], v221, s[4:5] offset:384
	v_mfma_f32_16x16x32_bf16 v[38:41], v[174:177], v[166:169], v[38:41]
	s_waitcnt vmcnt(8)
	ds_write_b128 v2, v[58:61] offset:28672
	v_mfma_f32_16x16x32_bf16 v[50:53], v[178:181], v[166:169], v[50:53]
	v_mfma_f32_16x16x32_bf16 v[54:57], v[182:185], v[166:169], v[54:57]
	v_mfma_f32_16x16x32_bf16 v[22:25], v[186:189], v[166:169], v[22:25]
	s_setprio 0
	s_waitcnt lgkmcnt(0)
	s_barrier
; template <int MODE>
; __device__ __forceinline__ void gemm_tile(const Params& P, int tm, int tn, unsigned char* smem) {
;     ...
;     for (int kt = 0; kt < 16; ++kt) {
;         unsigned char* sA = (kt & 1) ? sA1 : sA0; unsigned char* sB = (kt & 1) ? sB1 : sB0;
;         unsigned char* nA = (kt & 1) ? sA0 : sA1; unsigned char* nB = (kt & 1) ? sB0 : sB1;
;         bf16x8 fa[4], fb[4], ga[4], gb[4];
;         const int ch0 = ((g ^ sw) << 4), ch1 = (((4 + g) ^ sw) << 4);
;         const unsigned ko = (unsigned)(kt + 2) * 128u;
;         const unsigned koa = ko + ((MODE == 2 && kt + 2 >= 8) ? (unsigned)(ZC_FQ - 512) * 2u : 0u);
;         const bool wr_ok = kt < 15, ld_ok = kt < 14;
; #pragma unroll
;         for (int i = 0; i < 4; ++i) { fa[i] = *(const bf16x8*)(sA + arow_off + i * 2048 + ch0); fb[i] = *(const bf16x8*)(sB + brow_off + i * 2048 + ch0); }
;         __builtin_amdgcn_sched_barrier(0);
;         __builtin_amdgcn_s_setprio(2);
;         if (wr_ok) *(uint4*)(nA + soff0) = ra0;
;         if (ld_ok) ra0 = *(const uint4*)(Ab + (aoff + 0u * LDA + koa));
;         ga[0] = *(const bf16x8*)(sA + arow_off + 0 * 2048 + ch1); gb[0] = *(const bf16x8*)(sB + brow_off + 0 * 2048 + ch1);
;         __builtin_amdgcn_sched_barrier(0);
; #pragma unroll
;         for (int j = 0; j < 4; ++j) acc[0][j] = __builtin_amdgcn_mfma_f32_16x16x32_bf16(fb[j], fa[0], acc[0][j], 0, 0, 0);
;         __builtin_amdgcn_sched_barrier(0);
;         if (wr_ok) *(uint4*)(nA + soff0 + 4096) = ra1;
;         if (ld_ok) ra1 = *(const uint4*)(Ab + (aoff + 32u * LDA + koa));
;         ga[1] = *(const bf16x8*)(sA + arow_off + 1 * 2048 + ch1); gb[1] = *(const bf16x8*)(sB + brow_off + 1 * 2048 + ch1);
;         __builtin_amdgcn_sched_barrier(0);
; #pragma unroll
;         for (int j = 0; j < 4; ++j) acc[1][j] = __builtin_amdgcn_mfma_f32_16x16x32_bf16(fb[j], fa[1], acc[1][j], 0, 0, 0);
;         __builtin_amdgcn_sched_barrier(0);
;         if (wr_ok) *(uint4*)(nA + soff0 + 8192) = ra2;
;         if (ld_ok) ra2 = *(const uint4*)(Ab + (aoff + 64u * LDA + koa));
;         ga[2] = *(const bf16x8*)(sA + arow_off + 2 * 2048 + ch1); gb[2] = *(const bf16x8*)(sB + brow_off + 2 * 2048 + ch1);
;         __builtin_amdgcn_sched_barrier(0);
; #pragma unroll
;         for (int j = 0; j < 4; ++j) acc[2][j] = __builtin_amdgcn_mfma_f32_16x16x32_bf16(fb[j], fa[2], acc[2][j], 0, 0, 0);
	ds_read_b128 v[58:61], v6
	ds_read_b128 v[120:123], v6 offset:2048
	ds_read_b128 v[124:127], v7 offset:16384
	ds_read_b128 v[132:135], v7 offset:18432
	ds_read_b128 v[146:149], v6 offset:4096
	ds_read_b128 v[154:157], v6 offset:6144
	ds_read_b128 v[158:161], v7 offset:20480
	ds_read_b128 v[162:165], v7 offset:22528
	s_setprio 2
	s_waitcnt lgkmcnt(5)
	v_mfma_f32_16x16x32_bf16 v[26:29], v[124:127], v[58:61], v[26:29]
	global_load_dwordx4 v[166:169], v8, s[36:37] offset:512
	s_waitcnt lgkmcnt(0)
	v_mfma_f32_16x16x32_bf16 v[10:13], v[162:165], v[58:61], v[10:13]
	s_waitcnt vmcnt(8)
	ds_write_b128 v2, v[170:173] offset:32768
	v_mfma_f32_16x16x32_bf16 v[88:91], v[132:135], v[58:61], v[88:91]
	ds_read_b128 v[170:173], v3
	v_mfma_f32_16x16x32_bf16 v[100:103], v[158:161], v[58:61], v[100:103]
	ds_read_b128 v[174:177], v4 offset:16384
	global_load_dwordx4 v[58:61], v216, s[36:37] offset:512
	v_mfma_f32_16x16x32_bf16 v[30:33], v[124:127], v[120:123], v[30:33]
	s_waitcnt vmcnt(8)
	ds_write_b128 v2, v[62:65] offset:36864
	v_mfma_f32_16x16x32_bf16 v[42:45], v[132:135], v[120:123], v[42:45]
	ds_read_b128 v[62:65], v3 offset:2048
	v_mfma_f32_16x16x32_bf16 v[14:17], v[162:165], v[120:123], v[14:17]
	ds_read_b128 v[178:181], v4 offset:18432
	v_mfma_f32_16x16x32_bf16 v[104:107], v[158:161], v[120:123], v[104:107]
	global_load_dwordx4 v[120:123], v217, s[36:37] offset:512
	v_mfma_f32_16x16x32_bf16 v[34:37], v[124:127], v[146:149], v[34:37]
	s_waitcnt vmcnt(8)
	ds_write_b128 v2, v[84:87] offset:40960
	v_mfma_f32_16x16x32_bf16 v[46:49], v[132:135], v[146:149], v[46:49]
	ds_read_b128 v[84:87], v3 offset:4096
	v_mfma_f32_16x16x32_bf16 v[18:21], v[162:165], v[146:149], v[18:21]
	ds_read_b128 v[182:185], v4 offset:20480
	v_mfma_f32_16x16x32_bf16 v[112:115], v[158:161], v[146:149], v[112:115]
	global_load_dwordx4 v[146:149], v218, s[36:37] offset:512
	v_mfma_f32_16x16x32_bf16 v[38:41], v[124:127], v[154:157], v[38:41]
	s_waitcnt vmcnt(8)
	ds_write_b128 v2, v[150:153] offset:45056
	v_mfma_f32_16x16x32_bf16 v[50:53], v[132:135], v[154:157], v[50:53]
	ds_read_b128 v[150:153], v3 offset:6144
	v_mfma_f32_16x16x32_bf16 v[54:57], v[158:161], v[154:157], v[54:57]
	ds_read_b128 v[186:189], v4 offset:22528
	v_mfma_f32_16x16x32_bf16 v[22:25], v[162:165], v[154:157], v[22:25]
	global_load_dwordx4 v[124:127], v5, s[4:5] offset:512
	s_waitcnt vmcnt(8)
	ds_write_b128 v2, v[96:99] offset:49152
	s_waitcnt lgkmcnt(10)
	v_mfma_f32_16x16x32_bf16 v[26:29], v[174:177], v[170:173], v[26:29]
	s_waitcnt lgkmcnt(1)
	v_mfma_f32_16x16x32_bf16 v[10:13], v[186:189], v[170:173], v[10:13]
	v_mfma_f32_16x16x32_bf16 v[88:91], v[178:181], v[170:173], v[88:91]
	v_mfma_f32_16x16x32_bf16 v[96:99], v[182:185], v[170:173], v[100:103]
	global_load_dwordx4 v[100:103], v219, s[4:5] offset:512
	s_waitcnt vmcnt(8)
	ds_write_b128 v2, v[92:95] offset:53248
	v_mfma_f32_16x16x32_bf16 v[30:33], v[174:177], v[62:65], v[30:33]
	v_mfma_f32_16x16x32_bf16 v[42:45], v[178:181], v[62:65], v[42:45]
	v_mfma_f32_16x16x32_bf16 v[14:17], v[186:189], v[62:65], v[14:17]
	v_mfma_f32_16x16x32_bf16 v[92:95], v[182:185], v[62:65], v[104:107]
	global_load_dwordx4 v[62:65], v220, s[4:5] offset:512
	v_mfma_f32_16x16x32_bf16 v[34:37], v[174:177], v[84:87], v[34:37]
	s_waitcnt vmcnt(8)
	ds_write_b128 v2, v[108:111] offset:57344
	v_mfma_f32_16x16x32_bf16 v[46:49], v[178:181], v[84:87], v[46:49]
	v_mfma_f32_16x16x32_bf16 v[18:21], v[186:189], v[84:87], v[18:21]
	v_mfma_f32_16x16x32_bf16 v[104:107], v[182:185], v[84:87], v[112:115]
	global_load_dwordx4 v[84:87], v221, s[4:5] offset:512
	v_mfma_f32_16x16x32_bf16 v[38:41], v[174:177], v[150:153], v[38:41]
	s_waitcnt vmcnt(8)
	ds_write_b128 v2, v[116:119] offset:61440
	v_mfma_f32_16x16x32_bf16 v[50:53], v[178:181], v[150:153], v[50:53]
	v_mfma_f32_16x16x32_bf16 v[54:57], v[182:185], v[150:153], v[54:57]
	v_mfma_f32_16x16x32_bf16 v[22:25], v[186:189], v[150:153], v[22:25]
	s_setprio 0
	s_waitcnt lgkmcnt(0)
	s_barrier
	ds_read_b128 v[108:111], v6 offset:32768
	ds_read_b128 v[112:115], v6 offset:34816
	ds_read_b128 v[116:119], v7 offset:49152
	ds_read_b128 v[132:135], v7 offset:51200
	ds_read_b128 v[150:153], v6 offset:36864
	ds_read_b128 v[154:157], v6 offset:38912
	ds_read_b128 v[158:161], v7 offset:53248
	ds_read_b128 v[162:165], v7 offset:55296
	s_setprio 2
	s_waitcnt lgkmcnt(5)
	v_mfma_f32_16x16x32_bf16 v[26:29], v[116:119], v[108:111], v[26:29]
	global_load_dwordx4 v[170:173], v8, s[36:37] offset:640
	s_waitcnt lgkmcnt(0)
	v_mfma_f32_16x16x32_bf16 v[10:13], v[162:165], v[108:111], v[10:13]
	s_waitcnt vmcnt(8)
	ds_write_b128 v2, v[166:169]
	v_mfma_f32_16x16x32_bf16 v[88:91], v[132:135], v[108:111], v[88:91]
	ds_read_b128 v[166:169], v3 offset:32768
	v_mfma_f32_16x16x32_bf16 v[96:99], v[158:161], v[108:111], v[96:99]
	ds_read_b128 v[174:177], v4 offset:49152
	global_load_dwordx4 v[108:111], v216, s[36:37] offset:640
	v_mfma_f32_16x16x32_bf16 v[30:33], v[116:119], v[112:115], v[30:33]
	s_waitcnt vmcnt(8)
	ds_write_b128 v2, v[58:61] offset:4096
	v_mfma_f32_16x16x32_bf16 v[42:45], v[132:135], v[112:115], v[42:45]
	ds_read_b128 v[58:61], v3 offset:34816
	v_mfma_f32_16x16x32_bf16 v[14:17], v[162:165], v[112:115], v[14:17]
	ds_read_b128 v[178:181], v4 offset:51200
	v_mfma_f32_16x16x32_bf16 v[92:95], v[158:161], v[112:115], v[92:95]
	global_load_dwordx4 v[112:115], v217, s[36:37] offset:640
	v_mfma_f32_16x16x32_bf16 v[34:37], v[116:119], v[150:153], v[34:37]
	s_waitcnt vmcnt(8)
; template <int MODE>
; __device__ __forceinline__ void gemm_tile(const Params& P, int tm, int tn, unsigned char* smem) {
;     ...
;     for (int kt = 0; kt < 16; ++kt) {
;         unsigned char* sA = (kt & 1) ? sA1 : sA0; unsigned char* sB = (kt & 1) ? sB1 : sB0;
;         unsigned char* nA = (kt & 1) ? sA0 : sA1; unsigned char* nB = (kt & 1) ? sB0 : sB1;
;         bf16x8 fa[4], fb[4], ga[4], gb[4];
;         const int ch0 = ((g ^ sw) << 4), ch1 = (((4 + g) ^ sw) << 4);
;         const unsigned ko = (unsigned)(kt + 2) * 128u;
;         const unsigned koa = ko + ((MODE == 2 && kt + 2 >= 8) ? (unsigned)(ZC_FQ - 512) * 2u : 0u);
;         const bool wr_ok = kt < 15, ld_ok = kt < 14;
; #pragma unroll
;         for (int i = 0; i < 4; ++i) { fa[i] = *(const bf16x8*)(sA + arow_off + i * 2048 + ch0); fb[i] = *(const bf16x8*)(sB + brow_off + i * 2048 + ch0); }
;         __builtin_amdgcn_sched_barrier(0);
;         __builtin_amdgcn_s_setprio(2);
;         if (wr_ok) *(uint4*)(nA + soff0) = ra0;
;         if (ld_ok) ra0 = *(const uint4*)(Ab + (aoff + 0u * LDA + koa));
;         ga[0] = *(const bf16x8*)(sA + arow_off + 0 * 2048 + ch1); gb[0] = *(const bf16x8*)(sB + brow_off + 0 * 2048 + ch1);
;         __builtin_amdgcn_sched_barrier(0);
; #pragma unroll
;         for (int j = 0; j < 4; ++j) acc[0][j] = __builtin_amdgcn_mfma_f32_16x16x32_bf16(fb[j], fa[0], acc[0][j], 0, 0, 0);
;         __builtin_amdgcn_sched_barrier(0);
;         if (wr_ok) *(uint4*)(nA + soff0 + 4096) = ra1;
;         if (ld_ok) ra1 = *(const uint4*)(Ab + (aoff + 32u * LDA + koa));
;         ga[1] = *(const bf16x8*)(sA + arow_off + 1 * 2048 + ch1); gb[1] = *(const bf16x8*)(sB + brow_off + 1 * 2048 + ch1);
;         __builtin_amdgcn_sched_barrier(0);
; #pragma unroll
;         for (int j = 0; j < 4; ++j) acc[1][j] = __builtin_amdgcn_mfma_f32_16x16x32_bf16(fb[j], fa[1], acc[1][j], 0, 0, 0);
;         __builtin_amdgcn_sched_barrier(0);
;         if (wr_ok) *(uint4*)(nA + soff0 + 8192) = ra2;
;         if (ld_ok) ra2 = *(const uint4*)(Ab + (aoff + 64u * LDA + koa));
;         ga[2] = *(const bf16x8*)(sA + arow_off + 2 * 2048 + ch1); gb[2] = *(const bf16x8*)(sB + brow_off + 2 * 2048 + ch1);
;         __builtin_amdgcn_sched_barrier(0);
; #pragma unroll
;         for (int j = 0; j < 4; ++j) acc[2][j] = __builtin_amdgcn_mfma_f32_16x16x32_bf16(fb[j], fa[2], acc[2][j], 0, 0, 0);
	ds_write_b128 v2, v[120:123] offset:8192
	v_mfma_f32_16x16x32_bf16 v[46:49], v[132:135], v[150:153], v[46:49]
	ds_read_b128 v[120:123], v3 offset:36864
	v_mfma_f32_16x16x32_bf16 v[18:21], v[162:165], v[150:153], v[18:21]
	ds_read_b128 v[182:185], v4 offset:53248
	v_mfma_f32_16x16x32_bf16 v[104:107], v[158:161], v[150:153], v[104:107]
	global_load_dwordx4 v[150:153], v218, s[36:37] offset:640
	v_mfma_f32_16x16x32_bf16 v[38:41], v[116:119], v[154:157], v[38:41]
	s_waitcnt vmcnt(8)
	ds_write_b128 v2, v[146:149] offset:12288
	v_mfma_f32_16x16x32_bf16 v[50:53], v[132:135], v[154:157], v[50:53]
	ds_read_b128 v[146:149], v3 offset:38912
	v_mfma_f32_16x16x32_bf16 v[54:57], v[158:161], v[154:157], v[54:57]
	ds_read_b128 v[186:189], v4 offset:55296
	v_mfma_f32_16x16x32_bf16 v[22:25], v[162:165], v[154:157], v[22:25]
	s_waitcnt lgkmcnt(9)
	v_mfma_f32_16x16x32_bf16 v[26:29], v[174:177], v[166:169], v[26:29]
	global_load_dwordx4 v[116:119], v5, s[4:5] offset:640
	s_waitcnt lgkmcnt(0)
	v_mfma_f32_16x16x32_bf16 v[10:13], v[186:189], v[166:169], v[10:13]
	s_waitcnt vmcnt(8)
	ds_write_b128 v2, v[124:127] offset:16384
	v_mfma_f32_16x16x32_bf16 v[88:91], v[178:181], v[166:169], v[88:91]
	v_mfma_f32_16x16x32_bf16 v[96:99], v[182:185], v[166:169], v[96:99]
	global_load_dwordx4 v[124:127], v219, s[4:5] offset:640
	v_mfma_f32_16x16x32_bf16 v[30:33], v[174:177], v[58:61], v[30:33]
	s_waitcnt vmcnt(8)
	ds_write_b128 v2, v[100:103] offset:20480
	v_mfma_f32_16x16x32_bf16 v[42:45], v[178:181], v[58:61], v[42:45]
	v_mfma_f32_16x16x32_bf16 v[14:17], v[186:189], v[58:61], v[14:17]
	v_mfma_f32_16x16x32_bf16 v[92:95], v[182:185], v[58:61], v[92:95]
	global_load_dwordx4 v[58:61], v220, s[4:5] offset:640
	s_waitcnt vmcnt(8)
	ds_write_b128 v2, v[62:65] offset:24576
	v_mfma_f32_16x16x32_bf16 v[34:37], v[174:177], v[120:123], v[34:37]
	v_mfma_f32_16x16x32_bf16 v[46:49], v[178:181], v[120:123], v[46:49]
	v_mfma_f32_16x16x32_bf16 v[62:65], v[182:185], v[120:123], v[104:107]
	v_mfma_f32_16x16x32_bf16 v[18:21], v[186:189], v[120:123], v[18:21]
	global_load_dwordx4 v[100:103], v221, s[4:5] offset:640
	v_mfma_f32_16x16x32_bf16 v[38:41], v[174:177], v[146:149], v[38:41]
	s_waitcnt vmcnt(8)
	ds_write_b128 v2, v[84:87] offset:28672
	v_mfma_f32_16x16x32_bf16 v[50:53], v[178:181], v[146:149], v[50:53]
	v_mfma_f32_16x16x32_bf16 v[54:57], v[182:185], v[146:149], v[54:57]
	v_mfma_f32_16x16x32_bf16 v[22:25], v[186:189], v[146:149], v[22:25]
	s_setprio 0
	s_waitcnt lgkmcnt(0)
	s_barrier
	ds_read_b128 v[84:87], v6
	ds_read_b128 v[104:107], v6 offset:2048
	ds_read_b128 v[120:123], v7 offset:16384
	ds_read_b128 v[132:135], v7 offset:18432
	ds_read_b128 v[146:149], v6 offset:4096
	ds_read_b128 v[154:157], v6 offset:6144
	ds_read_b128 v[158:161], v7 offset:20480
	ds_read_b128 v[162:165], v7 offset:22528
	s_setprio 2
	s_waitcnt lgkmcnt(5)
	v_mfma_f32_16x16x32_bf16 v[26:29], v[120:123], v[84:87], v[26:29]
	global_load_dwordx4 v[166:169], v8, s[36:37] offset:768
	s_waitcnt lgkmcnt(0)
	v_mfma_f32_16x16x32_bf16 v[10:13], v[162:165], v[84:87], v[10:13]
	s_waitcnt vmcnt(8)
	ds_write_b128 v2, v[170:173] offset:32768
	v_mfma_f32_16x16x32_bf16 v[88:91], v[132:135], v[84:87], v[88:91]
	ds_read_b128 v[170:173], v3
	v_mfma_f32_16x16x32_bf16 v[96:99], v[158:161], v[84:87], v[96:99]
	ds_read_b128 v[174:177], v4 offset:16384
	global_load_dwordx4 v[84:87], v216, s[36:37] offset:768
	v_mfma_f32_16x16x32_bf16 v[30:33], v[120:123], v[104:107], v[30:33]
	s_waitcnt vmcnt(8)
	ds_write_b128 v2, v[108:111] offset:36864
	v_mfma_f32_16x16x32_bf16 v[42:45], v[132:135], v[104:107], v[42:45]
	ds_read_b128 v[108:111], v3 offset:2048
	v_mfma_f32_16x16x32_bf16 v[14:17], v[162:165], v[104:107], v[14:17]
	ds_read_b128 v[178:181], v4 offset:18432
	v_mfma_f32_16x16x32_bf16 v[92:95], v[158:161], v[104:107], v[92:95]
	global_load_dwordx4 v[104:107], v217, s[36:37] offset:768
	v_mfma_f32_16x16x32_bf16 v[34:37], v[120:123], v[146:149], v[34:37]
	s_waitcnt vmcnt(8)
	ds_write_b128 v2, v[112:115] offset:40960
	v_mfma_f32_16x16x32_bf16 v[46:49], v[132:135], v[146:149], v[46:49]
	ds_read_b128 v[112:115], v3 offset:4096
	v_mfma_f32_16x16x32_bf16 v[62:65], v[158:161], v[146:149], v[62:65]
	ds_read_b128 v[182:185], v4 offset:20480
	v_mfma_f32_16x16x32_bf16 v[18:21], v[162:165], v[146:149], v[18:21]
	global_load_dwordx4 v[146:149], v218, s[36:37] offset:768
	v_mfma_f32_16x16x32_bf16 v[38:41], v[120:123], v[154:157], v[38:41]
	s_waitcnt vmcnt(8)
	ds_write_b128 v2, v[150:153] offset:45056
	v_mfma_f32_16x16x32_bf16 v[50:53], v[132:135], v[154:157], v[50:53]
	ds_read_b128 v[150:153], v3 offset:6144
	v_mfma_f32_16x16x32_bf16 v[54:57], v[158:161], v[154:157], v[54:57]
	ds_read_b128 v[186:189], v4 offset:22528
	v_mfma_f32_16x16x32_bf16 v[22:25], v[162:165], v[154:157], v[22:25]
	s_waitcnt lgkmcnt(9)
	v_mfma_f32_16x16x32_bf16 v[26:29], v[174:177], v[170:173], v[26:29]
	global_load_dwordx4 v[120:123], v5, s[4:5] offset:768
	s_waitcnt lgkmcnt(0)
	v_mfma_f32_16x16x32_bf16 v[10:13], v[186:189], v[170:173], v[10:13]
	s_waitcnt vmcnt(8)
	ds_write_b128 v2, v[116:119] offset:49152
	v_mfma_f32_16x16x32_bf16 v[88:91], v[178:181], v[170:173], v[88:91]
	v_mfma_f32_16x16x32_bf16 v[96:99], v[182:185], v[170:173], v[96:99]
	global_load_dwordx4 v[116:119], v219, s[4:5] offset:768
	v_mfma_f32_16x16x32_bf16 v[30:33], v[174:177], v[108:111], v[30:33]
	s_waitcnt vmcnt(8)
	ds_write_b128 v2, v[124:127] offset:53248
	v_mfma_f32_16x16x32_bf16 v[42:45], v[178:181], v[108:111], v[42:45]
	v_mfma_f32_16x16x32_bf16 v[14:17], v[186:189], v[108:111], v[14:17]
	v_mfma_f32_16x16x32_bf16 v[92:95], v[182:185], v[108:111], v[92:95]
	global_load_dwordx4 v[108:111], v220, s[4:5] offset:768
	s_waitcnt vmcnt(8)
	ds_write_b128 v2, v[58:61] offset:57344
	v_mfma_f32_16x16x32_bf16 v[34:37], v[174:177], v[112:115], v[34:37]
	v_mfma_f32_16x16x32_bf16 v[46:49], v[178:181], v[112:115], v[46:49]
	v_mfma_f32_16x16x32_bf16 v[58:61], v[182:185], v[112:115], v[62:65]
	v_mfma_f32_16x16x32_bf16 v[18:21], v[186:189], v[112:115], v[18:21]
	global_load_dwordx4 v[62:65], v221, s[4:5] offset:768
	v_mfma_f32_16x16x32_bf16 v[38:41], v[174:177], v[150:153], v[38:41]
	s_waitcnt vmcnt(8)
	ds_write_b128 v2, v[100:103] offset:61440
	v_mfma_f32_16x16x32_bf16 v[50:53], v[178:181], v[150:153], v[50:53]
	v_mfma_f32_16x16x32_bf16 v[54:57], v[182:185], v[150:153], v[54:57]
	v_mfma_f32_16x16x32_bf16 v[22:25], v[186:189], v[150:153], v[22:25]
	s_setprio 0
	s_waitcnt lgkmcnt(0)
	s_barrier
; template <int MODE>
; __device__ __forceinline__ void gemm_tile(const Params& P, int tm, int tn, unsigned char* smem) {
;     ...
;     for (int kt = 0; kt < 16; ++kt) {
;         unsigned char* sA = (kt & 1) ? sA1 : sA0; unsigned char* sB = (kt & 1) ? sB1 : sB0;
;         unsigned char* nA = (kt & 1) ? sA0 : sA1; unsigned char* nB = (kt & 1) ? sB0 : sB1;
;         bf16x8 fa[4], fb[4], ga[4], gb[4];
;         const int ch0 = ((g ^ sw) << 4), ch1 = (((4 + g) ^ sw) << 4);
;         const unsigned ko = (unsigned)(kt + 2) * 128u;
;         const unsigned koa = ko + ((MODE == 2 && kt + 2 >= 8) ? (unsigned)(ZC_FQ - 512) * 2u : 0u);
;         const bool wr_ok = kt < 15, ld_ok = kt < 14;
; #pragma unroll
;         for (int i = 0; i < 4; ++i) { fa[i] = *(const bf16x8*)(sA + arow_off + i * 2048 + ch0); fb[i] = *(const bf16x8*)(sB + brow_off + i * 2048 + ch0); }
;         __builtin_amdgcn_sched_barrier(0);
;         __builtin_amdgcn_s_setprio(2);
;         if (wr_ok) *(uint4*)(nA + soff0) = ra0;
;         if (ld_ok) ra0 = *(const uint4*)(Ab + (aoff + 0u * LDA + koa));
;         ga[0] = *(const bf16x8*)(sA + arow_off + 0 * 2048 + ch1); gb[0] = *(const bf16x8*)(sB + brow_off + 0 * 2048 + ch1);
;         __builtin_amdgcn_sched_barrier(0);
; #pragma unroll
;         for (int j = 0; j < 4; ++j) acc[0][j] = __builtin_amdgcn_mfma_f32_16x16x32_bf16(fb[j], fa[0], acc[0][j], 0, 0, 0);
;         __builtin_amdgcn_sched_barrier(0);
;         if (wr_ok) *(uint4*)(nA + soff0 + 4096) = ra1;
;         if (ld_ok) ra1 = *(const uint4*)(Ab + (aoff + 32u * LDA + koa));
;         ga[1] = *(const bf16x8*)(sA + arow_off + 1 * 2048 + ch1); gb[1] = *(const bf16x8*)(sB + brow_off + 1 * 2048 + ch1);
;         __builtin_amdgcn_sched_barrier(0);
; #pragma unroll
;         for (int j = 0; j < 4; ++j) acc[1][j] = __builtin_amdgcn_mfma_f32_16x16x32_bf16(fb[j], fa[1], acc[1][j], 0, 0, 0);
;         __builtin_amdgcn_sched_barrier(0);
;         if (wr_ok) *(uint4*)(nA + soff0 + 8192) = ra2;
;         if (ld_ok) ra2 = *(const uint4*)(Ab + (aoff + 64u * LDA + koa));
;         ga[2] = *(const bf16x8*)(sA + arow_off + 2 * 2048 + ch1); gb[2] = *(const bf16x8*)(sB + brow_off + 2 * 2048 + ch1);
;         __builtin_amdgcn_sched_barrier(0);
; #pragma unroll
;         for (int j = 0; j < 4; ++j) acc[2][j] = __builtin_amdgcn_mfma_f32_16x16x32_bf16(fb[j], fa[2], acc[2][j], 0, 0, 0);
	ds_read_b128 v[100:103], v6 offset:32768
	ds_read_b128 v[112:115], v6 offset:34816
	ds_read_b128 v[124:127], v7 offset:49152
	ds_read_b128 v[132:135], v7 offset:51200
	ds_read_b128 v[150:153], v6 offset:36864
	ds_read_b128 v[154:157], v6 offset:38912
	ds_read_b128 v[158:161], v7 offset:53248
	ds_read_b128 v[162:165], v7 offset:55296
	s_setprio 2
	s_waitcnt lgkmcnt(5)
	v_mfma_f32_16x16x32_bf16 v[26:29], v[124:127], v[100:103], v[26:29]
	global_load_dwordx4 v[170:173], v8, s[36:37] offset:896
	s_waitcnt lgkmcnt(0)
	v_mfma_f32_16x16x32_bf16 v[10:13], v[162:165], v[100:103], v[10:13]
	s_waitcnt vmcnt(8)
	ds_write_b128 v2, v[166:169]
	v_mfma_f32_16x16x32_bf16 v[88:91], v[132:135], v[100:103], v[88:91]
	ds_read_b128 v[166:169], v3 offset:32768
	v_mfma_f32_16x16x32_bf16 v[96:99], v[158:161], v[100:103], v[96:99]
	ds_read_b128 v[174:177], v4 offset:49152
	global_load_dwordx4 v[100:103], v216, s[36:37] offset:896
	v_mfma_f32_16x16x32_bf16 v[30:33], v[124:127], v[112:115], v[30:33]
	s_waitcnt vmcnt(8)
	ds_write_b128 v2, v[84:87] offset:4096
	v_mfma_f32_16x16x32_bf16 v[42:45], v[132:135], v[112:115], v[42:45]
	ds_read_b128 v[84:87], v3 offset:34816
	v_mfma_f32_16x16x32_bf16 v[14:17], v[162:165], v[112:115], v[14:17]
	ds_read_b128 v[178:181], v4 offset:51200
	v_mfma_f32_16x16x32_bf16 v[92:95], v[158:161], v[112:115], v[92:95]
	global_load_dwordx4 v[112:115], v217, s[36:37] offset:896
	v_mfma_f32_16x16x32_bf16 v[34:37], v[124:127], v[150:153], v[34:37]
	s_waitcnt vmcnt(8)
	ds_write_b128 v2, v[104:107] offset:8192
	v_mfma_f32_16x16x32_bf16 v[46:49], v[132:135], v[150:153], v[46:49]
	ds_read_b128 v[104:107], v3 offset:36864
	v_mfma_f32_16x16x32_bf16 v[58:61], v[158:161], v[150:153], v[58:61]
	ds_read_b128 v[182:185], v4 offset:53248
	v_mfma_f32_16x16x32_bf16 v[18:21], v[162:165], v[150:153], v[18:21]
	global_load_dwordx4 v[150:153], v218, s[36:37] offset:896
	v_mfma_f32_16x16x32_bf16 v[38:41], v[124:127], v[154:157], v[38:41]
	s_waitcnt vmcnt(8)
	ds_write_b128 v2, v[146:149] offset:12288
	v_mfma_f32_16x16x32_bf16 v[50:53], v[132:135], v[154:157], v[50:53]
	ds_read_b128 v[146:149], v3 offset:38912
	v_mfma_f32_16x16x32_bf16 v[54:57], v[158:161], v[154:157], v[54:57]
	ds_read_b128 v[186:189], v4 offset:55296
	v_mfma_f32_16x16x32_bf16 v[22:25], v[162:165], v[154:157], v[22:25]
	s_waitcnt lgkmcnt(9)
	v_mfma_f32_16x16x32_bf16 v[26:29], v[174:177], v[166:169], v[26:29]
	global_load_dwordx4 v[124:127], v5, s[4:5] offset:896
	s_waitcnt lgkmcnt(0)
	v_mfma_f32_16x16x32_bf16 v[10:13], v[186:189], v[166:169], v[10:13]
	s_waitcnt vmcnt(8)
	ds_write_b128 v2, v[120:123] offset:16384
	v_mfma_f32_16x16x32_bf16 v[88:91], v[178:181], v[166:169], v[88:91]
	v_mfma_f32_16x16x32_bf16 v[96:99], v[182:185], v[166:169], v[96:99]
	global_load_dwordx4 v[120:123], v219, s[4:5] offset:896
	v_mfma_f32_16x16x32_bf16 v[30:33], v[174:177], v[84:87], v[30:33]
	s_waitcnt vmcnt(8)
	ds_write_b128 v2, v[116:119] offset:20480
	v_mfma_f32_16x16x32_bf16 v[42:45], v[178:181], v[84:87], v[42:45]
	v_mfma_f32_16x16x32_bf16 v[14:17], v[186:189], v[84:87], v[14:17]
	v_mfma_f32_16x16x32_bf16 v[92:95], v[182:185], v[84:87], v[92:95]
	global_load_dwordx4 v[84:87], v220, s[4:5] offset:896
	v_mfma_f32_16x16x32_bf16 v[34:37], v[174:177], v[104:107], v[34:37]
	s_waitcnt vmcnt(8)
	ds_write_b128 v2, v[108:111] offset:24576
	v_mfma_f32_16x16x32_bf16 v[46:49], v[178:181], v[104:107], v[46:49]
	v_mfma_f32_16x16x32_bf16 v[58:61], v[182:185], v[104:107], v[58:61]
	v_mfma_f32_16x16x32_bf16 v[18:21], v[186:189], v[104:107], v[18:21]
	global_load_dwordx4 v[104:107], v221, s[4:5] offset:896
	v_mfma_f32_16x16x32_bf16 v[38:41], v[174:177], v[146:149], v[38:41]
	s_waitcnt vmcnt(8)
	ds_write_b128 v2, v[62:65] offset:28672
	v_mfma_f32_16x16x32_bf16 v[50:53], v[178:181], v[146:149], v[50:53]
	v_mfma_f32_16x16x32_bf16 v[54:57], v[182:185], v[146:149], v[54:57]
	v_mfma_f32_16x16x32_bf16 v[22:25], v[186:189], v[146:149], v[22:25]
	s_setprio 0
	s_waitcnt lgkmcnt(0)
	s_barrier
	ds_read_b128 v[62:65], v6
	ds_read_b128 v[108:111], v6 offset:2048
	ds_read_b128 v[116:119], v7 offset:16384
	ds_read_b128 v[132:135], v7 offset:18432
	ds_read_b128 v[146:149], v6 offset:4096
	ds_read_b128 v[154:157], v6 offset:6144
	ds_read_b128 v[158:161], v7 offset:20480
	ds_read_b128 v[162:165], v7 offset:22528
	s_setprio 2
	s_waitcnt lgkmcnt(5)
	v_mfma_f32_16x16x32_bf16 v[26:29], v[116:119], v[62:65], v[26:29]
	global_load_dwordx4 v[166:169], v8, s[36:37] offset:1024
	s_waitcnt lgkmcnt(0)
	v_mfma_f32_16x16x32_bf16 v[10:13], v[162:165], v[62:65], v[10:13]
	s_waitcnt vmcnt(8)
	ds_write_b128 v2, v[170:173] offset:32768
	v_mfma_f32_16x16x32_bf16 v[88:91], v[132:135], v[62:65], v[88:91]
	ds_read_b128 v[170:173], v3
	v_mfma_f32_16x16x32_bf16 v[96:99], v[158:161], v[62:65], v[96:99]
	ds_read_b128 v[174:177], v4 offset:16384
	global_load_dwordx4 v[62:65], v216, s[36:37] offset:1024
	v_mfma_f32_16x16x32_bf16 v[30:33], v[116:119], v[108:111], v[30:33]
	s_waitcnt vmcnt(8)
	ds_write_b128 v2, v[100:103] offset:36864
	v_mfma_f32_16x16x32_bf16 v[42:45], v[132:135], v[108:111], v[42:45]
	ds_read_b128 v[100:103], v3 offset:2048
	v_mfma_f32_16x16x32_bf16 v[14:17], v[162:165], v[108:111], v[14:17]
	ds_read_b128 v[178:181], v4 offset:18432
	v_mfma_f32_16x16x32_bf16 v[92:95], v[158:161], v[108:111], v[92:95]
	global_load_dwordx4 v[108:111], v217, s[36:37] offset:1024
	v_mfma_f32_16x16x32_bf16 v[34:37], v[116:119], v[146:149], v[34:37]
	s_waitcnt vmcnt(8)
; template <int MODE>
; __device__ __forceinline__ void gemm_tile(const Params& P, int tm, int tn, unsigned char* smem) {
;     ...
;     for (int kt = 0; kt < 16; ++kt) {
;         unsigned char* sA = (kt & 1) ? sA1 : sA0; unsigned char* sB = (kt & 1) ? sB1 : sB0;
;         unsigned char* nA = (kt & 1) ? sA0 : sA1; unsigned char* nB = (kt & 1) ? sB0 : sB1;
;         bf16x8 fa[4], fb[4], ga[4], gb[4];
;         const int ch0 = ((g ^ sw) << 4), ch1 = (((4 + g) ^ sw) << 4);
;         const unsigned ko = (unsigned)(kt + 2) * 128u;
;         const unsigned koa = ko + ((MODE == 2 && kt + 2 >= 8) ? (unsigned)(ZC_FQ - 512) * 2u : 0u);
;         const bool wr_ok = kt < 15, ld_ok = kt < 14;
; #pragma unroll
;         for (int i = 0; i < 4; ++i) { fa[i] = *(const bf16x8*)(sA + arow_off + i * 2048 + ch0); fb[i] = *(const bf16x8*)(sB + brow_off + i * 2048 + ch0); }
;         __builtin_amdgcn_sched_barrier(0);
;         __builtin_amdgcn_s_setprio(2);
;         if (wr_ok) *(uint4*)(nA + soff0) = ra0;
;         if (ld_ok) ra0 = *(const uint4*)(Ab + (aoff + 0u * LDA + koa));
;         ga[0] = *(const bf16x8*)(sA + arow_off + 0 * 2048 + ch1); gb[0] = *(const bf16x8*)(sB + brow_off + 0 * 2048 + ch1);
;         __builtin_amdgcn_sched_barrier(0);
; #pragma unroll
;         for (int j = 0; j < 4; ++j) acc[0][j] = __builtin_amdgcn_mfma_f32_16x16x32_bf16(fb[j], fa[0], acc[0][j], 0, 0, 0);
;         __builtin_amdgcn_sched_barrier(0);
;         if (wr_ok) *(uint4*)(nA + soff0 + 4096) = ra1;
;         if (ld_ok) ra1 = *(const uint4*)(Ab + (aoff + 32u * LDA + koa));
;         ga[1] = *(const bf16x8*)(sA + arow_off + 1 * 2048 + ch1); gb[1] = *(const bf16x8*)(sB + brow_off + 1 * 2048 + ch1);
;         __builtin_amdgcn_sched_barrier(0);
; #pragma unroll
;         for (int j = 0; j < 4; ++j) acc[1][j] = __builtin_amdgcn_mfma_f32_16x16x32_bf16(fb[j], fa[1], acc[1][j], 0, 0, 0);
;         __builtin_amdgcn_sched_barrier(0);
;         if (wr_ok) *(uint4*)(nA + soff0 + 8192) = ra2;
;         if (ld_ok) ra2 = *(const uint4*)(Ab + (aoff + 64u * LDA + koa));
;         ga[2] = *(const bf16x8*)(sA + arow_off + 2 * 2048 + ch1); gb[2] = *(const bf16x8*)(sB + brow_off + 2 * 2048 + ch1);
;         __builtin_amdgcn_sched_barrier(0);
; #pragma unroll
;         for (int j = 0; j < 4; ++j) acc[2][j] = __builtin_amdgcn_mfma_f32_16x16x32_bf16(fb[j], fa[2], acc[2][j], 0, 0, 0);
	ds_write_b128 v2, v[112:115] offset:40960
	v_mfma_f32_16x16x32_bf16 v[46:49], v[132:135], v[146:149], v[46:49]
	ds_read_b128 v[112:115], v3 offset:4096
	v_mfma_f32_16x16x32_bf16 v[58:61], v[158:161], v[146:149], v[58:61]
	ds_read_b128 v[182:185], v4 offset:20480
	v_mfma_f32_16x16x32_bf16 v[18:21], v[162:165], v[146:149], v[18:21]
	global_load_dwordx4 v[146:149], v218, s[36:37] offset:1024
	v_mfma_f32_16x16x32_bf16 v[38:41], v[116:119], v[154:157], v[38:41]
	s_waitcnt vmcnt(8)
	ds_write_b128 v2, v[150:153] offset:45056
	v_mfma_f32_16x16x32_bf16 v[50:53], v[132:135], v[154:157], v[50:53]
	ds_read_b128 v[150:153], v3 offset:6144
	v_mfma_f32_16x16x32_bf16 v[54:57], v[158:161], v[154:157], v[54:57]
	ds_read_b128 v[186:189], v4 offset:22528
	v_mfma_f32_16x16x32_bf16 v[22:25], v[162:165], v[154:157], v[22:25]
	s_waitcnt lgkmcnt(9)
	v_mfma_f32_16x16x32_bf16 v[26:29], v[174:177], v[170:173], v[26:29]
	global_load_dwordx4 v[116:119], v5, s[4:5] offset:1024
	s_waitcnt lgkmcnt(0)
	v_mfma_f32_16x16x32_bf16 v[10:13], v[186:189], v[170:173], v[10:13]
	s_waitcnt vmcnt(8)
	ds_write_b128 v2, v[124:127] offset:49152
	v_mfma_f32_16x16x32_bf16 v[88:91], v[178:181], v[170:173], v[88:91]
	v_mfma_f32_16x16x32_bf16 v[96:99], v[182:185], v[170:173], v[96:99]
	global_load_dwordx4 v[124:127], v219, s[4:5] offset:1024
	v_mfma_f32_16x16x32_bf16 v[30:33], v[174:177], v[100:103], v[30:33]
	s_waitcnt vmcnt(8)
	ds_write_b128 v2, v[120:123] offset:53248
	v_mfma_f32_16x16x32_bf16 v[42:45], v[178:181], v[100:103], v[42:45]
	v_mfma_f32_16x16x32_bf16 v[14:17], v[186:189], v[100:103], v[14:17]
	v_mfma_f32_16x16x32_bf16 v[92:95], v[182:185], v[100:103], v[92:95]
	global_load_dwordx4 v[100:103], v220, s[4:5] offset:1024
	v_mfma_f32_16x16x32_bf16 v[34:37], v[174:177], v[112:115], v[34:37]
	s_waitcnt vmcnt(8)
	ds_write_b128 v2, v[84:87] offset:57344
	v_mfma_f32_16x16x32_bf16 v[46:49], v[178:181], v[112:115], v[46:49]
	v_mfma_f32_16x16x32_bf16 v[58:61], v[182:185], v[112:115], v[58:61]
	v_mfma_f32_16x16x32_bf16 v[18:21], v[186:189], v[112:115], v[18:21]
	global_load_dwordx4 v[84:87], v221, s[4:5] offset:1024
	v_mfma_f32_16x16x32_bf16 v[38:41], v[174:177], v[150:153], v[38:41]
	s_waitcnt vmcnt(8)
	ds_write_b128 v2, v[104:107] offset:61440
	v_mfma_f32_16x16x32_bf16 v[50:53], v[178:181], v[150:153], v[50:53]
	v_mfma_f32_16x16x32_bf16 v[54:57], v[182:185], v[150:153], v[54:57]
	v_mfma_f32_16x16x32_bf16 v[22:25], v[186:189], v[150:153], v[22:25]
	s_setprio 0
	s_waitcnt lgkmcnt(0)
	s_barrier
	ds_read_b128 v[104:107], v6 offset:32768
	ds_read_b128 v[112:115], v6 offset:34816
	ds_read_b128 v[120:123], v7 offset:49152
	ds_read_b128 v[132:135], v7 offset:51200
	ds_read_b128 v[150:153], v6 offset:36864
	ds_read_b128 v[154:157], v6 offset:38912
	ds_read_b128 v[158:161], v7 offset:53248
	ds_read_b128 v[162:165], v7 offset:55296
	s_setprio 2
	s_waitcnt lgkmcnt(5)
	v_mfma_f32_16x16x32_bf16 v[26:29], v[120:123], v[104:107], v[26:29]
	global_load_dwordx4 v[170:173], v8, s[36:37] offset:1152
	s_waitcnt lgkmcnt(0)
	v_mfma_f32_16x16x32_bf16 v[10:13], v[162:165], v[104:107], v[10:13]
	s_waitcnt vmcnt(8)
	ds_write_b128 v2, v[166:169]
	v_mfma_f32_16x16x32_bf16 v[88:91], v[132:135], v[104:107], v[88:91]
	ds_read_b128 v[166:169], v3 offset:32768
	v_mfma_f32_16x16x32_bf16 v[96:99], v[158:161], v[104:107], v[96:99]
	ds_read_b128 v[174:177], v4 offset:49152
	global_load_dwordx4 v[104:107], v216, s[36:37] offset:1152
	v_mfma_f32_16x16x32_bf16 v[30:33], v[120:123], v[112:115], v[30:33]
	s_waitcnt vmcnt(8)
	ds_write_b128 v2, v[62:65] offset:4096
	v_mfma_f32_16x16x32_bf16 v[42:45], v[132:135], v[112:115], v[42:45]
	ds_read_b128 v[62:65], v3 offset:34816
	v_mfma_f32_16x16x32_bf16 v[14:17], v[162:165], v[112:115], v[14:17]
	ds_read_b128 v[178:181], v4 offset:51200
	v_mfma_f32_16x16x32_bf16 v[92:95], v[158:161], v[112:115], v[92:95]
	global_load_dwordx4 v[112:115], v217, s[36:37] offset:1152
	v_mfma_f32_16x16x32_bf16 v[34:37], v[120:123], v[150:153], v[34:37]
	s_waitcnt vmcnt(8)
	ds_write_b128 v2, v[108:111] offset:8192
	v_mfma_f32_16x16x32_bf16 v[46:49], v[132:135], v[150:153], v[46:49]
	ds_read_b128 v[108:111], v3 offset:36864
	v_mfma_f32_16x16x32_bf16 v[58:61], v[158:161], v[150:153], v[58:61]
	ds_read_b128 v[182:185], v4 offset:53248
	v_mfma_f32_16x16x32_bf16 v[18:21], v[162:165], v[150:153], v[18:21]
	global_load_dwordx4 v[150:153], v218, s[36:37] offset:1152
	v_mfma_f32_16x16x32_bf16 v[38:41], v[120:123], v[154:157], v[38:41]
	s_waitcnt vmcnt(8)
	ds_write_b128 v2, v[146:149] offset:12288
	v_mfma_f32_16x16x32_bf16 v[50:53], v[132:135], v[154:157], v[50:53]
	ds_read_b128 v[146:149], v3 offset:38912
	v_mfma_f32_16x16x32_bf16 v[54:57], v[158:161], v[154:157], v[54:57]
	ds_read_b128 v[186:189], v4 offset:55296
	v_mfma_f32_16x16x32_bf16 v[22:25], v[162:165], v[154:157], v[22:25]
	s_waitcnt lgkmcnt(9)
	v_mfma_f32_16x16x32_bf16 v[26:29], v[174:177], v[166:169], v[26:29]
	global_load_dwordx4 v[120:123], v5, s[4:5] offset:1152
	s_waitcnt lgkmcnt(0)
	v_mfma_f32_16x16x32_bf16 v[10:13], v[186:189], v[166:169], v[10:13]
	s_waitcnt vmcnt(8)
	ds_write_b128 v2, v[116:119] offset:16384
	v_mfma_f32_16x16x32_bf16 v[88:91], v[178:181], v[166:169], v[88:91]
	v_mfma_f32_16x16x32_bf16 v[96:99], v[182:185], v[166:169], v[96:99]
	global_load_dwordx4 v[116:119], v219, s[4:5] offset:1152
	v_mfma_f32_16x16x32_bf16 v[30:33], v[174:177], v[62:65], v[30:33]
	s_waitcnt vmcnt(8)
	ds_write_b128 v2, v[124:127] offset:20480
	v_mfma_f32_16x16x32_bf16 v[42:45], v[178:181], v[62:65], v[42:45]
	v_mfma_f32_16x16x32_bf16 v[14:17], v[186:189], v[62:65], v[14:17]
	v_mfma_f32_16x16x32_bf16 v[92:95], v[182:185], v[62:65], v[92:95]
	global_load_dwordx4 v[62:65], v220, s[4:5] offset:1152
	v_mfma_f32_16x16x32_bf16 v[34:37], v[174:177], v[108:111], v[34:37]
	s_waitcnt vmcnt(8)
	ds_write_b128 v2, v[100:103] offset:24576
	v_mfma_f32_16x16x32_bf16 v[46:49], v[178:181], v[108:111], v[46:49]
	v_mfma_f32_16x16x32_bf16 v[58:61], v[182:185], v[108:111], v[58:61]
	v_mfma_f32_16x16x32_bf16 v[18:21], v[186:189], v[108:111], v[18:21]
	global_load_dwordx4 v[100:103], v221, s[4:5] offset:1152
	v_mfma_f32_16x16x32_bf16 v[38:41], v[174:177], v[146:149], v[38:41]
	s_waitcnt vmcnt(8)
	ds_write_b128 v2, v[84:87] offset:28672
	v_mfma_f32_16x16x32_bf16 v[50:53], v[178:181], v[146:149], v[50:53]
	v_mfma_f32_16x16x32_bf16 v[54:57], v[182:185], v[146:149], v[54:57]
	v_mfma_f32_16x16x32_bf16 v[22:25], v[186:189], v[146:149], v[22:25]
	s_setprio 0
	s_waitcnt lgkmcnt(0)
	s_barrier
; template <int MODE>
; __device__ __forceinline__ void gemm_tile(const Params& P, int tm, int tn, unsigned char* smem) {
;     ...
;     for (int kt = 0; kt < 16; ++kt) {
;         unsigned char* sA = (kt & 1) ? sA1 : sA0; unsigned char* sB = (kt & 1) ? sB1 : sB0;
;         unsigned char* nA = (kt & 1) ? sA0 : sA1; unsigned char* nB = (kt & 1) ? sB0 : sB1;
;         bf16x8 fa[4], fb[4], ga[4], gb[4];
;         const int ch0 = ((g ^ sw) << 4), ch1 = (((4 + g) ^ sw) << 4);
;         const unsigned ko = (unsigned)(kt + 2) * 128u;
;         const unsigned koa = ko + ((MODE == 2 && kt + 2 >= 8) ? (unsigned)(ZC_FQ - 512) * 2u : 0u);
;         const bool wr_ok = kt < 15, ld_ok = kt < 14;
; #pragma unroll
;         for (int i = 0; i < 4; ++i) { fa[i] = *(const bf16x8*)(sA + arow_off + i * 2048 + ch0); fb[i] = *(const bf16x8*)(sB + brow_off + i * 2048 + ch0); }
;         __builtin_amdgcn_sched_barrier(0);
;         __builtin_amdgcn_s_setprio(2);
;         if (wr_ok) *(uint4*)(nA + soff0) = ra0;
;         if (ld_ok) ra0 = *(const uint4*)(Ab + (aoff + 0u * LDA + koa));
;         ga[0] = *(const bf16x8*)(sA + arow_off + 0 * 2048 + ch1); gb[0] = *(const bf16x8*)(sB + brow_off + 0 * 2048 + ch1);
;         __builtin_amdgcn_sched_barrier(0);
; #pragma unroll
;         for (int j = 0; j < 4; ++j) acc[0][j] = __builtin_amdgcn_mfma_f32_16x16x32_bf16(fb[j], fa[0], acc[0][j], 0, 0, 0);
;         __builtin_amdgcn_sched_barrier(0);
;         if (wr_ok) *(uint4*)(nA + soff0 + 4096) = ra1;
;         if (ld_ok) ra1 = *(const uint4*)(Ab + (aoff + 32u * LDA + koa));
;         ga[1] = *(const bf16x8*)(sA + arow_off + 1 * 2048 + ch1); gb[1] = *(const bf16x8*)(sB + brow_off + 1 * 2048 + ch1);
;         __builtin_amdgcn_sched_barrier(0);
; #pragma unroll
;         for (int j = 0; j < 4; ++j) acc[1][j] = __builtin_amdgcn_mfma_f32_16x16x32_bf16(fb[j], fa[1], acc[1][j], 0, 0, 0);
;         __builtin_amdgcn_sched_barrier(0);
;         if (wr_ok) *(uint4*)(nA + soff0 + 8192) = ra2;
;         if (ld_ok) ra2 = *(const uint4*)(Ab + (aoff + 64u * LDA + koa));
;         ga[2] = *(const bf16x8*)(sA + arow_off + 2 * 2048 + ch1); gb[2] = *(const bf16x8*)(sB + brow_off + 2 * 2048 + ch1);
;         __builtin_amdgcn_sched_barrier(0);
; #pragma unroll
;         for (int j = 0; j < 4; ++j) acc[2][j] = __builtin_amdgcn_mfma_f32_16x16x32_bf16(fb[j], fa[2], acc[2][j], 0, 0, 0);
	ds_read_b128 v[84:87], v6
	ds_read_b128 v[108:111], v6 offset:2048
	ds_read_b128 v[124:127], v7 offset:16384
	ds_read_b128 v[132:135], v7 offset:18432
	ds_read_b128 v[146:149], v6 offset:4096
	ds_read_b128 v[154:157], v6 offset:6144
	ds_read_b128 v[158:161], v7 offset:20480
	ds_read_b128 v[162:165], v7 offset:22528
	s_setprio 2
	s_waitcnt lgkmcnt(5)
	v_mfma_f32_16x16x32_bf16 v[26:29], v[124:127], v[84:87], v[26:29]
	global_load_dwordx4 v[166:169], v8, s[36:37] offset:1280
	s_waitcnt lgkmcnt(0)
	v_mfma_f32_16x16x32_bf16 v[10:13], v[162:165], v[84:87], v[10:13]
	s_waitcnt vmcnt(8)
	ds_write_b128 v2, v[170:173] offset:32768
	v_mfma_f32_16x16x32_bf16 v[88:91], v[132:135], v[84:87], v[88:91]
	ds_read_b128 v[170:173], v3
	v_mfma_f32_16x16x32_bf16 v[96:99], v[158:161], v[84:87], v[96:99]
	ds_read_b128 v[174:177], v4 offset:16384
	global_load_dwordx4 v[84:87], v216, s[36:37] offset:1280
	v_mfma_f32_16x16x32_bf16 v[30:33], v[124:127], v[108:111], v[30:33]
	s_waitcnt vmcnt(8)
	ds_write_b128 v2, v[104:107] offset:36864
	v_mfma_f32_16x16x32_bf16 v[42:45], v[132:135], v[108:111], v[42:45]
	ds_read_b128 v[104:107], v3 offset:2048
	v_mfma_f32_16x16x32_bf16 v[14:17], v[162:165], v[108:111], v[14:17]
	ds_read_b128 v[178:181], v4 offset:18432
	v_mfma_f32_16x16x32_bf16 v[92:95], v[158:161], v[108:111], v[92:95]
	global_load_dwordx4 v[108:111], v217, s[36:37] offset:1280
	v_mfma_f32_16x16x32_bf16 v[34:37], v[124:127], v[146:149], v[34:37]
	s_waitcnt vmcnt(8)
	ds_write_b128 v2, v[112:115] offset:40960
	v_mfma_f32_16x16x32_bf16 v[46:49], v[132:135], v[146:149], v[46:49]
	ds_read_b128 v[112:115], v3 offset:4096
	v_mfma_f32_16x16x32_bf16 v[58:61], v[158:161], v[146:149], v[58:61]
	ds_read_b128 v[182:185], v4 offset:20480
	v_mfma_f32_16x16x32_bf16 v[18:21], v[162:165], v[146:149], v[18:21]
	global_load_dwordx4 v[146:149], v218, s[36:37] offset:1280
	v_mfma_f32_16x16x32_bf16 v[38:41], v[124:127], v[154:157], v[38:41]
	s_waitcnt vmcnt(8)
	ds_write_b128 v2, v[150:153] offset:45056
	v_mfma_f32_16x16x32_bf16 v[50:53], v[132:135], v[154:157], v[50:53]
	ds_read_b128 v[150:153], v3 offset:6144
	v_mfma_f32_16x16x32_bf16 v[54:57], v[158:161], v[154:157], v[54:57]
	ds_read_b128 v[186:189], v4 offset:22528
	v_mfma_f32_16x16x32_bf16 v[22:25], v[162:165], v[154:157], v[22:25]
	s_waitcnt lgkmcnt(9)
	v_mfma_f32_16x16x32_bf16 v[26:29], v[174:177], v[170:173], v[26:29]
	global_load_dwordx4 v[124:127], v5, s[4:5] offset:1280
	s_waitcnt lgkmcnt(0)
	v_mfma_f32_16x16x32_bf16 v[10:13], v[186:189], v[170:173], v[10:13]
	s_waitcnt vmcnt(8)
	ds_write_b128 v2, v[120:123] offset:49152
	v_mfma_f32_16x16x32_bf16 v[88:91], v[178:181], v[170:173], v[88:91]
	v_mfma_f32_16x16x32_bf16 v[96:99], v[182:185], v[170:173], v[96:99]
	global_load_dwordx4 v[120:123], v219, s[4:5] offset:1280
	v_mfma_f32_16x16x32_bf16 v[30:33], v[174:177], v[104:107], v[30:33]
	s_waitcnt vmcnt(8)
	ds_write_b128 v2, v[116:119] offset:53248
	v_mfma_f32_16x16x32_bf16 v[42:45], v[178:181], v[104:107], v[42:45]
	v_mfma_f32_16x16x32_bf16 v[14:17], v[186:189], v[104:107], v[14:17]
	v_mfma_f32_16x16x32_bf16 v[92:95], v[182:185], v[104:107], v[92:95]
	global_load_dwordx4 v[104:107], v220, s[4:5] offset:1280
	v_mfma_f32_16x16x32_bf16 v[34:37], v[174:177], v[112:115], v[34:37]
	s_waitcnt vmcnt(8)
	ds_write_b128 v2, v[62:65] offset:57344
	v_mfma_f32_16x16x32_bf16 v[46:49], v[178:181], v[112:115], v[46:49]
	v_mfma_f32_16x16x32_bf16 v[58:61], v[182:185], v[112:115], v[58:61]
	v_mfma_f32_16x16x32_bf16 v[18:21], v[186:189], v[112:115], v[18:21]
	global_load_dwordx4 v[62:65], v221, s[4:5] offset:1280
	v_mfma_f32_16x16x32_bf16 v[38:41], v[174:177], v[150:153], v[38:41]
	s_waitcnt vmcnt(8)
	ds_write_b128 v2, v[100:103] offset:61440
	v_mfma_f32_16x16x32_bf16 v[50:53], v[178:181], v[150:153], v[50:53]
	v_mfma_f32_16x16x32_bf16 v[54:57], v[182:185], v[150:153], v[54:57]
	v_mfma_f32_16x16x32_bf16 v[22:25], v[186:189], v[150:153], v[22:25]
	s_setprio 0
	s_waitcnt lgkmcnt(0)
	s_barrier
	ds_read_b128 v[100:103], v6 offset:32768
	ds_read_b128 v[112:115], v6 offset:34816
	ds_read_b128 v[116:119], v7 offset:49152
	ds_read_b128 v[132:135], v7 offset:51200
	ds_read_b128 v[150:153], v6 offset:36864
	ds_read_b128 v[154:157], v6 offset:38912
	ds_read_b128 v[158:161], v7 offset:53248
	ds_read_b128 v[162:165], v7 offset:55296
	s_setprio 2
	s_waitcnt lgkmcnt(5)
	v_mfma_f32_16x16x32_bf16 v[26:29], v[116:119], v[100:103], v[26:29]
	global_load_dwordx4 v[170:173], v8, s[36:37] offset:1408
	s_waitcnt lgkmcnt(0)
	v_mfma_f32_16x16x32_bf16 v[10:13], v[162:165], v[100:103], v[10:13]
	s_waitcnt vmcnt(8)
	ds_write_b128 v2, v[166:169]
	v_mfma_f32_16x16x32_bf16 v[88:91], v[132:135], v[100:103], v[88:91]
	ds_read_b128 v[166:169], v3 offset:32768
	v_mfma_f32_16x16x32_bf16 v[96:99], v[158:161], v[100:103], v[96:99]
	ds_read_b128 v[174:177], v4 offset:49152
	global_load_dwordx4 v[100:103], v216, s[36:37] offset:1408
	v_mfma_f32_16x16x32_bf16 v[30:33], v[116:119], v[112:115], v[30:33]
	s_waitcnt vmcnt(8)
	ds_write_b128 v2, v[84:87] offset:4096
	v_mfma_f32_16x16x32_bf16 v[42:45], v[132:135], v[112:115], v[42:45]
	ds_read_b128 v[84:87], v3 offset:34816
	v_mfma_f32_16x16x32_bf16 v[14:17], v[162:165], v[112:115], v[14:17]
	ds_read_b128 v[178:181], v4 offset:51200
	v_mfma_f32_16x16x32_bf16 v[92:95], v[158:161], v[112:115], v[92:95]
	global_load_dwordx4 v[112:115], v217, s[36:37] offset:1408
	v_mfma_f32_16x16x32_bf16 v[34:37], v[116:119], v[150:153], v[34:37]
	s_waitcnt vmcnt(8)
; template <int MODE>
; __device__ __forceinline__ void gemm_tile(const Params& P, int tm, int tn, unsigned char* smem) {
;     ...
;     for (int kt = 0; kt < 16; ++kt) {
;         unsigned char* sA = (kt & 1) ? sA1 : sA0; unsigned char* sB = (kt & 1) ? sB1 : sB0;
;         unsigned char* nA = (kt & 1) ? sA0 : sA1; unsigned char* nB = (kt & 1) ? sB0 : sB1;
;         bf16x8 fa[4], fb[4], ga[4], gb[4];
;         const int ch0 = ((g ^ sw) << 4), ch1 = (((4 + g) ^ sw) << 4);
;         const unsigned ko = (unsigned)(kt + 2) * 128u;
;         const unsigned koa = ko + ((MODE == 2 && kt + 2 >= 8) ? (unsigned)(ZC_FQ - 512) * 2u : 0u);
;         const bool wr_ok = kt < 15, ld_ok = kt < 14;
; #pragma unroll
;         for (int i = 0; i < 4; ++i) { fa[i] = *(const bf16x8*)(sA + arow_off + i * 2048 + ch0); fb[i] = *(const bf16x8*)(sB + brow_off + i * 2048 + ch0); }
;         __builtin_amdgcn_sched_barrier(0);
;         __builtin_amdgcn_s_setprio(2);
;         if (wr_ok) *(uint4*)(nA + soff0) = ra0;
;         if (ld_ok) ra0 = *(const uint4*)(Ab + (aoff + 0u * LDA + koa));
;         ga[0] = *(const bf16x8*)(sA + arow_off + 0 * 2048 + ch1); gb[0] = *(const bf16x8*)(sB + brow_off + 0 * 2048 + ch1);
;         __builtin_amdgcn_sched_barrier(0);
; #pragma unroll
;         for (int j = 0; j < 4; ++j) acc[0][j] = __builtin_amdgcn_mfma_f32_16x16x32_bf16(fb[j], fa[0], acc[0][j], 0, 0, 0);
;         __builtin_amdgcn_sched_barrier(0);
;         if (wr_ok) *(uint4*)(nA + soff0 + 4096) = ra1;
;         if (ld_ok) ra1 = *(const uint4*)(Ab + (aoff + 32u * LDA + koa));
;         ga[1] = *(const bf16x8*)(sA + arow_off + 1 * 2048 + ch1); gb[1] = *(const bf16x8*)(sB + brow_off + 1 * 2048 + ch1);
;         __builtin_amdgcn_sched_barrier(0);
; #pragma unroll
;         for (int j = 0; j < 4; ++j) acc[1][j] = __builtin_amdgcn_mfma_f32_16x16x32_bf16(fb[j], fa[1], acc[1][j], 0, 0, 0);
;         __builtin_amdgcn_sched_barrier(0);
;         if (wr_ok) *(uint4*)(nA + soff0 + 8192) = ra2;
;         if (ld_ok) ra2 = *(const uint4*)(Ab + (aoff + 64u * LDA + koa));
;         ga[2] = *(const bf16x8*)(sA + arow_off + 2 * 2048 + ch1); gb[2] = *(const bf16x8*)(sB + brow_off + 2 * 2048 + ch1);
;         __builtin_amdgcn_sched_barrier(0);
; #pragma unroll
;         for (int j = 0; j < 4; ++j) acc[2][j] = __builtin_amdgcn_mfma_f32_16x16x32_bf16(fb[j], fa[2], acc[2][j], 0, 0, 0);
	ds_write_b128 v2, v[108:111] offset:8192
	v_mfma_f32_16x16x32_bf16 v[46:49], v[132:135], v[150:153], v[46:49]
	ds_read_b128 v[108:111], v3 offset:36864
	v_mfma_f32_16x16x32_bf16 v[58:61], v[158:161], v[150:153], v[58:61]
	ds_read_b128 v[182:185], v4 offset:53248
	v_mfma_f32_16x16x32_bf16 v[18:21], v[162:165], v[150:153], v[18:21]
	global_load_dwordx4 v[150:153], v218, s[36:37] offset:1408
	v_mfma_f32_16x16x32_bf16 v[38:41], v[116:119], v[154:157], v[38:41]
	s_waitcnt vmcnt(8)
	ds_write_b128 v2, v[146:149] offset:12288
	v_mfma_f32_16x16x32_bf16 v[50:53], v[132:135], v[154:157], v[50:53]
	ds_read_b128 v[146:149], v3 offset:38912
	v_mfma_f32_16x16x32_bf16 v[54:57], v[158:161], v[154:157], v[54:57]
	ds_read_b128 v[186:189], v4 offset:55296
	v_mfma_f32_16x16x32_bf16 v[22:25], v[162:165], v[154:157], v[22:25]
	s_waitcnt lgkmcnt(9)
	v_mfma_f32_16x16x32_bf16 v[26:29], v[174:177], v[166:169], v[26:29]
	global_load_dwordx4 v[116:119], v5, s[4:5] offset:1408
	s_waitcnt lgkmcnt(0)
	v_mfma_f32_16x16x32_bf16 v[10:13], v[186:189], v[166:169], v[10:13]
	s_waitcnt vmcnt(8)
	ds_write_b128 v2, v[124:127] offset:16384
	v_mfma_f32_16x16x32_bf16 v[88:91], v[178:181], v[166:169], v[88:91]
	v_mfma_f32_16x16x32_bf16 v[96:99], v[182:185], v[166:169], v[96:99]
	global_load_dwordx4 v[124:127], v219, s[4:5] offset:1408
	v_mfma_f32_16x16x32_bf16 v[30:33], v[174:177], v[84:87], v[30:33]
	s_waitcnt vmcnt(8)
	ds_write_b128 v2, v[120:123] offset:20480
	v_mfma_f32_16x16x32_bf16 v[42:45], v[178:181], v[84:87], v[42:45]
	v_mfma_f32_16x16x32_bf16 v[14:17], v[186:189], v[84:87], v[14:17]
	v_mfma_f32_16x16x32_bf16 v[92:95], v[182:185], v[84:87], v[92:95]
	global_load_dwordx4 v[84:87], v220, s[4:5] offset:1408
	v_mfma_f32_16x16x32_bf16 v[34:37], v[174:177], v[108:111], v[34:37]
	s_waitcnt vmcnt(8)
	ds_write_b128 v2, v[104:107] offset:24576
	v_mfma_f32_16x16x32_bf16 v[46:49], v[178:181], v[108:111], v[46:49]
	v_mfma_f32_16x16x32_bf16 v[58:61], v[182:185], v[108:111], v[58:61]
	v_mfma_f32_16x16x32_bf16 v[18:21], v[186:189], v[108:111], v[18:21]
	global_load_dwordx4 v[104:107], v221, s[4:5] offset:1408
	v_mfma_f32_16x16x32_bf16 v[38:41], v[174:177], v[146:149], v[38:41]
	s_waitcnt vmcnt(8)
	ds_write_b128 v2, v[62:65] offset:28672
	v_mfma_f32_16x16x32_bf16 v[50:53], v[178:181], v[146:149], v[50:53]
	v_mfma_f32_16x16x32_bf16 v[54:57], v[182:185], v[146:149], v[54:57]
	v_mfma_f32_16x16x32_bf16 v[22:25], v[186:189], v[146:149], v[22:25]
	s_setprio 0
	s_waitcnt lgkmcnt(0)
	s_barrier
	ds_read_b128 v[62:65], v6
	ds_read_b128 v[108:111], v6 offset:2048
	ds_read_b128 v[120:123], v7 offset:16384
	ds_read_b128 v[132:135], v7 offset:18432
	ds_read_b128 v[146:149], v6 offset:4096
	ds_read_b128 v[154:157], v6 offset:6144
	ds_read_b128 v[158:161], v7 offset:20480
	ds_read_b128 v[162:165], v7 offset:22528
	s_setprio 2
	s_waitcnt lgkmcnt(5)
	v_mfma_f32_16x16x32_bf16 v[26:29], v[120:123], v[62:65], v[26:29]
	global_load_dwordx4 v[166:169], v8, s[36:37] offset:1536
	s_waitcnt lgkmcnt(0)
	v_mfma_f32_16x16x32_bf16 v[10:13], v[162:165], v[62:65], v[10:13]
	s_waitcnt vmcnt(8)
	ds_write_b128 v2, v[170:173] offset:32768
	v_mfma_f32_16x16x32_bf16 v[88:91], v[132:135], v[62:65], v[88:91]
	ds_read_b128 v[170:173], v3
	v_mfma_f32_16x16x32_bf16 v[96:99], v[158:161], v[62:65], v[96:99]
	ds_read_b128 v[174:177], v4 offset:16384
	global_load_dwordx4 v[62:65], v216, s[36:37] offset:1536
	v_mfma_f32_16x16x32_bf16 v[30:33], v[120:123], v[108:111], v[30:33]
	s_waitcnt vmcnt(8)
	ds_write_b128 v2, v[100:103] offset:36864
	v_mfma_f32_16x16x32_bf16 v[42:45], v[132:135], v[108:111], v[42:45]
	ds_read_b128 v[100:103], v3 offset:2048
	v_mfma_f32_16x16x32_bf16 v[14:17], v[162:165], v[108:111], v[14:17]
	ds_read_b128 v[178:181], v4 offset:18432
	v_mfma_f32_16x16x32_bf16 v[92:95], v[158:161], v[108:111], v[92:95]
	global_load_dwordx4 v[108:111], v217, s[36:37] offset:1536
	v_mfma_f32_16x16x32_bf16 v[34:37], v[120:123], v[146:149], v[34:37]
	s_waitcnt vmcnt(8)
	ds_write_b128 v2, v[112:115] offset:40960
	v_mfma_f32_16x16x32_bf16 v[46:49], v[132:135], v[146:149], v[46:49]
	ds_read_b128 v[112:115], v3 offset:4096
	v_mfma_f32_16x16x32_bf16 v[58:61], v[158:161], v[146:149], v[58:61]
	ds_read_b128 v[182:185], v4 offset:20480
	v_mfma_f32_16x16x32_bf16 v[18:21], v[162:165], v[146:149], v[18:21]
	global_load_dwordx4 v[146:149], v218, s[36:37] offset:1536
	v_mfma_f32_16x16x32_bf16 v[38:41], v[120:123], v[154:157], v[38:41]
	s_waitcnt vmcnt(8)
	ds_write_b128 v2, v[150:153] offset:45056
	v_mfma_f32_16x16x32_bf16 v[50:53], v[132:135], v[154:157], v[50:53]
	ds_read_b128 v[150:153], v3 offset:6144
	v_mfma_f32_16x16x32_bf16 v[54:57], v[158:161], v[154:157], v[54:57]
	ds_read_b128 v[186:189], v4 offset:22528
	v_mfma_f32_16x16x32_bf16 v[22:25], v[162:165], v[154:157], v[22:25]
	s_waitcnt lgkmcnt(9)
	v_mfma_f32_16x16x32_bf16 v[26:29], v[174:177], v[170:173], v[26:29]
	global_load_dwordx4 v[120:123], v5, s[4:5] offset:1536
	s_waitcnt lgkmcnt(0)
	v_mfma_f32_16x16x32_bf16 v[10:13], v[186:189], v[170:173], v[10:13]
	s_waitcnt vmcnt(8)
	ds_write_b128 v2, v[116:119] offset:49152
	v_mfma_f32_16x16x32_bf16 v[88:91], v[178:181], v[170:173], v[88:91]
	v_mfma_f32_16x16x32_bf16 v[96:99], v[182:185], v[170:173], v[96:99]
	global_load_dwordx4 v[116:119], v219, s[4:5] offset:1536
	v_mfma_f32_16x16x32_bf16 v[30:33], v[174:177], v[100:103], v[30:33]
	s_waitcnt vmcnt(8)
	ds_write_b128 v2, v[124:127] offset:53248
	v_mfma_f32_16x16x32_bf16 v[42:45], v[178:181], v[100:103], v[42:45]
	v_mfma_f32_16x16x32_bf16 v[14:17], v[186:189], v[100:103], v[14:17]
	v_mfma_f32_16x16x32_bf16 v[92:95], v[182:185], v[100:103], v[92:95]
	global_load_dwordx4 v[100:103], v220, s[4:5] offset:1536
	v_mfma_f32_16x16x32_bf16 v[34:37], v[174:177], v[112:115], v[34:37]
	s_waitcnt vmcnt(8)
	ds_write_b128 v2, v[84:87] offset:57344
	v_mfma_f32_16x16x32_bf16 v[46:49], v[178:181], v[112:115], v[46:49]
	v_mfma_f32_16x16x32_bf16 v[58:61], v[182:185], v[112:115], v[58:61]
	v_mfma_f32_16x16x32_bf16 v[18:21], v[186:189], v[112:115], v[18:21]
	global_load_dwordx4 v[84:87], v221, s[4:5] offset:1536
	v_mfma_f32_16x16x32_bf16 v[38:41], v[174:177], v[150:153], v[38:41]
	s_waitcnt vmcnt(8)
	ds_write_b128 v2, v[104:107] offset:61440
	v_mfma_f32_16x16x32_bf16 v[50:53], v[178:181], v[150:153], v[50:53]
	v_mfma_f32_16x16x32_bf16 v[54:57], v[182:185], v[150:153], v[54:57]
	v_mfma_f32_16x16x32_bf16 v[22:25], v[186:189], v[150:153], v[22:25]
	s_setprio 0
	s_waitcnt lgkmcnt(0)
	s_barrier
; template <int MODE>
; __device__ __forceinline__ void gemm_tile(const Params& P, int tm, int tn, unsigned char* smem) {
;     ...
;     for (int kt = 0; kt < 16; ++kt) {
;         unsigned char* sA = (kt & 1) ? sA1 : sA0; unsigned char* sB = (kt & 1) ? sB1 : sB0;
;         unsigned char* nA = (kt & 1) ? sA0 : sA1; unsigned char* nB = (kt & 1) ? sB0 : sB1;
;         bf16x8 fa[4], fb[4], ga[4], gb[4];
;         const int ch0 = ((g ^ sw) << 4), ch1 = (((4 + g) ^ sw) << 4);
;         const unsigned ko = (unsigned)(kt + 2) * 128u;
;         const unsigned koa = ko + ((MODE == 2 && kt + 2 >= 8) ? (unsigned)(ZC_FQ - 512) * 2u : 0u);
;         const bool wr_ok = kt < 15, ld_ok = kt < 14;
; #pragma unroll
;         for (int i = 0; i < 4; ++i) { fa[i] = *(const bf16x8*)(sA + arow_off + i * 2048 + ch0); fb[i] = *(const bf16x8*)(sB + brow_off + i * 2048 + ch0); }
;         __builtin_amdgcn_sched_barrier(0);
;         __builtin_amdgcn_s_setprio(2);
;         if (wr_ok) *(uint4*)(nA + soff0) = ra0;
;         if (ld_ok) ra0 = *(const uint4*)(Ab + (aoff + 0u * LDA + koa));
;         ga[0] = *(const bf16x8*)(sA + arow_off + 0 * 2048 + ch1); gb[0] = *(const bf16x8*)(sB + brow_off + 0 * 2048 + ch1);
;         __builtin_amdgcn_sched_barrier(0);
; #pragma unroll
;         for (int j = 0; j < 4; ++j) acc[0][j] = __builtin_amdgcn_mfma_f32_16x16x32_bf16(fb[j], fa[0], acc[0][j], 0, 0, 0);
;         __builtin_amdgcn_sched_barrier(0);
;         if (wr_ok) *(uint4*)(nA + soff0 + 4096) = ra1;
;         if (ld_ok) ra1 = *(const uint4*)(Ab + (aoff + 32u * LDA + koa));
;         ga[1] = *(const bf16x8*)(sA + arow_off + 1 * 2048 + ch1); gb[1] = *(const bf16x8*)(sB + brow_off + 1 * 2048 + ch1);
;         __builtin_amdgcn_sched_barrier(0);
; #pragma unroll
;         for (int j = 0; j < 4; ++j) acc[1][j] = __builtin_amdgcn_mfma_f32_16x16x32_bf16(fb[j], fa[1], acc[1][j], 0, 0, 0);
;         __builtin_amdgcn_sched_barrier(0);
;         if (wr_ok) *(uint4*)(nA + soff0 + 8192) = ra2;
;         if (ld_ok) ra2 = *(const uint4*)(Ab + (aoff + 64u * LDA + koa));
;         ga[2] = *(const bf16x8*)(sA + arow_off + 2 * 2048 + ch1); gb[2] = *(const bf16x8*)(sB + brow_off + 2 * 2048 + ch1);
;         __builtin_amdgcn_sched_barrier(0);
; #pragma unroll
;         for (int j = 0; j < 4; ++j) acc[2][j] = __builtin_amdgcn_mfma_f32_16x16x32_bf16(fb[j], fa[2], acc[2][j], 0, 0, 0);
	ds_read_b128 v[104:107], v6 offset:32768
	ds_read_b128 v[112:115], v6 offset:34816
	ds_read_b128 v[124:127], v7 offset:49152
	ds_read_b128 v[132:135], v7 offset:51200
	ds_read_b128 v[150:153], v6 offset:36864
	ds_read_b128 v[154:157], v6 offset:38912
	ds_read_b128 v[158:161], v7 offset:53248
	ds_read_b128 v[162:165], v7 offset:55296
	s_setprio 2
	s_waitcnt lgkmcnt(5)
	v_mfma_f32_16x16x32_bf16 v[26:29], v[124:127], v[104:107], v[26:29]
	global_load_dwordx4 v[170:173], v8, s[36:37] offset:1664
	s_waitcnt lgkmcnt(0)
	v_mfma_f32_16x16x32_bf16 v[10:13], v[162:165], v[104:107], v[10:13]
	s_waitcnt vmcnt(8)
	ds_write_b128 v2, v[166:169]
	v_mfma_f32_16x16x32_bf16 v[88:91], v[132:135], v[104:107], v[88:91]
	ds_read_b128 v[166:169], v3 offset:32768
	v_mfma_f32_16x16x32_bf16 v[96:99], v[158:161], v[104:107], v[96:99]
	ds_read_b128 v[174:177], v4 offset:49152
	global_load_dwordx4 v[104:107], v216, s[36:37] offset:1664
	v_mfma_f32_16x16x32_bf16 v[30:33], v[124:127], v[112:115], v[30:33]
	s_waitcnt vmcnt(8)
	ds_write_b128 v2, v[62:65] offset:4096
	v_mfma_f32_16x16x32_bf16 v[42:45], v[132:135], v[112:115], v[42:45]
	ds_read_b128 v[62:65], v3 offset:34816
	v_mfma_f32_16x16x32_bf16 v[14:17], v[162:165], v[112:115], v[14:17]
	ds_read_b128 v[178:181], v4 offset:51200
	v_mfma_f32_16x16x32_bf16 v[92:95], v[158:161], v[112:115], v[92:95]
	global_load_dwordx4 v[112:115], v217, s[36:37] offset:1664
	v_mfma_f32_16x16x32_bf16 v[34:37], v[124:127], v[150:153], v[34:37]
	s_waitcnt vmcnt(8)
	ds_write_b128 v2, v[108:111] offset:8192
	v_mfma_f32_16x16x32_bf16 v[46:49], v[132:135], v[150:153], v[46:49]
	ds_read_b128 v[108:111], v3 offset:36864
	v_mfma_f32_16x16x32_bf16 v[58:61], v[158:161], v[150:153], v[58:61]
	ds_read_b128 v[182:185], v4 offset:53248
	v_mfma_f32_16x16x32_bf16 v[18:21], v[162:165], v[150:153], v[18:21]
	global_load_dwordx4 v[150:153], v218, s[36:37] offset:1664
	v_mfma_f32_16x16x32_bf16 v[38:41], v[124:127], v[154:157], v[38:41]
	s_waitcnt vmcnt(8)
	ds_write_b128 v2, v[146:149] offset:12288
	v_mfma_f32_16x16x32_bf16 v[50:53], v[132:135], v[154:157], v[50:53]
	ds_read_b128 v[146:149], v3 offset:38912
	v_mfma_f32_16x16x32_bf16 v[54:57], v[158:161], v[154:157], v[54:57]
	ds_read_b128 v[186:189], v4 offset:55296
	v_mfma_f32_16x16x32_bf16 v[22:25], v[162:165], v[154:157], v[22:25]
	s_waitcnt lgkmcnt(9)
	v_mfma_f32_16x16x32_bf16 v[26:29], v[174:177], v[166:169], v[26:29]
	global_load_dwordx4 v[124:127], v5, s[4:5] offset:1664
	s_waitcnt lgkmcnt(0)
	v_mfma_f32_16x16x32_bf16 v[10:13], v[186:189], v[166:169], v[10:13]
	s_waitcnt vmcnt(8)
	ds_write_b128 v2, v[120:123] offset:16384
	v_mfma_f32_16x16x32_bf16 v[88:91], v[178:181], v[166:169], v[88:91]
	v_mfma_f32_16x16x32_bf16 v[96:99], v[182:185], v[166:169], v[96:99]
	global_load_dwordx4 v[120:123], v219, s[4:5] offset:1664
	v_mfma_f32_16x16x32_bf16 v[30:33], v[174:177], v[62:65], v[30:33]
	s_waitcnt vmcnt(8)
	ds_write_b128 v2, v[116:119] offset:20480
	v_mfma_f32_16x16x32_bf16 v[42:45], v[178:181], v[62:65], v[42:45]
	v_mfma_f32_16x16x32_bf16 v[14:17], v[186:189], v[62:65], v[14:17]
	v_mfma_f32_16x16x32_bf16 v[92:95], v[182:185], v[62:65], v[92:95]
	global_load_dwordx4 v[62:65], v220, s[4:5] offset:1664
	v_mfma_f32_16x16x32_bf16 v[34:37], v[174:177], v[108:111], v[34:37]
	s_waitcnt vmcnt(8)
	ds_write_b128 v2, v[100:103] offset:24576
	v_mfma_f32_16x16x32_bf16 v[46:49], v[178:181], v[108:111], v[46:49]
	v_mfma_f32_16x16x32_bf16 v[58:61], v[182:185], v[108:111], v[58:61]
	v_mfma_f32_16x16x32_bf16 v[18:21], v[186:189], v[108:111], v[18:21]
	global_load_dwordx4 v[100:103], v221, s[4:5] offset:1664
	v_mfma_f32_16x16x32_bf16 v[38:41], v[174:177], v[146:149], v[38:41]
	s_waitcnt vmcnt(8)
	ds_write_b128 v2, v[84:87] offset:28672
	v_mfma_f32_16x16x32_bf16 v[50:53], v[178:181], v[146:149], v[50:53]
	v_mfma_f32_16x16x32_bf16 v[54:57], v[182:185], v[146:149], v[54:57]
	v_mfma_f32_16x16x32_bf16 v[22:25], v[186:189], v[146:149], v[22:25]
	s_setprio 0
	s_waitcnt lgkmcnt(0)
	s_barrier
	ds_read_b128 v[84:87], v6
	ds_read_b128 v[108:111], v6 offset:2048
	ds_read_b128 v[116:119], v7 offset:16384
	ds_read_b128 v[132:135], v7 offset:18432
	ds_read_b128 v[146:149], v6 offset:4096
	ds_read_b128 v[154:157], v6 offset:6144
	ds_read_b128 v[158:161], v7 offset:20480
	ds_read_b128 v[162:165], v7 offset:22528
	s_setprio 2
	s_waitcnt lgkmcnt(5)
	v_mfma_f32_16x16x32_bf16 v[26:29], v[116:119], v[84:87], v[26:29]
	global_load_dwordx4 v[166:169], v8, s[36:37] offset:1792
	s_waitcnt lgkmcnt(0)
	v_mfma_f32_16x16x32_bf16 v[10:13], v[162:165], v[84:87], v[10:13]
	s_waitcnt vmcnt(8)
	ds_write_b128 v2, v[170:173] offset:32768
	v_mfma_f32_16x16x32_bf16 v[88:91], v[132:135], v[84:87], v[88:91]
	ds_read_b128 v[170:173], v3
	v_mfma_f32_16x16x32_bf16 v[96:99], v[158:161], v[84:87], v[96:99]
	ds_read_b128 v[174:177], v4 offset:16384
	global_load_dwordx4 v[84:87], v216, s[36:37] offset:1792
	v_mfma_f32_16x16x32_bf16 v[30:33], v[116:119], v[108:111], v[30:33]
	s_waitcnt vmcnt(8)
	ds_write_b128 v2, v[104:107] offset:36864
	v_mfma_f32_16x16x32_bf16 v[42:45], v[132:135], v[108:111], v[42:45]
	ds_read_b128 v[104:107], v3 offset:2048
	v_mfma_f32_16x16x32_bf16 v[14:17], v[162:165], v[108:111], v[14:17]
	ds_read_b128 v[178:181], v4 offset:18432
	v_mfma_f32_16x16x32_bf16 v[92:95], v[158:161], v[108:111], v[92:95]
	global_load_dwordx4 v[108:111], v217, s[36:37] offset:1792
	v_mfma_f32_16x16x32_bf16 v[34:37], v[116:119], v[146:149], v[34:37]
	s_waitcnt vmcnt(8)
; template <int MODE>
; __device__ __forceinline__ void gemm_tile(const Params& P, int tm, int tn, unsigned char* smem) {
;     ...
;     for (int kt = 0; kt < 16; ++kt) {
;         unsigned char* sA = (kt & 1) ? sA1 : sA0; unsigned char* sB = (kt & 1) ? sB1 : sB0;
;         unsigned char* nA = (kt & 1) ? sA0 : sA1; unsigned char* nB = (kt & 1) ? sB0 : sB1;
;         bf16x8 fa[4], fb[4], ga[4], gb[4];
;         const int ch0 = ((g ^ sw) << 4), ch1 = (((4 + g) ^ sw) << 4);
;         const unsigned ko = (unsigned)(kt + 2) * 128u;
;         const unsigned koa = ko + ((MODE == 2 && kt + 2 >= 8) ? (unsigned)(ZC_FQ - 512) * 2u : 0u);
;         const bool wr_ok = kt < 15, ld_ok = kt < 14;
; #pragma unroll
;         for (int i = 0; i < 4; ++i) { fa[i] = *(const bf16x8*)(sA + arow_off + i * 2048 + ch0); fb[i] = *(const bf16x8*)(sB + brow_off + i * 2048 + ch0); }
;         __builtin_amdgcn_sched_barrier(0);
;         __builtin_amdgcn_s_setprio(2);
;         if (wr_ok) *(uint4*)(nA + soff0) = ra0;
;         if (ld_ok) ra0 = *(const uint4*)(Ab + (aoff + 0u * LDA + koa));
;         ga[0] = *(const bf16x8*)(sA + arow_off + 0 * 2048 + ch1); gb[0] = *(const bf16x8*)(sB + brow_off + 0 * 2048 + ch1);
;         __builtin_amdgcn_sched_barrier(0);
; #pragma unroll
;         for (int j = 0; j < 4; ++j) acc[0][j] = __builtin_amdgcn_mfma_f32_16x16x32_bf16(fb[j], fa[0], acc[0][j], 0, 0, 0);
;         __builtin_amdgcn_sched_barrier(0);
;         if (wr_ok) *(uint4*)(nA + soff0 + 4096) = ra1;
;         if (ld_ok) ra1 = *(const uint4*)(Ab + (aoff + 32u * LDA + koa));
;         ga[1] = *(const bf16x8*)(sA + arow_off + 1 * 2048 + ch1); gb[1] = *(const bf16x8*)(sB + brow_off + 1 * 2048 + ch1);
;         __builtin_amdgcn_sched_barrier(0);
; #pragma unroll
;         for (int j = 0; j < 4; ++j) acc[1][j] = __builtin_amdgcn_mfma_f32_16x16x32_bf16(fb[j], fa[1], acc[1][j], 0, 0, 0);
;         __builtin_amdgcn_sched_barrier(0);
;         if (wr_ok) *(uint4*)(nA + soff0 + 8192) = ra2;
;         if (ld_ok) ra2 = *(const uint4*)(Ab + (aoff + 64u * LDA + koa));
;         ga[2] = *(const bf16x8*)(sA + arow_off + 2 * 2048 + ch1); gb[2] = *(const bf16x8*)(sB + brow_off + 2 * 2048 + ch1);
;         __builtin_amdgcn_sched_barrier(0);
; #pragma unroll
;         for (int j = 0; j < 4; ++j) acc[2][j] = __builtin_amdgcn_mfma_f32_16x16x32_bf16(fb[j], fa[2], acc[2][j], 0, 0, 0);
	ds_write_b128 v2, v[112:115] offset:40960
	v_mfma_f32_16x16x32_bf16 v[46:49], v[132:135], v[146:149], v[46:49]
	ds_read_b128 v[112:115], v3 offset:4096
	v_mfma_f32_16x16x32_bf16 v[58:61], v[158:161], v[146:149], v[58:61]
	ds_read_b128 v[182:185], v4 offset:20480
	v_mfma_f32_16x16x32_bf16 v[18:21], v[162:165], v[146:149], v[18:21]
	global_load_dwordx4 v[146:149], v218, s[36:37] offset:1792
	v_mfma_f32_16x16x32_bf16 v[38:41], v[116:119], v[154:157], v[38:41]
	s_waitcnt vmcnt(8)
	ds_write_b128 v2, v[150:153] offset:45056
	v_mfma_f32_16x16x32_bf16 v[50:53], v[132:135], v[154:157], v[50:53]
	ds_read_b128 v[150:153], v3 offset:6144
	v_mfma_f32_16x16x32_bf16 v[54:57], v[158:161], v[154:157], v[54:57]
	ds_read_b128 v[186:189], v4 offset:22528
	v_mfma_f32_16x16x32_bf16 v[22:25], v[162:165], v[154:157], v[22:25]
	s_waitcnt lgkmcnt(9)
	v_mfma_f32_16x16x32_bf16 v[26:29], v[174:177], v[170:173], v[26:29]
	global_load_dwordx4 v[116:119], v5, s[4:5] offset:1792
	s_waitcnt lgkmcnt(0)
	v_mfma_f32_16x16x32_bf16 v[10:13], v[186:189], v[170:173], v[10:13]
	s_waitcnt vmcnt(8)
	ds_write_b128 v2, v[124:127] offset:49152
	v_mfma_f32_16x16x32_bf16 v[88:91], v[178:181], v[170:173], v[88:91]
	v_mfma_f32_16x16x32_bf16 v[96:99], v[182:185], v[170:173], v[96:99]
	global_load_dwordx4 v[124:127], v219, s[4:5] offset:1792
	v_mfma_f32_16x16x32_bf16 v[30:33], v[174:177], v[104:107], v[30:33]
	s_waitcnt vmcnt(8)
	ds_write_b128 v2, v[120:123] offset:53248
	v_mfma_f32_16x16x32_bf16 v[42:45], v[178:181], v[104:107], v[42:45]
	v_mfma_f32_16x16x32_bf16 v[14:17], v[186:189], v[104:107], v[14:17]
	v_mfma_f32_16x16x32_bf16 v[92:95], v[182:185], v[104:107], v[92:95]
	global_load_dwordx4 v[104:107], v220, s[4:5] offset:1792
	v_mfma_f32_16x16x32_bf16 v[34:37], v[174:177], v[112:115], v[34:37]
	s_waitcnt vmcnt(8)
	ds_write_b128 v2, v[62:65] offset:57344
	v_mfma_f32_16x16x32_bf16 v[46:49], v[178:181], v[112:115], v[46:49]
	v_mfma_f32_16x16x32_bf16 v[58:61], v[182:185], v[112:115], v[58:61]
	v_mfma_f32_16x16x32_bf16 v[18:21], v[186:189], v[112:115], v[18:21]
	global_load_dwordx4 v[62:65], v221, s[4:5] offset:1792
	v_mfma_f32_16x16x32_bf16 v[38:41], v[174:177], v[150:153], v[38:41]
	s_waitcnt vmcnt(8)
	ds_write_b128 v2, v[100:103] offset:61440
	v_mfma_f32_16x16x32_bf16 v[50:53], v[178:181], v[150:153], v[50:53]
	v_mfma_f32_16x16x32_bf16 v[54:57], v[182:185], v[150:153], v[54:57]
	v_mfma_f32_16x16x32_bf16 v[22:25], v[186:189], v[150:153], v[22:25]
	s_setprio 0
	s_waitcnt lgkmcnt(0)
	s_barrier
	ds_read_b128 v[100:103], v6 offset:32768
	ds_read_b128 v[112:115], v6 offset:34816
	ds_read_b128 v[120:123], v7 offset:49152
	ds_read_b128 v[132:135], v7 offset:51200
	ds_read_b128 v[150:153], v6 offset:36864
	ds_read_b128 v[154:157], v6 offset:38912
	ds_read_b128 v[158:161], v7 offset:53248
	ds_read_b128 v[162:165], v7 offset:55296
	s_setprio 2
	s_waitcnt lgkmcnt(5)
	v_mfma_f32_16x16x32_bf16 v[26:29], v[120:123], v[100:103], v[26:29]
	global_load_dwordx4 v[170:173], v8, s[36:37] offset:1920
	s_waitcnt lgkmcnt(0)
	v_mfma_f32_16x16x32_bf16 v[10:13], v[162:165], v[100:103], v[10:13]
	s_waitcnt vmcnt(8)
	ds_write_b128 v2, v[166:169]
	v_mfma_f32_16x16x32_bf16 v[88:91], v[132:135], v[100:103], v[88:91]
	ds_read_b128 v[166:169], v3 offset:32768
	v_mfma_f32_16x16x32_bf16 v[96:99], v[158:161], v[100:103], v[96:99]
	ds_read_b128 v[174:177], v4 offset:49152
	global_load_dwordx4 v[100:103], v216, s[36:37] offset:1920
	v_mfma_f32_16x16x32_bf16 v[30:33], v[120:123], v[112:115], v[30:33]
	s_waitcnt vmcnt(8)
	ds_write_b128 v2, v[84:87] offset:4096
	v_mfma_f32_16x16x32_bf16 v[42:45], v[132:135], v[112:115], v[42:45]
	ds_read_b128 v[84:87], v3 offset:34816
	v_mfma_f32_16x16x32_bf16 v[14:17], v[162:165], v[112:115], v[14:17]
	ds_read_b128 v[178:181], v4 offset:51200
	v_mfma_f32_16x16x32_bf16 v[92:95], v[158:161], v[112:115], v[92:95]
	global_load_dwordx4 v[112:115], v217, s[36:37] offset:1920
	v_mfma_f32_16x16x32_bf16 v[34:37], v[120:123], v[150:153], v[34:37]
	s_waitcnt vmcnt(8)
	ds_write_b128 v2, v[108:111] offset:8192
	v_mfma_f32_16x16x32_bf16 v[46:49], v[132:135], v[150:153], v[46:49]
	ds_read_b128 v[108:111], v3 offset:36864
	v_mfma_f32_16x16x32_bf16 v[58:61], v[158:161], v[150:153], v[58:61]
	ds_read_b128 v[182:185], v4 offset:53248
	v_mfma_f32_16x16x32_bf16 v[18:21], v[162:165], v[150:153], v[18:21]
	v_add_u32_e32 v8, 0x30780, v8
	global_load_dwordx4 v[150:153], v8, s[36:37]
	s_waitcnt vmcnt(8)
	ds_write_b128 v2, v[146:149] offset:12288
	ds_read_b128 v[146:149], v3 offset:38912
	ds_read_b128 v[186:189], v4 offset:55296
	v_mfma_f32_16x16x32_bf16 v[38:41], v[120:123], v[154:157], v[38:41]
	v_mfma_f32_16x16x32_bf16 v[50:53], v[132:135], v[154:157], v[50:53]
	v_mfma_f32_16x16x32_bf16 v[54:57], v[158:161], v[154:157], v[54:57]
	v_mfma_f32_16x16x32_bf16 v[22:25], v[162:165], v[154:157], v[22:25]
	s_waitcnt lgkmcnt(9)
	v_mfma_f32_16x16x32_bf16 v[26:29], v[174:177], v[166:169], v[26:29]
	global_load_dwordx4 v[120:123], v5, s[4:5] offset:1920
	s_waitcnt lgkmcnt(0)
	v_mfma_f32_16x16x32_bf16 v[8:11], v[186:189], v[166:169], v[10:13]
	s_waitcnt vmcnt(8)
	ds_write_b128 v2, v[116:119] offset:16384
	v_mfma_f32_16x16x32_bf16 v[88:91], v[178:181], v[166:169], v[88:91]
	v_mfma_f32_16x16x32_bf16 v[96:99], v[182:185], v[166:169], v[96:99]
	s_nop 0
	global_load_dwordx4 v[116:119], v219, s[4:5] offset:1920
	s_waitcnt vmcnt(8)
	ds_write_b128 v2, v[124:127] offset:20480
	v_mfma_f32_16x16x32_bf16 v[30:33], v[174:177], v[84:87], v[30:33]
	v_mfma_f32_16x16x32_bf16 v[42:45], v[178:181], v[84:87], v[42:45]
	v_mfma_f32_16x16x32_bf16 v[12:15], v[186:189], v[84:87], v[14:17]
	v_mfma_f32_16x16x32_bf16 v[92:95], v[182:185], v[84:87], v[92:95]
	s_nop 1
	global_load_dwordx4 v[84:87], v220, s[4:5] offset:1920
	s_waitcnt vmcnt(8)
	ds_write_b128 v2, v[104:107] offset:24576
	v_mfma_f32_16x16x32_bf16 v[34:37], v[174:177], v[108:111], v[34:37]
	v_mfma_f32_16x16x32_bf16 v[46:49], v[178:181], v[108:111], v[46:49]
	v_mfma_f32_16x16x32_bf16 v[58:61], v[182:185], v[108:111], v[58:61]
	v_mfma_f32_16x16x32_bf16 v[16:19], v[186:189], v[108:111], v[18:21]
	v_add_u32_e32 v5, 0x30780, v5
	global_load_dwordx4 v[104:107], v5, s[4:5]
	s_waitcnt vmcnt(8)
	ds_write_b128 v2, v[62:65] offset:28672
	v_mfma_f32_16x16x32_bf16 v[38:41], v[174:177], v[146:149], v[38:41]
	v_mfma_f32_16x16x32_bf16 v[50:53], v[178:181], v[146:149], v[50:53]
	v_mfma_f32_16x16x32_bf16 v[54:57], v[182:185], v[146:149], v[54:57]
	v_mfma_f32_16x16x32_bf16 v[20:23], v[186:189], v[146:149], v[22:25]
	s_setprio 0
	s_waitcnt lgkmcnt(0)
	s_barrier
; template <int MODE>
; __device__ __forceinline__ void gemm_tile(const Params& P, int tm, int tn, unsigned char* smem) {
;     ...
;     for (int kt = 0; kt < 16; ++kt) {
;         unsigned char* sA = (kt & 1) ? sA1 : sA0; unsigned char* sB = (kt & 1) ? sB1 : sB0;
;         unsigned char* nA = (kt & 1) ? sA0 : sA1; unsigned char* nB = (kt & 1) ? sB0 : sB1;
;         bf16x8 fa[4], fb[4], ga[4], gb[4];
;         const int ch0 = ((g ^ sw) << 4), ch1 = (((4 + g) ^ sw) << 4);
;         const unsigned ko = (unsigned)(kt + 2) * 128u;
;         const unsigned koa = ko + ((MODE == 2 && kt + 2 >= 8) ? (unsigned)(ZC_FQ - 512) * 2u : 0u);
;         const bool wr_ok = kt < 15, ld_ok = kt < 14;
; #pragma unroll
;         for (int i = 0; i < 4; ++i) { fa[i] = *(const bf16x8*)(sA + arow_off + i * 2048 + ch0); fb[i] = *(const bf16x8*)(sB + brow_off + i * 2048 + ch0); }
;         __builtin_amdgcn_sched_barrier(0);
;         __builtin_amdgcn_s_setprio(2);
;         if (wr_ok) *(uint4*)(nA + soff0) = ra0;
;         if (ld_ok) ra0 = *(const uint4*)(Ab + (aoff + 0u * LDA + koa));
;         ga[0] = *(const bf16x8*)(sA + arow_off + 0 * 2048 + ch1); gb[0] = *(const bf16x8*)(sB + brow_off + 0 * 2048 + ch1);
;         __builtin_amdgcn_sched_barrier(0);
; #pragma unroll
;         for (int j = 0; j < 4; ++j) acc[0][j] = __builtin_amdgcn_mfma_f32_16x16x32_bf16(fb[j], fa[0], acc[0][j], 0, 0, 0);
;         __builtin_amdgcn_sched_barrier(0);
;         if (wr_ok) *(uint4*)(nA + soff0 + 4096) = ra1;
;         if (ld_ok) ra1 = *(const uint4*)(Ab + (aoff + 32u * LDA + koa));
;         ga[1] = *(const bf16x8*)(sA + arow_off + 1 * 2048 + ch1); gb[1] = *(const bf16x8*)(sB + brow_off + 1 * 2048 + ch1);
;         __builtin_amdgcn_sched_barrier(0);
; #pragma unroll
;         for (int j = 0; j < 4; ++j) acc[1][j] = __builtin_amdgcn_mfma_f32_16x16x32_bf16(fb[j], fa[1], acc[1][j], 0, 0, 0);
;         __builtin_amdgcn_sched_barrier(0);
;         if (wr_ok) *(uint4*)(nA + soff0 + 8192) = ra2;
;         if (ld_ok) ra2 = *(const uint4*)(Ab + (aoff + 64u * LDA + koa));
;         ga[2] = *(const bf16x8*)(sA + arow_off + 2 * 2048 + ch1); gb[2] = *(const bf16x8*)(sB + brow_off + 2 * 2048 + ch1);
;         __builtin_amdgcn_sched_barrier(0);
; #pragma unroll
;         for (int j = 0; j < 4; ++j) acc[2][j] = __builtin_amdgcn_mfma_f32_16x16x32_bf16(fb[j], fa[2], acc[2][j], 0, 0, 0);
	ds_read_b128 v[62:65], v6
	ds_read_b128 v[108:111], v6 offset:2048
	ds_read_b128 v[124:127], v7 offset:16384
	ds_read_b128 v[132:135], v7 offset:18432
	ds_read_b128 v[146:149], v6 offset:4096
	ds_read_b128 v[154:157], v6 offset:6144
	ds_read_b128 v[158:161], v7 offset:20480
	ds_read_b128 v[162:165], v7 offset:22528
	s_setprio 2
	s_waitcnt lgkmcnt(5)
	v_mfma_f32_16x16x32_bf16 v[24:27], v[124:127], v[62:65], v[26:29]
	s_waitcnt lgkmcnt(0)
	v_mfma_f32_16x16x32_bf16 v[8:11], v[162:165], v[62:65], v[8:11]
	s_waitcnt vmcnt(7)
	ds_write_b128 v2, v[170:173] offset:32768
	v_mfma_f32_16x16x32_bf16 v[88:91], v[132:135], v[62:65], v[88:91]
	ds_read_b128 v[166:169], v3
	v_mfma_f32_16x16x32_bf16 v[96:99], v[158:161], v[62:65], v[96:99]
	ds_read_b128 v[170:173], v4 offset:16384
	v_mfma_f32_16x16x32_bf16 v[28:31], v[124:127], v[108:111], v[30:33]
	s_waitcnt vmcnt(6)
	ds_write_b128 v2, v[100:103] offset:36864
	v_mfma_f32_16x16x32_bf16 v[42:45], v[132:135], v[108:111], v[42:45]
	ds_read_b128 v[62:65], v3 offset:2048
	v_mfma_f32_16x16x32_bf16 v[12:15], v[162:165], v[108:111], v[12:15]
	ds_read_b128 v[100:103], v4 offset:18432
	v_mfma_f32_16x16x32_bf16 v[92:95], v[158:161], v[108:111], v[92:95]
	v_mfma_f32_16x16x32_bf16 v[32:35], v[124:127], v[146:149], v[34:37]
	s_waitcnt vmcnt(5)
	ds_write_b128 v2, v[112:115] offset:40960
	v_mfma_f32_16x16x32_bf16 v[46:49], v[132:135], v[146:149], v[46:49]
	ds_read_b128 v[108:111], v3 offset:4096
	v_mfma_f32_16x16x32_bf16 v[58:61], v[158:161], v[146:149], v[58:61]
	ds_read_b128 v[112:115], v4 offset:20480
	v_mfma_f32_16x16x32_bf16 v[16:19], v[162:165], v[146:149], v[16:19]
	v_mfma_f32_16x16x32_bf16 v[36:39], v[124:127], v[154:157], v[38:41]
	s_waitcnt vmcnt(4)
	ds_write_b128 v2, v[150:153] offset:45056
	v_mfma_f32_16x16x32_bf16 v[50:53], v[132:135], v[154:157], v[50:53]
	ds_read_b128 v[146:149], v3 offset:6144
	v_mfma_f32_16x16x32_bf16 v[54:57], v[158:161], v[154:157], v[54:57]
	ds_read_b128 v[150:153], v4 offset:22528
	v_mfma_f32_16x16x32_bf16 v[20:23], v[162:165], v[154:157], v[20:23]
	s_waitcnt lgkmcnt(9)
	v_mfma_f32_16x16x32_bf16 v[24:27], v[170:173], v[166:169], v[24:27]
	s_waitcnt lgkmcnt(0)
	v_mfma_f32_16x16x32_bf16 v[8:11], v[150:153], v[166:169], v[8:11]
	s_waitcnt vmcnt(3)
	ds_write_b128 v2, v[120:123] offset:49152
	v_mfma_f32_16x16x32_bf16 v[88:91], v[100:103], v[166:169], v[88:91]
	v_mfma_f32_16x16x32_bf16 v[96:99], v[112:115], v[166:169], v[96:99]
	v_mfma_f32_16x16x32_bf16 v[28:31], v[170:173], v[62:65], v[28:31]
	s_waitcnt vmcnt(2)
	ds_write_b128 v2, v[116:119] offset:53248
	v_mfma_f32_16x16x32_bf16 v[40:43], v[100:103], v[62:65], v[42:45]
	v_mfma_f32_16x16x32_bf16 v[12:15], v[150:153], v[62:65], v[12:15]
	v_mfma_f32_16x16x32_bf16 v[92:95], v[112:115], v[62:65], v[92:95]
	v_mfma_f32_16x16x32_bf16 v[32:35], v[170:173], v[108:111], v[32:35]
	s_waitcnt vmcnt(1)
	ds_write_b128 v2, v[84:87] offset:57344
	v_mfma_f32_16x16x32_bf16 v[44:47], v[100:103], v[108:111], v[46:49]
	v_mfma_f32_16x16x32_bf16 v[58:61], v[112:115], v[108:111], v[58:61]
	v_mfma_f32_16x16x32_bf16 v[16:19], v[150:153], v[108:111], v[16:19]
	v_mfma_f32_16x16x32_bf16 v[36:39], v[170:173], v[146:149], v[36:39]
	s_waitcnt vmcnt(0)
	ds_write_b128 v2, v[104:107] offset:61440
	v_mfma_f32_16x16x32_bf16 v[48:51], v[100:103], v[146:149], v[50:53]
	v_mfma_f32_16x16x32_bf16 v[52:55], v[112:115], v[146:149], v[54:57]
	v_mfma_f32_16x16x32_bf16 v[20:23], v[150:153], v[146:149], v[20:23]
	s_setprio 0
	s_waitcnt lgkmcnt(0)
	s_barrier
	ds_read_b128 v[62:65], v6 offset:32768
	ds_read_b128 v[84:87], v6 offset:34816
	ds_read_b128 v[100:103], v7 offset:49152
	ds_read_b128 v[104:107], v7 offset:51200
	ds_read_b128 v[108:111], v6 offset:36864
	ds_read_b128 v[112:115], v6 offset:38912
	ds_read_b128 v[116:119], v7 offset:53248
	ds_read_b128 v[120:123], v7 offset:55296
	s_setprio 2
	s_waitcnt lgkmcnt(5)
	v_mfma_f32_16x16x32_bf16 v[24:27], v[100:103], v[62:65], v[24:27]
	s_waitcnt lgkmcnt(0)
	v_mfma_f32_16x16x32_bf16 v[6:9], v[120:123], v[62:65], v[8:11]
	ds_read_b128 v[124:127], v3 offset:32768
	v_mfma_f32_16x16x32_bf16 v[88:91], v[104:107], v[62:65], v[88:91]
	ds_read_b128 v[132:135], v4 offset:49152
	v_mfma_f32_16x16x32_bf16 v[96:99], v[116:119], v[62:65], v[96:99]
	v_mfma_f32_16x16x32_bf16 v[28:31], v[100:103], v[84:87], v[28:31]
	ds_read_b128 v[146:149], v3 offset:34816
	v_mfma_f32_16x16x32_bf16 v[40:43], v[104:107], v[84:87], v[40:43]
	ds_read_b128 v[150:153], v4 offset:51200
	v_mfma_f32_16x16x32_bf16 v[10:13], v[120:123], v[84:87], v[12:15]
	v_mfma_f32_16x16x32_bf16 v[92:95], v[116:119], v[84:87], v[92:95]
	v_mfma_f32_16x16x32_bf16 v[14:17], v[120:123], v[108:111], v[16:19]
	ds_read_b128 v[84:87], v3 offset:36864
	v_mfma_f32_16x16x32_bf16 v[158:161], v[100:103], v[108:111], v[32:35]
	ds_read_b128 v[154:157], v4 offset:53248
	v_mfma_f32_16x16x32_bf16 v[162:165], v[104:107], v[108:111], v[44:47]
	v_mfma_f32_16x16x32_bf16 v[166:169], v[116:119], v[108:111], v[58:61]
	v_mfma_f32_16x16x32_bf16 v[100:103], v[100:103], v[112:115], v[36:39]
	ds_read_b128 v[108:111], v3 offset:38912
	v_mfma_f32_16x16x32_bf16 v[104:107], v[104:107], v[112:115], v[48:51]
	ds_read_b128 v[2:5], v4 offset:55296
	v_mfma_f32_16x16x32_bf16 v[116:119], v[116:119], v[112:115], v[52:55]
	v_mfma_f32_16x16x32_bf16 v[112:115], v[120:123], v[112:115], v[20:23]
	s_waitcnt lgkmcnt(6)
	v_mfma_f32_16x16x32_bf16 v[62:65], v[132:135], v[124:127], v[24:27]
	s_waitcnt lgkmcnt(4)
	v_mfma_f32_16x16x32_bf16 v[58:61], v[150:153], v[124:127], v[88:91]
	s_waitcnt lgkmcnt(2)
	v_mfma_f32_16x16x32_bf16 v[54:57], v[154:157], v[124:127], v[96:99]
	s_waitcnt lgkmcnt(0)
	v_mfma_f32_16x16x32_bf16 v[50:53], v[2:5], v[124:127], v[6:9]
	v_mfma_f32_16x16x32_bf16 v[46:49], v[132:135], v[146:149], v[28:31]
	v_mfma_f32_16x16x32_bf16 v[42:45], v[150:153], v[146:149], v[40:43]
	v_mfma_f32_16x16x32_bf16 v[38:41], v[154:157], v[146:149], v[92:95]
	v_mfma_f32_16x16x32_bf16 v[34:37], v[2:5], v[146:149], v[10:13]
	v_mfma_f32_16x16x32_bf16 v[30:33], v[132:135], v[84:87], v[158:161]
	v_mfma_f32_16x16x32_bf16 v[26:29], v[150:153], v[84:87], v[162:165]
	v_mfma_f32_16x16x32_bf16 v[22:25], v[154:157], v[84:87], v[166:169]
	v_mfma_f32_16x16x32_bf16 v[18:21], v[2:5], v[84:87], v[14:17]
	v_mfma_f32_16x16x32_bf16 v[14:17], v[132:135], v[108:111], v[100:103]
	v_mfma_f32_16x16x32_bf16 v[10:13], v[150:153], v[108:111], v[104:107]
	v_mfma_f32_16x16x32_bf16 v[6:9], v[154:157], v[108:111], v[116:119]
	v_mfma_f32_16x16x32_bf16 v[2:5], v[2:5], v[108:111], v[112:115]
	s_setprio 0
	s_and_b32 s1, s0, -8
	s_cmp_lg_u32 s1, 16
	s_barrier
; template <int MODE>
; __device__ __forceinline__ void gemm_tile(const Params& P, int tm, int tn, unsigned char* smem) {
;     ...
;     if (MODE == 1) {
;         if (n0 >= ZC_FQ && n0 < ZC_FV) {
;             const bool isk = n0 >= ZC_FK;
;             const float* gain = isk ? P.f_k_norm : P.f_q_norm;
;             const float scl = isk ? 1.0f : 0.125f * LOG2E;
;             float gn[4][4];
; #pragma unroll
;             for (int j = 0; j < 4; ++j)
; #pragma unroll
;                 for (int r = 0; r < 4; ++r) gn[j][r] = gain[16 * j + 4 * g + r];
; #pragma unroll
;             for (int i = 0; i < 4; ++i) {
;                 float ss = 0.f;
; #pragma unroll
;                 for (int j = 0; j < 4; ++j)
; #pragma unroll
;                     for (int r = 0; r < 4; ++r) ss += acc[i][j][r] * acc[i][j][r];
;                 ss = x4_sum(ss);
;                 const float rstd = rsqrtf(ss * (1.0f / 64.0f) + EPS) * scl;
	s_cbranch_scc1 .LBB0_181
	v_mul_f32_e32 v66, v63, v63
	v_fmac_f32_e32 v66, v62, v62
	v_fmac_f32_e32 v66, v64, v64
	v_fmac_f32_e32 v66, v65, v65
	v_fmac_f32_e32 v66, v58, v58
	v_fmac_f32_e32 v66, v59, v59
	v_fmac_f32_e32 v66, v60, v60
	v_fmac_f32_e32 v66, v61, v61
	v_fmac_f32_e32 v66, v54, v54
	v_fmac_f32_e32 v66, v55, v55
	v_fmac_f32_e32 v66, v56, v56
	v_fmac_f32_e32 v66, v57, v57
	v_pk_mul_f32 v[84:85], v[50:51], v[50:51]
	v_pk_mul_f32 v[68:69], v[52:53], v[52:53]
	v_add_f32_e32 v66, v84, v66
	v_add_f32_e32 v66, v85, v66
	v_add_f32_e32 v66, v68, v66
	v_add_f32_e32 v66, v69, v66
	v_mov_b32_e32 v68, v66
	s_nop 1
	v_permlane32_swap_b32_e32 v66, v68
	v_add_f32_e32 v69, v66, v68
	v_mul_f32_e32 v66, v47, v47
	v_fmac_f32_e32 v66, v46, v46
	v_fmac_f32_e32 v66, v48, v48
	v_fmac_f32_e32 v66, v49, v49
	v_fmac_f32_e32 v66, v42, v42
	v_fmac_f32_e32 v66, v43, v43
	v_fmac_f32_e32 v66, v44, v44
	v_fmac_f32_e32 v66, v45, v45
	v_fmac_f32_e32 v66, v38, v38
	v_fmac_f32_e32 v66, v39, v39
	v_fmac_f32_e32 v66, v40, v40
	v_fmac_f32_e32 v66, v41, v41
	v_pk_mul_f32 v[88:89], v[34:35], v[34:35]
	v_pk_mul_f32 v[86:87], v[36:37], v[36:37]
	v_add_f32_e32 v66, v88, v66
	v_add_f32_e32 v66, v89, v66
	v_add_f32_e32 v66, v86, v66
	v_add_f32_e32 v66, v87, v66
	v_mov_b32_e32 v68, v66
	s_nop 1
	v_permlane32_swap_b32_e32 v66, v68
	v_add_f32_e32 v68, v66, v68
	v_mov_b32_e32 v85, v69
	v_mov_b32_e32 v84, v68
	s_nop 0
	v_permlane16_swap_b32_e32 v69, v85
	v_permlane16_swap_b32_e32 v68, v84
	v_pk_add_f32 v[84:85], v[68:69], v[84:85]
	v_mov_b64_e32 v[68:69], s[8:9]
	v_mul_f32_e32 v97, v31, v31
	s_cmp_gt_u32 s0, 19
	v_pk_fma_f32 v[88:89], v[84:85], s[6:7], v[68:69] op_sel_hi:[1,0,0]
	v_fmac_f32_e32 v97, v30, v30
	s_cselect_b64 s[0:1], -1, 0
	v_mul_f32_e32 v66, 0x4b800000, v89
	v_cmp_gt_f32_e32 vcc, s21, v89
	v_fmac_f32_e32 v97, v32, v32
	v_cndmask_b32_e64 v108, v78, 1.0, s[0:1]
	s_and_b64 s[0:1], s[0:1], exec
	v_cndmask_b32_e32 v66, v89, v66, vcc
	v_fmac_f32_e32 v97, v33, v33
	v_rsq_f32_e32 v66, v66
	v_mul_f32_e32 v70, 0x4b800000, v88
	v_cmp_gt_f32_e64 s[0:1], s21, v88
	v_fmac_f32_e32 v97, v26, v26
	v_fmac_f32_e32 v97, v27, v27
	v_cndmask_b32_e64 v70, v88, v70, s[0:1]
	v_rsq_f32_e32 v88, v70
	v_fmac_f32_e32 v97, v28, v28
	s_cselect_b32 s13, s41, s39
	s_cselect_b32 s12, s40, s38
	v_lshlrev_b32_e32 v96, 4, v83
	v_fmac_f32_e32 v97, v29, v29
	global_load_dwordx4 v[84:87], v96, s[12:13]
	v_mul_f32_e32 v70, 0x45800000, v66
	v_fmac_f32_e32 v97, v22, v22
	v_cndmask_b32_e32 v66, v66, v70, vcc
	v_fmac_f32_e32 v97, v23, v23
	v_mul_f32_e32 v70, v108, v66
	v_mul_f32_e32 v66, 0x45800000, v88
	v_fmac_f32_e32 v97, v24, v24
	v_cndmask_b32_e64 v66, v88, v66, s[0:1]
	global_load_dwordx4 v[88:91], v96, s[12:13] offset:64
	v_fmac_f32_e32 v97, v25, v25
	v_pk_mul_f32 v[94:95], v[18:19], v[18:19]
	v_pk_mul_f32 v[92:93], v[20:21], v[20:21]
	v_add_f32_e32 v94, v94, v97
	v_add_f32_e32 v94, v95, v94
	v_add_f32_e32 v92, v92, v94
	v_add_f32_e32 v97, v93, v92
	global_load_dwordx4 v[92:95], v96, s[12:13] offset:128
	v_mov_b32_e32 v98, v97
	s_nop 1
	v_permlane32_swap_b32_e32 v97, v98
	v_add_f32_e32 v101, v97, v98
	global_load_dwordx4 v[96:99], v96, s[12:13] offset:192
	v_mul_f32_e32 v100, v15, v15
	v_fmac_f32_e32 v100, v14, v14
	v_fmac_f32_e32 v100, v16, v16
	v_fmac_f32_e32 v100, v17, v17
	v_fmac_f32_e32 v100, v10, v10
	v_fmac_f32_e32 v100, v11, v11
	v_fmac_f32_e32 v100, v12, v12
	v_fmac_f32_e32 v100, v13, v13
	v_fmac_f32_e32 v100, v6, v6
	v_fmac_f32_e32 v100, v7, v7
	v_fmac_f32_e32 v100, v8, v8
	v_fmac_f32_e32 v100, v9, v9
	v_pk_mul_f32 v[106:107], v[2:3], v[2:3]
	v_pk_mul_f32 v[104:105], v[4:5], v[4:5]
	v_add_f32_e32 v100, v106, v100
	v_add_f32_e32 v100, v107, v100
	v_add_f32_e32 v100, v104, v100
	v_add_f32_e32 v100, v105, v100
	v_mov_b32_e32 v102, v100
	s_nop 1
	v_permlane32_swap_b32_e32 v100, v102
	v_add_f32_e32 v100, v100, v102
	v_mov_b32_e32 v103, v101
	v_mov_b32_e32 v102, v100
	s_nop 0
	v_permlane16_swap_b32_e32 v101, v103
	v_permlane16_swap_b32_e32 v100, v102
	v_pk_add_f32 v[100:101], v[100:101], v[102:103]
	v_mul_f32_e32 v66, v108, v66
	v_pk_fma_f32 v[68:69], v[100:101], s[6:7], v[68:69] op_sel_hi:[1,0,0]
	s_waitcnt vmcnt(3)
; template <int MODE>
; __device__ __forceinline__ void gemm_tile(const Params& P, int tm, int tn, unsigned char* smem) {
;     ...
; #pragma unroll
;                 for (int j = 0; j < 4; ++j)
; #pragma unroll
;                     for (int r = 0; r < 4; ++r) acc[i][j][r] *= rstd * gn[j][r];
	v_pk_mul_f32 v[102:103], v[84:85], v[70:71] op_sel_hi:[1,0]
	v_mul_f32_e32 v100, 0x4b800000, v69
	v_cmp_gt_f32_e32 vcc, s21, v69
	v_cmp_gt_f32_e64 s[0:1], s21, v68
	v_pk_mul_f32 v[62:63], v[62:63], v[102:103]
	v_cndmask_b32_e32 v69, v69, v100, vcc
	v_mul_f32_e32 v100, 0x4b800000, v68
	v_rsq_f32_e32 v69, v69
	v_cndmask_b32_e64 v68, v68, v100, s[0:1]
	v_rsq_f32_e32 v100, v68
	v_pk_mul_f32 v[102:103], v[84:85], v[66:67] op_sel_hi:[1,0]
	v_mul_f32_e32 v68, 0x45800000, v69
	v_cndmask_b32_e32 v68, v69, v68, vcc
	v_mul_f32_e32 v69, 0x45800000, v100
	v_cndmask_b32_e64 v69, v100, v69, s[0:1]
	v_mul_f32_e32 v68, v108, v68
	v_mul_f32_e32 v100, v108, v69
	v_pk_mul_f32 v[104:105], v[86:87], v[70:71] op_sel_hi:[1,0]
	v_pk_mul_f32 v[46:47], v[46:47], v[102:103]
	v_pk_mul_f32 v[102:103], v[84:85], v[68:69] op_sel_hi:[1,0]
	v_pk_mul_f32 v[84:85], v[84:85], v[100:101] op_sel_hi:[1,0]
	v_pk_mul_f32 v[64:65], v[64:65], v[104:105]
	v_pk_mul_f32 v[104:105], v[86:87], v[66:67] op_sel_hi:[1,0]
	v_pk_mul_f32 v[14:15], v[14:15], v[84:85]
	s_waitcnt vmcnt(2)
	v_pk_mul_f32 v[84:85], v[88:89], v[70:71] op_sel_hi:[1,0]
	v_pk_mul_f32 v[48:49], v[48:49], v[104:105]
	v_pk_mul_f32 v[104:105], v[86:87], v[68:69] op_sel_hi:[1,0]
	v_pk_mul_f32 v[86:87], v[86:87], v[100:101] op_sel_hi:[1,0]
	v_pk_mul_f32 v[58:59], v[58:59], v[84:85]
	v_pk_mul_f32 v[84:85], v[88:89], v[66:67] op_sel_hi:[1,0]
	v_pk_mul_f32 v[16:17], v[16:17], v[86:87]
	v_pk_mul_f32 v[86:87], v[90:91], v[70:71] op_sel_hi:[1,0]
	v_pk_mul_f32 v[42:43], v[42:43], v[84:85]
	v_pk_mul_f32 v[84:85], v[88:89], v[68:69] op_sel_hi:[1,0]
	v_pk_mul_f32 v[60:61], v[60:61], v[86:87]
	v_pk_mul_f32 v[86:87], v[90:91], v[66:67] op_sel_hi:[1,0]
	v_pk_mul_f32 v[26:27], v[26:27], v[84:85]
	v_pk_mul_f32 v[84:85], v[88:89], v[100:101] op_sel_hi:[1,0]
	v_pk_mul_f32 v[44:45], v[44:45], v[86:87]
	v_pk_mul_f32 v[86:87], v[90:91], v[68:69] op_sel_hi:[1,0]
	v_pk_mul_f32 v[10:11], v[10:11], v[84:85]
	s_waitcnt vmcnt(1)
	v_pk_mul_f32 v[84:85], v[92:93], v[70:71] op_sel_hi:[1,0]
	v_pk_mul_f32 v[28:29], v[28:29], v[86:87]
	v_pk_mul_f32 v[86:87], v[90:91], v[100:101] op_sel_hi:[1,0]
	v_pk_mul_f32 v[54:55], v[54:55], v[84:85]
	v_pk_mul_f32 v[84:85], v[92:93], v[66:67] op_sel_hi:[1,0]
	v_pk_mul_f32 v[12:13], v[12:13], v[86:87]
	v_pk_mul_f32 v[86:87], v[94:95], v[70:71] op_sel_hi:[1,0]
	v_pk_mul_f32 v[38:39], v[38:39], v[84:85]
	v_pk_mul_f32 v[84:85], v[92:93], v[68:69] op_sel_hi:[1,0]
	v_pk_mul_f32 v[56:57], v[56:57], v[86:87]
	v_pk_mul_f32 v[86:87], v[94:95], v[66:67] op_sel_hi:[1,0]
	v_pk_mul_f32 v[22:23], v[22:23], v[84:85]
	v_pk_mul_f32 v[84:85], v[92:93], v[100:101] op_sel_hi:[1,0]
	v_pk_mul_f32 v[40:41], v[40:41], v[86:87]
	v_pk_mul_f32 v[86:87], v[94:95], v[68:69] op_sel_hi:[1,0]
	v_pk_mul_f32 v[6:7], v[6:7], v[84:85]
	s_waitcnt vmcnt(0)
	v_pk_mul_f32 v[84:85], v[96:97], v[70:71] op_sel_hi:[1,0]
	v_pk_mul_f32 v[24:25], v[24:25], v[86:87]
	v_pk_mul_f32 v[86:87], v[94:95], v[100:101] op_sel_hi:[1,0]
	v_pk_mul_f32 v[50:51], v[50:51], v[84:85]
	v_pk_mul_f32 v[84:85], v[96:97], v[66:67] op_sel_hi:[1,0]
	v_pk_mul_f32 v[8:9], v[8:9], v[86:87]
	v_pk_mul_f32 v[86:87], v[98:99], v[70:71] op_sel_hi:[1,0]
	v_pk_mul_f32 v[34:35], v[34:35], v[84:85]
	v_pk_mul_f32 v[84:85], v[96:97], v[68:69] op_sel_hi:[1,0]
	v_pk_mul_f32 v[68:69], v[98:99], v[68:69] op_sel_hi:[1,0]
	v_pk_mul_f32 v[52:53], v[52:53], v[86:87]
	v_pk_mul_f32 v[86:87], v[98:99], v[66:67] op_sel_hi:[1,0]
	v_pk_mul_f32 v[20:21], v[20:21], v[68:69]
	v_pk_mul_f32 v[18:19], v[18:19], v[84:85]
	v_pk_mul_f32 v[68:69], v[96:97], v[100:101] op_sel_hi:[1,0]
	v_pk_mul_f32 v[84:85], v[98:99], v[100:101] op_sel_hi:[1,0]
	v_pk_mul_f32 v[32:33], v[32:33], v[104:105]
	v_pk_mul_f32 v[30:31], v[30:31], v[102:103]
	v_pk_mul_f32 v[36:37], v[36:37], v[86:87]
	v_pk_mul_f32 v[4:5], v[4:5], v[84:85]
	v_pk_mul_f32 v[2:3], v[2:3], v[68:69]
	s_branch .LBB0_181

; template <int MODE>
; __device__ __forceinline__ void gemm_tile(const Params& P, int tm, int tn, unsigned char* smem) {
;     ...
;     const int srow = tid >> 3, sc = tid & 7;
;     constexpr unsigned LDA = (MODE == 2 ? NZ : 1024) * 2u;
;     unsigned aoff, boff; int soff0;
;     {
;         int ar = m0 + srow;
;         if (MODE == 2) { const int b = ar >> 11, t = ar & 2047; ar = b * L + NMETA + t; }
;         aoff = (unsigned)ar * LDA + (unsigned)sc * 16u;
;         boff = (unsigned)(n0 + srow) * 2048u + (unsigned)sc * 16u;
;         soff0 = srow * 128 + ((sc ^ (srow & 7)) << 4);
;     }
;     const unsigned char* Ab = (const unsigned char*)A; const unsigned char* Bb = (const unsigned char*)Bt;
;     float4 ssp0, ssp1, ssp2, ssp3;
;     if (MODE == 3) {
;         const float* ssq = (const float*)(P.ws + WS_SSQ) + (size_t)(m0 + wr * 64 + lr) * 16 + 4 * g;
;         ssp0 = *(const float4*)(ssq); ssp1 = *(const float4*)(ssq + 16 * 16); ssp2 = *(const float4*)(ssq + 32 * 16); ssp3 = *(const float4*)(ssq + 48 * 16);
;     }
;     f32x4 acc[4][4];
; #pragma unroll
;     for (int i = 0; i < 4; ++i)
; #pragma unroll
;         for (int j = 0; j < 4; ++j) acc[i][j] = (f32x4){0.f, 0.f, 0.f, 0.f};
;     uint4 ra0, ra1, ra2, ra3, rb0, rb1, rb2, rb3;
;     ...
;     unsigned char* sA0 = smem; unsigned char* sB0 = smem + 16384; unsigned char* sA1 = smem + 32768; unsigned char* sB1 = smem + 49152;
;     G_LOAD(0)
;     G_WRITE(sA0, sB0)
;     __syncthreads();
;     const int arow_off = (wr * 64 + lr) * 128, brow_off = (wc * 64 + lr) * 128, sw = lr & 7;
;     G_LOAD(1)
;     for (int kt = 0; kt < 16; ++kt) {
;         unsigned char* sA = (kt & 1) ? sA1 : sA0; unsigned char* sB = (kt & 1) ? sB1 : sB0;
;         unsigned char* nA = (kt & 1) ? sA0 : sA1; unsigned char* nB = (kt & 1) ? sB0 : sB1;
;         bf16x8 fa[4], fb[4], ga[4], gb[4];
;         const int ch0 = ((g ^ sw) << 4), ch1 = (((4 + g) ^ sw) << 4);
;         const unsigned ko = (unsigned)(kt + 2) * 128u;
;         const unsigned koa = ko + ((MODE == 2 && kt + 2 >= 8) ? (unsigned)(ZC_FQ - 512) * 2u : 0u);
;         const bool wr_ok = kt < 15, ld_ok = kt < 14;
; #pragma unroll
;         for (int i = 0; i < 4; ++i) { fa[i] = *(const bf16x8*)(sA + arow_off + i * 2048 + ch0); fb[i] = *(const bf16x8*)(sB + brow_off + i * 2048 + ch0); }
;         __builtin_amdgcn_sched_barrier(0);
;         __builtin_amdgcn_s_setprio(2);
.LBB0_221:
	s_add_i32 s0, s14, s3
	s_mul_hi_i32 s1, s0, 0x92492493
	s_add_i32 s1, s1, s0
	s_lshr_b32 s6, s1, 31
	s_ashr_i32 s1, s1, 7
	s_add_i32 s1, s1, s6
	s_mul_i32 s6, s1, 0xffffff20
	s_lshl_b32 s1, s1, 3
	s_add_i32 s6, s6, s0
	s_sub_i32 s7, 0x81, s1
	s_cmpk_gt_i32 s0, 0xdff
	s_cselect_b32 s0, s7, 8
	s_abs_i32 s7, s0
	v_cvt_f32_u32_e32 v2, s7
	s_sub_i32 s10, 0, s7
	s_abs_i32 s8, s6
	s_xor_b32 s9, s6, s0
	v_rcp_iflag_f32_e32 v2, v2
	s_ashr_i32 s9, s9, 31
	v_mov_b32_e32 v69, v0
	v_mul_f32_e32 v2, 0x4f7ffffe, v2
	v_cvt_u32_f32_e32 v2, v2
	v_lshlrev_b32_e32 v3, 4, v69
	v_and_b32_e32 v5, 0x70, v3
	v_and_b32_e32 v78, 15, v69
	v_readfirstlane_b32 s11, v2
	s_mul_i32 s10, s10, s11
	s_mul_hi_u32 s10, s11, s10
	s_add_i32 s11, s11, s10
	s_mul_hi_u32 s10, s8, s11
	s_mul_i32 s11, s10, s7
	s_sub_i32 s8, s8, s11
	s_add_i32 s12, s10, 1
	s_sub_i32 s11, s8, s7
	s_cmp_ge_u32 s8, s7
	s_cselect_b32 s10, s12, s10
	s_cselect_b32 s8, s11, s8
	s_add_i32 s11, s10, 1
	s_cmp_ge_u32 s8, s7
	s_cselect_b32 s7, s11, s10
	s_xor_b32 s7, s7, s9
	s_sub_i32 s7, s7, s9
	s_mul_i32 s0, s7, s0
	s_add_i32 s6, s6, s1
	s_sub_i32 s0, s6, s0
	s_lshl_b32 s11, s0, 7
	v_ashrrev_i32_e32 v2, 3, v69
	s_lshl_b32 s6, s7, 7
	v_add_u32_e32 v4, s11, v2
	v_add_u32_e32 v3, s6, v2
	v_lshl_or_b32 v8, v4, 11, v5
	v_lshl_or_b32 v3, v3, 11, v5
	s_add_u32 s0, s28, 0xc075800
	v_add_u32_e32 v9, 0x10000, v8
	s_addc_u32 s1, s29, 0
	v_add_u32_e32 v22, 0x20000, v8
	global_load_dwordx4 v[4:7], v9, s[36:37]
	global_load_dwordx4 v[10:13], v22, s[36:37]
	global_load_dwordx4 v[14:17], v8, s[36:37]
	global_load_dwordx4 v[18:21], v3, s[0:1]
	v_add_u32_e32 v9, 0x20000, v3
	v_add_u32_e32 v30, 0x30000, v3
	global_load_dwordx4 v[22:25], v9, s[0:1]
	global_load_dwordx4 v[26:29], v30, s[0:1]
	v_add_u32_e32 v9, 0x30000, v8
	v_add_u32_e32 v38, 0x10000, v3
	global_load_dwordx4 v[30:33], v9, s[36:37]
	global_load_dwordx4 v[34:37], v38, s[0:1]
	v_xor_b32_e32 v9, v2, v69
	s_movk_i32 s8, 0x70
	v_lshlrev_b32_e32 v2, 7, v2
	v_lshlrev_b32_e32 v9, 4, v9
	v_and_or_b32 v2, v9, s8, v2
	v_add_u32_e32 v2, 0, v2
	v_or_b32_e32 v45, 0x80, v8
	v_or_b32_e32 v9, 0x80, v3
	v_add_u32_e32 v42, 0x10080, v3
	v_add_u32_e32 v43, 0x20080, v3
	v_add_u32_e32 v44, 0x30080, v3
	v_add_u32_e32 v46, 0x10080, v8
	v_add_u32_e32 v47, 0x20080, v8
	v_add_u32_e32 v48, 0x30080, v8
	v_ashrrev_i32_e32 v79, 7, v69
	v_bfe_u32 v80, v69, 6, 1
	v_bfe_u32 v81, v69, 4, 2
	s_waitcnt vmcnt(5)
	ds_write_b128 v2, v[14:17]
	s_waitcnt vmcnt(4)
	ds_write_b128 v2, v[18:21] offset:16384
	s_waitcnt vmcnt(3)
	ds_write_b128 v2, v[22:25] offset:24576
	s_waitcnt vmcnt(2)
	ds_write_b128 v2, v[26:29] offset:28672
	ds_write_b128 v2, v[4:7] offset:4096
	ds_write_b128 v2, v[10:13] offset:8192
	s_waitcnt vmcnt(1)
	ds_write_b128 v2, v[30:33] offset:12288
	s_waitcnt vmcnt(0)
	ds_write_b128 v2, v[34:37] offset:20480
	s_waitcnt lgkmcnt(0)
	s_barrier
	global_load_dwordx4 v[10:13], v45, s[36:37]
	global_load_dwordx4 v[14:17], v46, s[36:37]
	global_load_dwordx4 v[18:21], v47, s[36:37]
	global_load_dwordx4 v[22:25], v48, s[36:37]
	global_load_dwordx4 v[26:29], v9, s[0:1]
	global_load_dwordx4 v[30:33], v42, s[0:1]
	global_load_dwordx4 v[34:37], v43, s[0:1]
	global_load_dwordx4 v[38:41], v44, s[0:1]
	v_lshrrev_b32_e32 v4, 4, v69
	v_lshlrev_b32_e32 v5, 7, v78
	v_and_b32_e32 v9, 7, v69
	v_lshl_or_b32 v6, v79, 13, v5
	v_bitop3_b32 v4, v4, v9, 3 bitop3:0x6c
	v_lshl_or_b32 v5, v80, 13, v5
	v_lshlrev_b32_e32 v4, 4, v4
	v_add_u32_e32 v66, 0, v6
	v_add_u32_e32 v6, v66, v4
	v_add_u32_e32 v5, 0, v5
	v_add_u32_e32 v7, v5, v4
	ds_read_b128 v[42:45], v6
	ds_read_b128 v[46:49], v6 offset:2048
	ds_read_b128 v[50:53], v7 offset:16384
	ds_read_b128 v[54:57], v7 offset:18432
	ds_read_b128 v[58:61], v6 offset:4096
	ds_read_b128 v[62:65], v6 offset:6144
	ds_read_b128 v[82:85], v7 offset:20480
	ds_read_b128 v[86:89], v7 offset:22528
	v_bitop3_b32 v4, v81, v9, 4 bitop3:0x36
	v_lshlrev_b32_e32 v9, 4, v4
	s_setprio 2
	global_load_dwordx4 v[90:93], v8, s[36:37] offset:256
	s_waitcnt vmcnt(8)
	ds_write_b128 v2, v[10:13] offset:32768
	v_add_u32_e32 v4, v66, v9
	v_add_u32_e32 v5, v5, v9
	ds_read_b128 v[10:13], v4
	ds_read_b128 v[94:97], v5 offset:16384
	s_waitcnt lgkmcnt(8)
	v_mfma_f32_16x16x32_bf16 v[98:101], v[50:53], v[42:45], 0
	s_waitcnt lgkmcnt(7)
	v_mfma_f32_16x16x32_bf16 v[102:105], v[54:57], v[42:45], 0
	s_waitcnt lgkmcnt(4)
	v_mfma_f32_16x16x32_bf16 v[106:109], v[82:85], v[42:45], 0
	s_waitcnt lgkmcnt(3)
	v_mfma_f32_16x16x32_bf16 v[42:45], v[86:89], v[42:45], 0
	v_add_u32_e32 v222, 0x10000, v8
	global_load_dwordx4 v[110:113], v222, s[36:37] offset:256
	s_waitcnt vmcnt(8)
	ds_write_b128 v2, v[14:17] offset:36864
	ds_read_b128 v[14:17], v4 offset:2048
	ds_read_b128 v[114:117], v5 offset:18432
	v_mfma_f32_16x16x32_bf16 v[118:121], v[50:53], v[46:49], 0
	v_mfma_f32_16x16x32_bf16 v[122:125], v[54:57], v[46:49], 0
	v_mfma_f32_16x16x32_bf16 v[126:129], v[82:85], v[46:49], 0
	v_mfma_f32_16x16x32_bf16 v[46:49], v[86:89], v[46:49], 0
	v_add_u32_e32 v223, 0x20000, v8
	global_load_dwordx4 v[132:135], v223, s[36:37] offset:256
	s_waitcnt vmcnt(8)
	ds_write_b128 v2, v[18:21] offset:40960
	ds_read_b128 v[18:21], v4 offset:4096
	ds_read_b128 v[146:149], v5 offset:20480
	v_mfma_f32_16x16x32_bf16 v[150:153], v[50:53], v[58:61], 0
	v_mfma_f32_16x16x32_bf16 v[154:157], v[54:57], v[58:61], 0
	v_mfma_f32_16x16x32_bf16 v[158:161], v[82:85], v[58:61], 0
	v_mfma_f32_16x16x32_bf16 v[58:61], v[86:89], v[58:61], 0
	v_add_u32_e32 v224, 0x30000, v8
	global_load_dwordx4 v[162:165], v224, s[36:37] offset:256
	s_waitcnt vmcnt(8)
; template <int MODE>
; __device__ __forceinline__ void gemm_tile(const Params& P, int tm, int tn, unsigned char* smem) {
;     ...
;     for (int kt = 0; kt < 16; ++kt) {
;         unsigned char* sA = (kt & 1) ? sA1 : sA0; unsigned char* sB = (kt & 1) ? sB1 : sB0;
;         unsigned char* nA = (kt & 1) ? sA0 : sA1; unsigned char* nB = (kt & 1) ? sB0 : sB1;
;         bf16x8 fa[4], fb[4], ga[4], gb[4];
;         const int ch0 = ((g ^ sw) << 4), ch1 = (((4 + g) ^ sw) << 4);
;         const unsigned ko = (unsigned)(kt + 2) * 128u;
;         const unsigned koa = ko + ((MODE == 2 && kt + 2 >= 8) ? (unsigned)(ZC_FQ - 512) * 2u : 0u);
;         const bool wr_ok = kt < 15, ld_ok = kt < 14;
; #pragma unroll
;         for (int i = 0; i < 4; ++i) { fa[i] = *(const bf16x8*)(sA + arow_off + i * 2048 + ch0); fb[i] = *(const bf16x8*)(sB + brow_off + i * 2048 + ch0); }
;         __builtin_amdgcn_sched_barrier(0);
;         __builtin_amdgcn_s_setprio(2);
;         if (wr_ok) *(uint4*)(nA + soff0) = ra0;
;         if (ld_ok) ra0 = *(const uint4*)(Ab + (aoff + 0u * LDA + koa));
;         ga[0] = *(const bf16x8*)(sA + arow_off + 0 * 2048 + ch1); gb[0] = *(const bf16x8*)(sB + brow_off + 0 * 2048 + ch1);
;         __builtin_amdgcn_sched_barrier(0);
; #pragma unroll
;         for (int j = 0; j < 4; ++j) acc[0][j] = __builtin_amdgcn_mfma_f32_16x16x32_bf16(fb[j], fa[0], acc[0][j], 0, 0, 0);
;         __builtin_amdgcn_sched_barrier(0);
;         if (wr_ok) *(uint4*)(nA + soff0 + 4096) = ra1;
;         if (ld_ok) ra1 = *(const uint4*)(Ab + (aoff + 32u * LDA + koa));
;         ga[1] = *(const bf16x8*)(sA + arow_off + 1 * 2048 + ch1); gb[1] = *(const bf16x8*)(sB + brow_off + 1 * 2048 + ch1);
;         __builtin_amdgcn_sched_barrier(0);
; #pragma unroll
;         for (int j = 0; j < 4; ++j) acc[1][j] = __builtin_amdgcn_mfma_f32_16x16x32_bf16(fb[j], fa[1], acc[1][j], 0, 0, 0);
;         __builtin_amdgcn_sched_barrier(0);
;         if (wr_ok) *(uint4*)(nA + soff0 + 8192) = ra2;
;         if (ld_ok) ra2 = *(const uint4*)(Ab + (aoff + 64u * LDA + koa));
;         ga[2] = *(const bf16x8*)(sA + arow_off + 2 * 2048 + ch1); gb[2] = *(const bf16x8*)(sB + brow_off + 2 * 2048 + ch1);
;         __builtin_amdgcn_sched_barrier(0);
; #pragma unroll
;         for (int j = 0; j < 4; ++j) acc[2][j] = __builtin_amdgcn_mfma_f32_16x16x32_bf16(fb[j], fa[2], acc[2][j], 0, 0, 0);
	ds_write_b128 v2, v[22:25] offset:45056
	ds_read_b128 v[22:25], v4 offset:6144
	ds_read_b128 v[166:169], v5 offset:22528
	v_mfma_f32_16x16x32_bf16 v[50:53], v[50:53], v[62:65], 0
	v_mfma_f32_16x16x32_bf16 v[54:57], v[54:57], v[62:65], 0
	v_mfma_f32_16x16x32_bf16 v[82:85], v[82:85], v[62:65], 0
	v_mfma_f32_16x16x32_bf16 v[62:65], v[86:89], v[62:65], 0
	global_load_dwordx4 v[86:89], v3, s[0:1] offset:256
	s_waitcnt vmcnt(8)
	ds_write_b128 v2, v[26:29] offset:49152
	s_waitcnt lgkmcnt(10)
	v_mfma_f32_16x16x32_bf16 v[26:29], v[94:97], v[10:13], v[98:101]
	s_waitcnt lgkmcnt(7)
	v_mfma_f32_16x16x32_bf16 v[98:101], v[114:117], v[10:13], v[102:105]
	s_waitcnt lgkmcnt(4)
	v_mfma_f32_16x16x32_bf16 v[102:105], v[146:149], v[10:13], v[106:109]
	s_waitcnt lgkmcnt(1)
	v_mfma_f32_16x16x32_bf16 v[10:13], v[166:169], v[10:13], v[42:45]
	v_add_u32_e32 v225, 0x10000, v3
	global_load_dwordx4 v[42:45], v225, s[0:1] offset:256
	s_waitcnt vmcnt(8)
	ds_write_b128 v2, v[30:33] offset:53248
	v_mfma_f32_16x16x32_bf16 v[30:33], v[94:97], v[14:17], v[118:121]
	v_mfma_f32_16x16x32_bf16 v[106:109], v[114:117], v[14:17], v[122:125]
	v_mfma_f32_16x16x32_bf16 v[118:121], v[146:149], v[14:17], v[126:129]
	v_mfma_f32_16x16x32_bf16 v[14:17], v[166:169], v[14:17], v[46:49]
	v_add_u32_e32 v226, 0x20000, v3
	global_load_dwordx4 v[46:49], v226, s[0:1] offset:256
	s_waitcnt vmcnt(8)
	ds_write_b128 v2, v[34:37] offset:57344
	v_mfma_f32_16x16x32_bf16 v[34:37], v[94:97], v[18:21], v[150:153]
	v_mfma_f32_16x16x32_bf16 v[122:125], v[114:117], v[18:21], v[154:157]
	v_mfma_f32_16x16x32_bf16 v[126:129], v[146:149], v[18:21], v[158:161]
	v_mfma_f32_16x16x32_bf16 v[18:21], v[166:169], v[18:21], v[58:61]
	v_add_u32_e32 v227, 0x30000, v3
	global_load_dwordx4 v[58:61], v227, s[0:1] offset:256
	s_waitcnt vmcnt(8)
	ds_write_b128 v2, v[38:41] offset:61440
	v_mfma_f32_16x16x32_bf16 v[38:41], v[94:97], v[22:25], v[50:53]
	v_mfma_f32_16x16x32_bf16 v[50:53], v[114:117], v[22:25], v[54:57]
	v_mfma_f32_16x16x32_bf16 v[54:57], v[146:149], v[22:25], v[82:85]
	v_mfma_f32_16x16x32_bf16 v[22:25], v[166:169], v[22:25], v[62:65]
	s_setprio 0
	s_waitcnt lgkmcnt(0)
	s_barrier
	ds_read_b128 v[62:65], v6 offset:32768
	ds_read_b128 v[82:85], v6 offset:34816
	ds_read_b128 v[94:97], v7 offset:49152
	ds_read_b128 v[114:117], v7 offset:51200
	ds_read_b128 v[146:149], v6 offset:36864
	ds_read_b128 v[150:153], v6 offset:38912
	ds_read_b128 v[154:157], v7 offset:53248
	ds_read_b128 v[158:161], v7 offset:55296
	s_setprio 2
	s_waitcnt lgkmcnt(5)
	v_mfma_f32_16x16x32_bf16 v[26:29], v[94:97], v[62:65], v[26:29]
	global_load_dwordx4 v[166:169], v8, s[36:37] offset:384
	s_waitcnt lgkmcnt(0)
	v_mfma_f32_16x16x32_bf16 v[10:13], v[158:161], v[62:65], v[10:13]
	s_waitcnt vmcnt(8)
	ds_write_b128 v2, v[90:93]
	v_mfma_f32_16x16x32_bf16 v[98:101], v[114:117], v[62:65], v[98:101]
	ds_read_b128 v[90:93], v4 offset:32768
	v_mfma_f32_16x16x32_bf16 v[102:105], v[154:157], v[62:65], v[102:105]
	ds_read_b128 v[170:173], v5 offset:49152
	global_load_dwordx4 v[62:65], v222, s[36:37] offset:384
	v_mfma_f32_16x16x32_bf16 v[30:33], v[94:97], v[82:85], v[30:33]
	s_waitcnt vmcnt(8)
	ds_write_b128 v2, v[110:113] offset:4096
	v_mfma_f32_16x16x32_bf16 v[14:17], v[158:161], v[82:85], v[14:17]
	ds_read_b128 v[110:113], v4 offset:34816
	v_mfma_f32_16x16x32_bf16 v[106:109], v[114:117], v[82:85], v[106:109]
	ds_read_b128 v[174:177], v5 offset:51200
	v_mfma_f32_16x16x32_bf16 v[118:121], v[154:157], v[82:85], v[118:121]
	global_load_dwordx4 v[82:85], v223, s[36:37] offset:384
	v_mfma_f32_16x16x32_bf16 v[34:37], v[94:97], v[146:149], v[34:37]
	s_waitcnt vmcnt(8)
	ds_write_b128 v2, v[132:135] offset:8192
	v_mfma_f32_16x16x32_bf16 v[18:21], v[158:161], v[146:149], v[18:21]
	ds_read_b128 v[132:135], v4 offset:36864
	v_mfma_f32_16x16x32_bf16 v[122:125], v[114:117], v[146:149], v[122:125]
	ds_read_b128 v[178:181], v5 offset:53248
	v_mfma_f32_16x16x32_bf16 v[126:129], v[154:157], v[146:149], v[126:129]
	global_load_dwordx4 v[146:149], v224, s[36:37] offset:384
	v_mfma_f32_16x16x32_bf16 v[38:41], v[94:97], v[150:153], v[38:41]
	s_waitcnt vmcnt(8)
	ds_write_b128 v2, v[162:165] offset:12288
	v_mfma_f32_16x16x32_bf16 v[50:53], v[114:117], v[150:153], v[50:53]
	ds_read_b128 v[162:165], v4 offset:38912
	v_mfma_f32_16x16x32_bf16 v[54:57], v[154:157], v[150:153], v[54:57]
	ds_read_b128 v[182:185], v5 offset:55296
	v_mfma_f32_16x16x32_bf16 v[22:25], v[158:161], v[150:153], v[22:25]
	global_load_dwordx4 v[94:97], v3, s[0:1] offset:384
	s_waitcnt vmcnt(8)
	ds_write_b128 v2, v[86:89] offset:16384
	s_waitcnt lgkmcnt(10)
	v_mfma_f32_16x16x32_bf16 v[26:29], v[170:173], v[90:93], v[26:29]
	s_waitcnt lgkmcnt(1)
	v_mfma_f32_16x16x32_bf16 v[10:13], v[182:185], v[90:93], v[10:13]
	v_mfma_f32_16x16x32_bf16 v[86:89], v[174:177], v[90:93], v[98:101]
	v_mfma_f32_16x16x32_bf16 v[98:101], v[178:181], v[90:93], v[102:105]
	global_load_dwordx4 v[90:93], v225, s[0:1] offset:384
	s_waitcnt vmcnt(8)
	ds_write_b128 v2, v[42:45] offset:20480
	v_mfma_f32_16x16x32_bf16 v[30:33], v[170:173], v[110:113], v[30:33]
	v_mfma_f32_16x16x32_bf16 v[42:45], v[174:177], v[110:113], v[106:109]
	v_mfma_f32_16x16x32_bf16 v[14:17], v[182:185], v[110:113], v[14:17]
	v_mfma_f32_16x16x32_bf16 v[102:105], v[178:181], v[110:113], v[118:121]
	global_load_dwordx4 v[106:109], v226, s[0:1] offset:384
	s_waitcnt vmcnt(8)
	ds_write_b128 v2, v[46:49] offset:24576
	v_mfma_f32_16x16x32_bf16 v[34:37], v[170:173], v[132:135], v[34:37]
	v_mfma_f32_16x16x32_bf16 v[46:49], v[174:177], v[132:135], v[122:125]
	v_mfma_f32_16x16x32_bf16 v[18:21], v[182:185], v[132:135], v[18:21]
	v_mfma_f32_16x16x32_bf16 v[110:113], v[178:181], v[132:135], v[126:129]
	global_load_dwordx4 v[114:117], v227, s[0:1] offset:384
	v_mfma_f32_16x16x32_bf16 v[38:41], v[170:173], v[162:165], v[38:41]
	s_waitcnt vmcnt(8)
	ds_write_b128 v2, v[58:61] offset:28672
	v_mfma_f32_16x16x32_bf16 v[50:53], v[174:177], v[162:165], v[50:53]
	v_mfma_f32_16x16x32_bf16 v[54:57], v[178:181], v[162:165], v[54:57]
	v_mfma_f32_16x16x32_bf16 v[22:25], v[182:185], v[162:165], v[22:25]
	s_setprio 0
	s_waitcnt lgkmcnt(0)
	s_barrier
; template <int MODE>
; __device__ __forceinline__ void gemm_tile(const Params& P, int tm, int tn, unsigned char* smem) {
;     ...
;     for (int kt = 0; kt < 16; ++kt) {
;         unsigned char* sA = (kt & 1) ? sA1 : sA0; unsigned char* sB = (kt & 1) ? sB1 : sB0;
;         unsigned char* nA = (kt & 1) ? sA0 : sA1; unsigned char* nB = (kt & 1) ? sB0 : sB1;
;         bf16x8 fa[4], fb[4], ga[4], gb[4];
;         const int ch0 = ((g ^ sw) << 4), ch1 = (((4 + g) ^ sw) << 4);
;         const unsigned ko = (unsigned)(kt + 2) * 128u;
;         const unsigned koa = ko + ((MODE == 2 && kt + 2 >= 8) ? (unsigned)(ZC_FQ - 512) * 2u : 0u);
;         const bool wr_ok = kt < 15, ld_ok = kt < 14;
; #pragma unroll
;         for (int i = 0; i < 4; ++i) { fa[i] = *(const bf16x8*)(sA + arow_off + i * 2048 + ch0); fb[i] = *(const bf16x8*)(sB + brow_off + i * 2048 + ch0); }
;         __builtin_amdgcn_sched_barrier(0);
;         __builtin_amdgcn_s_setprio(2);
;         if (wr_ok) *(uint4*)(nA + soff0) = ra0;
;         if (ld_ok) ra0 = *(const uint4*)(Ab + (aoff + 0u * LDA + koa));
;         ga[0] = *(const bf16x8*)(sA + arow_off + 0 * 2048 + ch1); gb[0] = *(const bf16x8*)(sB + brow_off + 0 * 2048 + ch1);
;         __builtin_amdgcn_sched_barrier(0);
; #pragma unroll
;         for (int j = 0; j < 4; ++j) acc[0][j] = __builtin_amdgcn_mfma_f32_16x16x32_bf16(fb[j], fa[0], acc[0][j], 0, 0, 0);
;         __builtin_amdgcn_sched_barrier(0);
;         if (wr_ok) *(uint4*)(nA + soff0 + 4096) = ra1;
;         if (ld_ok) ra1 = *(const uint4*)(Ab + (aoff + 32u * LDA + koa));
;         ga[1] = *(const bf16x8*)(sA + arow_off + 1 * 2048 + ch1); gb[1] = *(const bf16x8*)(sB + brow_off + 1 * 2048 + ch1);
;         __builtin_amdgcn_sched_barrier(0);
; #pragma unroll
;         for (int j = 0; j < 4; ++j) acc[1][j] = __builtin_amdgcn_mfma_f32_16x16x32_bf16(fb[j], fa[1], acc[1][j], 0, 0, 0);
;         __builtin_amdgcn_sched_barrier(0);
;         if (wr_ok) *(uint4*)(nA + soff0 + 8192) = ra2;
;         if (ld_ok) ra2 = *(const uint4*)(Ab + (aoff + 64u * LDA + koa));
;         ga[2] = *(const bf16x8*)(sA + arow_off + 2 * 2048 + ch1); gb[2] = *(const bf16x8*)(sB + brow_off + 2 * 2048 + ch1);
;         __builtin_amdgcn_sched_barrier(0);
; #pragma unroll
;         for (int j = 0; j < 4; ++j) acc[2][j] = __builtin_amdgcn_mfma_f32_16x16x32_bf16(fb[j], fa[2], acc[2][j], 0, 0, 0);
	ds_read_b128 v[58:61], v6
	ds_read_b128 v[118:121], v6 offset:2048
	ds_read_b128 v[122:125], v7 offset:16384
	ds_read_b128 v[126:129], v7 offset:18432
	ds_read_b128 v[132:135], v6 offset:4096
	ds_read_b128 v[150:153], v6 offset:6144
	ds_read_b128 v[154:157], v7 offset:20480
	ds_read_b128 v[158:161], v7 offset:22528
	s_setprio 2
	s_waitcnt lgkmcnt(5)
	v_mfma_f32_16x16x32_bf16 v[26:29], v[122:125], v[58:61], v[26:29]
	global_load_dwordx4 v[162:165], v8, s[36:37] offset:512
	s_waitcnt lgkmcnt(0)
	v_mfma_f32_16x16x32_bf16 v[10:13], v[158:161], v[58:61], v[10:13]
	s_waitcnt vmcnt(8)
	ds_write_b128 v2, v[166:169] offset:32768
	v_mfma_f32_16x16x32_bf16 v[86:89], v[126:129], v[58:61], v[86:89]
	ds_read_b128 v[166:169], v4
	v_mfma_f32_16x16x32_bf16 v[98:101], v[154:157], v[58:61], v[98:101]
	ds_read_b128 v[170:173], v5 offset:16384
	global_load_dwordx4 v[58:61], v222, s[36:37] offset:512
	v_mfma_f32_16x16x32_bf16 v[30:33], v[122:125], v[118:121], v[30:33]
	s_waitcnt vmcnt(8)
	ds_write_b128 v2, v[62:65] offset:36864
	v_mfma_f32_16x16x32_bf16 v[42:45], v[126:129], v[118:121], v[42:45]
	ds_read_b128 v[62:65], v4 offset:2048
	v_mfma_f32_16x16x32_bf16 v[14:17], v[158:161], v[118:121], v[14:17]
	ds_read_b128 v[174:177], v5 offset:18432
	v_mfma_f32_16x16x32_bf16 v[102:105], v[154:157], v[118:121], v[102:105]
	global_load_dwordx4 v[118:121], v223, s[36:37] offset:512
	v_mfma_f32_16x16x32_bf16 v[34:37], v[122:125], v[132:135], v[34:37]
	s_waitcnt vmcnt(8)
	ds_write_b128 v2, v[82:85] offset:40960
	v_mfma_f32_16x16x32_bf16 v[46:49], v[126:129], v[132:135], v[46:49]
	ds_read_b128 v[82:85], v4 offset:4096
	v_mfma_f32_16x16x32_bf16 v[18:21], v[158:161], v[132:135], v[18:21]
	ds_read_b128 v[178:181], v5 offset:20480
	v_mfma_f32_16x16x32_bf16 v[110:113], v[154:157], v[132:135], v[110:113]
	global_load_dwordx4 v[132:135], v224, s[36:37] offset:512
	v_mfma_f32_16x16x32_bf16 v[38:41], v[122:125], v[150:153], v[38:41]
	s_waitcnt vmcnt(8)
	ds_write_b128 v2, v[146:149] offset:45056
	v_mfma_f32_16x16x32_bf16 v[50:53], v[126:129], v[150:153], v[50:53]
	ds_read_b128 v[146:149], v4 offset:6144
	v_mfma_f32_16x16x32_bf16 v[54:57], v[154:157], v[150:153], v[54:57]
	ds_read_b128 v[182:185], v5 offset:22528
	v_mfma_f32_16x16x32_bf16 v[22:25], v[158:161], v[150:153], v[22:25]
	global_load_dwordx4 v[122:125], v3, s[0:1] offset:512
	s_waitcnt vmcnt(8)
	ds_write_b128 v2, v[94:97] offset:49152
	s_waitcnt lgkmcnt(10)
	v_mfma_f32_16x16x32_bf16 v[26:29], v[170:173], v[166:169], v[26:29]
	s_waitcnt lgkmcnt(1)
	v_mfma_f32_16x16x32_bf16 v[10:13], v[182:185], v[166:169], v[10:13]
	v_mfma_f32_16x16x32_bf16 v[86:89], v[174:177], v[166:169], v[86:89]
	v_mfma_f32_16x16x32_bf16 v[94:97], v[178:181], v[166:169], v[98:101]
	global_load_dwordx4 v[98:101], v225, s[0:1] offset:512
	s_waitcnt vmcnt(8)
	ds_write_b128 v2, v[90:93] offset:53248
	v_mfma_f32_16x16x32_bf16 v[30:33], v[170:173], v[62:65], v[30:33]
	v_mfma_f32_16x16x32_bf16 v[42:45], v[174:177], v[62:65], v[42:45]
	v_mfma_f32_16x16x32_bf16 v[14:17], v[182:185], v[62:65], v[14:17]
	v_mfma_f32_16x16x32_bf16 v[90:93], v[178:181], v[62:65], v[102:105]
	global_load_dwordx4 v[62:65], v226, s[0:1] offset:512
	v_mfma_f32_16x16x32_bf16 v[34:37], v[170:173], v[82:85], v[34:37]
	s_waitcnt vmcnt(8)
	ds_write_b128 v2, v[106:109] offset:57344
	v_mfma_f32_16x16x32_bf16 v[46:49], v[174:177], v[82:85], v[46:49]
	v_mfma_f32_16x16x32_bf16 v[18:21], v[182:185], v[82:85], v[18:21]
	v_mfma_f32_16x16x32_bf16 v[102:105], v[178:181], v[82:85], v[110:113]
	global_load_dwordx4 v[82:85], v227, s[0:1] offset:512
	v_mfma_f32_16x16x32_bf16 v[38:41], v[170:173], v[146:149], v[38:41]
	s_waitcnt vmcnt(8)
	ds_write_b128 v2, v[114:117] offset:61440
	v_mfma_f32_16x16x32_bf16 v[50:53], v[174:177], v[146:149], v[50:53]
	v_mfma_f32_16x16x32_bf16 v[54:57], v[178:181], v[146:149], v[54:57]
	v_mfma_f32_16x16x32_bf16 v[22:25], v[182:185], v[146:149], v[22:25]
	s_setprio 0
	s_waitcnt lgkmcnt(0)
	s_barrier
	ds_read_b128 v[106:109], v6 offset:32768
	ds_read_b128 v[110:113], v6 offset:34816
	ds_read_b128 v[114:117], v7 offset:49152
	ds_read_b128 v[126:129], v7 offset:51200
	ds_read_b128 v[146:149], v6 offset:36864
	ds_read_b128 v[150:153], v6 offset:38912
	ds_read_b128 v[154:157], v7 offset:53248
	ds_read_b128 v[158:161], v7 offset:55296
	s_setprio 2
	s_waitcnt lgkmcnt(5)
	v_mfma_f32_16x16x32_bf16 v[26:29], v[114:117], v[106:109], v[26:29]
	global_load_dwordx4 v[166:169], v8, s[36:37] offset:640
	s_waitcnt lgkmcnt(0)
	v_mfma_f32_16x16x32_bf16 v[10:13], v[158:161], v[106:109], v[10:13]
	s_waitcnt vmcnt(8)
	ds_write_b128 v2, v[162:165]
	v_mfma_f32_16x16x32_bf16 v[86:89], v[126:129], v[106:109], v[86:89]
	ds_read_b128 v[162:165], v4 offset:32768
	v_mfma_f32_16x16x32_bf16 v[94:97], v[154:157], v[106:109], v[94:97]
	ds_read_b128 v[170:173], v5 offset:49152
	global_load_dwordx4 v[106:109], v222, s[36:37] offset:640
	v_mfma_f32_16x16x32_bf16 v[30:33], v[114:117], v[110:113], v[30:33]
	s_waitcnt vmcnt(8)
	ds_write_b128 v2, v[58:61] offset:4096
	v_mfma_f32_16x16x32_bf16 v[42:45], v[126:129], v[110:113], v[42:45]
	ds_read_b128 v[58:61], v4 offset:34816
	v_mfma_f32_16x16x32_bf16 v[14:17], v[158:161], v[110:113], v[14:17]
	ds_read_b128 v[174:177], v5 offset:51200
	v_mfma_f32_16x16x32_bf16 v[90:93], v[154:157], v[110:113], v[90:93]
	global_load_dwordx4 v[110:113], v223, s[36:37] offset:640
	v_mfma_f32_16x16x32_bf16 v[34:37], v[114:117], v[146:149], v[34:37]
	s_waitcnt vmcnt(8)
; template <int MODE>
; __device__ __forceinline__ void gemm_tile(const Params& P, int tm, int tn, unsigned char* smem) {
;     ...
;     for (int kt = 0; kt < 16; ++kt) {
;         unsigned char* sA = (kt & 1) ? sA1 : sA0; unsigned char* sB = (kt & 1) ? sB1 : sB0;
;         unsigned char* nA = (kt & 1) ? sA0 : sA1; unsigned char* nB = (kt & 1) ? sB0 : sB1;
;         bf16x8 fa[4], fb[4], ga[4], gb[4];
;         const int ch0 = ((g ^ sw) << 4), ch1 = (((4 + g) ^ sw) << 4);
;         const unsigned ko = (unsigned)(kt + 2) * 128u;
;         const unsigned koa = ko + ((MODE == 2 && kt + 2 >= 8) ? (unsigned)(ZC_FQ - 512) * 2u : 0u);
;         const bool wr_ok = kt < 15, ld_ok = kt < 14;
; #pragma unroll
;         for (int i = 0; i < 4; ++i) { fa[i] = *(const bf16x8*)(sA + arow_off + i * 2048 + ch0); fb[i] = *(const bf16x8*)(sB + brow_off + i * 2048 + ch0); }
;         __builtin_amdgcn_sched_barrier(0);
;         __builtin_amdgcn_s_setprio(2);
;         if (wr_ok) *(uint4*)(nA + soff0) = ra0;
;         if (ld_ok) ra0 = *(const uint4*)(Ab + (aoff + 0u * LDA + koa));
;         ga[0] = *(const bf16x8*)(sA + arow_off + 0 * 2048 + ch1); gb[0] = *(const bf16x8*)(sB + brow_off + 0 * 2048 + ch1);
;         __builtin_amdgcn_sched_barrier(0);
; #pragma unroll
;         for (int j = 0; j < 4; ++j) acc[0][j] = __builtin_amdgcn_mfma_f32_16x16x32_bf16(fb[j], fa[0], acc[0][j], 0, 0, 0);
;         __builtin_amdgcn_sched_barrier(0);
;         if (wr_ok) *(uint4*)(nA + soff0 + 4096) = ra1;
;         if (ld_ok) ra1 = *(const uint4*)(Ab + (aoff + 32u * LDA + koa));
;         ga[1] = *(const bf16x8*)(sA + arow_off + 1 * 2048 + ch1); gb[1] = *(const bf16x8*)(sB + brow_off + 1 * 2048 + ch1);
;         __builtin_amdgcn_sched_barrier(0);
; #pragma unroll
;         for (int j = 0; j < 4; ++j) acc[1][j] = __builtin_amdgcn_mfma_f32_16x16x32_bf16(fb[j], fa[1], acc[1][j], 0, 0, 0);
;         __builtin_amdgcn_sched_barrier(0);
;         if (wr_ok) *(uint4*)(nA + soff0 + 8192) = ra2;
;         if (ld_ok) ra2 = *(const uint4*)(Ab + (aoff + 64u * LDA + koa));
;         ga[2] = *(const bf16x8*)(sA + arow_off + 2 * 2048 + ch1); gb[2] = *(const bf16x8*)(sB + brow_off + 2 * 2048 + ch1);
;         __builtin_amdgcn_sched_barrier(0);
; #pragma unroll
;         for (int j = 0; j < 4; ++j) acc[2][j] = __builtin_amdgcn_mfma_f32_16x16x32_bf16(fb[j], fa[2], acc[2][j], 0, 0, 0);
	ds_write_b128 v2, v[118:121] offset:8192
	v_mfma_f32_16x16x32_bf16 v[46:49], v[126:129], v[146:149], v[46:49]
	ds_read_b128 v[118:121], v4 offset:36864
	v_mfma_f32_16x16x32_bf16 v[18:21], v[158:161], v[146:149], v[18:21]
	ds_read_b128 v[178:181], v5 offset:53248
	v_mfma_f32_16x16x32_bf16 v[102:105], v[154:157], v[146:149], v[102:105]
	global_load_dwordx4 v[146:149], v224, s[36:37] offset:640
	v_mfma_f32_16x16x32_bf16 v[38:41], v[114:117], v[150:153], v[38:41]
	s_waitcnt vmcnt(8)
	ds_write_b128 v2, v[132:135] offset:12288
	v_mfma_f32_16x16x32_bf16 v[50:53], v[126:129], v[150:153], v[50:53]
	ds_read_b128 v[132:135], v4 offset:38912
	v_mfma_f32_16x16x32_bf16 v[54:57], v[154:157], v[150:153], v[54:57]
	ds_read_b128 v[182:185], v5 offset:55296
	v_mfma_f32_16x16x32_bf16 v[22:25], v[158:161], v[150:153], v[22:25]
	s_waitcnt lgkmcnt(9)
	v_mfma_f32_16x16x32_bf16 v[26:29], v[170:173], v[162:165], v[26:29]
	global_load_dwordx4 v[114:117], v3, s[0:1] offset:640
	s_waitcnt lgkmcnt(0)
	v_mfma_f32_16x16x32_bf16 v[10:13], v[182:185], v[162:165], v[10:13]
	s_waitcnt vmcnt(8)
	ds_write_b128 v2, v[122:125] offset:16384
	v_mfma_f32_16x16x32_bf16 v[86:89], v[174:177], v[162:165], v[86:89]
	v_mfma_f32_16x16x32_bf16 v[94:97], v[178:181], v[162:165], v[94:97]
	global_load_dwordx4 v[122:125], v225, s[0:1] offset:640
	v_mfma_f32_16x16x32_bf16 v[30:33], v[170:173], v[58:61], v[30:33]
	s_waitcnt vmcnt(8)
	ds_write_b128 v2, v[98:101] offset:20480
	v_mfma_f32_16x16x32_bf16 v[42:45], v[174:177], v[58:61], v[42:45]
	v_mfma_f32_16x16x32_bf16 v[14:17], v[182:185], v[58:61], v[14:17]
	v_mfma_f32_16x16x32_bf16 v[90:93], v[178:181], v[58:61], v[90:93]
	global_load_dwordx4 v[58:61], v226, s[0:1] offset:640
	s_waitcnt vmcnt(8)
	ds_write_b128 v2, v[62:65] offset:24576
	v_mfma_f32_16x16x32_bf16 v[34:37], v[170:173], v[118:121], v[34:37]
	v_mfma_f32_16x16x32_bf16 v[46:49], v[174:177], v[118:121], v[46:49]
	v_mfma_f32_16x16x32_bf16 v[62:65], v[178:181], v[118:121], v[102:105]
	v_mfma_f32_16x16x32_bf16 v[18:21], v[182:185], v[118:121], v[18:21]
	global_load_dwordx4 v[98:101], v227, s[0:1] offset:640
	v_mfma_f32_16x16x32_bf16 v[38:41], v[170:173], v[132:135], v[38:41]
	s_waitcnt vmcnt(8)
	ds_write_b128 v2, v[82:85] offset:28672
	v_mfma_f32_16x16x32_bf16 v[50:53], v[174:177], v[132:135], v[50:53]
	v_mfma_f32_16x16x32_bf16 v[54:57], v[178:181], v[132:135], v[54:57]
	v_mfma_f32_16x16x32_bf16 v[22:25], v[182:185], v[132:135], v[22:25]
	s_setprio 0
	s_waitcnt lgkmcnt(0)
	s_barrier
	ds_read_b128 v[82:85], v6
	ds_read_b128 v[102:105], v6 offset:2048
	ds_read_b128 v[118:121], v7 offset:16384
	ds_read_b128 v[126:129], v7 offset:18432
	ds_read_b128 v[132:135], v6 offset:4096
	ds_read_b128 v[150:153], v6 offset:6144
	ds_read_b128 v[154:157], v7 offset:20480
	ds_read_b128 v[158:161], v7 offset:22528
	s_setprio 2
	s_waitcnt lgkmcnt(5)
	v_mfma_f32_16x16x32_bf16 v[26:29], v[118:121], v[82:85], v[26:29]
	global_load_dwordx4 v[162:165], v8, s[36:37] offset:768
	s_waitcnt lgkmcnt(0)
	v_mfma_f32_16x16x32_bf16 v[10:13], v[158:161], v[82:85], v[10:13]
	s_waitcnt vmcnt(8)
	ds_write_b128 v2, v[166:169] offset:32768
	v_mfma_f32_16x16x32_bf16 v[86:89], v[126:129], v[82:85], v[86:89]
	ds_read_b128 v[166:169], v4
	v_mfma_f32_16x16x32_bf16 v[94:97], v[154:157], v[82:85], v[94:97]
	ds_read_b128 v[170:173], v5 offset:16384
	global_load_dwordx4 v[82:85], v222, s[36:37] offset:768
	v_mfma_f32_16x16x32_bf16 v[30:33], v[118:121], v[102:105], v[30:33]
	s_waitcnt vmcnt(8)
	ds_write_b128 v2, v[106:109] offset:36864
	v_mfma_f32_16x16x32_bf16 v[42:45], v[126:129], v[102:105], v[42:45]
	ds_read_b128 v[106:109], v4 offset:2048
	v_mfma_f32_16x16x32_bf16 v[14:17], v[158:161], v[102:105], v[14:17]
	ds_read_b128 v[174:177], v5 offset:18432
	v_mfma_f32_16x16x32_bf16 v[90:93], v[154:157], v[102:105], v[90:93]
	global_load_dwordx4 v[102:105], v223, s[36:37] offset:768
	v_mfma_f32_16x16x32_bf16 v[34:37], v[118:121], v[132:135], v[34:37]
	s_waitcnt vmcnt(8)
	ds_write_b128 v2, v[110:113] offset:40960
	v_mfma_f32_16x16x32_bf16 v[46:49], v[126:129], v[132:135], v[46:49]
	ds_read_b128 v[110:113], v4 offset:4096
	v_mfma_f32_16x16x32_bf16 v[62:65], v[154:157], v[132:135], v[62:65]
	ds_read_b128 v[178:181], v5 offset:20480
	v_mfma_f32_16x16x32_bf16 v[18:21], v[158:161], v[132:135], v[18:21]
	global_load_dwordx4 v[132:135], v224, s[36:37] offset:768
	v_mfma_f32_16x16x32_bf16 v[38:41], v[118:121], v[150:153], v[38:41]
	s_waitcnt vmcnt(8)
	ds_write_b128 v2, v[146:149] offset:45056
	v_mfma_f32_16x16x32_bf16 v[50:53], v[126:129], v[150:153], v[50:53]
	ds_read_b128 v[146:149], v4 offset:6144
	v_mfma_f32_16x16x32_bf16 v[54:57], v[154:157], v[150:153], v[54:57]
	ds_read_b128 v[182:185], v5 offset:22528
	v_mfma_f32_16x16x32_bf16 v[22:25], v[158:161], v[150:153], v[22:25]
	s_waitcnt lgkmcnt(9)
	v_mfma_f32_16x16x32_bf16 v[26:29], v[170:173], v[166:169], v[26:29]
	global_load_dwordx4 v[118:121], v3, s[0:1] offset:768
	s_waitcnt lgkmcnt(0)
	v_mfma_f32_16x16x32_bf16 v[10:13], v[182:185], v[166:169], v[10:13]
	s_waitcnt vmcnt(8)
	ds_write_b128 v2, v[114:117] offset:49152
	v_mfma_f32_16x16x32_bf16 v[86:89], v[174:177], v[166:169], v[86:89]
	v_mfma_f32_16x16x32_bf16 v[94:97], v[178:181], v[166:169], v[94:97]
	global_load_dwordx4 v[114:117], v225, s[0:1] offset:768
	v_mfma_f32_16x16x32_bf16 v[30:33], v[170:173], v[106:109], v[30:33]
	s_waitcnt vmcnt(8)
	ds_write_b128 v2, v[122:125] offset:53248
	v_mfma_f32_16x16x32_bf16 v[42:45], v[174:177], v[106:109], v[42:45]
	v_mfma_f32_16x16x32_bf16 v[14:17], v[182:185], v[106:109], v[14:17]
	v_mfma_f32_16x16x32_bf16 v[90:93], v[178:181], v[106:109], v[90:93]
	global_load_dwordx4 v[106:109], v226, s[0:1] offset:768
	s_waitcnt vmcnt(8)
	ds_write_b128 v2, v[58:61] offset:57344
	v_mfma_f32_16x16x32_bf16 v[34:37], v[170:173], v[110:113], v[34:37]
	v_mfma_f32_16x16x32_bf16 v[46:49], v[174:177], v[110:113], v[46:49]
	v_mfma_f32_16x16x32_bf16 v[58:61], v[178:181], v[110:113], v[62:65]
	v_mfma_f32_16x16x32_bf16 v[18:21], v[182:185], v[110:113], v[18:21]
	global_load_dwordx4 v[62:65], v227, s[0:1] offset:768
	v_mfma_f32_16x16x32_bf16 v[38:41], v[170:173], v[146:149], v[38:41]
	s_waitcnt vmcnt(8)
	ds_write_b128 v2, v[98:101] offset:61440
	v_mfma_f32_16x16x32_bf16 v[50:53], v[174:177], v[146:149], v[50:53]
	v_mfma_f32_16x16x32_bf16 v[54:57], v[178:181], v[146:149], v[54:57]
	v_mfma_f32_16x16x32_bf16 v[22:25], v[182:185], v[146:149], v[22:25]
	s_setprio 0
	s_waitcnt lgkmcnt(0)
	s_barrier
; template <int MODE>
; __device__ __forceinline__ void gemm_tile(const Params& P, int tm, int tn, unsigned char* smem) {
;     ...
; #pragma unroll
;         for (int i = 0; i < 4; ++i) { fa[i] = *(const bf16x8*)(sA + arow_off + i * 2048 + ch0); fb[i] = *(const bf16x8*)(sB + brow_off + i * 2048 + ch0); }
;         __builtin_amdgcn_sched_barrier(0);
;         __builtin_amdgcn_s_setprio(2);
;         if (wr_ok) *(uint4*)(nA + soff0) = ra0;
;         if (ld_ok) ra0 = *(const uint4*)(Ab + (aoff + 0u * LDA + koa));
;         ga[0] = *(const bf16x8*)(sA + arow_off + 0 * 2048 + ch1); gb[0] = *(const bf16x8*)(sB + brow_off + 0 * 2048 + ch1);
;         __builtin_amdgcn_sched_barrier(0);
; #pragma unroll
;         for (int j = 0; j < 4; ++j) acc[0][j] = __builtin_amdgcn_mfma_f32_16x16x32_bf16(fb[j], fa[0], acc[0][j], 0, 0, 0);
;         __builtin_amdgcn_sched_barrier(0);
;         if (wr_ok) *(uint4*)(nA + soff0 + 4096) = ra1;
;         if (ld_ok) ra1 = *(const uint4*)(Ab + (aoff + 32u * LDA + koa));
;         ga[1] = *(const bf16x8*)(sA + arow_off + 1 * 2048 + ch1); gb[1] = *(const bf16x8*)(sB + brow_off + 1 * 2048 + ch1);
;         __builtin_amdgcn_sched_barrier(0);
; #pragma unroll
;         for (int j = 0; j < 4; ++j) acc[1][j] = __builtin_amdgcn_mfma_f32_16x16x32_bf16(fb[j], fa[1], acc[1][j], 0, 0, 0);
;         __builtin_amdgcn_sched_barrier(0);
;         if (wr_ok) *(uint4*)(nA + soff0 + 8192) = ra2;
;         if (ld_ok) ra2 = *(const uint4*)(Ab + (aoff + 64u * LDA + koa));
;         ga[2] = *(const bf16x8*)(sA + arow_off + 2 * 2048 + ch1); gb[2] = *(const bf16x8*)(sB + brow_off + 2 * 2048 + ch1);
;         __builtin_amdgcn_sched_barrier(0);
; #pragma unroll
;         for (int j = 0; j < 4; ++j) acc[2][j] = __builtin_amdgcn_mfma_f32_16x16x32_bf16(fb[j], fa[2], acc[2][j], 0, 0, 0);
;         __builtin_amdgcn_sched_barrier(0);
;         if (wr_ok) *(uint4*)(nA + soff0 + 12288) = ra3;
;         if (ld_ok) ra3 = *(const uint4*)(Ab + (aoff + 96u * LDA + koa));
;         ga[3] = *(const bf16x8*)(sA + arow_off + 3 * 2048 + ch1); gb[3] = *(const bf16x8*)(sB + brow_off + 3 * 2048 + ch1);
;         __builtin_amdgcn_sched_barrier(0);
; #pragma unroll
;         for (int j = 0; j < 4; ++j) acc[3][j] = __builtin_amdgcn_mfma_f32_16x16x32_bf16(fb[j], fa[3], acc[3][j], 0, 0, 0);
;         __builtin_amdgcn_sched_barrier(0);
;         if (wr_ok) *(uint4*)(nB + soff0) = rb0;
	ds_read_b128 v[98:101], v6 offset:32768
	ds_read_b128 v[110:113], v6 offset:34816
	ds_read_b128 v[122:125], v7 offset:49152
	ds_read_b128 v[126:129], v7 offset:51200
	ds_read_b128 v[146:149], v6 offset:36864
	ds_read_b128 v[150:153], v6 offset:38912
	ds_read_b128 v[154:157], v7 offset:53248
	ds_read_b128 v[158:161], v7 offset:55296
	s_setprio 2
	s_waitcnt lgkmcnt(5)
	v_mfma_f32_16x16x32_bf16 v[26:29], v[122:125], v[98:101], v[26:29]
	global_load_dwordx4 v[166:169], v8, s[36:37] offset:896
	s_waitcnt lgkmcnt(0)
	v_mfma_f32_16x16x32_bf16 v[10:13], v[158:161], v[98:101], v[10:13]
	s_waitcnt vmcnt(8)
	ds_write_b128 v2, v[162:165]
	v_mfma_f32_16x16x32_bf16 v[86:89], v[126:129], v[98:101], v[86:89]
	ds_read_b128 v[162:165], v4 offset:32768
	v_mfma_f32_16x16x32_bf16 v[94:97], v[154:157], v[98:101], v[94:97]
	ds_read_b128 v[170:173], v5 offset:49152
	global_load_dwordx4 v[98:101], v222, s[36:37] offset:896
	v_mfma_f32_16x16x32_bf16 v[30:33], v[122:125], v[110:113], v[30:33]
	s_waitcnt vmcnt(8)
	ds_write_b128 v2, v[82:85] offset:4096
	v_mfma_f32_16x16x32_bf16 v[42:45], v[126:129], v[110:113], v[42:45]
	ds_read_b128 v[82:85], v4 offset:34816
	v_mfma_f32_16x16x32_bf16 v[14:17], v[158:161], v[110:113], v[14:17]
	ds_read_b128 v[174:177], v5 offset:51200
	v_mfma_f32_16x16x32_bf16 v[90:93], v[154:157], v[110:113], v[90:93]
	global_load_dwordx4 v[110:113], v223, s[36:37] offset:896
	v_mfma_f32_16x16x32_bf16 v[34:37], v[122:125], v[146:149], v[34:37]
	s_waitcnt vmcnt(8)
	ds_write_b128 v2, v[102:105] offset:8192
	v_mfma_f32_16x16x32_bf16 v[46:49], v[126:129], v[146:149], v[46:49]
	ds_read_b128 v[102:105], v4 offset:36864
	v_mfma_f32_16x16x32_bf16 v[58:61], v[154:157], v[146:149], v[58:61]
	ds_read_b128 v[178:181], v5 offset:53248
	v_mfma_f32_16x16x32_bf16 v[18:21], v[158:161], v[146:149], v[18:21]
	global_load_dwordx4 v[146:149], v224, s[36:37] offset:896
	v_mfma_f32_16x16x32_bf16 v[38:41], v[122:125], v[150:153], v[38:41]
	s_waitcnt vmcnt(8)
	ds_write_b128 v2, v[132:135] offset:12288
	v_mfma_f32_16x16x32_bf16 v[50:53], v[126:129], v[150:153], v[50:53]
	ds_read_b128 v[132:135], v4 offset:38912
	v_mfma_f32_16x16x32_bf16 v[54:57], v[154:157], v[150:153], v[54:57]
	ds_read_b128 v[182:185], v5 offset:55296
	v_mfma_f32_16x16x32_bf16 v[22:25], v[158:161], v[150:153], v[22:25]
	s_waitcnt lgkmcnt(9)
	v_mfma_f32_16x16x32_bf16 v[26:29], v[170:173], v[162:165], v[26:29]
	global_load_dwordx4 v[122:125], v3, s[0:1] offset:896
	s_waitcnt lgkmcnt(0)
	v_mfma_f32_16x16x32_bf16 v[10:13], v[182:185], v[162:165], v[10:13]
	s_waitcnt vmcnt(8)
	ds_write_b128 v2, v[118:121] offset:16384
	v_mfma_f32_16x16x32_bf16 v[86:89], v[174:177], v[162:165], v[86:89]
	v_mfma_f32_16x16x32_bf16 v[94:97], v[178:181], v[162:165], v[94:97]
	global_load_dwordx4 v[118:121], v225, s[0:1] offset:896
	v_mfma_f32_16x16x32_bf16 v[30:33], v[170:173], v[82:85], v[30:33]
	s_waitcnt vmcnt(8)
	ds_write_b128 v2, v[114:117] offset:20480
	v_mfma_f32_16x16x32_bf16 v[42:45], v[174:177], v[82:85], v[42:45]
	v_mfma_f32_16x16x32_bf16 v[14:17], v[182:185], v[82:85], v[14:17]
	v_mfma_f32_16x16x32_bf16 v[90:93], v[178:181], v[82:85], v[90:93]
	global_load_dwordx4 v[82:85], v226, s[0:1] offset:896
	v_mfma_f32_16x16x32_bf16 v[34:37], v[170:173], v[102:105], v[34:37]
	s_waitcnt vmcnt(8)
	ds_write_b128 v2, v[106:109] offset:24576
	v_mfma_f32_16x16x32_bf16 v[46:49], v[174:177], v[102:105], v[46:49]
	v_mfma_f32_16x16x32_bf16 v[58:61], v[178:181], v[102:105], v[58:61]
	v_mfma_f32_16x16x32_bf16 v[18:21], v[182:185], v[102:105], v[18:21]
	global_load_dwordx4 v[102:105], v227, s[0:1] offset:896
	v_mfma_f32_16x16x32_bf16 v[38:41], v[170:173], v[132:135], v[38:41]
	s_waitcnt vmcnt(8)
	ds_write_b128 v2, v[62:65] offset:28672
	v_mfma_f32_16x16x32_bf16 v[50:53], v[174:177], v[132:135], v[50:53]
	v_mfma_f32_16x16x32_bf16 v[54:57], v[178:181], v[132:135], v[54:57]
	v_mfma_f32_16x16x32_bf16 v[22:25], v[182:185], v[132:135], v[22:25]
	s_setprio 0
	s_waitcnt lgkmcnt(0)
	s_barrier
	ds_read_b128 v[62:65], v6
	ds_read_b128 v[106:109], v6 offset:2048
	ds_read_b128 v[114:117], v7 offset:16384
	ds_read_b128 v[126:129], v7 offset:18432
	ds_read_b128 v[132:135], v6 offset:4096
	ds_read_b128 v[150:153], v6 offset:6144
	ds_read_b128 v[154:157], v7 offset:20480
	ds_read_b128 v[158:161], v7 offset:22528
	s_setprio 2
	s_waitcnt lgkmcnt(5)
	v_mfma_f32_16x16x32_bf16 v[26:29], v[114:117], v[62:65], v[26:29]
	global_load_dwordx4 v[162:165], v8, s[36:37] offset:1024
	s_waitcnt lgkmcnt(0)
	v_mfma_f32_16x16x32_bf16 v[10:13], v[158:161], v[62:65], v[10:13]
	s_waitcnt vmcnt(8)
	ds_write_b128 v2, v[166:169] offset:32768
	v_mfma_f32_16x16x32_bf16 v[86:89], v[126:129], v[62:65], v[86:89]
	ds_read_b128 v[166:169], v4
	v_mfma_f32_16x16x32_bf16 v[94:97], v[154:157], v[62:65], v[94:97]
	ds_read_b128 v[170:173], v5 offset:16384
	global_load_dwordx4 v[62:65], v222, s[36:37] offset:1024
	v_mfma_f32_16x16x32_bf16 v[30:33], v[114:117], v[106:109], v[30:33]
	s_waitcnt vmcnt(8)
	ds_write_b128 v2, v[98:101] offset:36864
	v_mfma_f32_16x16x32_bf16 v[42:45], v[126:129], v[106:109], v[42:45]
	ds_read_b128 v[98:101], v4 offset:2048
	v_mfma_f32_16x16x32_bf16 v[14:17], v[158:161], v[106:109], v[14:17]
	ds_read_b128 v[174:177], v5 offset:18432
	v_mfma_f32_16x16x32_bf16 v[90:93], v[154:157], v[106:109], v[90:93]
	global_load_dwordx4 v[106:109], v223, s[36:37] offset:1024
	v_mfma_f32_16x16x32_bf16 v[34:37], v[114:117], v[132:135], v[34:37]
	s_waitcnt vmcnt(8)
; template <int MODE>
; __device__ __forceinline__ void gemm_tile(const Params& P, int tm, int tn, unsigned char* smem) {
;     ...
; #pragma unroll
;         for (int i = 0; i < 4; ++i) { fa[i] = *(const bf16x8*)(sA + arow_off + i * 2048 + ch0); fb[i] = *(const bf16x8*)(sB + brow_off + i * 2048 + ch0); }
;         __builtin_amdgcn_sched_barrier(0);
;         __builtin_amdgcn_s_setprio(2);
;         if (wr_ok) *(uint4*)(nA + soff0) = ra0;
;         if (ld_ok) ra0 = *(const uint4*)(Ab + (aoff + 0u * LDA + koa));
;         ga[0] = *(const bf16x8*)(sA + arow_off + 0 * 2048 + ch1); gb[0] = *(const bf16x8*)(sB + brow_off + 0 * 2048 + ch1);
;         __builtin_amdgcn_sched_barrier(0);
; #pragma unroll
;         for (int j = 0; j < 4; ++j) acc[0][j] = __builtin_amdgcn_mfma_f32_16x16x32_bf16(fb[j], fa[0], acc[0][j], 0, 0, 0);
;         __builtin_amdgcn_sched_barrier(0);
;         if (wr_ok) *(uint4*)(nA + soff0 + 4096) = ra1;
;         if (ld_ok) ra1 = *(const uint4*)(Ab + (aoff + 32u * LDA + koa));
;         ga[1] = *(const bf16x8*)(sA + arow_off + 1 * 2048 + ch1); gb[1] = *(const bf16x8*)(sB + brow_off + 1 * 2048 + ch1);
;         __builtin_amdgcn_sched_barrier(0);
; #pragma unroll
;         for (int j = 0; j < 4; ++j) acc[1][j] = __builtin_amdgcn_mfma_f32_16x16x32_bf16(fb[j], fa[1], acc[1][j], 0, 0, 0);
;         __builtin_amdgcn_sched_barrier(0);
;         if (wr_ok) *(uint4*)(nA + soff0 + 8192) = ra2;
;         if (ld_ok) ra2 = *(const uint4*)(Ab + (aoff + 64u * LDA + koa));
;         ga[2] = *(const bf16x8*)(sA + arow_off + 2 * 2048 + ch1); gb[2] = *(const bf16x8*)(sB + brow_off + 2 * 2048 + ch1);
;         __builtin_amdgcn_sched_barrier(0);
; #pragma unroll
;         for (int j = 0; j < 4; ++j) acc[2][j] = __builtin_amdgcn_mfma_f32_16x16x32_bf16(fb[j], fa[2], acc[2][j], 0, 0, 0);
;         __builtin_amdgcn_sched_barrier(0);
;         if (wr_ok) *(uint4*)(nA + soff0 + 12288) = ra3;
;         if (ld_ok) ra3 = *(const uint4*)(Ab + (aoff + 96u * LDA + koa));
;         ga[3] = *(const bf16x8*)(sA + arow_off + 3 * 2048 + ch1); gb[3] = *(const bf16x8*)(sB + brow_off + 3 * 2048 + ch1);
;         __builtin_amdgcn_sched_barrier(0);
; #pragma unroll
;         for (int j = 0; j < 4; ++j) acc[3][j] = __builtin_amdgcn_mfma_f32_16x16x32_bf16(fb[j], fa[3], acc[3][j], 0, 0, 0);
;         __builtin_amdgcn_sched_barrier(0);
;         if (wr_ok) *(uint4*)(nB + soff0) = rb0;
	ds_write_b128 v2, v[110:113] offset:40960
	v_mfma_f32_16x16x32_bf16 v[46:49], v[126:129], v[132:135], v[46:49]
	ds_read_b128 v[110:113], v4 offset:4096
	v_mfma_f32_16x16x32_bf16 v[58:61], v[154:157], v[132:135], v[58:61]
	ds_read_b128 v[178:181], v5 offset:20480
	v_mfma_f32_16x16x32_bf16 v[18:21], v[158:161], v[132:135], v[18:21]
	global_load_dwordx4 v[132:135], v224, s[36:37] offset:1024
	v_mfma_f32_16x16x32_bf16 v[38:41], v[114:117], v[150:153], v[38:41]
	s_waitcnt vmcnt(8)
	ds_write_b128 v2, v[146:149] offset:45056
	v_mfma_f32_16x16x32_bf16 v[50:53], v[126:129], v[150:153], v[50:53]
	ds_read_b128 v[146:149], v4 offset:6144
	v_mfma_f32_16x16x32_bf16 v[54:57], v[154:157], v[150:153], v[54:57]
	ds_read_b128 v[182:185], v5 offset:22528
	v_mfma_f32_16x16x32_bf16 v[22:25], v[158:161], v[150:153], v[22:25]
	s_waitcnt lgkmcnt(9)
	v_mfma_f32_16x16x32_bf16 v[26:29], v[170:173], v[166:169], v[26:29]
	global_load_dwordx4 v[114:117], v3, s[0:1] offset:1024
	s_waitcnt lgkmcnt(0)
	v_mfma_f32_16x16x32_bf16 v[10:13], v[182:185], v[166:169], v[10:13]
	s_waitcnt vmcnt(8)
	ds_write_b128 v2, v[122:125] offset:49152
	v_mfma_f32_16x16x32_bf16 v[86:89], v[174:177], v[166:169], v[86:89]
	v_mfma_f32_16x16x32_bf16 v[94:97], v[178:181], v[166:169], v[94:97]
	global_load_dwordx4 v[122:125], v225, s[0:1] offset:1024
	v_mfma_f32_16x16x32_bf16 v[30:33], v[170:173], v[98:101], v[30:33]
	s_waitcnt vmcnt(8)
	ds_write_b128 v2, v[118:121] offset:53248
	v_mfma_f32_16x16x32_bf16 v[42:45], v[174:177], v[98:101], v[42:45]
	v_mfma_f32_16x16x32_bf16 v[14:17], v[182:185], v[98:101], v[14:17]
	v_mfma_f32_16x16x32_bf16 v[90:93], v[178:181], v[98:101], v[90:93]
	global_load_dwordx4 v[98:101], v226, s[0:1] offset:1024
	v_mfma_f32_16x16x32_bf16 v[34:37], v[170:173], v[110:113], v[34:37]
	s_waitcnt vmcnt(8)
	ds_write_b128 v2, v[82:85] offset:57344
	v_mfma_f32_16x16x32_bf16 v[46:49], v[174:177], v[110:113], v[46:49]
	v_mfma_f32_16x16x32_bf16 v[58:61], v[178:181], v[110:113], v[58:61]
	v_mfma_f32_16x16x32_bf16 v[18:21], v[182:185], v[110:113], v[18:21]
	global_load_dwordx4 v[82:85], v227, s[0:1] offset:1024
	v_mfma_f32_16x16x32_bf16 v[38:41], v[170:173], v[146:149], v[38:41]
	s_waitcnt vmcnt(8)
	ds_write_b128 v2, v[102:105] offset:61440
	v_mfma_f32_16x16x32_bf16 v[50:53], v[174:177], v[146:149], v[50:53]
	v_mfma_f32_16x16x32_bf16 v[54:57], v[178:181], v[146:149], v[54:57]
	v_mfma_f32_16x16x32_bf16 v[22:25], v[182:185], v[146:149], v[22:25]
	s_setprio 0
	s_waitcnt lgkmcnt(0)
	s_barrier
	ds_read_b128 v[102:105], v6 offset:32768
	ds_read_b128 v[110:113], v6 offset:34816
	ds_read_b128 v[118:121], v7 offset:49152
	ds_read_b128 v[126:129], v7 offset:51200
	ds_read_b128 v[146:149], v6 offset:36864
	ds_read_b128 v[150:153], v6 offset:38912
	ds_read_b128 v[154:157], v7 offset:53248
	ds_read_b128 v[158:161], v7 offset:55296
	s_setprio 2
	s_waitcnt lgkmcnt(5)
	v_mfma_f32_16x16x32_bf16 v[26:29], v[118:121], v[102:105], v[26:29]
	global_load_dwordx4 v[166:169], v8, s[36:37] offset:1152
	s_waitcnt lgkmcnt(0)
	v_mfma_f32_16x16x32_bf16 v[10:13], v[158:161], v[102:105], v[10:13]
	s_waitcnt vmcnt(8)
	ds_write_b128 v2, v[162:165]
	v_mfma_f32_16x16x32_bf16 v[86:89], v[126:129], v[102:105], v[86:89]
	ds_read_b128 v[162:165], v4 offset:32768
	v_mfma_f32_16x16x32_bf16 v[94:97], v[154:157], v[102:105], v[94:97]
	ds_read_b128 v[170:173], v5 offset:49152
	global_load_dwordx4 v[102:105], v222, s[36:37] offset:1152
	v_mfma_f32_16x16x32_bf16 v[30:33], v[118:121], v[110:113], v[30:33]
	s_waitcnt vmcnt(8)
	ds_write_b128 v2, v[62:65] offset:4096
	v_mfma_f32_16x16x32_bf16 v[42:45], v[126:129], v[110:113], v[42:45]
	ds_read_b128 v[62:65], v4 offset:34816
	v_mfma_f32_16x16x32_bf16 v[14:17], v[158:161], v[110:113], v[14:17]
	ds_read_b128 v[174:177], v5 offset:51200
	v_mfma_f32_16x16x32_bf16 v[90:93], v[154:157], v[110:113], v[90:93]
	global_load_dwordx4 v[110:113], v223, s[36:37] offset:1152
	v_mfma_f32_16x16x32_bf16 v[34:37], v[118:121], v[146:149], v[34:37]
	s_waitcnt vmcnt(8)
	ds_write_b128 v2, v[106:109] offset:8192
	v_mfma_f32_16x16x32_bf16 v[46:49], v[126:129], v[146:149], v[46:49]
	ds_read_b128 v[106:109], v4 offset:36864
	v_mfma_f32_16x16x32_bf16 v[58:61], v[154:157], v[146:149], v[58:61]
	ds_read_b128 v[178:181], v5 offset:53248
	v_mfma_f32_16x16x32_bf16 v[18:21], v[158:161], v[146:149], v[18:21]
	global_load_dwordx4 v[146:149], v224, s[36:37] offset:1152
	v_mfma_f32_16x16x32_bf16 v[38:41], v[118:121], v[150:153], v[38:41]
	s_waitcnt vmcnt(8)
	ds_write_b128 v2, v[132:135] offset:12288
	v_mfma_f32_16x16x32_bf16 v[50:53], v[126:129], v[150:153], v[50:53]
	ds_read_b128 v[132:135], v4 offset:38912
	v_mfma_f32_16x16x32_bf16 v[54:57], v[154:157], v[150:153], v[54:57]
	ds_read_b128 v[182:185], v5 offset:55296
	v_mfma_f32_16x16x32_bf16 v[22:25], v[158:161], v[150:153], v[22:25]
	s_waitcnt lgkmcnt(9)
	v_mfma_f32_16x16x32_bf16 v[26:29], v[170:173], v[162:165], v[26:29]
	global_load_dwordx4 v[118:121], v3, s[0:1] offset:1152
	s_waitcnt lgkmcnt(0)
	v_mfma_f32_16x16x32_bf16 v[10:13], v[182:185], v[162:165], v[10:13]
	s_waitcnt vmcnt(8)
	ds_write_b128 v2, v[114:117] offset:16384
	v_mfma_f32_16x16x32_bf16 v[86:89], v[174:177], v[162:165], v[86:89]
	v_mfma_f32_16x16x32_bf16 v[94:97], v[178:181], v[162:165], v[94:97]
	global_load_dwordx4 v[114:117], v225, s[0:1] offset:1152
	v_mfma_f32_16x16x32_bf16 v[30:33], v[170:173], v[62:65], v[30:33]
	s_waitcnt vmcnt(8)
	ds_write_b128 v2, v[122:125] offset:20480
	v_mfma_f32_16x16x32_bf16 v[42:45], v[174:177], v[62:65], v[42:45]
	v_mfma_f32_16x16x32_bf16 v[14:17], v[182:185], v[62:65], v[14:17]
	v_mfma_f32_16x16x32_bf16 v[90:93], v[178:181], v[62:65], v[90:93]
	global_load_dwordx4 v[62:65], v226, s[0:1] offset:1152
	v_mfma_f32_16x16x32_bf16 v[34:37], v[170:173], v[106:109], v[34:37]
	s_waitcnt vmcnt(8)
	ds_write_b128 v2, v[98:101] offset:24576
	v_mfma_f32_16x16x32_bf16 v[46:49], v[174:177], v[106:109], v[46:49]
	v_mfma_f32_16x16x32_bf16 v[58:61], v[178:181], v[106:109], v[58:61]
	v_mfma_f32_16x16x32_bf16 v[18:21], v[182:185], v[106:109], v[18:21]
	global_load_dwordx4 v[98:101], v227, s[0:1] offset:1152
	v_mfma_f32_16x16x32_bf16 v[38:41], v[170:173], v[132:135], v[38:41]
	s_waitcnt vmcnt(8)
	ds_write_b128 v2, v[82:85] offset:28672
	v_mfma_f32_16x16x32_bf16 v[50:53], v[174:177], v[132:135], v[50:53]
	v_mfma_f32_16x16x32_bf16 v[54:57], v[178:181], v[132:135], v[54:57]
	v_mfma_f32_16x16x32_bf16 v[22:25], v[182:185], v[132:135], v[22:25]
	s_setprio 0
	s_waitcnt lgkmcnt(0)
	s_barrier
; template <int MODE>
; __device__ __forceinline__ void gemm_tile(const Params& P, int tm, int tn, unsigned char* smem) {
;     ...
; #pragma unroll
;         for (int i = 0; i < 4; ++i) { fa[i] = *(const bf16x8*)(sA + arow_off + i * 2048 + ch0); fb[i] = *(const bf16x8*)(sB + brow_off + i * 2048 + ch0); }
;         __builtin_amdgcn_sched_barrier(0);
;         __builtin_amdgcn_s_setprio(2);
;         if (wr_ok) *(uint4*)(nA + soff0) = ra0;
;         if (ld_ok) ra0 = *(const uint4*)(Ab + (aoff + 0u * LDA + koa));
;         ga[0] = *(const bf16x8*)(sA + arow_off + 0 * 2048 + ch1); gb[0] = *(const bf16x8*)(sB + brow_off + 0 * 2048 + ch1);
;         __builtin_amdgcn_sched_barrier(0);
; #pragma unroll
;         for (int j = 0; j < 4; ++j) acc[0][j] = __builtin_amdgcn_mfma_f32_16x16x32_bf16(fb[j], fa[0], acc[0][j], 0, 0, 0);
;         __builtin_amdgcn_sched_barrier(0);
;         if (wr_ok) *(uint4*)(nA + soff0 + 4096) = ra1;
;         if (ld_ok) ra1 = *(const uint4*)(Ab + (aoff + 32u * LDA + koa));
;         ga[1] = *(const bf16x8*)(sA + arow_off + 1 * 2048 + ch1); gb[1] = *(const bf16x8*)(sB + brow_off + 1 * 2048 + ch1);
;         __builtin_amdgcn_sched_barrier(0);
; #pragma unroll
;         for (int j = 0; j < 4; ++j) acc[1][j] = __builtin_amdgcn_mfma_f32_16x16x32_bf16(fb[j], fa[1], acc[1][j], 0, 0, 0);
;         __builtin_amdgcn_sched_barrier(0);
;         if (wr_ok) *(uint4*)(nA + soff0 + 8192) = ra2;
;         if (ld_ok) ra2 = *(const uint4*)(Ab + (aoff + 64u * LDA + koa));
;         ga[2] = *(const bf16x8*)(sA + arow_off + 2 * 2048 + ch1); gb[2] = *(const bf16x8*)(sB + brow_off + 2 * 2048 + ch1);
;         __builtin_amdgcn_sched_barrier(0);
; #pragma unroll
;         for (int j = 0; j < 4; ++j) acc[2][j] = __builtin_amdgcn_mfma_f32_16x16x32_bf16(fb[j], fa[2], acc[2][j], 0, 0, 0);
;         __builtin_amdgcn_sched_barrier(0);
;         if (wr_ok) *(uint4*)(nA + soff0 + 12288) = ra3;
;         if (ld_ok) ra3 = *(const uint4*)(Ab + (aoff + 96u * LDA + koa));
;         ga[3] = *(const bf16x8*)(sA + arow_off + 3 * 2048 + ch1); gb[3] = *(const bf16x8*)(sB + brow_off + 3 * 2048 + ch1);
;         __builtin_amdgcn_sched_barrier(0);
; #pragma unroll
;         for (int j = 0; j < 4; ++j) acc[3][j] = __builtin_amdgcn_mfma_f32_16x16x32_bf16(fb[j], fa[3], acc[3][j], 0, 0, 0);
;         __builtin_amdgcn_sched_barrier(0);
;         if (wr_ok) *(uint4*)(nB + soff0) = rb0;
	ds_read_b128 v[82:85], v6
	ds_read_b128 v[106:109], v6 offset:2048
	ds_read_b128 v[122:125], v7 offset:16384
	ds_read_b128 v[126:129], v7 offset:18432
	ds_read_b128 v[132:135], v6 offset:4096
	ds_read_b128 v[150:153], v6 offset:6144
	ds_read_b128 v[154:157], v7 offset:20480
	ds_read_b128 v[158:161], v7 offset:22528
	s_setprio 2
	s_waitcnt lgkmcnt(5)
	v_mfma_f32_16x16x32_bf16 v[26:29], v[122:125], v[82:85], v[26:29]
	global_load_dwordx4 v[162:165], v8, s[36:37] offset:1280
	s_waitcnt lgkmcnt(0)
	v_mfma_f32_16x16x32_bf16 v[10:13], v[158:161], v[82:85], v[10:13]
	s_waitcnt vmcnt(8)
	ds_write_b128 v2, v[166:169] offset:32768
	v_mfma_f32_16x16x32_bf16 v[86:89], v[126:129], v[82:85], v[86:89]
	ds_read_b128 v[166:169], v4
	v_mfma_f32_16x16x32_bf16 v[94:97], v[154:157], v[82:85], v[94:97]
	ds_read_b128 v[170:173], v5 offset:16384
	global_load_dwordx4 v[82:85], v222, s[36:37] offset:1280
	v_mfma_f32_16x16x32_bf16 v[30:33], v[122:125], v[106:109], v[30:33]
	s_waitcnt vmcnt(8)
	ds_write_b128 v2, v[102:105] offset:36864
	v_mfma_f32_16x16x32_bf16 v[42:45], v[126:129], v[106:109], v[42:45]
	ds_read_b128 v[102:105], v4 offset:2048
	v_mfma_f32_16x16x32_bf16 v[14:17], v[158:161], v[106:109], v[14:17]
	ds_read_b128 v[174:177], v5 offset:18432
	v_mfma_f32_16x16x32_bf16 v[90:93], v[154:157], v[106:109], v[90:93]
	global_load_dwordx4 v[106:109], v223, s[36:37] offset:1280
	v_mfma_f32_16x16x32_bf16 v[34:37], v[122:125], v[132:135], v[34:37]
	s_waitcnt vmcnt(8)
	ds_write_b128 v2, v[110:113] offset:40960
	v_mfma_f32_16x16x32_bf16 v[46:49], v[126:129], v[132:135], v[46:49]
	ds_read_b128 v[110:113], v4 offset:4096
	v_mfma_f32_16x16x32_bf16 v[58:61], v[154:157], v[132:135], v[58:61]
	ds_read_b128 v[178:181], v5 offset:20480
	v_mfma_f32_16x16x32_bf16 v[18:21], v[158:161], v[132:135], v[18:21]
	global_load_dwordx4 v[132:135], v224, s[36:37] offset:1280
	v_mfma_f32_16x16x32_bf16 v[38:41], v[122:125], v[150:153], v[38:41]
	s_waitcnt vmcnt(8)
	ds_write_b128 v2, v[146:149] offset:45056
	v_mfma_f32_16x16x32_bf16 v[50:53], v[126:129], v[150:153], v[50:53]
	ds_read_b128 v[146:149], v4 offset:6144
	v_mfma_f32_16x16x32_bf16 v[54:57], v[154:157], v[150:153], v[54:57]
	ds_read_b128 v[182:185], v5 offset:22528
	v_mfma_f32_16x16x32_bf16 v[22:25], v[158:161], v[150:153], v[22:25]
	s_waitcnt lgkmcnt(9)
	v_mfma_f32_16x16x32_bf16 v[26:29], v[170:173], v[166:169], v[26:29]
	global_load_dwordx4 v[122:125], v3, s[0:1] offset:1280
	s_waitcnt lgkmcnt(0)
	v_mfma_f32_16x16x32_bf16 v[10:13], v[182:185], v[166:169], v[10:13]
	s_waitcnt vmcnt(8)
	ds_write_b128 v2, v[118:121] offset:49152
	v_mfma_f32_16x16x32_bf16 v[86:89], v[174:177], v[166:169], v[86:89]
	v_mfma_f32_16x16x32_bf16 v[94:97], v[178:181], v[166:169], v[94:97]
	global_load_dwordx4 v[118:121], v225, s[0:1] offset:1280
	v_mfma_f32_16x16x32_bf16 v[30:33], v[170:173], v[102:105], v[30:33]
	s_waitcnt vmcnt(8)
	ds_write_b128 v2, v[114:117] offset:53248
	v_mfma_f32_16x16x32_bf16 v[42:45], v[174:177], v[102:105], v[42:45]
	v_mfma_f32_16x16x32_bf16 v[14:17], v[182:185], v[102:105], v[14:17]
	v_mfma_f32_16x16x32_bf16 v[90:93], v[178:181], v[102:105], v[90:93]
	global_load_dwordx4 v[102:105], v226, s[0:1] offset:1280
	v_mfma_f32_16x16x32_bf16 v[34:37], v[170:173], v[110:113], v[34:37]
	s_waitcnt vmcnt(8)
	ds_write_b128 v2, v[62:65] offset:57344
	v_mfma_f32_16x16x32_bf16 v[46:49], v[174:177], v[110:113], v[46:49]
	v_mfma_f32_16x16x32_bf16 v[58:61], v[178:181], v[110:113], v[58:61]
	v_mfma_f32_16x16x32_bf16 v[18:21], v[182:185], v[110:113], v[18:21]
	global_load_dwordx4 v[62:65], v227, s[0:1] offset:1280
	v_mfma_f32_16x16x32_bf16 v[38:41], v[170:173], v[146:149], v[38:41]
	s_waitcnt vmcnt(8)
	ds_write_b128 v2, v[98:101] offset:61440
	v_mfma_f32_16x16x32_bf16 v[50:53], v[174:177], v[146:149], v[50:53]
	v_mfma_f32_16x16x32_bf16 v[54:57], v[178:181], v[146:149], v[54:57]
	v_mfma_f32_16x16x32_bf16 v[22:25], v[182:185], v[146:149], v[22:25]
	s_setprio 0
	s_waitcnt lgkmcnt(0)
	s_barrier
	ds_read_b128 v[98:101], v6 offset:32768
	ds_read_b128 v[110:113], v6 offset:34816
	ds_read_b128 v[114:117], v7 offset:49152
	ds_read_b128 v[126:129], v7 offset:51200
	ds_read_b128 v[146:149], v6 offset:36864
	ds_read_b128 v[150:153], v6 offset:38912
	ds_read_b128 v[154:157], v7 offset:53248
	ds_read_b128 v[158:161], v7 offset:55296
	s_setprio 2
	s_waitcnt lgkmcnt(5)
	v_mfma_f32_16x16x32_bf16 v[26:29], v[114:117], v[98:101], v[26:29]
	global_load_dwordx4 v[166:169], v8, s[36:37] offset:1408
	s_waitcnt lgkmcnt(0)
	v_mfma_f32_16x16x32_bf16 v[10:13], v[158:161], v[98:101], v[10:13]
	s_waitcnt vmcnt(8)
	ds_write_b128 v2, v[162:165]
	v_mfma_f32_16x16x32_bf16 v[86:89], v[126:129], v[98:101], v[86:89]
	ds_read_b128 v[162:165], v4 offset:32768
	v_mfma_f32_16x16x32_bf16 v[94:97], v[154:157], v[98:101], v[94:97]
	ds_read_b128 v[170:173], v5 offset:49152
	global_load_dwordx4 v[98:101], v222, s[36:37] offset:1408
	v_mfma_f32_16x16x32_bf16 v[30:33], v[114:117], v[110:113], v[30:33]
	s_waitcnt vmcnt(8)
	ds_write_b128 v2, v[82:85] offset:4096
	v_mfma_f32_16x16x32_bf16 v[42:45], v[126:129], v[110:113], v[42:45]
	ds_read_b128 v[82:85], v4 offset:34816
	v_mfma_f32_16x16x32_bf16 v[14:17], v[158:161], v[110:113], v[14:17]
	ds_read_b128 v[174:177], v5 offset:51200
	v_mfma_f32_16x16x32_bf16 v[90:93], v[154:157], v[110:113], v[90:93]
	global_load_dwordx4 v[110:113], v223, s[36:37] offset:1408
	v_mfma_f32_16x16x32_bf16 v[34:37], v[114:117], v[146:149], v[34:37]
	s_waitcnt vmcnt(8)
; template <int MODE>
; __device__ __forceinline__ void gemm_tile(const Params& P, int tm, int tn, unsigned char* smem) {
;     ...
; #pragma unroll
;         for (int i = 0; i < 4; ++i) { fa[i] = *(const bf16x8*)(sA + arow_off + i * 2048 + ch0); fb[i] = *(const bf16x8*)(sB + brow_off + i * 2048 + ch0); }
;         __builtin_amdgcn_sched_barrier(0);
;         __builtin_amdgcn_s_setprio(2);
;         if (wr_ok) *(uint4*)(nA + soff0) = ra0;
;         if (ld_ok) ra0 = *(const uint4*)(Ab + (aoff + 0u * LDA + koa));
;         ga[0] = *(const bf16x8*)(sA + arow_off + 0 * 2048 + ch1); gb[0] = *(const bf16x8*)(sB + brow_off + 0 * 2048 + ch1);
;         __builtin_amdgcn_sched_barrier(0);
; #pragma unroll
;         for (int j = 0; j < 4; ++j) acc[0][j] = __builtin_amdgcn_mfma_f32_16x16x32_bf16(fb[j], fa[0], acc[0][j], 0, 0, 0);
;         __builtin_amdgcn_sched_barrier(0);
;         if (wr_ok) *(uint4*)(nA + soff0 + 4096) = ra1;
;         if (ld_ok) ra1 = *(const uint4*)(Ab + (aoff + 32u * LDA + koa));
;         ga[1] = *(const bf16x8*)(sA + arow_off + 1 * 2048 + ch1); gb[1] = *(const bf16x8*)(sB + brow_off + 1 * 2048 + ch1);
;         __builtin_amdgcn_sched_barrier(0);
; #pragma unroll
;         for (int j = 0; j < 4; ++j) acc[1][j] = __builtin_amdgcn_mfma_f32_16x16x32_bf16(fb[j], fa[1], acc[1][j], 0, 0, 0);
;         __builtin_amdgcn_sched_barrier(0);
;         if (wr_ok) *(uint4*)(nA + soff0 + 8192) = ra2;
;         if (ld_ok) ra2 = *(const uint4*)(Ab + (aoff + 64u * LDA + koa));
;         ga[2] = *(const bf16x8*)(sA + arow_off + 2 * 2048 + ch1); gb[2] = *(const bf16x8*)(sB + brow_off + 2 * 2048 + ch1);
;         __builtin_amdgcn_sched_barrier(0);
; #pragma unroll
;         for (int j = 0; j < 4; ++j) acc[2][j] = __builtin_amdgcn_mfma_f32_16x16x32_bf16(fb[j], fa[2], acc[2][j], 0, 0, 0);
;         __builtin_amdgcn_sched_barrier(0);
;         if (wr_ok) *(uint4*)(nA + soff0 + 12288) = ra3;
;         if (ld_ok) ra3 = *(const uint4*)(Ab + (aoff + 96u * LDA + koa));
;         ga[3] = *(const bf16x8*)(sA + arow_off + 3 * 2048 + ch1); gb[3] = *(const bf16x8*)(sB + brow_off + 3 * 2048 + ch1);
;         __builtin_amdgcn_sched_barrier(0);
; #pragma unroll
;         for (int j = 0; j < 4; ++j) acc[3][j] = __builtin_amdgcn_mfma_f32_16x16x32_bf16(fb[j], fa[3], acc[3][j], 0, 0, 0);
;         __builtin_amdgcn_sched_barrier(0);
;         if (wr_ok) *(uint4*)(nB + soff0) = rb0;
	ds_write_b128 v2, v[106:109] offset:8192
	v_mfma_f32_16x16x32_bf16 v[46:49], v[126:129], v[146:149], v[46:49]
	ds_read_b128 v[106:109], v4 offset:36864
	v_mfma_f32_16x16x32_bf16 v[58:61], v[154:157], v[146:149], v[58:61]
	ds_read_b128 v[178:181], v5 offset:53248
	v_mfma_f32_16x16x32_bf16 v[18:21], v[158:161], v[146:149], v[18:21]
	global_load_dwordx4 v[146:149], v224, s[36:37] offset:1408
	v_mfma_f32_16x16x32_bf16 v[38:41], v[114:117], v[150:153], v[38:41]
	s_waitcnt vmcnt(8)
	ds_write_b128 v2, v[132:135] offset:12288
	v_mfma_f32_16x16x32_bf16 v[50:53], v[126:129], v[150:153], v[50:53]
	ds_read_b128 v[132:135], v4 offset:38912
	v_mfma_f32_16x16x32_bf16 v[54:57], v[154:157], v[150:153], v[54:57]
	ds_read_b128 v[182:185], v5 offset:55296
	v_mfma_f32_16x16x32_bf16 v[22:25], v[158:161], v[150:153], v[22:25]
	s_waitcnt lgkmcnt(9)
	v_mfma_f32_16x16x32_bf16 v[26:29], v[170:173], v[162:165], v[26:29]
	global_load_dwordx4 v[114:117], v3, s[0:1] offset:1408
	s_waitcnt lgkmcnt(0)
	v_mfma_f32_16x16x32_bf16 v[10:13], v[182:185], v[162:165], v[10:13]
	s_waitcnt vmcnt(8)
	ds_write_b128 v2, v[122:125] offset:16384
	v_mfma_f32_16x16x32_bf16 v[86:89], v[174:177], v[162:165], v[86:89]
	v_mfma_f32_16x16x32_bf16 v[94:97], v[178:181], v[162:165], v[94:97]
	global_load_dwordx4 v[122:125], v225, s[0:1] offset:1408
	v_mfma_f32_16x16x32_bf16 v[30:33], v[170:173], v[82:85], v[30:33]
	s_waitcnt vmcnt(8)
	ds_write_b128 v2, v[118:121] offset:20480
	v_mfma_f32_16x16x32_bf16 v[42:45], v[174:177], v[82:85], v[42:45]
	v_mfma_f32_16x16x32_bf16 v[14:17], v[182:185], v[82:85], v[14:17]
	v_mfma_f32_16x16x32_bf16 v[90:93], v[178:181], v[82:85], v[90:93]
	global_load_dwordx4 v[82:85], v226, s[0:1] offset:1408
	v_mfma_f32_16x16x32_bf16 v[34:37], v[170:173], v[106:109], v[34:37]
	s_waitcnt vmcnt(8)
	ds_write_b128 v2, v[102:105] offset:24576
	v_mfma_f32_16x16x32_bf16 v[46:49], v[174:177], v[106:109], v[46:49]
	v_mfma_f32_16x16x32_bf16 v[58:61], v[178:181], v[106:109], v[58:61]
	v_mfma_f32_16x16x32_bf16 v[18:21], v[182:185], v[106:109], v[18:21]
	global_load_dwordx4 v[102:105], v227, s[0:1] offset:1408
	v_mfma_f32_16x16x32_bf16 v[38:41], v[170:173], v[132:135], v[38:41]
	s_waitcnt vmcnt(8)
	ds_write_b128 v2, v[62:65] offset:28672
	v_mfma_f32_16x16x32_bf16 v[50:53], v[174:177], v[132:135], v[50:53]
	v_mfma_f32_16x16x32_bf16 v[54:57], v[178:181], v[132:135], v[54:57]
	v_mfma_f32_16x16x32_bf16 v[22:25], v[182:185], v[132:135], v[22:25]
	s_setprio 0
	s_waitcnt lgkmcnt(0)
	s_barrier
	ds_read_b128 v[62:65], v6
	ds_read_b128 v[106:109], v6 offset:2048
	ds_read_b128 v[118:121], v7 offset:16384
	ds_read_b128 v[126:129], v7 offset:18432
	ds_read_b128 v[132:135], v6 offset:4096
	ds_read_b128 v[150:153], v6 offset:6144
	ds_read_b128 v[154:157], v7 offset:20480
	ds_read_b128 v[158:161], v7 offset:22528
	s_setprio 2
	s_waitcnt lgkmcnt(5)
	v_mfma_f32_16x16x32_bf16 v[26:29], v[118:121], v[62:65], v[26:29]
	global_load_dwordx4 v[162:165], v8, s[36:37] offset:1536
	s_waitcnt lgkmcnt(0)
	v_mfma_f32_16x16x32_bf16 v[10:13], v[158:161], v[62:65], v[10:13]
	s_waitcnt vmcnt(8)
	ds_write_b128 v2, v[166:169] offset:32768
	v_mfma_f32_16x16x32_bf16 v[86:89], v[126:129], v[62:65], v[86:89]
	ds_read_b128 v[166:169], v4
	v_mfma_f32_16x16x32_bf16 v[94:97], v[154:157], v[62:65], v[94:97]
	ds_read_b128 v[170:173], v5 offset:16384
	global_load_dwordx4 v[62:65], v222, s[36:37] offset:1536
	v_mfma_f32_16x16x32_bf16 v[30:33], v[118:121], v[106:109], v[30:33]
	s_waitcnt vmcnt(8)
	ds_write_b128 v2, v[98:101] offset:36864
	v_mfma_f32_16x16x32_bf16 v[42:45], v[126:129], v[106:109], v[42:45]
	ds_read_b128 v[98:101], v4 offset:2048
	v_mfma_f32_16x16x32_bf16 v[14:17], v[158:161], v[106:109], v[14:17]
	ds_read_b128 v[174:177], v5 offset:18432
	v_mfma_f32_16x16x32_bf16 v[90:93], v[154:157], v[106:109], v[90:93]
	global_load_dwordx4 v[106:109], v223, s[36:37] offset:1536
	v_mfma_f32_16x16x32_bf16 v[34:37], v[118:121], v[132:135], v[34:37]
	s_waitcnt vmcnt(8)
	ds_write_b128 v2, v[110:113] offset:40960
	v_mfma_f32_16x16x32_bf16 v[46:49], v[126:129], v[132:135], v[46:49]
	ds_read_b128 v[110:113], v4 offset:4096
	v_mfma_f32_16x16x32_bf16 v[58:61], v[154:157], v[132:135], v[58:61]
	ds_read_b128 v[178:181], v5 offset:20480
	v_mfma_f32_16x16x32_bf16 v[18:21], v[158:161], v[132:135], v[18:21]
	global_load_dwordx4 v[132:135], v224, s[36:37] offset:1536
	v_mfma_f32_16x16x32_bf16 v[38:41], v[118:121], v[150:153], v[38:41]
	s_waitcnt vmcnt(8)
	ds_write_b128 v2, v[146:149] offset:45056
	v_mfma_f32_16x16x32_bf16 v[50:53], v[126:129], v[150:153], v[50:53]
	ds_read_b128 v[146:149], v4 offset:6144
	v_mfma_f32_16x16x32_bf16 v[54:57], v[154:157], v[150:153], v[54:57]
	ds_read_b128 v[182:185], v5 offset:22528
	v_mfma_f32_16x16x32_bf16 v[22:25], v[158:161], v[150:153], v[22:25]
	s_waitcnt lgkmcnt(9)
	v_mfma_f32_16x16x32_bf16 v[26:29], v[170:173], v[166:169], v[26:29]
	global_load_dwordx4 v[118:121], v3, s[0:1] offset:1536
	s_waitcnt lgkmcnt(0)
	v_mfma_f32_16x16x32_bf16 v[10:13], v[182:185], v[166:169], v[10:13]
	s_waitcnt vmcnt(8)
	ds_write_b128 v2, v[114:117] offset:49152
	v_mfma_f32_16x16x32_bf16 v[86:89], v[174:177], v[166:169], v[86:89]
	v_mfma_f32_16x16x32_bf16 v[94:97], v[178:181], v[166:169], v[94:97]
	global_load_dwordx4 v[114:117], v225, s[0:1] offset:1536
	v_mfma_f32_16x16x32_bf16 v[30:33], v[170:173], v[98:101], v[30:33]
	s_waitcnt vmcnt(8)
	ds_write_b128 v2, v[122:125] offset:53248
	v_mfma_f32_16x16x32_bf16 v[42:45], v[174:177], v[98:101], v[42:45]
	v_mfma_f32_16x16x32_bf16 v[14:17], v[182:185], v[98:101], v[14:17]
	v_mfma_f32_16x16x32_bf16 v[90:93], v[178:181], v[98:101], v[90:93]
	global_load_dwordx4 v[98:101], v226, s[0:1] offset:1536
	v_mfma_f32_16x16x32_bf16 v[34:37], v[170:173], v[110:113], v[34:37]
	s_waitcnt vmcnt(8)
	ds_write_b128 v2, v[82:85] offset:57344
	v_mfma_f32_16x16x32_bf16 v[46:49], v[174:177], v[110:113], v[46:49]
	v_mfma_f32_16x16x32_bf16 v[58:61], v[178:181], v[110:113], v[58:61]
	v_mfma_f32_16x16x32_bf16 v[18:21], v[182:185], v[110:113], v[18:21]
	global_load_dwordx4 v[82:85], v227, s[0:1] offset:1536
	v_mfma_f32_16x16x32_bf16 v[38:41], v[170:173], v[146:149], v[38:41]
	s_waitcnt vmcnt(8)
	ds_write_b128 v2, v[102:105] offset:61440
	v_mfma_f32_16x16x32_bf16 v[50:53], v[174:177], v[146:149], v[50:53]
	v_mfma_f32_16x16x32_bf16 v[54:57], v[178:181], v[146:149], v[54:57]
	v_mfma_f32_16x16x32_bf16 v[22:25], v[182:185], v[146:149], v[22:25]
	s_setprio 0
	s_waitcnt lgkmcnt(0)
	s_barrier
; template <int MODE>
; __device__ __forceinline__ void gemm_tile(const Params& P, int tm, int tn, unsigned char* smem) {
;     ...
; #pragma unroll
;         for (int i = 0; i < 4; ++i) { fa[i] = *(const bf16x8*)(sA + arow_off + i * 2048 + ch0); fb[i] = *(const bf16x8*)(sB + brow_off + i * 2048 + ch0); }
;         __builtin_amdgcn_sched_barrier(0);
;         __builtin_amdgcn_s_setprio(2);
;         if (wr_ok) *(uint4*)(nA + soff0) = ra0;
;         if (ld_ok) ra0 = *(const uint4*)(Ab + (aoff + 0u * LDA + koa));
;         ga[0] = *(const bf16x8*)(sA + arow_off + 0 * 2048 + ch1); gb[0] = *(const bf16x8*)(sB + brow_off + 0 * 2048 + ch1);
;         __builtin_amdgcn_sched_barrier(0);
; #pragma unroll
;         for (int j = 0; j < 4; ++j) acc[0][j] = __builtin_amdgcn_mfma_f32_16x16x32_bf16(fb[j], fa[0], acc[0][j], 0, 0, 0);
;         __builtin_amdgcn_sched_barrier(0);
;         if (wr_ok) *(uint4*)(nA + soff0 + 4096) = ra1;
;         if (ld_ok) ra1 = *(const uint4*)(Ab + (aoff + 32u * LDA + koa));
;         ga[1] = *(const bf16x8*)(sA + arow_off + 1 * 2048 + ch1); gb[1] = *(const bf16x8*)(sB + brow_off + 1 * 2048 + ch1);
;         __builtin_amdgcn_sched_barrier(0);
; #pragma unroll
;         for (int j = 0; j < 4; ++j) acc[1][j] = __builtin_amdgcn_mfma_f32_16x16x32_bf16(fb[j], fa[1], acc[1][j], 0, 0, 0);
;         __builtin_amdgcn_sched_barrier(0);
;         if (wr_ok) *(uint4*)(nA + soff0 + 8192) = ra2;
;         if (ld_ok) ra2 = *(const uint4*)(Ab + (aoff + 64u * LDA + koa));
;         ga[2] = *(const bf16x8*)(sA + arow_off + 2 * 2048 + ch1); gb[2] = *(const bf16x8*)(sB + brow_off + 2 * 2048 + ch1);
;         __builtin_amdgcn_sched_barrier(0);
; #pragma unroll
;         for (int j = 0; j < 4; ++j) acc[2][j] = __builtin_amdgcn_mfma_f32_16x16x32_bf16(fb[j], fa[2], acc[2][j], 0, 0, 0);
;         __builtin_amdgcn_sched_barrier(0);
;         if (wr_ok) *(uint4*)(nA + soff0 + 12288) = ra3;
;         if (ld_ok) ra3 = *(const uint4*)(Ab + (aoff + 96u * LDA + koa));
;         ga[3] = *(const bf16x8*)(sA + arow_off + 3 * 2048 + ch1); gb[3] = *(const bf16x8*)(sB + brow_off + 3 * 2048 + ch1);
;         __builtin_amdgcn_sched_barrier(0);
; #pragma unroll
;         for (int j = 0; j < 4; ++j) acc[3][j] = __builtin_amdgcn_mfma_f32_16x16x32_bf16(fb[j], fa[3], acc[3][j], 0, 0, 0);
;         __builtin_amdgcn_sched_barrier(0);
;         if (wr_ok) *(uint4*)(nB + soff0) = rb0;
	ds_read_b128 v[102:105], v6 offset:32768
	ds_read_b128 v[110:113], v6 offset:34816
	ds_read_b128 v[122:125], v7 offset:49152
	ds_read_b128 v[126:129], v7 offset:51200
	ds_read_b128 v[146:149], v6 offset:36864
	ds_read_b128 v[150:153], v6 offset:38912
	ds_read_b128 v[154:157], v7 offset:53248
	ds_read_b128 v[158:161], v7 offset:55296
	s_setprio 2
	s_waitcnt lgkmcnt(5)
	v_mfma_f32_16x16x32_bf16 v[26:29], v[122:125], v[102:105], v[26:29]
	global_load_dwordx4 v[166:169], v8, s[36:37] offset:1664
	s_waitcnt lgkmcnt(0)
	v_mfma_f32_16x16x32_bf16 v[10:13], v[158:161], v[102:105], v[10:13]
	s_waitcnt vmcnt(8)
	ds_write_b128 v2, v[162:165]
	v_mfma_f32_16x16x32_bf16 v[86:89], v[126:129], v[102:105], v[86:89]
	ds_read_b128 v[162:165], v4 offset:32768
	v_mfma_f32_16x16x32_bf16 v[94:97], v[154:157], v[102:105], v[94:97]
	ds_read_b128 v[170:173], v5 offset:49152
	global_load_dwordx4 v[102:105], v222, s[36:37] offset:1664
	v_mfma_f32_16x16x32_bf16 v[30:33], v[122:125], v[110:113], v[30:33]
	s_waitcnt vmcnt(8)
	ds_write_b128 v2, v[62:65] offset:4096
	v_mfma_f32_16x16x32_bf16 v[42:45], v[126:129], v[110:113], v[42:45]
	ds_read_b128 v[62:65], v4 offset:34816
	v_mfma_f32_16x16x32_bf16 v[14:17], v[158:161], v[110:113], v[14:17]
	ds_read_b128 v[174:177], v5 offset:51200
	v_mfma_f32_16x16x32_bf16 v[90:93], v[154:157], v[110:113], v[90:93]
	global_load_dwordx4 v[110:113], v223, s[36:37] offset:1664
	v_mfma_f32_16x16x32_bf16 v[34:37], v[122:125], v[146:149], v[34:37]
	s_waitcnt vmcnt(8)
	ds_write_b128 v2, v[106:109] offset:8192
	v_mfma_f32_16x16x32_bf16 v[46:49], v[126:129], v[146:149], v[46:49]
	ds_read_b128 v[106:109], v4 offset:36864
	v_mfma_f32_16x16x32_bf16 v[58:61], v[154:157], v[146:149], v[58:61]
	ds_read_b128 v[178:181], v5 offset:53248
	v_mfma_f32_16x16x32_bf16 v[18:21], v[158:161], v[146:149], v[18:21]
	global_load_dwordx4 v[146:149], v224, s[36:37] offset:1664
	v_mfma_f32_16x16x32_bf16 v[38:41], v[122:125], v[150:153], v[38:41]
	s_waitcnt vmcnt(8)
	ds_write_b128 v2, v[132:135] offset:12288
	v_mfma_f32_16x16x32_bf16 v[50:53], v[126:129], v[150:153], v[50:53]
	ds_read_b128 v[132:135], v4 offset:38912
	v_mfma_f32_16x16x32_bf16 v[54:57], v[154:157], v[150:153], v[54:57]
	ds_read_b128 v[182:185], v5 offset:55296
	v_mfma_f32_16x16x32_bf16 v[22:25], v[158:161], v[150:153], v[22:25]
	s_waitcnt lgkmcnt(9)
	v_mfma_f32_16x16x32_bf16 v[26:29], v[170:173], v[162:165], v[26:29]
	global_load_dwordx4 v[122:125], v3, s[0:1] offset:1664
	s_waitcnt lgkmcnt(0)
	v_mfma_f32_16x16x32_bf16 v[10:13], v[182:185], v[162:165], v[10:13]
	s_waitcnt vmcnt(8)
	ds_write_b128 v2, v[118:121] offset:16384
	v_mfma_f32_16x16x32_bf16 v[86:89], v[174:177], v[162:165], v[86:89]
	v_mfma_f32_16x16x32_bf16 v[94:97], v[178:181], v[162:165], v[94:97]
	global_load_dwordx4 v[118:121], v225, s[0:1] offset:1664
	v_mfma_f32_16x16x32_bf16 v[30:33], v[170:173], v[62:65], v[30:33]
	s_waitcnt vmcnt(8)
	ds_write_b128 v2, v[114:117] offset:20480
	v_mfma_f32_16x16x32_bf16 v[42:45], v[174:177], v[62:65], v[42:45]
	v_mfma_f32_16x16x32_bf16 v[14:17], v[182:185], v[62:65], v[14:17]
	v_mfma_f32_16x16x32_bf16 v[90:93], v[178:181], v[62:65], v[90:93]
	global_load_dwordx4 v[62:65], v226, s[0:1] offset:1664
	v_mfma_f32_16x16x32_bf16 v[34:37], v[170:173], v[106:109], v[34:37]
	s_waitcnt vmcnt(8)
	ds_write_b128 v2, v[98:101] offset:24576
	v_mfma_f32_16x16x32_bf16 v[46:49], v[174:177], v[106:109], v[46:49]
	v_mfma_f32_16x16x32_bf16 v[58:61], v[178:181], v[106:109], v[58:61]
	v_mfma_f32_16x16x32_bf16 v[18:21], v[182:185], v[106:109], v[18:21]
	global_load_dwordx4 v[98:101], v227, s[0:1] offset:1664
	v_mfma_f32_16x16x32_bf16 v[38:41], v[170:173], v[132:135], v[38:41]
	s_waitcnt vmcnt(8)
	ds_write_b128 v2, v[82:85] offset:28672
	v_mfma_f32_16x16x32_bf16 v[50:53], v[174:177], v[132:135], v[50:53]
	v_mfma_f32_16x16x32_bf16 v[54:57], v[178:181], v[132:135], v[54:57]
	v_mfma_f32_16x16x32_bf16 v[22:25], v[182:185], v[132:135], v[22:25]
	s_setprio 0
	s_waitcnt lgkmcnt(0)
	s_barrier
	ds_read_b128 v[82:85], v6
	ds_read_b128 v[106:109], v6 offset:2048
	ds_read_b128 v[114:117], v7 offset:16384
	ds_read_b128 v[126:129], v7 offset:18432
	ds_read_b128 v[132:135], v6 offset:4096
	ds_read_b128 v[150:153], v6 offset:6144
	ds_read_b128 v[154:157], v7 offset:20480
	ds_read_b128 v[158:161], v7 offset:22528
	s_setprio 2
	s_waitcnt lgkmcnt(5)
	v_mfma_f32_16x16x32_bf16 v[26:29], v[114:117], v[82:85], v[26:29]
	global_load_dwordx4 v[162:165], v8, s[36:37] offset:1792
	s_waitcnt lgkmcnt(0)
	v_mfma_f32_16x16x32_bf16 v[10:13], v[158:161], v[82:85], v[10:13]
	s_waitcnt vmcnt(8)
	ds_write_b128 v2, v[166:169] offset:32768
	v_mfma_f32_16x16x32_bf16 v[86:89], v[126:129], v[82:85], v[86:89]
	ds_read_b128 v[166:169], v4
	v_mfma_f32_16x16x32_bf16 v[94:97], v[154:157], v[82:85], v[94:97]
	ds_read_b128 v[170:173], v5 offset:16384
	global_load_dwordx4 v[82:85], v222, s[36:37] offset:1792
	v_mfma_f32_16x16x32_bf16 v[30:33], v[114:117], v[106:109], v[30:33]
	s_waitcnt vmcnt(8)
	ds_write_b128 v2, v[102:105] offset:36864
	v_mfma_f32_16x16x32_bf16 v[42:45], v[126:129], v[106:109], v[42:45]
	ds_read_b128 v[102:105], v4 offset:2048
	v_mfma_f32_16x16x32_bf16 v[14:17], v[158:161], v[106:109], v[14:17]
	ds_read_b128 v[174:177], v5 offset:18432
	v_mfma_f32_16x16x32_bf16 v[90:93], v[154:157], v[106:109], v[90:93]
	global_load_dwordx4 v[106:109], v223, s[36:37] offset:1792
	v_mfma_f32_16x16x32_bf16 v[34:37], v[114:117], v[132:135], v[34:37]
	s_waitcnt vmcnt(8)
; template <int MODE>
; __device__ __forceinline__ void gemm_tile(const Params& P, int tm, int tn, unsigned char* smem) {
;     ...
; #pragma unroll
;         for (int i = 0; i < 4; ++i) { fa[i] = *(const bf16x8*)(sA + arow_off + i * 2048 + ch0); fb[i] = *(const bf16x8*)(sB + brow_off + i * 2048 + ch0); }
;         __builtin_amdgcn_sched_barrier(0);
;         __builtin_amdgcn_s_setprio(2);
;         if (wr_ok) *(uint4*)(nA + soff0) = ra0;
;         if (ld_ok) ra0 = *(const uint4*)(Ab + (aoff + 0u * LDA + koa));
;         ga[0] = *(const bf16x8*)(sA + arow_off + 0 * 2048 + ch1); gb[0] = *(const bf16x8*)(sB + brow_off + 0 * 2048 + ch1);
;         __builtin_amdgcn_sched_barrier(0);
; #pragma unroll
;         for (int j = 0; j < 4; ++j) acc[0][j] = __builtin_amdgcn_mfma_f32_16x16x32_bf16(fb[j], fa[0], acc[0][j], 0, 0, 0);
;         __builtin_amdgcn_sched_barrier(0);
;         if (wr_ok) *(uint4*)(nA + soff0 + 4096) = ra1;
;         if (ld_ok) ra1 = *(const uint4*)(Ab + (aoff + 32u * LDA + koa));
;         ga[1] = *(const bf16x8*)(sA + arow_off + 1 * 2048 + ch1); gb[1] = *(const bf16x8*)(sB + brow_off + 1 * 2048 + ch1);
;         __builtin_amdgcn_sched_barrier(0);
; #pragma unroll
;         for (int j = 0; j < 4; ++j) acc[1][j] = __builtin_amdgcn_mfma_f32_16x16x32_bf16(fb[j], fa[1], acc[1][j], 0, 0, 0);
;         __builtin_amdgcn_sched_barrier(0);
;         if (wr_ok) *(uint4*)(nA + soff0 + 8192) = ra2;
;         if (ld_ok) ra2 = *(const uint4*)(Ab + (aoff + 64u * LDA + koa));
;         ga[2] = *(const bf16x8*)(sA + arow_off + 2 * 2048 + ch1); gb[2] = *(const bf16x8*)(sB + brow_off + 2 * 2048 + ch1);
;         __builtin_amdgcn_sched_barrier(0);
; #pragma unroll
;         for (int j = 0; j < 4; ++j) acc[2][j] = __builtin_amdgcn_mfma_f32_16x16x32_bf16(fb[j], fa[2], acc[2][j], 0, 0, 0);
;         __builtin_amdgcn_sched_barrier(0);
;         if (wr_ok) *(uint4*)(nA + soff0 + 12288) = ra3;
;         if (ld_ok) ra3 = *(const uint4*)(Ab + (aoff + 96u * LDA + koa));
;         ga[3] = *(const bf16x8*)(sA + arow_off + 3 * 2048 + ch1); gb[3] = *(const bf16x8*)(sB + brow_off + 3 * 2048 + ch1);
;         __builtin_amdgcn_sched_barrier(0);
; #pragma unroll
;         for (int j = 0; j < 4; ++j) acc[3][j] = __builtin_amdgcn_mfma_f32_16x16x32_bf16(fb[j], fa[3], acc[3][j], 0, 0, 0);
;         __builtin_amdgcn_sched_barrier(0);
;         if (wr_ok) *(uint4*)(nB + soff0) = rb0;
	ds_write_b128 v2, v[110:113] offset:40960
	v_mfma_f32_16x16x32_bf16 v[46:49], v[126:129], v[132:135], v[46:49]
	ds_read_b128 v[110:113], v4 offset:4096
	v_mfma_f32_16x16x32_bf16 v[58:61], v[154:157], v[132:135], v[58:61]
	ds_read_b128 v[178:181], v5 offset:20480
	v_mfma_f32_16x16x32_bf16 v[18:21], v[158:161], v[132:135], v[18:21]
	global_load_dwordx4 v[132:135], v224, s[36:37] offset:1792
	v_mfma_f32_16x16x32_bf16 v[38:41], v[114:117], v[150:153], v[38:41]
	s_waitcnt vmcnt(8)
	ds_write_b128 v2, v[146:149] offset:45056
	v_mfma_f32_16x16x32_bf16 v[50:53], v[126:129], v[150:153], v[50:53]
	ds_read_b128 v[146:149], v4 offset:6144
	v_mfma_f32_16x16x32_bf16 v[54:57], v[154:157], v[150:153], v[54:57]
	ds_read_b128 v[182:185], v5 offset:22528
	v_mfma_f32_16x16x32_bf16 v[22:25], v[158:161], v[150:153], v[22:25]
	s_waitcnt lgkmcnt(9)
	v_mfma_f32_16x16x32_bf16 v[26:29], v[170:173], v[166:169], v[26:29]
	global_load_dwordx4 v[114:117], v3, s[0:1] offset:1792
	s_waitcnt lgkmcnt(0)
	v_mfma_f32_16x16x32_bf16 v[10:13], v[182:185], v[166:169], v[10:13]
	s_waitcnt vmcnt(8)
	ds_write_b128 v2, v[122:125] offset:49152
	v_mfma_f32_16x16x32_bf16 v[86:89], v[174:177], v[166:169], v[86:89]
	v_mfma_f32_16x16x32_bf16 v[94:97], v[178:181], v[166:169], v[94:97]
	global_load_dwordx4 v[122:125], v225, s[0:1] offset:1792
	v_mfma_f32_16x16x32_bf16 v[30:33], v[170:173], v[102:105], v[30:33]
	s_waitcnt vmcnt(8)
	ds_write_b128 v2, v[118:121] offset:53248
	v_mfma_f32_16x16x32_bf16 v[42:45], v[174:177], v[102:105], v[42:45]
	v_mfma_f32_16x16x32_bf16 v[14:17], v[182:185], v[102:105], v[14:17]
	v_mfma_f32_16x16x32_bf16 v[90:93], v[178:181], v[102:105], v[90:93]
	global_load_dwordx4 v[102:105], v226, s[0:1] offset:1792
	v_mfma_f32_16x16x32_bf16 v[34:37], v[170:173], v[110:113], v[34:37]
	s_waitcnt vmcnt(8)
	ds_write_b128 v2, v[62:65] offset:57344
	v_mfma_f32_16x16x32_bf16 v[46:49], v[174:177], v[110:113], v[46:49]
	v_mfma_f32_16x16x32_bf16 v[58:61], v[178:181], v[110:113], v[58:61]
	v_mfma_f32_16x16x32_bf16 v[18:21], v[182:185], v[110:113], v[18:21]
	global_load_dwordx4 v[62:65], v227, s[0:1] offset:1792
	v_mfma_f32_16x16x32_bf16 v[38:41], v[170:173], v[146:149], v[38:41]
	s_waitcnt vmcnt(8)
	ds_write_b128 v2, v[98:101] offset:61440
	v_mfma_f32_16x16x32_bf16 v[50:53], v[174:177], v[146:149], v[50:53]
	v_mfma_f32_16x16x32_bf16 v[54:57], v[178:181], v[146:149], v[54:57]
	v_mfma_f32_16x16x32_bf16 v[22:25], v[182:185], v[146:149], v[22:25]
	s_setprio 0
	s_waitcnt lgkmcnt(0)
	s_barrier
	ds_read_b128 v[98:101], v6 offset:32768
	ds_read_b128 v[110:113], v6 offset:34816
	ds_read_b128 v[118:121], v7 offset:49152
	ds_read_b128 v[126:129], v7 offset:51200
	ds_read_b128 v[146:149], v6 offset:36864
	ds_read_b128 v[150:153], v6 offset:38912
	ds_read_b128 v[154:157], v7 offset:53248
	ds_read_b128 v[158:161], v7 offset:55296
	s_setprio 2
	s_waitcnt lgkmcnt(5)
	v_mfma_f32_16x16x32_bf16 v[26:29], v[118:121], v[98:101], v[26:29]
	global_load_dwordx4 v[166:169], v8, s[36:37] offset:1920
	s_waitcnt lgkmcnt(0)
	v_mfma_f32_16x16x32_bf16 v[10:13], v[158:161], v[98:101], v[10:13]
	s_waitcnt vmcnt(8)
	ds_write_b128 v2, v[162:165]
	v_mfma_f32_16x16x32_bf16 v[86:89], v[126:129], v[98:101], v[86:89]
	ds_read_b128 v[162:165], v4 offset:32768
	v_mfma_f32_16x16x32_bf16 v[94:97], v[154:157], v[98:101], v[94:97]
	ds_read_b128 v[170:173], v5 offset:49152
	global_load_dwordx4 v[98:101], v222, s[36:37] offset:1920
	v_mfma_f32_16x16x32_bf16 v[30:33], v[118:121], v[110:113], v[30:33]
	s_waitcnt vmcnt(8)
	ds_write_b128 v2, v[82:85] offset:4096
	v_mfma_f32_16x16x32_bf16 v[42:45], v[126:129], v[110:113], v[42:45]
	ds_read_b128 v[82:85], v4 offset:34816
	v_mfma_f32_16x16x32_bf16 v[14:17], v[158:161], v[110:113], v[14:17]
	ds_read_b128 v[174:177], v5 offset:51200
	v_mfma_f32_16x16x32_bf16 v[90:93], v[154:157], v[110:113], v[90:93]
	global_load_dwordx4 v[110:113], v223, s[36:37] offset:1920
	v_mfma_f32_16x16x32_bf16 v[34:37], v[118:121], v[146:149], v[34:37]
	s_waitcnt vmcnt(8)
	ds_write_b128 v2, v[106:109] offset:8192
	v_mfma_f32_16x16x32_bf16 v[46:49], v[126:129], v[146:149], v[46:49]
	ds_read_b128 v[106:109], v4 offset:36864
	v_mfma_f32_16x16x32_bf16 v[58:61], v[154:157], v[146:149], v[58:61]
	ds_read_b128 v[178:181], v5 offset:53248
	v_mfma_f32_16x16x32_bf16 v[18:21], v[158:161], v[146:149], v[18:21]
	v_add_u32_e32 v8, 0x30780, v8
	global_load_dwordx4 v[146:149], v8, s[36:37]
	s_waitcnt vmcnt(8)
	ds_write_b128 v2, v[132:135] offset:12288
	ds_read_b128 v[132:135], v4 offset:38912
	ds_read_b128 v[182:185], v5 offset:55296
	v_mfma_f32_16x16x32_bf16 v[38:41], v[118:121], v[150:153], v[38:41]
	v_mfma_f32_16x16x32_bf16 v[50:53], v[126:129], v[150:153], v[50:53]
	v_mfma_f32_16x16x32_bf16 v[54:57], v[154:157], v[150:153], v[54:57]
	v_mfma_f32_16x16x32_bf16 v[22:25], v[158:161], v[150:153], v[22:25]
	s_waitcnt lgkmcnt(9)
	v_mfma_f32_16x16x32_bf16 v[26:29], v[170:173], v[162:165], v[26:29]
	global_load_dwordx4 v[118:121], v3, s[0:1] offset:1920
	s_waitcnt lgkmcnt(0)
	v_mfma_f32_16x16x32_bf16 v[8:11], v[182:185], v[162:165], v[10:13]
	s_waitcnt vmcnt(8)
	ds_write_b128 v2, v[114:117] offset:16384
	v_mfma_f32_16x16x32_bf16 v[86:89], v[174:177], v[162:165], v[86:89]
	v_mfma_f32_16x16x32_bf16 v[94:97], v[178:181], v[162:165], v[94:97]
	s_nop 0
	global_load_dwordx4 v[114:117], v225, s[0:1] offset:1920
	s_waitcnt vmcnt(8)
	ds_write_b128 v2, v[122:125] offset:20480
	v_mfma_f32_16x16x32_bf16 v[30:33], v[170:173], v[82:85], v[30:33]
	v_mfma_f32_16x16x32_bf16 v[42:45], v[174:177], v[82:85], v[42:45]
	v_mfma_f32_16x16x32_bf16 v[12:15], v[182:185], v[82:85], v[14:17]
	v_mfma_f32_16x16x32_bf16 v[90:93], v[178:181], v[82:85], v[90:93]
	s_nop 1
	global_load_dwordx4 v[82:85], v226, s[0:1] offset:1920
	s_waitcnt vmcnt(8)
	ds_write_b128 v2, v[102:105] offset:24576
	v_mfma_f32_16x16x32_bf16 v[34:37], v[170:173], v[106:109], v[34:37]
	v_mfma_f32_16x16x32_bf16 v[46:49], v[174:177], v[106:109], v[46:49]
	v_mfma_f32_16x16x32_bf16 v[58:61], v[178:181], v[106:109], v[58:61]
	v_mfma_f32_16x16x32_bf16 v[16:19], v[182:185], v[106:109], v[18:21]
	v_add_u32_e32 v3, 0x30780, v3
	global_load_dwordx4 v[102:105], v3, s[0:1]
	s_waitcnt vmcnt(8)
	ds_write_b128 v2, v[62:65] offset:28672
	v_mfma_f32_16x16x32_bf16 v[38:41], v[170:173], v[132:135], v[38:41]
	v_mfma_f32_16x16x32_bf16 v[50:53], v[174:177], v[132:135], v[50:53]
	v_mfma_f32_16x16x32_bf16 v[54:57], v[178:181], v[132:135], v[54:57]
	v_mfma_f32_16x16x32_bf16 v[20:23], v[182:185], v[132:135], v[22:25]
	s_setprio 0
	s_waitcnt lgkmcnt(0)
	s_barrier
; template <int MODE>
; __device__ __forceinline__ void gemm_tile(const Params& P, int tm, int tn, unsigned char* smem) {
;     ...
; #pragma unroll
;         for (int i = 0; i < 4; ++i) { fa[i] = *(const bf16x8*)(sA + arow_off + i * 2048 + ch0); fb[i] = *(const bf16x8*)(sB + brow_off + i * 2048 + ch0); }
;         __builtin_amdgcn_sched_barrier(0);
;         __builtin_amdgcn_s_setprio(2);
;         if (wr_ok) *(uint4*)(nA + soff0) = ra0;
;         if (ld_ok) ra0 = *(const uint4*)(Ab + (aoff + 0u * LDA + koa));
;         ga[0] = *(const bf16x8*)(sA + arow_off + 0 * 2048 + ch1); gb[0] = *(const bf16x8*)(sB + brow_off + 0 * 2048 + ch1);
;         __builtin_amdgcn_sched_barrier(0);
; #pragma unroll
;         for (int j = 0; j < 4; ++j) acc[0][j] = __builtin_amdgcn_mfma_f32_16x16x32_bf16(fb[j], fa[0], acc[0][j], 0, 0, 0);
;         __builtin_amdgcn_sched_barrier(0);
;         if (wr_ok) *(uint4*)(nA + soff0 + 4096) = ra1;
;         if (ld_ok) ra1 = *(const uint4*)(Ab + (aoff + 32u * LDA + koa));
;         ga[1] = *(const bf16x8*)(sA + arow_off + 1 * 2048 + ch1); gb[1] = *(const bf16x8*)(sB + brow_off + 1 * 2048 + ch1);
;         __builtin_amdgcn_sched_barrier(0);
; #pragma unroll
;         for (int j = 0; j < 4; ++j) acc[1][j] = __builtin_amdgcn_mfma_f32_16x16x32_bf16(fb[j], fa[1], acc[1][j], 0, 0, 0);
;         __builtin_amdgcn_sched_barrier(0);
;         if (wr_ok) *(uint4*)(nA + soff0 + 8192) = ra2;
;         if (ld_ok) ra2 = *(const uint4*)(Ab + (aoff + 64u * LDA + koa));
;         ga[2] = *(const bf16x8*)(sA + arow_off + 2 * 2048 + ch1); gb[2] = *(const bf16x8*)(sB + brow_off + 2 * 2048 + ch1);
;         __builtin_amdgcn_sched_barrier(0);
; #pragma unroll
;         for (int j = 0; j < 4; ++j) acc[2][j] = __builtin_amdgcn_mfma_f32_16x16x32_bf16(fb[j], fa[2], acc[2][j], 0, 0, 0);
;         __builtin_amdgcn_sched_barrier(0);
;         if (wr_ok) *(uint4*)(nA + soff0 + 12288) = ra3;
;         if (ld_ok) ra3 = *(const uint4*)(Ab + (aoff + 96u * LDA + koa));
;         ga[3] = *(const bf16x8*)(sA + arow_off + 3 * 2048 + ch1); gb[3] = *(const bf16x8*)(sB + brow_off + 3 * 2048 + ch1);
;         __builtin_amdgcn_sched_barrier(0);
; #pragma unroll
;         for (int j = 0; j < 4; ++j) acc[3][j] = __builtin_amdgcn_mfma_f32_16x16x32_bf16(fb[j], fa[3], acc[3][j], 0, 0, 0);
;         __builtin_amdgcn_sched_barrier(0);
;         if (wr_ok) *(uint4*)(nB + soff0) = rb0;
	ds_read_b128 v[62:65], v6
	ds_read_b128 v[106:109], v6 offset:2048
	ds_read_b128 v[122:125], v7 offset:16384
	ds_read_b128 v[126:129], v7 offset:18432
	ds_read_b128 v[132:135], v6 offset:4096
	ds_read_b128 v[150:153], v6 offset:6144
	ds_read_b128 v[154:157], v7 offset:20480
	ds_read_b128 v[158:161], v7 offset:22528
	s_setprio 2
	s_waitcnt lgkmcnt(5)
	v_mfma_f32_16x16x32_bf16 v[24:27], v[122:125], v[62:65], v[26:29]
	s_waitcnt lgkmcnt(0)
	v_mfma_f32_16x16x32_bf16 v[8:11], v[158:161], v[62:65], v[8:11]
	s_waitcnt vmcnt(7)
	ds_write_b128 v2, v[166:169] offset:32768
	v_mfma_f32_16x16x32_bf16 v[86:89], v[126:129], v[62:65], v[86:89]
	ds_read_b128 v[162:165], v4
	v_mfma_f32_16x16x32_bf16 v[94:97], v[154:157], v[62:65], v[94:97]
	ds_read_b128 v[166:169], v5 offset:16384
	v_mfma_f32_16x16x32_bf16 v[28:31], v[122:125], v[106:109], v[30:33]
	s_waitcnt vmcnt(6)
	ds_write_b128 v2, v[98:101] offset:36864
	v_mfma_f32_16x16x32_bf16 v[42:45], v[126:129], v[106:109], v[42:45]
	ds_read_b128 v[62:65], v4 offset:2048
	v_mfma_f32_16x16x32_bf16 v[12:15], v[158:161], v[106:109], v[12:15]
	ds_read_b128 v[98:101], v5 offset:18432
	v_mfma_f32_16x16x32_bf16 v[90:93], v[154:157], v[106:109], v[90:93]
	v_mfma_f32_16x16x32_bf16 v[32:35], v[122:125], v[132:135], v[34:37]
	s_waitcnt vmcnt(5)
	ds_write_b128 v2, v[110:113] offset:40960
	v_mfma_f32_16x16x32_bf16 v[46:49], v[126:129], v[132:135], v[46:49]
	ds_read_b128 v[106:109], v4 offset:4096
	v_mfma_f32_16x16x32_bf16 v[58:61], v[154:157], v[132:135], v[58:61]
	ds_read_b128 v[110:113], v5 offset:20480
	v_mfma_f32_16x16x32_bf16 v[16:19], v[158:161], v[132:135], v[16:19]
	v_mfma_f32_16x16x32_bf16 v[36:39], v[122:125], v[150:153], v[38:41]
	s_waitcnt vmcnt(4)
	ds_write_b128 v2, v[146:149] offset:45056
	v_mfma_f32_16x16x32_bf16 v[50:53], v[126:129], v[150:153], v[50:53]
	ds_read_b128 v[132:135], v4 offset:6144
	v_mfma_f32_16x16x32_bf16 v[54:57], v[154:157], v[150:153], v[54:57]
	ds_read_b128 v[146:149], v5 offset:22528
	v_mfma_f32_16x16x32_bf16 v[20:23], v[158:161], v[150:153], v[20:23]
	s_waitcnt lgkmcnt(9)
	v_mfma_f32_16x16x32_bf16 v[24:27], v[166:169], v[162:165], v[24:27]
	s_waitcnt lgkmcnt(0)
	v_mfma_f32_16x16x32_bf16 v[8:11], v[146:149], v[162:165], v[8:11]
	s_waitcnt vmcnt(3)
	ds_write_b128 v2, v[118:121] offset:49152
	v_mfma_f32_16x16x32_bf16 v[86:89], v[98:101], v[162:165], v[86:89]
	v_mfma_f32_16x16x32_bf16 v[94:97], v[110:113], v[162:165], v[94:97]
	v_mfma_f32_16x16x32_bf16 v[28:31], v[166:169], v[62:65], v[28:31]
	s_waitcnt vmcnt(2)
	ds_write_b128 v2, v[114:117] offset:53248
	v_mfma_f32_16x16x32_bf16 v[40:43], v[98:101], v[62:65], v[42:45]
	v_mfma_f32_16x16x32_bf16 v[12:15], v[146:149], v[62:65], v[12:15]
	v_mfma_f32_16x16x32_bf16 v[90:93], v[110:113], v[62:65], v[90:93]
	v_mfma_f32_16x16x32_bf16 v[32:35], v[166:169], v[106:109], v[32:35]
	s_waitcnt vmcnt(1)
	ds_write_b128 v2, v[82:85] offset:57344
	v_mfma_f32_16x16x32_bf16 v[44:47], v[98:101], v[106:109], v[46:49]
	v_mfma_f32_16x16x32_bf16 v[58:61], v[110:113], v[106:109], v[58:61]
	v_mfma_f32_16x16x32_bf16 v[16:19], v[146:149], v[106:109], v[16:19]
	v_mfma_f32_16x16x32_bf16 v[36:39], v[166:169], v[132:135], v[36:39]
	s_waitcnt vmcnt(0)
	ds_write_b128 v2, v[102:105] offset:61440
	v_mfma_f32_16x16x32_bf16 v[48:51], v[98:101], v[132:135], v[50:53]
	v_mfma_f32_16x16x32_bf16 v[52:55], v[110:113], v[132:135], v[54:57]
	v_mfma_f32_16x16x32_bf16 v[20:23], v[146:149], v[132:135], v[20:23]
	s_setprio 0
	s_waitcnt lgkmcnt(0)
	s_barrier
	ds_read_b128 v[62:65], v6 offset:32768
	ds_read_b128 v[82:85], v6 offset:34816
	ds_read_b128 v[98:101], v7 offset:49152
	ds_read_b128 v[102:105], v7 offset:51200
	ds_read_b128 v[106:109], v6 offset:36864
	ds_read_b128 v[110:113], v6 offset:38912
	ds_read_b128 v[114:117], v7 offset:53248
	ds_read_b128 v[118:121], v7 offset:55296
	s_setprio 2
	s_waitcnt lgkmcnt(5)
	v_mfma_f32_16x16x32_bf16 v[24:27], v[98:101], v[62:65], v[24:27]
	s_waitcnt lgkmcnt(0)
	v_mfma_f32_16x16x32_bf16 v[6:9], v[118:121], v[62:65], v[8:11]
	ds_read_b128 v[122:125], v4 offset:32768
	v_mfma_f32_16x16x32_bf16 v[86:89], v[102:105], v[62:65], v[86:89]
	ds_read_b128 v[126:129], v5 offset:49152
	v_mfma_f32_16x16x32_bf16 v[94:97], v[114:117], v[62:65], v[94:97]
	v_mfma_f32_16x16x32_bf16 v[28:31], v[98:101], v[82:85], v[28:31]
	ds_read_b128 v[132:135], v4 offset:34816
	v_mfma_f32_16x16x32_bf16 v[40:43], v[102:105], v[82:85], v[40:43]
	ds_read_b128 v[146:149], v5 offset:51200
	v_mfma_f32_16x16x32_bf16 v[10:13], v[118:121], v[82:85], v[12:15]
	v_mfma_f32_16x16x32_bf16 v[90:93], v[114:117], v[82:85], v[90:93]
	v_mfma_f32_16x16x32_bf16 v[14:17], v[118:121], v[106:109], v[16:19]
	ds_read_b128 v[82:85], v4 offset:36864
	v_mfma_f32_16x16x32_bf16 v[154:157], v[98:101], v[106:109], v[32:35]
	ds_read_b128 v[150:153], v5 offset:53248
	v_mfma_f32_16x16x32_bf16 v[158:161], v[102:105], v[106:109], v[44:47]
	v_mfma_f32_16x16x32_bf16 v[162:165], v[114:117], v[106:109], v[58:61]
	v_mfma_f32_16x16x32_bf16 v[98:101], v[98:101], v[110:113], v[36:39]
	ds_read_b128 v[106:109], v4 offset:38912
	v_mfma_f32_16x16x32_bf16 v[102:105], v[102:105], v[110:113], v[48:51]
	ds_read_b128 v[2:5], v5 offset:55296
	v_mfma_f32_16x16x32_bf16 v[114:117], v[114:117], v[110:113], v[52:55]
	v_mfma_f32_16x16x32_bf16 v[110:113], v[118:121], v[110:113], v[20:23]
	s_waitcnt lgkmcnt(6)
	v_mfma_f32_16x16x32_bf16 v[62:65], v[126:129], v[122:125], v[24:27]
	s_waitcnt lgkmcnt(4)
	v_mfma_f32_16x16x32_bf16 v[58:61], v[146:149], v[122:125], v[86:89]
	s_waitcnt lgkmcnt(2)
	v_mfma_f32_16x16x32_bf16 v[54:57], v[150:153], v[122:125], v[94:97]
	s_waitcnt lgkmcnt(0)
	v_mfma_f32_16x16x32_bf16 v[50:53], v[2:5], v[122:125], v[6:9]
	v_mfma_f32_16x16x32_bf16 v[46:49], v[126:129], v[132:135], v[28:31]
	v_mfma_f32_16x16x32_bf16 v[42:45], v[146:149], v[132:135], v[40:43]
	v_mfma_f32_16x16x32_bf16 v[38:41], v[150:153], v[132:135], v[90:93]
	v_mfma_f32_16x16x32_bf16 v[34:37], v[2:5], v[132:135], v[10:13]
	v_mfma_f32_16x16x32_bf16 v[30:33], v[126:129], v[82:85], v[154:157]
	v_mfma_f32_16x16x32_bf16 v[26:29], v[146:149], v[82:85], v[158:161]
	v_mfma_f32_16x16x32_bf16 v[22:25], v[150:153], v[82:85], v[162:165]
	v_mfma_f32_16x16x32_bf16 v[18:21], v[2:5], v[82:85], v[14:17]
	v_mfma_f32_16x16x32_bf16 v[14:17], v[126:129], v[106:109], v[98:101]
	v_mfma_f32_16x16x32_bf16 v[10:13], v[146:149], v[106:109], v[102:105]
	v_mfma_f32_16x16x32_bf16 v[6:9], v[150:153], v[106:109], v[114:117]
	v_mfma_f32_16x16x32_bf16 v[2:5], v[2:5], v[106:109], v[110:113]
	s_setprio 0
	s_and_b32 s0, s7, -8
	s_cmp_lg_u32 s0, 16
	s_barrier
; template <int MODE>
; __device__ __forceinline__ void gemm_tile(const Params& P, int tm, int tn, unsigned char* smem) {
;     ...
;     if (MODE == 1) {
;         if (n0 >= ZC_FQ && n0 < ZC_FV) {
;             const bool isk = n0 >= ZC_FK;
;             const float* gain = isk ? P.f_k_norm : P.f_q_norm;
;             const float scl = isk ? 1.0f : 0.125f * LOG2E;
;             float gn[4][4];
; #pragma unroll
;             for (int j = 0; j < 4; ++j)
; #pragma unroll
;                 for (int r = 0; r < 4; ++r) gn[j][r] = gain[16 * j + 4 * g + r];
; #pragma unroll
;             for (int i = 0; i < 4; ++i) {
;                 float ss = 0.f;
; #pragma unroll
;                 for (int j = 0; j < 4; ++j)
; #pragma unroll
;                     for (int r = 0; r < 4; ++r) ss += acc[i][j][r] * acc[i][j][r];
;                 ss = x4_sum(ss);
;                 const float rstd = rsqrtf(ss * (1.0f / 64.0f) + EPS) * scl;
	s_cbranch_scc1 .LBB0_223
	v_mul_f32_e32 v68, v63, v63
	v_fmac_f32_e32 v68, v62, v62
	v_fmac_f32_e32 v68, v64, v64
	v_fmac_f32_e32 v68, v65, v65
	v_fmac_f32_e32 v68, v58, v58
	v_fmac_f32_e32 v68, v59, v59
	v_fmac_f32_e32 v68, v60, v60
	v_fmac_f32_e32 v68, v61, v61
	v_fmac_f32_e32 v68, v54, v54
	v_fmac_f32_e32 v68, v55, v55
	v_fmac_f32_e32 v68, v56, v56
	s_cmp_gt_u32 s7, 19
	v_fmac_f32_e32 v68, v57, v57
	v_pk_mul_f32 v[82:83], v[50:51], v[50:51]
	v_mov_b32_e32 v66, 0x3e38aa3b
	s_cselect_b64 s[0:1], -1, 0
	v_add_f32_e32 v68, v82, v68
	v_cndmask_b32_e64 v106, v66, 1.0, s[0:1]
	v_pk_mul_f32 v[66:67], v[52:53], v[52:53]
	v_add_f32_e32 v68, v83, v68
	v_add_f32_e32 v66, v66, v68
	v_add_f32_e32 v66, v67, v66
	v_mov_b32_e32 v67, v66
	s_nop 1
	v_permlane32_swap_b32_e32 v66, v67
	v_add_f32_e32 v67, v66, v67
	v_mul_f32_e32 v66, v47, v47
	v_fmac_f32_e32 v66, v46, v46
	v_fmac_f32_e32 v66, v48, v48
	v_fmac_f32_e32 v66, v49, v49
	v_fmac_f32_e32 v66, v42, v42
	v_fmac_f32_e32 v66, v43, v43
	v_fmac_f32_e32 v66, v44, v44
	v_fmac_f32_e32 v66, v45, v45
	v_fmac_f32_e32 v66, v38, v38
	v_fmac_f32_e32 v66, v39, v39
	v_fmac_f32_e32 v66, v40, v40
	v_fmac_f32_e32 v66, v41, v41
	v_pk_mul_f32 v[86:87], v[34:35], v[34:35]
	v_pk_mul_f32 v[84:85], v[36:37], v[36:37]
	v_add_f32_e32 v66, v86, v66
	v_add_f32_e32 v66, v87, v66
	v_add_f32_e32 v66, v84, v66
	v_add_f32_e32 v66, v85, v66
	v_mov_b32_e32 v68, v66
	s_nop 1
	v_permlane32_swap_b32_e32 v66, v68
	v_add_f32_e32 v66, v66, v68
	s_and_b64 s[0:1], s[0:1], exec
	v_mov_b32_e32 v83, v67
	v_mov_b32_e32 v82, v66
	s_nop 0
	v_permlane16_swap_b32_e32 v67, v83
	v_permlane16_swap_b32_e32 v66, v82
	s_mov_b32 s0, 0x358637bd
	v_pk_add_f32 v[82:83], v[66:67], v[82:83]
	s_mov_b32 s10, 0x3c800000
	v_mov_b64_e32 v[66:67], s[0:1]
	v_mul_f32_e32 v95, v31, v31
	v_pk_fma_f32 v[86:87], v[82:83], s[10:11], v[66:67] op_sel_hi:[1,0,0]
	s_mov_b32 s7, 0x800000
	v_fmac_f32_e32 v95, v30, v30
	v_mul_f32_e32 v68, 0x4b800000, v87
	v_cmp_gt_f32_e32 vcc, s7, v87
	v_fmac_f32_e32 v95, v32, v32
	v_fmac_f32_e32 v95, v33, v33
	v_cndmask_b32_e32 v68, v87, v68, vcc
	v_rsq_f32_e32 v68, v68
	v_mul_f32_e32 v70, 0x4b800000, v86
	v_cmp_gt_f32_e64 s[0:1], s7, v86
	v_fmac_f32_e32 v95, v26, v26
	v_fmac_f32_e32 v95, v27, v27
	v_cndmask_b32_e64 v70, v86, v70, s[0:1]
	v_rsq_f32_e32 v86, v70
	v_fmac_f32_e32 v95, v28, v28
	s_cselect_b32 s9, s41, s39
	s_cselect_b32 s8, s40, s38
	v_lshlrev_b32_e32 v94, 4, v81
	v_fmac_f32_e32 v95, v29, v29
	global_load_dwordx4 v[82:85], v94, s[8:9]
	v_mul_f32_e32 v70, 0x45800000, v68
	v_fmac_f32_e32 v95, v22, v22
	v_cndmask_b32_e32 v68, v68, v70, vcc
	v_fmac_f32_e32 v95, v23, v23
	v_mul_f32_e32 v70, v106, v68
	v_mul_f32_e32 v68, 0x45800000, v86
	v_fmac_f32_e32 v95, v24, v24
	v_cndmask_b32_e64 v68, v86, v68, s[0:1]
	global_load_dwordx4 v[86:89], v94, s[8:9] offset:64
	v_fmac_f32_e32 v95, v25, v25
	v_pk_mul_f32 v[92:93], v[18:19], v[18:19]
	v_pk_mul_f32 v[90:91], v[20:21], v[20:21]
	v_add_f32_e32 v92, v92, v95
	v_add_f32_e32 v92, v93, v92
	v_add_f32_e32 v90, v90, v92
	v_add_f32_e32 v95, v91, v90
	global_load_dwordx4 v[90:93], v94, s[8:9] offset:128
	v_mov_b32_e32 v96, v95
	s_nop 1
	v_permlane32_swap_b32_e32 v95, v96
	v_add_f32_e32 v99, v95, v96
	global_load_dwordx4 v[94:97], v94, s[8:9] offset:192
	v_mul_f32_e32 v98, v15, v15
	v_fmac_f32_e32 v98, v14, v14
	v_fmac_f32_e32 v98, v16, v16
	v_fmac_f32_e32 v98, v17, v17
	v_fmac_f32_e32 v98, v10, v10
	v_fmac_f32_e32 v98, v11, v11
	v_fmac_f32_e32 v98, v12, v12
	v_fmac_f32_e32 v98, v13, v13
	v_fmac_f32_e32 v98, v6, v6
	v_fmac_f32_e32 v98, v7, v7
	v_fmac_f32_e32 v98, v8, v8
	v_fmac_f32_e32 v98, v9, v9
	v_pk_mul_f32 v[104:105], v[2:3], v[2:3]
	v_pk_mul_f32 v[102:103], v[4:5], v[4:5]
	v_add_f32_e32 v98, v104, v98
	v_add_f32_e32 v98, v105, v98
	v_add_f32_e32 v98, v102, v98
	v_add_f32_e32 v98, v103, v98
	v_mov_b32_e32 v100, v98
	s_nop 1
	v_permlane32_swap_b32_e32 v98, v100
	v_add_f32_e32 v98, v98, v100
	v_mov_b32_e32 v101, v99
	v_mov_b32_e32 v100, v98
	s_nop 0
	v_permlane16_swap_b32_e32 v99, v101
	v_permlane16_swap_b32_e32 v98, v100
	v_pk_add_f32 v[98:99], v[98:99], v[100:101]
	v_mul_f32_e32 v68, v106, v68
	v_pk_fma_f32 v[66:67], v[98:99], s[10:11], v[66:67] op_sel_hi:[1,0,0]
	s_waitcnt vmcnt(3)
; template <int MODE>
; __device__ __forceinline__ void gemm_tile(const Params& P, int tm, int tn, unsigned char* smem) {
;     ...
; #pragma unroll
;                 for (int j = 0; j < 4; ++j)
; #pragma unroll
;                     for (int r = 0; r < 4; ++r) acc[i][j][r] *= rstd * gn[j][r];
;             }
	v_pk_mul_f32 v[100:101], v[82:83], v[70:71] op_sel_hi:[1,0]
	v_mul_f32_e32 v98, 0x4b800000, v67
	v_cmp_gt_f32_e32 vcc, s7, v67
	v_cmp_gt_f32_e64 s[0:1], s7, v66
	v_pk_mul_f32 v[62:63], v[62:63], v[100:101]
	v_cndmask_b32_e32 v67, v67, v98, vcc
	v_mul_f32_e32 v98, 0x4b800000, v66
	v_rsq_f32_e32 v67, v67
	v_cndmask_b32_e64 v66, v66, v98, s[0:1]
	v_rsq_f32_e32 v98, v66
	v_pk_mul_f32 v[100:101], v[82:83], v[68:69] op_sel_hi:[1,0]
	v_mul_f32_e32 v66, 0x45800000, v67
	v_cndmask_b32_e32 v66, v67, v66, vcc
	v_mul_f32_e32 v67, 0x45800000, v98
	v_cndmask_b32_e64 v67, v98, v67, s[0:1]
	v_mul_f32_e32 v66, v106, v66
	v_mul_f32_e32 v98, v106, v67
	v_pk_mul_f32 v[102:103], v[84:85], v[70:71] op_sel_hi:[1,0]
	v_pk_mul_f32 v[46:47], v[46:47], v[100:101]
	v_pk_mul_f32 v[100:101], v[82:83], v[66:67] op_sel_hi:[1,0]
	v_pk_mul_f32 v[82:83], v[82:83], v[98:99] op_sel_hi:[1,0]
	v_pk_mul_f32 v[64:65], v[64:65], v[102:103]
	v_pk_mul_f32 v[102:103], v[84:85], v[68:69] op_sel_hi:[1,0]
	v_pk_mul_f32 v[14:15], v[14:15], v[82:83]
	s_waitcnt vmcnt(2)
	v_pk_mul_f32 v[82:83], v[86:87], v[70:71] op_sel_hi:[1,0]
	v_pk_mul_f32 v[48:49], v[48:49], v[102:103]
	v_pk_mul_f32 v[102:103], v[84:85], v[66:67] op_sel_hi:[1,0]
	v_pk_mul_f32 v[84:85], v[84:85], v[98:99] op_sel_hi:[1,0]
	v_pk_mul_f32 v[58:59], v[58:59], v[82:83]
	v_pk_mul_f32 v[82:83], v[86:87], v[68:69] op_sel_hi:[1,0]
	v_pk_mul_f32 v[16:17], v[16:17], v[84:85]
	v_pk_mul_f32 v[84:85], v[88:89], v[70:71] op_sel_hi:[1,0]
	v_pk_mul_f32 v[42:43], v[42:43], v[82:83]
	v_pk_mul_f32 v[82:83], v[86:87], v[66:67] op_sel_hi:[1,0]
	v_pk_mul_f32 v[60:61], v[60:61], v[84:85]
	v_pk_mul_f32 v[84:85], v[88:89], v[68:69] op_sel_hi:[1,0]
	v_pk_mul_f32 v[26:27], v[26:27], v[82:83]
	v_pk_mul_f32 v[82:83], v[86:87], v[98:99] op_sel_hi:[1,0]
	v_pk_mul_f32 v[44:45], v[44:45], v[84:85]
	v_pk_mul_f32 v[84:85], v[88:89], v[66:67] op_sel_hi:[1,0]
	v_pk_mul_f32 v[10:11], v[10:11], v[82:83]
	s_waitcnt vmcnt(1)
	v_pk_mul_f32 v[82:83], v[90:91], v[70:71] op_sel_hi:[1,0]
	v_pk_mul_f32 v[28:29], v[28:29], v[84:85]
	v_pk_mul_f32 v[84:85], v[88:89], v[98:99] op_sel_hi:[1,0]
	v_pk_mul_f32 v[54:55], v[54:55], v[82:83]
	v_pk_mul_f32 v[82:83], v[90:91], v[68:69] op_sel_hi:[1,0]
	v_pk_mul_f32 v[12:13], v[12:13], v[84:85]
	v_pk_mul_f32 v[84:85], v[92:93], v[70:71] op_sel_hi:[1,0]
	v_pk_mul_f32 v[38:39], v[38:39], v[82:83]
	v_pk_mul_f32 v[82:83], v[90:91], v[66:67] op_sel_hi:[1,0]
	v_pk_mul_f32 v[56:57], v[56:57], v[84:85]
	v_pk_mul_f32 v[84:85], v[92:93], v[68:69] op_sel_hi:[1,0]
	v_pk_mul_f32 v[22:23], v[22:23], v[82:83]
	v_pk_mul_f32 v[82:83], v[90:91], v[98:99] op_sel_hi:[1,0]
	v_pk_mul_f32 v[40:41], v[40:41], v[84:85]
	v_pk_mul_f32 v[84:85], v[92:93], v[66:67] op_sel_hi:[1,0]
	v_pk_mul_f32 v[6:7], v[6:7], v[82:83]
	s_waitcnt vmcnt(0)
	v_pk_mul_f32 v[82:83], v[94:95], v[70:71] op_sel_hi:[1,0]
	v_pk_mul_f32 v[24:25], v[24:25], v[84:85]
	v_pk_mul_f32 v[84:85], v[92:93], v[98:99] op_sel_hi:[1,0]
	v_pk_mul_f32 v[50:51], v[50:51], v[82:83]
	v_pk_mul_f32 v[82:83], v[94:95], v[68:69] op_sel_hi:[1,0]
	v_pk_mul_f32 v[8:9], v[8:9], v[84:85]
	v_pk_mul_f32 v[84:85], v[96:97], v[70:71] op_sel_hi:[1,0]
	v_pk_mul_f32 v[34:35], v[34:35], v[82:83]
	v_pk_mul_f32 v[82:83], v[94:95], v[66:67] op_sel_hi:[1,0]
	v_pk_mul_f32 v[66:67], v[96:97], v[66:67] op_sel_hi:[1,0]
	v_pk_mul_f32 v[52:53], v[52:53], v[84:85]
	v_pk_mul_f32 v[84:85], v[96:97], v[68:69] op_sel_hi:[1,0]
	v_pk_mul_f32 v[20:21], v[20:21], v[66:67]
	v_pk_mul_f32 v[18:19], v[18:19], v[82:83]
	v_pk_mul_f32 v[66:67], v[94:95], v[98:99] op_sel_hi:[1,0]
	v_pk_mul_f32 v[82:83], v[96:97], v[98:99] op_sel_hi:[1,0]
	v_pk_mul_f32 v[32:33], v[32:33], v[102:103]
	v_pk_mul_f32 v[30:31], v[30:31], v[100:101]
	v_pk_mul_f32 v[36:37], v[36:37], v[84:85]
	v_pk_mul_f32 v[4:5], v[4:5], v[82:83]
	v_pk_mul_f32 v[2:3], v[2:3], v[66:67]

; template <int MODE>
; __device__ __forceinline__ void gemm_tile(const Params& P, int tm, int tn, unsigned char* smem) {
;     ...
;     const int tid = opaque_tid(), lane = tid & 63, wave = tid >> 6, wr = wave >> 1, wc = wave & 1, g = lane >> 4, lr = lane & 15;
;     const int m0 = tm * 128, n0 = tn * 128;
;     const int srow = tid >> 3, sc = tid & 7;
;     constexpr unsigned LDA = (MODE == 2 ? NZ : 1024) * 2u;
;     unsigned aoff, boff; int soff0;
;     {
;         int ar = m0 + srow;
;         if (MODE == 2) { const int b = ar >> 11, t = ar & 2047; ar = b * L + NMETA + t; }
;         aoff = (unsigned)ar * LDA + (unsigned)sc * 16u;
;         boff = (unsigned)(n0 + srow) * 2048u + (unsigned)sc * 16u;
;         soff0 = srow * 128 + ((sc ^ (srow & 7)) << 4);
;     }
;     const unsigned char* Ab = (const unsigned char*)A; const unsigned char* Bb = (const unsigned char*)Bt;
;     float4 ssp0, ssp1, ssp2, ssp3;
;     if (MODE == 3) {
;         const float* ssq = (const float*)(P.ws + WS_SSQ) + (size_t)(m0 + wr * 64 + lr) * 16 + 4 * g;
;         ssp0 = *(const float4*)(ssq); ssp1 = *(const float4*)(ssq + 16 * 16); ssp2 = *(const float4*)(ssq + 32 * 16); ssp3 = *(const float4*)(ssq + 48 * 16);
;     }
;     f32x4 acc[4][4];
; #pragma unroll
;     for (int i = 0; i < 4; ++i)
; #pragma unroll
;         for (int j = 0; j < 4; ++j) acc[i][j] = (f32x4){0.f, 0.f, 0.f, 0.f};
;     uint4 ra0, ra1, ra2, ra3, rb0, rb1, rb2, rb3;
;     ...
;     unsigned char* sA0 = smem; unsigned char* sB0 = smem + 16384; unsigned char* sA1 = smem + 32768; unsigned char* sB1 = smem + 49152;
;     G_LOAD(0)
;     G_WRITE(sA0, sB0)
;     __syncthreads();
;     const int arow_off = (wr * 64 + lr) * 128, brow_off = (wc * 64 + lr) * 128, sw = lr & 7;
;     G_LOAD(1)
;     for (int kt = 0; kt < 16; ++kt) {
;         unsigned char* sA = (kt & 1) ? sA1 : sA0; unsigned char* sB = (kt & 1) ? sB1 : sB0;
;         unsigned char* nA = (kt & 1) ? sA0 : sA1; unsigned char* nB = (kt & 1) ? sB0 : sB1;
;         bf16x8 fa[4], fb[4], ga[4], gb[4];
;         const int ch0 = ((g ^ sw) << 4), ch1 = (((4 + g) ^ sw) << 4);
; __global__ void __launch_bounds__(256, 2) mega(Params P) {
;     ...
;         for (int tile = vb; tile < full; tile += G) P1_TILE(tile)
;         if (G == 512 && rem > 0 && rem <= 28) {
;             const int q = vb / 18, isT = (vb - 18 * q == 0) && q < rem;
;             if (isT) P1_TILE(full + q)
.LBB0_241:
	s_andn2_b64 vcc, exec, s[4:5]
	s_cbranch_vccnz .LBB0_245
	s_add_i32 s14, s14, s10
	s_mul_hi_i32 s0, s14, 0x92492493
	s_add_i32 s0, s0, s14
	s_lshr_b32 s1, s0, 31
	s_ashr_i32 s0, s0, 7
	s_add_i32 s0, s0, s1
	s_mul_i32 s1, s0, 0xffffff20
	s_lshl_b32 s0, s0, 3
	s_add_i32 s1, s1, s14
	s_sub_i32 s3, 0x81, s0
	s_cmpk_gt_i32 s14, 0xdff
	s_cselect_b32 s3, s3, 8
	s_abs_i32 s4, s3
	v_cvt_f32_u32_e32 v2, s4
	s_sub_i32 s7, 0, s4
	s_abs_i32 s5, s1
	s_xor_b32 s6, s1, s3
	v_rcp_iflag_f32_e32 v2, v2
	s_ashr_i32 s6, s6, 31
	v_mov_b32_e32 v69, v0
	v_mul_f32_e32 v2, 0x4f7ffffe, v2
	v_cvt_u32_f32_e32 v2, v2
	v_lshlrev_b32_e32 v3, 4, v69
	v_and_b32_e32 v5, 0x70, v3
	v_and_b32_e32 v78, 15, v69
	v_readfirstlane_b32 s8, v2
	s_mul_i32 s7, s7, s8
	s_mul_hi_u32 s7, s8, s7
	s_add_i32 s8, s8, s7
	s_mul_hi_u32 s7, s5, s8
	s_mul_i32 s8, s7, s4
	s_sub_i32 s5, s5, s8
	s_add_i32 s9, s7, 1
	s_sub_i32 s8, s5, s4
	s_cmp_ge_u32 s5, s4
	s_cselect_b32 s7, s9, s7
	s_cselect_b32 s5, s8, s5
	s_add_i32 s8, s7, 1
	s_cmp_ge_u32 s5, s4
	s_cselect_b32 s4, s8, s7
	s_xor_b32 s4, s4, s6
	s_sub_i32 s5, s4, s6
	s_mul_i32 s3, s5, s3
	s_add_i32 s1, s1, s0
	s_sub_i32 s0, s1, s3
	s_lshl_b32 s3, s0, 7
	v_ashrrev_i32_e32 v2, 3, v69
	s_lshl_b32 s4, s5, 7
	v_add_u32_e32 v4, s3, v2
	v_add_u32_e32 v3, s4, v2
	v_lshl_or_b32 v8, v4, 11, v5
	v_lshl_or_b32 v3, v3, 11, v5
	s_add_u32 s0, s28, 0xc075800
	v_add_u32_e32 v9, 0x10000, v8
	s_addc_u32 s1, s29, 0
	v_add_u32_e32 v22, 0x20000, v8
	global_load_dwordx4 v[4:7], v9, s[36:37]
	global_load_dwordx4 v[10:13], v22, s[36:37]
	global_load_dwordx4 v[14:17], v8, s[36:37]
	global_load_dwordx4 v[18:21], v3, s[0:1]
	v_add_u32_e32 v9, 0x20000, v3
	v_add_u32_e32 v30, 0x30000, v3
	global_load_dwordx4 v[22:25], v9, s[0:1]
	global_load_dwordx4 v[26:29], v30, s[0:1]
	v_add_u32_e32 v9, 0x30000, v8
	v_add_u32_e32 v38, 0x10000, v3
	global_load_dwordx4 v[30:33], v9, s[36:37]
	global_load_dwordx4 v[34:37], v38, s[0:1]
	v_xor_b32_e32 v9, v2, v69
	s_movk_i32 s6, 0x70
	v_lshlrev_b32_e32 v2, 7, v2
	v_lshlrev_b32_e32 v9, 4, v9
	v_and_or_b32 v2, v9, s6, v2
	v_add_u32_e32 v2, 0, v2
	v_or_b32_e32 v45, 0x80, v8
	v_or_b32_e32 v9, 0x80, v3
	v_add_u32_e32 v42, 0x10080, v3
	v_add_u32_e32 v43, 0x20080, v3
	v_add_u32_e32 v44, 0x30080, v3
	v_add_u32_e32 v46, 0x10080, v8
	v_add_u32_e32 v47, 0x20080, v8
	v_add_u32_e32 v48, 0x30080, v8
	v_ashrrev_i32_e32 v79, 7, v69
	v_bfe_u32 v80, v69, 6, 1
	v_bfe_u32 v81, v69, 4, 2
	s_waitcnt vmcnt(5)
	ds_write_b128 v2, v[14:17]
	s_waitcnt vmcnt(4)
	ds_write_b128 v2, v[18:21] offset:16384
	s_waitcnt vmcnt(3)
	ds_write_b128 v2, v[22:25] offset:24576
	s_waitcnt vmcnt(2)
	ds_write_b128 v2, v[26:29] offset:28672
	ds_write_b128 v2, v[4:7] offset:4096
	ds_write_b128 v2, v[10:13] offset:8192
	s_waitcnt vmcnt(1)
	ds_write_b128 v2, v[30:33] offset:12288
	s_waitcnt vmcnt(0)
	ds_write_b128 v2, v[34:37] offset:20480
	s_waitcnt lgkmcnt(0)
	s_barrier
	global_load_dwordx4 v[10:13], v45, s[36:37]
	global_load_dwordx4 v[14:17], v46, s[36:37]
	global_load_dwordx4 v[18:21], v47, s[36:37]
	global_load_dwordx4 v[22:25], v48, s[36:37]
	global_load_dwordx4 v[26:29], v9, s[0:1]
	global_load_dwordx4 v[30:33], v42, s[0:1]
	global_load_dwordx4 v[34:37], v43, s[0:1]
	global_load_dwordx4 v[38:41], v44, s[0:1]
	v_lshrrev_b32_e32 v4, 4, v69
	v_lshlrev_b32_e32 v5, 7, v78
	v_and_b32_e32 v9, 7, v69
	v_lshl_or_b32 v6, v79, 13, v5
	v_bitop3_b32 v4, v4, v9, 3 bitop3:0x6c
	v_lshl_or_b32 v5, v80, 13, v5
	v_lshlrev_b32_e32 v4, 4, v4
	v_add_u32_e32 v66, 0, v6
	v_add_u32_e32 v6, v66, v4
	v_add_u32_e32 v5, 0, v5
	v_add_u32_e32 v7, v5, v4
	ds_read_b128 v[42:45], v6
	ds_read_b128 v[46:49], v6 offset:2048
	ds_read_b128 v[50:53], v7 offset:16384
	ds_read_b128 v[54:57], v7 offset:18432
	ds_read_b128 v[58:61], v6 offset:4096
	ds_read_b128 v[62:65], v6 offset:6144
	ds_read_b128 v[82:85], v7 offset:20480
	ds_read_b128 v[86:89], v7 offset:22528
	v_bitop3_b32 v4, v81, v9, 4 bitop3:0x36
	v_lshlrev_b32_e32 v9, 4, v4
	s_setprio 2
	global_load_dwordx4 v[90:93], v8, s[36:37] offset:256
	s_waitcnt vmcnt(8)
	ds_write_b128 v2, v[10:13] offset:32768
	v_add_u32_e32 v4, v66, v9
	v_add_u32_e32 v5, v5, v9
	ds_read_b128 v[10:13], v4
	ds_read_b128 v[94:97], v5 offset:16384
	s_waitcnt lgkmcnt(8)
	v_mfma_f32_16x16x32_bf16 v[98:101], v[50:53], v[42:45], 0
	s_waitcnt lgkmcnt(7)
	v_mfma_f32_16x16x32_bf16 v[102:105], v[54:57], v[42:45], 0
	s_waitcnt lgkmcnt(4)
	v_mfma_f32_16x16x32_bf16 v[106:109], v[82:85], v[42:45], 0
	s_waitcnt lgkmcnt(3)
	v_mfma_f32_16x16x32_bf16 v[42:45], v[86:89], v[42:45], 0
	v_add_u32_e32 v228, 0x10000, v8
	global_load_dwordx4 v[110:113], v228, s[36:37] offset:256
	s_waitcnt vmcnt(8)
	ds_write_b128 v2, v[14:17] offset:36864
	ds_read_b128 v[14:17], v4 offset:2048
	ds_read_b128 v[114:117], v5 offset:18432
	v_mfma_f32_16x16x32_bf16 v[118:121], v[50:53], v[46:49], 0
	v_mfma_f32_16x16x32_bf16 v[122:125], v[54:57], v[46:49], 0
	v_mfma_f32_16x16x32_bf16 v[126:129], v[82:85], v[46:49], 0
	v_mfma_f32_16x16x32_bf16 v[46:49], v[86:89], v[46:49], 0
	v_add_u32_e32 v229, 0x20000, v8
	global_load_dwordx4 v[132:135], v229, s[36:37] offset:256
	s_waitcnt vmcnt(8)
	ds_write_b128 v2, v[18:21] offset:40960
	ds_read_b128 v[18:21], v4 offset:4096
	ds_read_b128 v[146:149], v5 offset:20480
	v_mfma_f32_16x16x32_bf16 v[150:153], v[50:53], v[58:61], 0
	v_mfma_f32_16x16x32_bf16 v[154:157], v[54:57], v[58:61], 0
	v_mfma_f32_16x16x32_bf16 v[158:161], v[82:85], v[58:61], 0
	v_mfma_f32_16x16x32_bf16 v[58:61], v[86:89], v[58:61], 0
	v_add_u32_e32 v230, 0x30000, v8
	global_load_dwordx4 v[162:165], v230, s[36:37] offset:256
	s_waitcnt vmcnt(8)
; template <int MODE>
; __device__ __forceinline__ void gemm_tile(const Params& P, int tm, int tn, unsigned char* smem) {
;     ...
; #pragma unroll
;         for (int i = 0; i < 4; ++i) { fa[i] = *(const bf16x8*)(sA + arow_off + i * 2048 + ch0); fb[i] = *(const bf16x8*)(sB + brow_off + i * 2048 + ch0); }
;         __builtin_amdgcn_sched_barrier(0);
;         __builtin_amdgcn_s_setprio(2);
;         if (wr_ok) *(uint4*)(nA + soff0) = ra0;
;         if (ld_ok) ra0 = *(const uint4*)(Ab + (aoff + 0u * LDA + koa));
;         ga[0] = *(const bf16x8*)(sA + arow_off + 0 * 2048 + ch1); gb[0] = *(const bf16x8*)(sB + brow_off + 0 * 2048 + ch1);
;         __builtin_amdgcn_sched_barrier(0);
; #pragma unroll
;         for (int j = 0; j < 4; ++j) acc[0][j] = __builtin_amdgcn_mfma_f32_16x16x32_bf16(fb[j], fa[0], acc[0][j], 0, 0, 0);
;         __builtin_amdgcn_sched_barrier(0);
;         if (wr_ok) *(uint4*)(nA + soff0 + 4096) = ra1;
;         if (ld_ok) ra1 = *(const uint4*)(Ab + (aoff + 32u * LDA + koa));
;         ga[1] = *(const bf16x8*)(sA + arow_off + 1 * 2048 + ch1); gb[1] = *(const bf16x8*)(sB + brow_off + 1 * 2048 + ch1);
;         __builtin_amdgcn_sched_barrier(0);
; #pragma unroll
;         for (int j = 0; j < 4; ++j) acc[1][j] = __builtin_amdgcn_mfma_f32_16x16x32_bf16(fb[j], fa[1], acc[1][j], 0, 0, 0);
;         __builtin_amdgcn_sched_barrier(0);
;         if (wr_ok) *(uint4*)(nA + soff0 + 8192) = ra2;
;         if (ld_ok) ra2 = *(const uint4*)(Ab + (aoff + 64u * LDA + koa));
;         ga[2] = *(const bf16x8*)(sA + arow_off + 2 * 2048 + ch1); gb[2] = *(const bf16x8*)(sB + brow_off + 2 * 2048 + ch1);
;         __builtin_amdgcn_sched_barrier(0);
; #pragma unroll
;         for (int j = 0; j < 4; ++j) acc[2][j] = __builtin_amdgcn_mfma_f32_16x16x32_bf16(fb[j], fa[2], acc[2][j], 0, 0, 0);
;         __builtin_amdgcn_sched_barrier(0);
;         if (wr_ok) *(uint4*)(nA + soff0 + 12288) = ra3;
;         if (ld_ok) ra3 = *(const uint4*)(Ab + (aoff + 96u * LDA + koa));
;         ga[3] = *(const bf16x8*)(sA + arow_off + 3 * 2048 + ch1); gb[3] = *(const bf16x8*)(sB + brow_off + 3 * 2048 + ch1);
;         __builtin_amdgcn_sched_barrier(0);
; #pragma unroll
;         for (int j = 0; j < 4; ++j) acc[3][j] = __builtin_amdgcn_mfma_f32_16x16x32_bf16(fb[j], fa[3], acc[3][j], 0, 0, 0);
;         __builtin_amdgcn_sched_barrier(0);
;         if (wr_ok) *(uint4*)(nB + soff0) = rb0;
	ds_write_b128 v2, v[22:25] offset:45056
	ds_read_b128 v[22:25], v4 offset:6144
	ds_read_b128 v[166:169], v5 offset:22528
	v_mfma_f32_16x16x32_bf16 v[50:53], v[50:53], v[62:65], 0
	v_mfma_f32_16x16x32_bf16 v[54:57], v[54:57], v[62:65], 0
	v_mfma_f32_16x16x32_bf16 v[82:85], v[82:85], v[62:65], 0
	v_mfma_f32_16x16x32_bf16 v[62:65], v[86:89], v[62:65], 0
	global_load_dwordx4 v[86:89], v3, s[0:1] offset:256
	s_waitcnt vmcnt(8)
	ds_write_b128 v2, v[26:29] offset:49152
	s_waitcnt lgkmcnt(10)
	v_mfma_f32_16x16x32_bf16 v[26:29], v[94:97], v[10:13], v[98:101]
	s_waitcnt lgkmcnt(7)
	v_mfma_f32_16x16x32_bf16 v[98:101], v[114:117], v[10:13], v[102:105]
	s_waitcnt lgkmcnt(4)
	v_mfma_f32_16x16x32_bf16 v[102:105], v[146:149], v[10:13], v[106:109]
	s_waitcnt lgkmcnt(1)
	v_mfma_f32_16x16x32_bf16 v[10:13], v[166:169], v[10:13], v[42:45]
	v_add_u32_e32 v231, 0x10000, v3
	global_load_dwordx4 v[42:45], v231, s[0:1] offset:256
	s_waitcnt vmcnt(8)
	ds_write_b128 v2, v[30:33] offset:53248
	v_mfma_f32_16x16x32_bf16 v[30:33], v[94:97], v[14:17], v[118:121]
	v_mfma_f32_16x16x32_bf16 v[106:109], v[114:117], v[14:17], v[122:125]
	v_mfma_f32_16x16x32_bf16 v[118:121], v[146:149], v[14:17], v[126:129]
	v_mfma_f32_16x16x32_bf16 v[14:17], v[166:169], v[14:17], v[46:49]
	v_add_u32_e32 v232, 0x20000, v3
	global_load_dwordx4 v[46:49], v232, s[0:1] offset:256
	s_waitcnt vmcnt(8)
	ds_write_b128 v2, v[34:37] offset:57344
	v_mfma_f32_16x16x32_bf16 v[34:37], v[94:97], v[18:21], v[150:153]
	v_mfma_f32_16x16x32_bf16 v[122:125], v[114:117], v[18:21], v[154:157]
	v_mfma_f32_16x16x32_bf16 v[126:129], v[146:149], v[18:21], v[158:161]
	v_mfma_f32_16x16x32_bf16 v[18:21], v[166:169], v[18:21], v[58:61]
	v_add_u32_e32 v233, 0x30000, v3
	global_load_dwordx4 v[58:61], v233, s[0:1] offset:256
	s_waitcnt vmcnt(8)
	ds_write_b128 v2, v[38:41] offset:61440
	v_mfma_f32_16x16x32_bf16 v[38:41], v[94:97], v[22:25], v[50:53]
	v_mfma_f32_16x16x32_bf16 v[50:53], v[114:117], v[22:25], v[54:57]
	v_mfma_f32_16x16x32_bf16 v[54:57], v[146:149], v[22:25], v[82:85]
	v_mfma_f32_16x16x32_bf16 v[22:25], v[166:169], v[22:25], v[62:65]
	s_setprio 0
	s_waitcnt lgkmcnt(0)
	s_barrier
	ds_read_b128 v[62:65], v6 offset:32768
	ds_read_b128 v[82:85], v6 offset:34816
	ds_read_b128 v[94:97], v7 offset:49152
	ds_read_b128 v[114:117], v7 offset:51200
	ds_read_b128 v[146:149], v6 offset:36864
	ds_read_b128 v[150:153], v6 offset:38912
	ds_read_b128 v[154:157], v7 offset:53248
	ds_read_b128 v[158:161], v7 offset:55296
	s_setprio 2
	s_waitcnt lgkmcnt(5)
	v_mfma_f32_16x16x32_bf16 v[26:29], v[94:97], v[62:65], v[26:29]
	global_load_dwordx4 v[166:169], v8, s[36:37] offset:384
	s_waitcnt lgkmcnt(0)
	v_mfma_f32_16x16x32_bf16 v[10:13], v[158:161], v[62:65], v[10:13]
	s_waitcnt vmcnt(8)
	ds_write_b128 v2, v[90:93]
	v_mfma_f32_16x16x32_bf16 v[98:101], v[114:117], v[62:65], v[98:101]
	ds_read_b128 v[90:93], v4 offset:32768
	v_mfma_f32_16x16x32_bf16 v[102:105], v[154:157], v[62:65], v[102:105]
	ds_read_b128 v[170:173], v5 offset:49152
	global_load_dwordx4 v[62:65], v228, s[36:37] offset:384
	v_mfma_f32_16x16x32_bf16 v[30:33], v[94:97], v[82:85], v[30:33]
	s_waitcnt vmcnt(8)
	ds_write_b128 v2, v[110:113] offset:4096
	v_mfma_f32_16x16x32_bf16 v[14:17], v[158:161], v[82:85], v[14:17]
	ds_read_b128 v[110:113], v4 offset:34816
	v_mfma_f32_16x16x32_bf16 v[106:109], v[114:117], v[82:85], v[106:109]
	ds_read_b128 v[174:177], v5 offset:51200
	v_mfma_f32_16x16x32_bf16 v[118:121], v[154:157], v[82:85], v[118:121]
	global_load_dwordx4 v[82:85], v229, s[36:37] offset:384
	v_mfma_f32_16x16x32_bf16 v[34:37], v[94:97], v[146:149], v[34:37]
	s_waitcnt vmcnt(8)
	ds_write_b128 v2, v[132:135] offset:8192
	v_mfma_f32_16x16x32_bf16 v[18:21], v[158:161], v[146:149], v[18:21]
	ds_read_b128 v[132:135], v4 offset:36864
	v_mfma_f32_16x16x32_bf16 v[122:125], v[114:117], v[146:149], v[122:125]
	ds_read_b128 v[178:181], v5 offset:53248
	v_mfma_f32_16x16x32_bf16 v[126:129], v[154:157], v[146:149], v[126:129]
	global_load_dwordx4 v[146:149], v230, s[36:37] offset:384
	v_mfma_f32_16x16x32_bf16 v[38:41], v[94:97], v[150:153], v[38:41]
	s_waitcnt vmcnt(8)
	ds_write_b128 v2, v[162:165] offset:12288
	v_mfma_f32_16x16x32_bf16 v[50:53], v[114:117], v[150:153], v[50:53]
	ds_read_b128 v[162:165], v4 offset:38912
	v_mfma_f32_16x16x32_bf16 v[54:57], v[154:157], v[150:153], v[54:57]
	ds_read_b128 v[182:185], v5 offset:55296
	v_mfma_f32_16x16x32_bf16 v[22:25], v[158:161], v[150:153], v[22:25]
	global_load_dwordx4 v[94:97], v3, s[0:1] offset:384
	s_waitcnt vmcnt(8)
	ds_write_b128 v2, v[86:89] offset:16384
	s_waitcnt lgkmcnt(10)
	v_mfma_f32_16x16x32_bf16 v[26:29], v[170:173], v[90:93], v[26:29]
	s_waitcnt lgkmcnt(1)
	v_mfma_f32_16x16x32_bf16 v[10:13], v[182:185], v[90:93], v[10:13]
	v_mfma_f32_16x16x32_bf16 v[86:89], v[174:177], v[90:93], v[98:101]
	v_mfma_f32_16x16x32_bf16 v[98:101], v[178:181], v[90:93], v[102:105]
	global_load_dwordx4 v[90:93], v231, s[0:1] offset:384
	s_waitcnt vmcnt(8)
	ds_write_b128 v2, v[42:45] offset:20480
	v_mfma_f32_16x16x32_bf16 v[30:33], v[170:173], v[110:113], v[30:33]
	v_mfma_f32_16x16x32_bf16 v[42:45], v[174:177], v[110:113], v[106:109]
	v_mfma_f32_16x16x32_bf16 v[14:17], v[182:185], v[110:113], v[14:17]
	v_mfma_f32_16x16x32_bf16 v[102:105], v[178:181], v[110:113], v[118:121]
	global_load_dwordx4 v[106:109], v232, s[0:1] offset:384
	s_waitcnt vmcnt(8)
	ds_write_b128 v2, v[46:49] offset:24576
	v_mfma_f32_16x16x32_bf16 v[34:37], v[170:173], v[132:135], v[34:37]
	v_mfma_f32_16x16x32_bf16 v[46:49], v[174:177], v[132:135], v[122:125]
	v_mfma_f32_16x16x32_bf16 v[18:21], v[182:185], v[132:135], v[18:21]
	v_mfma_f32_16x16x32_bf16 v[110:113], v[178:181], v[132:135], v[126:129]
	global_load_dwordx4 v[114:117], v233, s[0:1] offset:384
	v_mfma_f32_16x16x32_bf16 v[38:41], v[170:173], v[162:165], v[38:41]
	s_waitcnt vmcnt(8)
	ds_write_b128 v2, v[58:61] offset:28672
	v_mfma_f32_16x16x32_bf16 v[50:53], v[174:177], v[162:165], v[50:53]
	v_mfma_f32_16x16x32_bf16 v[54:57], v[178:181], v[162:165], v[54:57]
	v_mfma_f32_16x16x32_bf16 v[22:25], v[182:185], v[162:165], v[22:25]
	s_setprio 0
	s_waitcnt lgkmcnt(0)
	s_barrier
; template <int MODE>
; __device__ __forceinline__ void gemm_tile(const Params& P, int tm, int tn, unsigned char* smem) {
;     ...
; #pragma unroll
;         for (int i = 0; i < 4; ++i) { fa[i] = *(const bf16x8*)(sA + arow_off + i * 2048 + ch0); fb[i] = *(const bf16x8*)(sB + brow_off + i * 2048 + ch0); }
;         __builtin_amdgcn_sched_barrier(0);
;         __builtin_amdgcn_s_setprio(2);
;         if (wr_ok) *(uint4*)(nA + soff0) = ra0;
;         if (ld_ok) ra0 = *(const uint4*)(Ab + (aoff + 0u * LDA + koa));
;         ga[0] = *(const bf16x8*)(sA + arow_off + 0 * 2048 + ch1); gb[0] = *(const bf16x8*)(sB + brow_off + 0 * 2048 + ch1);
;         __builtin_amdgcn_sched_barrier(0);
; #pragma unroll
;         for (int j = 0; j < 4; ++j) acc[0][j] = __builtin_amdgcn_mfma_f32_16x16x32_bf16(fb[j], fa[0], acc[0][j], 0, 0, 0);
;         __builtin_amdgcn_sched_barrier(0);
;         if (wr_ok) *(uint4*)(nA + soff0 + 4096) = ra1;
;         if (ld_ok) ra1 = *(const uint4*)(Ab + (aoff + 32u * LDA + koa));
;         ga[1] = *(const bf16x8*)(sA + arow_off + 1 * 2048 + ch1); gb[1] = *(const bf16x8*)(sB + brow_off + 1 * 2048 + ch1);
;         __builtin_amdgcn_sched_barrier(0);
; #pragma unroll
;         for (int j = 0; j < 4; ++j) acc[1][j] = __builtin_amdgcn_mfma_f32_16x16x32_bf16(fb[j], fa[1], acc[1][j], 0, 0, 0);
;         __builtin_amdgcn_sched_barrier(0);
;         if (wr_ok) *(uint4*)(nA + soff0 + 8192) = ra2;
;         if (ld_ok) ra2 = *(const uint4*)(Ab + (aoff + 64u * LDA + koa));
;         ga[2] = *(const bf16x8*)(sA + arow_off + 2 * 2048 + ch1); gb[2] = *(const bf16x8*)(sB + brow_off + 2 * 2048 + ch1);
;         __builtin_amdgcn_sched_barrier(0);
; #pragma unroll
;         for (int j = 0; j < 4; ++j) acc[2][j] = __builtin_amdgcn_mfma_f32_16x16x32_bf16(fb[j], fa[2], acc[2][j], 0, 0, 0);
;         __builtin_amdgcn_sched_barrier(0);
;         if (wr_ok) *(uint4*)(nA + soff0 + 12288) = ra3;
;         if (ld_ok) ra3 = *(const uint4*)(Ab + (aoff + 96u * LDA + koa));
;         ga[3] = *(const bf16x8*)(sA + arow_off + 3 * 2048 + ch1); gb[3] = *(const bf16x8*)(sB + brow_off + 3 * 2048 + ch1);
;         __builtin_amdgcn_sched_barrier(0);
; #pragma unroll
;         for (int j = 0; j < 4; ++j) acc[3][j] = __builtin_amdgcn_mfma_f32_16x16x32_bf16(fb[j], fa[3], acc[3][j], 0, 0, 0);
;         __builtin_amdgcn_sched_barrier(0);
;         if (wr_ok) *(uint4*)(nB + soff0) = rb0;
	ds_read_b128 v[58:61], v6
	ds_read_b128 v[118:121], v6 offset:2048
	ds_read_b128 v[122:125], v7 offset:16384
	ds_read_b128 v[126:129], v7 offset:18432
	ds_read_b128 v[132:135], v6 offset:4096
	ds_read_b128 v[150:153], v6 offset:6144
	ds_read_b128 v[154:157], v7 offset:20480
	ds_read_b128 v[158:161], v7 offset:22528
	s_setprio 2
	s_waitcnt lgkmcnt(5)
	v_mfma_f32_16x16x32_bf16 v[26:29], v[122:125], v[58:61], v[26:29]
	global_load_dwordx4 v[162:165], v8, s[36:37] offset:512
	s_waitcnt lgkmcnt(0)
	v_mfma_f32_16x16x32_bf16 v[10:13], v[158:161], v[58:61], v[10:13]
	s_waitcnt vmcnt(8)
	ds_write_b128 v2, v[166:169] offset:32768
	v_mfma_f32_16x16x32_bf16 v[86:89], v[126:129], v[58:61], v[86:89]
	ds_read_b128 v[166:169], v4
	v_mfma_f32_16x16x32_bf16 v[98:101], v[154:157], v[58:61], v[98:101]
	ds_read_b128 v[170:173], v5 offset:16384
	global_load_dwordx4 v[58:61], v228, s[36:37] offset:512
	v_mfma_f32_16x16x32_bf16 v[30:33], v[122:125], v[118:121], v[30:33]
	s_waitcnt vmcnt(8)
	ds_write_b128 v2, v[62:65] offset:36864
	v_mfma_f32_16x16x32_bf16 v[42:45], v[126:129], v[118:121], v[42:45]
	ds_read_b128 v[62:65], v4 offset:2048
	v_mfma_f32_16x16x32_bf16 v[14:17], v[158:161], v[118:121], v[14:17]
	ds_read_b128 v[174:177], v5 offset:18432
	v_mfma_f32_16x16x32_bf16 v[102:105], v[154:157], v[118:121], v[102:105]
	global_load_dwordx4 v[118:121], v229, s[36:37] offset:512
	v_mfma_f32_16x16x32_bf16 v[34:37], v[122:125], v[132:135], v[34:37]
	s_waitcnt vmcnt(8)
	ds_write_b128 v2, v[82:85] offset:40960
	v_mfma_f32_16x16x32_bf16 v[46:49], v[126:129], v[132:135], v[46:49]
	ds_read_b128 v[82:85], v4 offset:4096
	v_mfma_f32_16x16x32_bf16 v[18:21], v[158:161], v[132:135], v[18:21]
	ds_read_b128 v[178:181], v5 offset:20480
	v_mfma_f32_16x16x32_bf16 v[110:113], v[154:157], v[132:135], v[110:113]
	global_load_dwordx4 v[132:135], v230, s[36:37] offset:512
	v_mfma_f32_16x16x32_bf16 v[38:41], v[122:125], v[150:153], v[38:41]
	s_waitcnt vmcnt(8)
	ds_write_b128 v2, v[146:149] offset:45056
	v_mfma_f32_16x16x32_bf16 v[50:53], v[126:129], v[150:153], v[50:53]
	ds_read_b128 v[146:149], v4 offset:6144
	v_mfma_f32_16x16x32_bf16 v[54:57], v[154:157], v[150:153], v[54:57]
	ds_read_b128 v[182:185], v5 offset:22528
	v_mfma_f32_16x16x32_bf16 v[22:25], v[158:161], v[150:153], v[22:25]
	global_load_dwordx4 v[122:125], v3, s[0:1] offset:512
	s_waitcnt vmcnt(8)
	ds_write_b128 v2, v[94:97] offset:49152
	s_waitcnt lgkmcnt(10)
	v_mfma_f32_16x16x32_bf16 v[26:29], v[170:173], v[166:169], v[26:29]
	s_waitcnt lgkmcnt(1)
	v_mfma_f32_16x16x32_bf16 v[10:13], v[182:185], v[166:169], v[10:13]
	v_mfma_f32_16x16x32_bf16 v[86:89], v[174:177], v[166:169], v[86:89]
	v_mfma_f32_16x16x32_bf16 v[94:97], v[178:181], v[166:169], v[98:101]
	global_load_dwordx4 v[98:101], v231, s[0:1] offset:512
	s_waitcnt vmcnt(8)
	ds_write_b128 v2, v[90:93] offset:53248
	v_mfma_f32_16x16x32_bf16 v[30:33], v[170:173], v[62:65], v[30:33]
	v_mfma_f32_16x16x32_bf16 v[42:45], v[174:177], v[62:65], v[42:45]
	v_mfma_f32_16x16x32_bf16 v[14:17], v[182:185], v[62:65], v[14:17]
	v_mfma_f32_16x16x32_bf16 v[90:93], v[178:181], v[62:65], v[102:105]
	global_load_dwordx4 v[62:65], v232, s[0:1] offset:512
	v_mfma_f32_16x16x32_bf16 v[34:37], v[170:173], v[82:85], v[34:37]
	s_waitcnt vmcnt(8)
	ds_write_b128 v2, v[106:109] offset:57344
	v_mfma_f32_16x16x32_bf16 v[46:49], v[174:177], v[82:85], v[46:49]
	v_mfma_f32_16x16x32_bf16 v[18:21], v[182:185], v[82:85], v[18:21]
	v_mfma_f32_16x16x32_bf16 v[102:105], v[178:181], v[82:85], v[110:113]
	global_load_dwordx4 v[82:85], v233, s[0:1] offset:512
	v_mfma_f32_16x16x32_bf16 v[38:41], v[170:173], v[146:149], v[38:41]
	s_waitcnt vmcnt(8)
	ds_write_b128 v2, v[114:117] offset:61440
	v_mfma_f32_16x16x32_bf16 v[50:53], v[174:177], v[146:149], v[50:53]
	v_mfma_f32_16x16x32_bf16 v[54:57], v[178:181], v[146:149], v[54:57]
	v_mfma_f32_16x16x32_bf16 v[22:25], v[182:185], v[146:149], v[22:25]
	s_setprio 0
	s_waitcnt lgkmcnt(0)
	s_barrier
	ds_read_b128 v[106:109], v6 offset:32768
	ds_read_b128 v[110:113], v6 offset:34816
	ds_read_b128 v[114:117], v7 offset:49152
	ds_read_b128 v[126:129], v7 offset:51200
	ds_read_b128 v[146:149], v6 offset:36864
	ds_read_b128 v[150:153], v6 offset:38912
	ds_read_b128 v[154:157], v7 offset:53248
	ds_read_b128 v[158:161], v7 offset:55296
	s_setprio 2
	s_waitcnt lgkmcnt(5)
	v_mfma_f32_16x16x32_bf16 v[26:29], v[114:117], v[106:109], v[26:29]
	global_load_dwordx4 v[166:169], v8, s[36:37] offset:640
	s_waitcnt lgkmcnt(0)
	v_mfma_f32_16x16x32_bf16 v[10:13], v[158:161], v[106:109], v[10:13]
	s_waitcnt vmcnt(8)
	ds_write_b128 v2, v[162:165]
	v_mfma_f32_16x16x32_bf16 v[86:89], v[126:129], v[106:109], v[86:89]
	ds_read_b128 v[162:165], v4 offset:32768
	v_mfma_f32_16x16x32_bf16 v[94:97], v[154:157], v[106:109], v[94:97]
	ds_read_b128 v[170:173], v5 offset:49152
	global_load_dwordx4 v[106:109], v228, s[36:37] offset:640
	v_mfma_f32_16x16x32_bf16 v[30:33], v[114:117], v[110:113], v[30:33]
	s_waitcnt vmcnt(8)
	ds_write_b128 v2, v[58:61] offset:4096
	v_mfma_f32_16x16x32_bf16 v[42:45], v[126:129], v[110:113], v[42:45]
	ds_read_b128 v[58:61], v4 offset:34816
	v_mfma_f32_16x16x32_bf16 v[14:17], v[158:161], v[110:113], v[14:17]
	ds_read_b128 v[174:177], v5 offset:51200
	v_mfma_f32_16x16x32_bf16 v[90:93], v[154:157], v[110:113], v[90:93]
	global_load_dwordx4 v[110:113], v229, s[36:37] offset:640
	v_mfma_f32_16x16x32_bf16 v[34:37], v[114:117], v[146:149], v[34:37]
	s_waitcnt vmcnt(8)
; template <int MODE>
; __device__ __forceinline__ void gemm_tile(const Params& P, int tm, int tn, unsigned char* smem) {
;     ...
; #pragma unroll
;         for (int i = 0; i < 4; ++i) { fa[i] = *(const bf16x8*)(sA + arow_off + i * 2048 + ch0); fb[i] = *(const bf16x8*)(sB + brow_off + i * 2048 + ch0); }
;         __builtin_amdgcn_sched_barrier(0);
;         __builtin_amdgcn_s_setprio(2);
;         if (wr_ok) *(uint4*)(nA + soff0) = ra0;
;         if (ld_ok) ra0 = *(const uint4*)(Ab + (aoff + 0u * LDA + koa));
;         ga[0] = *(const bf16x8*)(sA + arow_off + 0 * 2048 + ch1); gb[0] = *(const bf16x8*)(sB + brow_off + 0 * 2048 + ch1);
;         __builtin_amdgcn_sched_barrier(0);
; #pragma unroll
;         for (int j = 0; j < 4; ++j) acc[0][j] = __builtin_amdgcn_mfma_f32_16x16x32_bf16(fb[j], fa[0], acc[0][j], 0, 0, 0);
;         __builtin_amdgcn_sched_barrier(0);
;         if (wr_ok) *(uint4*)(nA + soff0 + 4096) = ra1;
;         if (ld_ok) ra1 = *(const uint4*)(Ab + (aoff + 32u * LDA + koa));
;         ga[1] = *(const bf16x8*)(sA + arow_off + 1 * 2048 + ch1); gb[1] = *(const bf16x8*)(sB + brow_off + 1 * 2048 + ch1);
;         __builtin_amdgcn_sched_barrier(0);
; #pragma unroll
;         for (int j = 0; j < 4; ++j) acc[1][j] = __builtin_amdgcn_mfma_f32_16x16x32_bf16(fb[j], fa[1], acc[1][j], 0, 0, 0);
;         __builtin_amdgcn_sched_barrier(0);
;         if (wr_ok) *(uint4*)(nA + soff0 + 8192) = ra2;
;         if (ld_ok) ra2 = *(const uint4*)(Ab + (aoff + 64u * LDA + koa));
;         ga[2] = *(const bf16x8*)(sA + arow_off + 2 * 2048 + ch1); gb[2] = *(const bf16x8*)(sB + brow_off + 2 * 2048 + ch1);
;         __builtin_amdgcn_sched_barrier(0);
; #pragma unroll
;         for (int j = 0; j < 4; ++j) acc[2][j] = __builtin_amdgcn_mfma_f32_16x16x32_bf16(fb[j], fa[2], acc[2][j], 0, 0, 0);
;         __builtin_amdgcn_sched_barrier(0);
;         if (wr_ok) *(uint4*)(nA + soff0 + 12288) = ra3;
;         if (ld_ok) ra3 = *(const uint4*)(Ab + (aoff + 96u * LDA + koa));
;         ga[3] = *(const bf16x8*)(sA + arow_off + 3 * 2048 + ch1); gb[3] = *(const bf16x8*)(sB + brow_off + 3 * 2048 + ch1);
;         __builtin_amdgcn_sched_barrier(0);
; #pragma unroll
;         for (int j = 0; j < 4; ++j) acc[3][j] = __builtin_amdgcn_mfma_f32_16x16x32_bf16(fb[j], fa[3], acc[3][j], 0, 0, 0);
;         __builtin_amdgcn_sched_barrier(0);
;         if (wr_ok) *(uint4*)(nB + soff0) = rb0;
	ds_write_b128 v2, v[118:121] offset:8192
	v_mfma_f32_16x16x32_bf16 v[46:49], v[126:129], v[146:149], v[46:49]
	ds_read_b128 v[118:121], v4 offset:36864
	v_mfma_f32_16x16x32_bf16 v[18:21], v[158:161], v[146:149], v[18:21]
	ds_read_b128 v[178:181], v5 offset:53248
	v_mfma_f32_16x16x32_bf16 v[102:105], v[154:157], v[146:149], v[102:105]
	global_load_dwordx4 v[146:149], v230, s[36:37] offset:640
	v_mfma_f32_16x16x32_bf16 v[38:41], v[114:117], v[150:153], v[38:41]
	s_waitcnt vmcnt(8)
	ds_write_b128 v2, v[132:135] offset:12288
	v_mfma_f32_16x16x32_bf16 v[50:53], v[126:129], v[150:153], v[50:53]
	ds_read_b128 v[132:135], v4 offset:38912
	v_mfma_f32_16x16x32_bf16 v[54:57], v[154:157], v[150:153], v[54:57]
	ds_read_b128 v[182:185], v5 offset:55296
	v_mfma_f32_16x16x32_bf16 v[22:25], v[158:161], v[150:153], v[22:25]
	s_waitcnt lgkmcnt(9)
	v_mfma_f32_16x16x32_bf16 v[26:29], v[170:173], v[162:165], v[26:29]
	global_load_dwordx4 v[114:117], v3, s[0:1] offset:640
	s_waitcnt lgkmcnt(0)
	v_mfma_f32_16x16x32_bf16 v[10:13], v[182:185], v[162:165], v[10:13]
	s_waitcnt vmcnt(8)
	ds_write_b128 v2, v[122:125] offset:16384
	v_mfma_f32_16x16x32_bf16 v[86:89], v[174:177], v[162:165], v[86:89]
	v_mfma_f32_16x16x32_bf16 v[94:97], v[178:181], v[162:165], v[94:97]
	global_load_dwordx4 v[122:125], v231, s[0:1] offset:640
	v_mfma_f32_16x16x32_bf16 v[30:33], v[170:173], v[58:61], v[30:33]
	s_waitcnt vmcnt(8)
	ds_write_b128 v2, v[98:101] offset:20480
	v_mfma_f32_16x16x32_bf16 v[42:45], v[174:177], v[58:61], v[42:45]
	v_mfma_f32_16x16x32_bf16 v[14:17], v[182:185], v[58:61], v[14:17]
	v_mfma_f32_16x16x32_bf16 v[90:93], v[178:181], v[58:61], v[90:93]
	global_load_dwordx4 v[58:61], v232, s[0:1] offset:640
	s_waitcnt vmcnt(8)
	ds_write_b128 v2, v[62:65] offset:24576
	v_mfma_f32_16x16x32_bf16 v[34:37], v[170:173], v[118:121], v[34:37]
	v_mfma_f32_16x16x32_bf16 v[46:49], v[174:177], v[118:121], v[46:49]
	v_mfma_f32_16x16x32_bf16 v[62:65], v[178:181], v[118:121], v[102:105]
	v_mfma_f32_16x16x32_bf16 v[18:21], v[182:185], v[118:121], v[18:21]
	global_load_dwordx4 v[98:101], v233, s[0:1] offset:640
	v_mfma_f32_16x16x32_bf16 v[38:41], v[170:173], v[132:135], v[38:41]
	s_waitcnt vmcnt(8)
	ds_write_b128 v2, v[82:85] offset:28672
	v_mfma_f32_16x16x32_bf16 v[50:53], v[174:177], v[132:135], v[50:53]
	v_mfma_f32_16x16x32_bf16 v[54:57], v[178:181], v[132:135], v[54:57]
	v_mfma_f32_16x16x32_bf16 v[22:25], v[182:185], v[132:135], v[22:25]
	s_setprio 0
	s_waitcnt lgkmcnt(0)
	s_barrier
	ds_read_b128 v[82:85], v6
	ds_read_b128 v[102:105], v6 offset:2048
	ds_read_b128 v[118:121], v7 offset:16384
	ds_read_b128 v[126:129], v7 offset:18432
	ds_read_b128 v[132:135], v6 offset:4096
	ds_read_b128 v[150:153], v6 offset:6144
	ds_read_b128 v[154:157], v7 offset:20480
	ds_read_b128 v[158:161], v7 offset:22528
	s_setprio 2
	s_waitcnt lgkmcnt(5)
	v_mfma_f32_16x16x32_bf16 v[26:29], v[118:121], v[82:85], v[26:29]
	global_load_dwordx4 v[162:165], v8, s[36:37] offset:768
	s_waitcnt lgkmcnt(0)
	v_mfma_f32_16x16x32_bf16 v[10:13], v[158:161], v[82:85], v[10:13]
	s_waitcnt vmcnt(8)
	ds_write_b128 v2, v[166:169] offset:32768
	v_mfma_f32_16x16x32_bf16 v[86:89], v[126:129], v[82:85], v[86:89]
	ds_read_b128 v[166:169], v4
	v_mfma_f32_16x16x32_bf16 v[94:97], v[154:157], v[82:85], v[94:97]
	ds_read_b128 v[170:173], v5 offset:16384
	global_load_dwordx4 v[82:85], v228, s[36:37] offset:768
	v_mfma_f32_16x16x32_bf16 v[30:33], v[118:121], v[102:105], v[30:33]
	s_waitcnt vmcnt(8)
	ds_write_b128 v2, v[106:109] offset:36864
	v_mfma_f32_16x16x32_bf16 v[42:45], v[126:129], v[102:105], v[42:45]
	ds_read_b128 v[106:109], v4 offset:2048
	v_mfma_f32_16x16x32_bf16 v[14:17], v[158:161], v[102:105], v[14:17]
	ds_read_b128 v[174:177], v5 offset:18432
	v_mfma_f32_16x16x32_bf16 v[90:93], v[154:157], v[102:105], v[90:93]
	global_load_dwordx4 v[102:105], v229, s[36:37] offset:768
	v_mfma_f32_16x16x32_bf16 v[34:37], v[118:121], v[132:135], v[34:37]
	s_waitcnt vmcnt(8)
	ds_write_b128 v2, v[110:113] offset:40960
	v_mfma_f32_16x16x32_bf16 v[46:49], v[126:129], v[132:135], v[46:49]
	ds_read_b128 v[110:113], v4 offset:4096
	v_mfma_f32_16x16x32_bf16 v[62:65], v[154:157], v[132:135], v[62:65]
	ds_read_b128 v[178:181], v5 offset:20480
	v_mfma_f32_16x16x32_bf16 v[18:21], v[158:161], v[132:135], v[18:21]
	global_load_dwordx4 v[132:135], v230, s[36:37] offset:768
	v_mfma_f32_16x16x32_bf16 v[38:41], v[118:121], v[150:153], v[38:41]
	s_waitcnt vmcnt(8)
	ds_write_b128 v2, v[146:149] offset:45056
	v_mfma_f32_16x16x32_bf16 v[50:53], v[126:129], v[150:153], v[50:53]
	ds_read_b128 v[146:149], v4 offset:6144
	v_mfma_f32_16x16x32_bf16 v[54:57], v[154:157], v[150:153], v[54:57]
	ds_read_b128 v[182:185], v5 offset:22528
	v_mfma_f32_16x16x32_bf16 v[22:25], v[158:161], v[150:153], v[22:25]
	s_waitcnt lgkmcnt(9)
	v_mfma_f32_16x16x32_bf16 v[26:29], v[170:173], v[166:169], v[26:29]
	global_load_dwordx4 v[118:121], v3, s[0:1] offset:768
	s_waitcnt lgkmcnt(0)
	v_mfma_f32_16x16x32_bf16 v[10:13], v[182:185], v[166:169], v[10:13]
	s_waitcnt vmcnt(8)
	ds_write_b128 v2, v[114:117] offset:49152
	v_mfma_f32_16x16x32_bf16 v[86:89], v[174:177], v[166:169], v[86:89]
	v_mfma_f32_16x16x32_bf16 v[94:97], v[178:181], v[166:169], v[94:97]
	global_load_dwordx4 v[114:117], v231, s[0:1] offset:768
	v_mfma_f32_16x16x32_bf16 v[30:33], v[170:173], v[106:109], v[30:33]
	s_waitcnt vmcnt(8)
	ds_write_b128 v2, v[122:125] offset:53248
	v_mfma_f32_16x16x32_bf16 v[42:45], v[174:177], v[106:109], v[42:45]
	v_mfma_f32_16x16x32_bf16 v[14:17], v[182:185], v[106:109], v[14:17]
	v_mfma_f32_16x16x32_bf16 v[90:93], v[178:181], v[106:109], v[90:93]
	global_load_dwordx4 v[106:109], v232, s[0:1] offset:768
	s_waitcnt vmcnt(8)
	ds_write_b128 v2, v[58:61] offset:57344
	v_mfma_f32_16x16x32_bf16 v[34:37], v[170:173], v[110:113], v[34:37]
	v_mfma_f32_16x16x32_bf16 v[46:49], v[174:177], v[110:113], v[46:49]
	v_mfma_f32_16x16x32_bf16 v[58:61], v[178:181], v[110:113], v[62:65]
	v_mfma_f32_16x16x32_bf16 v[18:21], v[182:185], v[110:113], v[18:21]
	global_load_dwordx4 v[62:65], v233, s[0:1] offset:768
	v_mfma_f32_16x16x32_bf16 v[38:41], v[170:173], v[146:149], v[38:41]
	s_waitcnt vmcnt(8)
	ds_write_b128 v2, v[98:101] offset:61440
	v_mfma_f32_16x16x32_bf16 v[50:53], v[174:177], v[146:149], v[50:53]
	v_mfma_f32_16x16x32_bf16 v[54:57], v[178:181], v[146:149], v[54:57]
	v_mfma_f32_16x16x32_bf16 v[22:25], v[182:185], v[146:149], v[22:25]
	s_setprio 0
	s_waitcnt lgkmcnt(0)
	s_barrier
; template <int MODE>
; __device__ __forceinline__ void gemm_tile(const Params& P, int tm, int tn, unsigned char* smem) {
;     ...
; #pragma unroll
;         for (int i = 0; i < 4; ++i) { fa[i] = *(const bf16x8*)(sA + arow_off + i * 2048 + ch0); fb[i] = *(const bf16x8*)(sB + brow_off + i * 2048 + ch0); }
;         __builtin_amdgcn_sched_barrier(0);
;         __builtin_amdgcn_s_setprio(2);
;         if (wr_ok) *(uint4*)(nA + soff0) = ra0;
;         if (ld_ok) ra0 = *(const uint4*)(Ab + (aoff + 0u * LDA + koa));
;         ga[0] = *(const bf16x8*)(sA + arow_off + 0 * 2048 + ch1); gb[0] = *(const bf16x8*)(sB + brow_off + 0 * 2048 + ch1);
;         __builtin_amdgcn_sched_barrier(0);
; #pragma unroll
;         for (int j = 0; j < 4; ++j) acc[0][j] = __builtin_amdgcn_mfma_f32_16x16x32_bf16(fb[j], fa[0], acc[0][j], 0, 0, 0);
;         __builtin_amdgcn_sched_barrier(0);
;         if (wr_ok) *(uint4*)(nA + soff0 + 4096) = ra1;
;         if (ld_ok) ra1 = *(const uint4*)(Ab + (aoff + 32u * LDA + koa));
;         ga[1] = *(const bf16x8*)(sA + arow_off + 1 * 2048 + ch1); gb[1] = *(const bf16x8*)(sB + brow_off + 1 * 2048 + ch1);
;         __builtin_amdgcn_sched_barrier(0);
; #pragma unroll
;         for (int j = 0; j < 4; ++j) acc[1][j] = __builtin_amdgcn_mfma_f32_16x16x32_bf16(fb[j], fa[1], acc[1][j], 0, 0, 0);
;         __builtin_amdgcn_sched_barrier(0);
;         if (wr_ok) *(uint4*)(nA + soff0 + 8192) = ra2;
;         if (ld_ok) ra2 = *(const uint4*)(Ab + (aoff + 64u * LDA + koa));
;         ga[2] = *(const bf16x8*)(sA + arow_off + 2 * 2048 + ch1); gb[2] = *(const bf16x8*)(sB + brow_off + 2 * 2048 + ch1);
;         __builtin_amdgcn_sched_barrier(0);
; #pragma unroll
;         for (int j = 0; j < 4; ++j) acc[2][j] = __builtin_amdgcn_mfma_f32_16x16x32_bf16(fb[j], fa[2], acc[2][j], 0, 0, 0);
;         __builtin_amdgcn_sched_barrier(0);
;         if (wr_ok) *(uint4*)(nA + soff0 + 12288) = ra3;
;         if (ld_ok) ra3 = *(const uint4*)(Ab + (aoff + 96u * LDA + koa));
;         ga[3] = *(const bf16x8*)(sA + arow_off + 3 * 2048 + ch1); gb[3] = *(const bf16x8*)(sB + brow_off + 3 * 2048 + ch1);
;         __builtin_amdgcn_sched_barrier(0);
; #pragma unroll
;         for (int j = 0; j < 4; ++j) acc[3][j] = __builtin_amdgcn_mfma_f32_16x16x32_bf16(fb[j], fa[3], acc[3][j], 0, 0, 0);
;         __builtin_amdgcn_sched_barrier(0);
;         if (wr_ok) *(uint4*)(nB + soff0) = rb0;
	ds_read_b128 v[98:101], v6 offset:32768
	ds_read_b128 v[110:113], v6 offset:34816
	ds_read_b128 v[122:125], v7 offset:49152
	ds_read_b128 v[126:129], v7 offset:51200
	ds_read_b128 v[146:149], v6 offset:36864
	ds_read_b128 v[150:153], v6 offset:38912
	ds_read_b128 v[154:157], v7 offset:53248
	ds_read_b128 v[158:161], v7 offset:55296
	s_setprio 2
	s_waitcnt lgkmcnt(5)
	v_mfma_f32_16x16x32_bf16 v[26:29], v[122:125], v[98:101], v[26:29]
	global_load_dwordx4 v[166:169], v8, s[36:37] offset:896
	s_waitcnt lgkmcnt(0)
	v_mfma_f32_16x16x32_bf16 v[10:13], v[158:161], v[98:101], v[10:13]
	s_waitcnt vmcnt(8)
	ds_write_b128 v2, v[162:165]
	v_mfma_f32_16x16x32_bf16 v[86:89], v[126:129], v[98:101], v[86:89]
	ds_read_b128 v[162:165], v4 offset:32768
	v_mfma_f32_16x16x32_bf16 v[94:97], v[154:157], v[98:101], v[94:97]
	ds_read_b128 v[170:173], v5 offset:49152
	global_load_dwordx4 v[98:101], v228, s[36:37] offset:896
	v_mfma_f32_16x16x32_bf16 v[30:33], v[122:125], v[110:113], v[30:33]
	s_waitcnt vmcnt(8)
	ds_write_b128 v2, v[82:85] offset:4096
	v_mfma_f32_16x16x32_bf16 v[42:45], v[126:129], v[110:113], v[42:45]
	ds_read_b128 v[82:85], v4 offset:34816
	v_mfma_f32_16x16x32_bf16 v[14:17], v[158:161], v[110:113], v[14:17]
	ds_read_b128 v[174:177], v5 offset:51200
	v_mfma_f32_16x16x32_bf16 v[90:93], v[154:157], v[110:113], v[90:93]
	global_load_dwordx4 v[110:113], v229, s[36:37] offset:896
	v_mfma_f32_16x16x32_bf16 v[34:37], v[122:125], v[146:149], v[34:37]
	s_waitcnt vmcnt(8)
	ds_write_b128 v2, v[102:105] offset:8192
	v_mfma_f32_16x16x32_bf16 v[46:49], v[126:129], v[146:149], v[46:49]
	ds_read_b128 v[102:105], v4 offset:36864
	v_mfma_f32_16x16x32_bf16 v[58:61], v[154:157], v[146:149], v[58:61]
	ds_read_b128 v[178:181], v5 offset:53248
	v_mfma_f32_16x16x32_bf16 v[18:21], v[158:161], v[146:149], v[18:21]
	global_load_dwordx4 v[146:149], v230, s[36:37] offset:896
	v_mfma_f32_16x16x32_bf16 v[38:41], v[122:125], v[150:153], v[38:41]
	s_waitcnt vmcnt(8)
	ds_write_b128 v2, v[132:135] offset:12288
	v_mfma_f32_16x16x32_bf16 v[50:53], v[126:129], v[150:153], v[50:53]
	ds_read_b128 v[132:135], v4 offset:38912
	v_mfma_f32_16x16x32_bf16 v[54:57], v[154:157], v[150:153], v[54:57]
	ds_read_b128 v[182:185], v5 offset:55296
	v_mfma_f32_16x16x32_bf16 v[22:25], v[158:161], v[150:153], v[22:25]
	s_waitcnt lgkmcnt(9)
	v_mfma_f32_16x16x32_bf16 v[26:29], v[170:173], v[162:165], v[26:29]
	global_load_dwordx4 v[122:125], v3, s[0:1] offset:896
	s_waitcnt lgkmcnt(0)
	v_mfma_f32_16x16x32_bf16 v[10:13], v[182:185], v[162:165], v[10:13]
	s_waitcnt vmcnt(8)
	ds_write_b128 v2, v[118:121] offset:16384
	v_mfma_f32_16x16x32_bf16 v[86:89], v[174:177], v[162:165], v[86:89]
	v_mfma_f32_16x16x32_bf16 v[94:97], v[178:181], v[162:165], v[94:97]
	global_load_dwordx4 v[118:121], v231, s[0:1] offset:896
	v_mfma_f32_16x16x32_bf16 v[30:33], v[170:173], v[82:85], v[30:33]
	s_waitcnt vmcnt(8)
	ds_write_b128 v2, v[114:117] offset:20480
	v_mfma_f32_16x16x32_bf16 v[42:45], v[174:177], v[82:85], v[42:45]
	v_mfma_f32_16x16x32_bf16 v[14:17], v[182:185], v[82:85], v[14:17]
	v_mfma_f32_16x16x32_bf16 v[90:93], v[178:181], v[82:85], v[90:93]
	global_load_dwordx4 v[82:85], v232, s[0:1] offset:896
	v_mfma_f32_16x16x32_bf16 v[34:37], v[170:173], v[102:105], v[34:37]
	s_waitcnt vmcnt(8)
	ds_write_b128 v2, v[106:109] offset:24576
	v_mfma_f32_16x16x32_bf16 v[46:49], v[174:177], v[102:105], v[46:49]
	v_mfma_f32_16x16x32_bf16 v[58:61], v[178:181], v[102:105], v[58:61]
	v_mfma_f32_16x16x32_bf16 v[18:21], v[182:185], v[102:105], v[18:21]
	global_load_dwordx4 v[102:105], v233, s[0:1] offset:896
	v_mfma_f32_16x16x32_bf16 v[38:41], v[170:173], v[132:135], v[38:41]
	s_waitcnt vmcnt(8)
	ds_write_b128 v2, v[62:65] offset:28672
	v_mfma_f32_16x16x32_bf16 v[50:53], v[174:177], v[132:135], v[50:53]
	v_mfma_f32_16x16x32_bf16 v[54:57], v[178:181], v[132:135], v[54:57]
	v_mfma_f32_16x16x32_bf16 v[22:25], v[182:185], v[132:135], v[22:25]
	s_setprio 0
	s_waitcnt lgkmcnt(0)
	s_barrier
	ds_read_b128 v[62:65], v6
	ds_read_b128 v[106:109], v6 offset:2048
	ds_read_b128 v[114:117], v7 offset:16384
	ds_read_b128 v[126:129], v7 offset:18432
	ds_read_b128 v[132:135], v6 offset:4096
	ds_read_b128 v[150:153], v6 offset:6144
	ds_read_b128 v[154:157], v7 offset:20480
	ds_read_b128 v[158:161], v7 offset:22528
	s_setprio 2
	s_waitcnt lgkmcnt(5)
	v_mfma_f32_16x16x32_bf16 v[26:29], v[114:117], v[62:65], v[26:29]
	global_load_dwordx4 v[162:165], v8, s[36:37] offset:1024
	s_waitcnt lgkmcnt(0)
	v_mfma_f32_16x16x32_bf16 v[10:13], v[158:161], v[62:65], v[10:13]
	s_waitcnt vmcnt(8)
	ds_write_b128 v2, v[166:169] offset:32768
	v_mfma_f32_16x16x32_bf16 v[86:89], v[126:129], v[62:65], v[86:89]
	ds_read_b128 v[166:169], v4
	v_mfma_f32_16x16x32_bf16 v[94:97], v[154:157], v[62:65], v[94:97]
	ds_read_b128 v[170:173], v5 offset:16384
	global_load_dwordx4 v[62:65], v228, s[36:37] offset:1024
	v_mfma_f32_16x16x32_bf16 v[30:33], v[114:117], v[106:109], v[30:33]
	s_waitcnt vmcnt(8)
	ds_write_b128 v2, v[98:101] offset:36864
	v_mfma_f32_16x16x32_bf16 v[42:45], v[126:129], v[106:109], v[42:45]
	ds_read_b128 v[98:101], v4 offset:2048
	v_mfma_f32_16x16x32_bf16 v[14:17], v[158:161], v[106:109], v[14:17]
	ds_read_b128 v[174:177], v5 offset:18432
	v_mfma_f32_16x16x32_bf16 v[90:93], v[154:157], v[106:109], v[90:93]
	global_load_dwordx4 v[106:109], v229, s[36:37] offset:1024
	v_mfma_f32_16x16x32_bf16 v[34:37], v[114:117], v[132:135], v[34:37]
	s_waitcnt vmcnt(8)
; template <int MODE>
; __device__ __forceinline__ void gemm_tile(const Params& P, int tm, int tn, unsigned char* smem) {
;     ...
; #pragma unroll
;         for (int i = 0; i < 4; ++i) { fa[i] = *(const bf16x8*)(sA + arow_off + i * 2048 + ch0); fb[i] = *(const bf16x8*)(sB + brow_off + i * 2048 + ch0); }
;         __builtin_amdgcn_sched_barrier(0);
;         __builtin_amdgcn_s_setprio(2);
;         if (wr_ok) *(uint4*)(nA + soff0) = ra0;
;         if (ld_ok) ra0 = *(const uint4*)(Ab + (aoff + 0u * LDA + koa));
;         ga[0] = *(const bf16x8*)(sA + arow_off + 0 * 2048 + ch1); gb[0] = *(const bf16x8*)(sB + brow_off + 0 * 2048 + ch1);
;         __builtin_amdgcn_sched_barrier(0);
; #pragma unroll
;         for (int j = 0; j < 4; ++j) acc[0][j] = __builtin_amdgcn_mfma_f32_16x16x32_bf16(fb[j], fa[0], acc[0][j], 0, 0, 0);
;         __builtin_amdgcn_sched_barrier(0);
;         if (wr_ok) *(uint4*)(nA + soff0 + 4096) = ra1;
;         if (ld_ok) ra1 = *(const uint4*)(Ab + (aoff + 32u * LDA + koa));
;         ga[1] = *(const bf16x8*)(sA + arow_off + 1 * 2048 + ch1); gb[1] = *(const bf16x8*)(sB + brow_off + 1 * 2048 + ch1);
;         __builtin_amdgcn_sched_barrier(0);
; #pragma unroll
;         for (int j = 0; j < 4; ++j) acc[1][j] = __builtin_amdgcn_mfma_f32_16x16x32_bf16(fb[j], fa[1], acc[1][j], 0, 0, 0);
;         __builtin_amdgcn_sched_barrier(0);
;         if (wr_ok) *(uint4*)(nA + soff0 + 8192) = ra2;
;         if (ld_ok) ra2 = *(const uint4*)(Ab + (aoff + 64u * LDA + koa));
;         ga[2] = *(const bf16x8*)(sA + arow_off + 2 * 2048 + ch1); gb[2] = *(const bf16x8*)(sB + brow_off + 2 * 2048 + ch1);
;         __builtin_amdgcn_sched_barrier(0);
; #pragma unroll
;         for (int j = 0; j < 4; ++j) acc[2][j] = __builtin_amdgcn_mfma_f32_16x16x32_bf16(fb[j], fa[2], acc[2][j], 0, 0, 0);
;         __builtin_amdgcn_sched_barrier(0);
;         if (wr_ok) *(uint4*)(nA + soff0 + 12288) = ra3;
;         if (ld_ok) ra3 = *(const uint4*)(Ab + (aoff + 96u * LDA + koa));
;         ga[3] = *(const bf16x8*)(sA + arow_off + 3 * 2048 + ch1); gb[3] = *(const bf16x8*)(sB + brow_off + 3 * 2048 + ch1);
;         __builtin_amdgcn_sched_barrier(0);
; #pragma unroll
;         for (int j = 0; j < 4; ++j) acc[3][j] = __builtin_amdgcn_mfma_f32_16x16x32_bf16(fb[j], fa[3], acc[3][j], 0, 0, 0);
;         __builtin_amdgcn_sched_barrier(0);
;         if (wr_ok) *(uint4*)(nB + soff0) = rb0;
	ds_write_b128 v2, v[110:113] offset:40960
	v_mfma_f32_16x16x32_bf16 v[46:49], v[126:129], v[132:135], v[46:49]
	ds_read_b128 v[110:113], v4 offset:4096
	v_mfma_f32_16x16x32_bf16 v[58:61], v[154:157], v[132:135], v[58:61]
	ds_read_b128 v[178:181], v5 offset:20480
	v_mfma_f32_16x16x32_bf16 v[18:21], v[158:161], v[132:135], v[18:21]
	global_load_dwordx4 v[132:135], v230, s[36:37] offset:1024
	v_mfma_f32_16x16x32_bf16 v[38:41], v[114:117], v[150:153], v[38:41]
	s_waitcnt vmcnt(8)
	ds_write_b128 v2, v[146:149] offset:45056
	v_mfma_f32_16x16x32_bf16 v[50:53], v[126:129], v[150:153], v[50:53]
	ds_read_b128 v[146:149], v4 offset:6144
	v_mfma_f32_16x16x32_bf16 v[54:57], v[154:157], v[150:153], v[54:57]
	ds_read_b128 v[182:185], v5 offset:22528
	v_mfma_f32_16x16x32_bf16 v[22:25], v[158:161], v[150:153], v[22:25]
	s_waitcnt lgkmcnt(9)
	v_mfma_f32_16x16x32_bf16 v[26:29], v[170:173], v[166:169], v[26:29]
	global_load_dwordx4 v[114:117], v3, s[0:1] offset:1024
	s_waitcnt lgkmcnt(0)
	v_mfma_f32_16x16x32_bf16 v[10:13], v[182:185], v[166:169], v[10:13]
	s_waitcnt vmcnt(8)
	ds_write_b128 v2, v[122:125] offset:49152
	v_mfma_f32_16x16x32_bf16 v[86:89], v[174:177], v[166:169], v[86:89]
	v_mfma_f32_16x16x32_bf16 v[94:97], v[178:181], v[166:169], v[94:97]
	global_load_dwordx4 v[122:125], v231, s[0:1] offset:1024
	v_mfma_f32_16x16x32_bf16 v[30:33], v[170:173], v[98:101], v[30:33]
	s_waitcnt vmcnt(8)
	ds_write_b128 v2, v[118:121] offset:53248
	v_mfma_f32_16x16x32_bf16 v[42:45], v[174:177], v[98:101], v[42:45]
	v_mfma_f32_16x16x32_bf16 v[14:17], v[182:185], v[98:101], v[14:17]
	v_mfma_f32_16x16x32_bf16 v[90:93], v[178:181], v[98:101], v[90:93]
	global_load_dwordx4 v[98:101], v232, s[0:1] offset:1024
	v_mfma_f32_16x16x32_bf16 v[34:37], v[170:173], v[110:113], v[34:37]
	s_waitcnt vmcnt(8)
	ds_write_b128 v2, v[82:85] offset:57344
	v_mfma_f32_16x16x32_bf16 v[46:49], v[174:177], v[110:113], v[46:49]
	v_mfma_f32_16x16x32_bf16 v[58:61], v[178:181], v[110:113], v[58:61]
	v_mfma_f32_16x16x32_bf16 v[18:21], v[182:185], v[110:113], v[18:21]
	global_load_dwordx4 v[82:85], v233, s[0:1] offset:1024
	v_mfma_f32_16x16x32_bf16 v[38:41], v[170:173], v[146:149], v[38:41]
	s_waitcnt vmcnt(8)
	ds_write_b128 v2, v[102:105] offset:61440
	v_mfma_f32_16x16x32_bf16 v[50:53], v[174:177], v[146:149], v[50:53]
	v_mfma_f32_16x16x32_bf16 v[54:57], v[178:181], v[146:149], v[54:57]
	v_mfma_f32_16x16x32_bf16 v[22:25], v[182:185], v[146:149], v[22:25]
	s_setprio 0
	s_waitcnt lgkmcnt(0)
	s_barrier
	ds_read_b128 v[102:105], v6 offset:32768
	ds_read_b128 v[110:113], v6 offset:34816
	ds_read_b128 v[118:121], v7 offset:49152
	ds_read_b128 v[126:129], v7 offset:51200
	ds_read_b128 v[146:149], v6 offset:36864
	ds_read_b128 v[150:153], v6 offset:38912
	ds_read_b128 v[154:157], v7 offset:53248
	ds_read_b128 v[158:161], v7 offset:55296
	s_setprio 2
	s_waitcnt lgkmcnt(5)
	v_mfma_f32_16x16x32_bf16 v[26:29], v[118:121], v[102:105], v[26:29]
	global_load_dwordx4 v[166:169], v8, s[36:37] offset:1152
	s_waitcnt lgkmcnt(0)
	v_mfma_f32_16x16x32_bf16 v[10:13], v[158:161], v[102:105], v[10:13]
	s_waitcnt vmcnt(8)
	ds_write_b128 v2, v[162:165]
	v_mfma_f32_16x16x32_bf16 v[86:89], v[126:129], v[102:105], v[86:89]
	ds_read_b128 v[162:165], v4 offset:32768
	v_mfma_f32_16x16x32_bf16 v[94:97], v[154:157], v[102:105], v[94:97]
	ds_read_b128 v[170:173], v5 offset:49152
	global_load_dwordx4 v[102:105], v228, s[36:37] offset:1152
	v_mfma_f32_16x16x32_bf16 v[30:33], v[118:121], v[110:113], v[30:33]
	s_waitcnt vmcnt(8)
	ds_write_b128 v2, v[62:65] offset:4096
	v_mfma_f32_16x16x32_bf16 v[42:45], v[126:129], v[110:113], v[42:45]
	ds_read_b128 v[62:65], v4 offset:34816
	v_mfma_f32_16x16x32_bf16 v[14:17], v[158:161], v[110:113], v[14:17]
	ds_read_b128 v[174:177], v5 offset:51200
	v_mfma_f32_16x16x32_bf16 v[90:93], v[154:157], v[110:113], v[90:93]
	global_load_dwordx4 v[110:113], v229, s[36:37] offset:1152
	v_mfma_f32_16x16x32_bf16 v[34:37], v[118:121], v[146:149], v[34:37]
	s_waitcnt vmcnt(8)
	ds_write_b128 v2, v[106:109] offset:8192
	v_mfma_f32_16x16x32_bf16 v[46:49], v[126:129], v[146:149], v[46:49]
	ds_read_b128 v[106:109], v4 offset:36864
	v_mfma_f32_16x16x32_bf16 v[58:61], v[154:157], v[146:149], v[58:61]
	ds_read_b128 v[178:181], v5 offset:53248
	v_mfma_f32_16x16x32_bf16 v[18:21], v[158:161], v[146:149], v[18:21]
	global_load_dwordx4 v[146:149], v230, s[36:37] offset:1152
	v_mfma_f32_16x16x32_bf16 v[38:41], v[118:121], v[150:153], v[38:41]
	s_waitcnt vmcnt(8)
	ds_write_b128 v2, v[132:135] offset:12288
	v_mfma_f32_16x16x32_bf16 v[50:53], v[126:129], v[150:153], v[50:53]
	ds_read_b128 v[132:135], v4 offset:38912
	v_mfma_f32_16x16x32_bf16 v[54:57], v[154:157], v[150:153], v[54:57]
	ds_read_b128 v[182:185], v5 offset:55296
	v_mfma_f32_16x16x32_bf16 v[22:25], v[158:161], v[150:153], v[22:25]
	s_waitcnt lgkmcnt(9)
	v_mfma_f32_16x16x32_bf16 v[26:29], v[170:173], v[162:165], v[26:29]
	global_load_dwordx4 v[118:121], v3, s[0:1] offset:1152
	s_waitcnt lgkmcnt(0)
	v_mfma_f32_16x16x32_bf16 v[10:13], v[182:185], v[162:165], v[10:13]
	s_waitcnt vmcnt(8)
	ds_write_b128 v2, v[114:117] offset:16384
	v_mfma_f32_16x16x32_bf16 v[86:89], v[174:177], v[162:165], v[86:89]
	v_mfma_f32_16x16x32_bf16 v[94:97], v[178:181], v[162:165], v[94:97]
	global_load_dwordx4 v[114:117], v231, s[0:1] offset:1152
	v_mfma_f32_16x16x32_bf16 v[30:33], v[170:173], v[62:65], v[30:33]
	s_waitcnt vmcnt(8)
	ds_write_b128 v2, v[122:125] offset:20480
	v_mfma_f32_16x16x32_bf16 v[42:45], v[174:177], v[62:65], v[42:45]
	v_mfma_f32_16x16x32_bf16 v[14:17], v[182:185], v[62:65], v[14:17]
	v_mfma_f32_16x16x32_bf16 v[90:93], v[178:181], v[62:65], v[90:93]
	global_load_dwordx4 v[62:65], v232, s[0:1] offset:1152
	v_mfma_f32_16x16x32_bf16 v[34:37], v[170:173], v[106:109], v[34:37]
	s_waitcnt vmcnt(8)
	ds_write_b128 v2, v[98:101] offset:24576
	v_mfma_f32_16x16x32_bf16 v[46:49], v[174:177], v[106:109], v[46:49]
	v_mfma_f32_16x16x32_bf16 v[58:61], v[178:181], v[106:109], v[58:61]
	v_mfma_f32_16x16x32_bf16 v[18:21], v[182:185], v[106:109], v[18:21]
	global_load_dwordx4 v[98:101], v233, s[0:1] offset:1152
	v_mfma_f32_16x16x32_bf16 v[38:41], v[170:173], v[132:135], v[38:41]
	s_waitcnt vmcnt(8)
	ds_write_b128 v2, v[82:85] offset:28672
	v_mfma_f32_16x16x32_bf16 v[50:53], v[174:177], v[132:135], v[50:53]
	v_mfma_f32_16x16x32_bf16 v[54:57], v[178:181], v[132:135], v[54:57]
	v_mfma_f32_16x16x32_bf16 v[22:25], v[182:185], v[132:135], v[22:25]
	s_setprio 0
	s_waitcnt lgkmcnt(0)
	s_barrier
; template <int MODE>
; __device__ __forceinline__ void gemm_tile(const Params& P, int tm, int tn, unsigned char* smem) {
;     ...
; #pragma unroll
;         for (int i = 0; i < 4; ++i) { fa[i] = *(const bf16x8*)(sA + arow_off + i * 2048 + ch0); fb[i] = *(const bf16x8*)(sB + brow_off + i * 2048 + ch0); }
;         __builtin_amdgcn_sched_barrier(0);
;         __builtin_amdgcn_s_setprio(2);
;         if (wr_ok) *(uint4*)(nA + soff0) = ra0;
;         if (ld_ok) ra0 = *(const uint4*)(Ab + (aoff + 0u * LDA + koa));
;         ga[0] = *(const bf16x8*)(sA + arow_off + 0 * 2048 + ch1); gb[0] = *(const bf16x8*)(sB + brow_off + 0 * 2048 + ch1);
;         __builtin_amdgcn_sched_barrier(0);
; #pragma unroll
;         for (int j = 0; j < 4; ++j) acc[0][j] = __builtin_amdgcn_mfma_f32_16x16x32_bf16(fb[j], fa[0], acc[0][j], 0, 0, 0);
;         __builtin_amdgcn_sched_barrier(0);
;         if (wr_ok) *(uint4*)(nA + soff0 + 4096) = ra1;
;         if (ld_ok) ra1 = *(const uint4*)(Ab + (aoff + 32u * LDA + koa));
;         ga[1] = *(const bf16x8*)(sA + arow_off + 1 * 2048 + ch1); gb[1] = *(const bf16x8*)(sB + brow_off + 1 * 2048 + ch1);
;         __builtin_amdgcn_sched_barrier(0);
; #pragma unroll
;         for (int j = 0; j < 4; ++j) acc[1][j] = __builtin_amdgcn_mfma_f32_16x16x32_bf16(fb[j], fa[1], acc[1][j], 0, 0, 0);
;         __builtin_amdgcn_sched_barrier(0);
;         if (wr_ok) *(uint4*)(nA + soff0 + 8192) = ra2;
;         if (ld_ok) ra2 = *(const uint4*)(Ab + (aoff + 64u * LDA + koa));
;         ga[2] = *(const bf16x8*)(sA + arow_off + 2 * 2048 + ch1); gb[2] = *(const bf16x8*)(sB + brow_off + 2 * 2048 + ch1);
;         __builtin_amdgcn_sched_barrier(0);
; #pragma unroll
;         for (int j = 0; j < 4; ++j) acc[2][j] = __builtin_amdgcn_mfma_f32_16x16x32_bf16(fb[j], fa[2], acc[2][j], 0, 0, 0);
;         __builtin_amdgcn_sched_barrier(0);
;         if (wr_ok) *(uint4*)(nA + soff0 + 12288) = ra3;
;         if (ld_ok) ra3 = *(const uint4*)(Ab + (aoff + 96u * LDA + koa));
;         ga[3] = *(const bf16x8*)(sA + arow_off + 3 * 2048 + ch1); gb[3] = *(const bf16x8*)(sB + brow_off + 3 * 2048 + ch1);
;         __builtin_amdgcn_sched_barrier(0);
; #pragma unroll
;         for (int j = 0; j < 4; ++j) acc[3][j] = __builtin_amdgcn_mfma_f32_16x16x32_bf16(fb[j], fa[3], acc[3][j], 0, 0, 0);
;         __builtin_amdgcn_sched_barrier(0);
;         if (wr_ok) *(uint4*)(nB + soff0) = rb0;
	ds_read_b128 v[82:85], v6
	ds_read_b128 v[106:109], v6 offset:2048
	ds_read_b128 v[122:125], v7 offset:16384
	ds_read_b128 v[126:129], v7 offset:18432
	ds_read_b128 v[132:135], v6 offset:4096
	ds_read_b128 v[150:153], v6 offset:6144
	ds_read_b128 v[154:157], v7 offset:20480
	ds_read_b128 v[158:161], v7 offset:22528
	s_setprio 2
	s_waitcnt lgkmcnt(5)
	v_mfma_f32_16x16x32_bf16 v[26:29], v[122:125], v[82:85], v[26:29]
	global_load_dwordx4 v[162:165], v8, s[36:37] offset:1280
	s_waitcnt lgkmcnt(0)
	v_mfma_f32_16x16x32_bf16 v[10:13], v[158:161], v[82:85], v[10:13]
	s_waitcnt vmcnt(8)
	ds_write_b128 v2, v[166:169] offset:32768
	v_mfma_f32_16x16x32_bf16 v[86:89], v[126:129], v[82:85], v[86:89]
	ds_read_b128 v[166:169], v4
	v_mfma_f32_16x16x32_bf16 v[94:97], v[154:157], v[82:85], v[94:97]
	ds_read_b128 v[170:173], v5 offset:16384
	global_load_dwordx4 v[82:85], v228, s[36:37] offset:1280
	v_mfma_f32_16x16x32_bf16 v[30:33], v[122:125], v[106:109], v[30:33]
	s_waitcnt vmcnt(8)
	ds_write_b128 v2, v[102:105] offset:36864
	v_mfma_f32_16x16x32_bf16 v[42:45], v[126:129], v[106:109], v[42:45]
	ds_read_b128 v[102:105], v4 offset:2048
	v_mfma_f32_16x16x32_bf16 v[14:17], v[158:161], v[106:109], v[14:17]
	ds_read_b128 v[174:177], v5 offset:18432
	v_mfma_f32_16x16x32_bf16 v[90:93], v[154:157], v[106:109], v[90:93]
	global_load_dwordx4 v[106:109], v229, s[36:37] offset:1280
	v_mfma_f32_16x16x32_bf16 v[34:37], v[122:125], v[132:135], v[34:37]
	s_waitcnt vmcnt(8)
	ds_write_b128 v2, v[110:113] offset:40960
	v_mfma_f32_16x16x32_bf16 v[46:49], v[126:129], v[132:135], v[46:49]
	ds_read_b128 v[110:113], v4 offset:4096
	v_mfma_f32_16x16x32_bf16 v[58:61], v[154:157], v[132:135], v[58:61]
	ds_read_b128 v[178:181], v5 offset:20480
	v_mfma_f32_16x16x32_bf16 v[18:21], v[158:161], v[132:135], v[18:21]
	global_load_dwordx4 v[132:135], v230, s[36:37] offset:1280
	v_mfma_f32_16x16x32_bf16 v[38:41], v[122:125], v[150:153], v[38:41]
	s_waitcnt vmcnt(8)
	ds_write_b128 v2, v[146:149] offset:45056
	v_mfma_f32_16x16x32_bf16 v[50:53], v[126:129], v[150:153], v[50:53]
	ds_read_b128 v[146:149], v4 offset:6144
	v_mfma_f32_16x16x32_bf16 v[54:57], v[154:157], v[150:153], v[54:57]
	ds_read_b128 v[182:185], v5 offset:22528
	v_mfma_f32_16x16x32_bf16 v[22:25], v[158:161], v[150:153], v[22:25]
	s_waitcnt lgkmcnt(9)
	v_mfma_f32_16x16x32_bf16 v[26:29], v[170:173], v[166:169], v[26:29]
	global_load_dwordx4 v[122:125], v3, s[0:1] offset:1280
	s_waitcnt lgkmcnt(0)
	v_mfma_f32_16x16x32_bf16 v[10:13], v[182:185], v[166:169], v[10:13]
	s_waitcnt vmcnt(8)
	ds_write_b128 v2, v[118:121] offset:49152
	v_mfma_f32_16x16x32_bf16 v[86:89], v[174:177], v[166:169], v[86:89]
	v_mfma_f32_16x16x32_bf16 v[94:97], v[178:181], v[166:169], v[94:97]
	global_load_dwordx4 v[118:121], v231, s[0:1] offset:1280
	v_mfma_f32_16x16x32_bf16 v[30:33], v[170:173], v[102:105], v[30:33]
	s_waitcnt vmcnt(8)
	ds_write_b128 v2, v[114:117] offset:53248
	v_mfma_f32_16x16x32_bf16 v[42:45], v[174:177], v[102:105], v[42:45]
	v_mfma_f32_16x16x32_bf16 v[14:17], v[182:185], v[102:105], v[14:17]
	v_mfma_f32_16x16x32_bf16 v[90:93], v[178:181], v[102:105], v[90:93]
	global_load_dwordx4 v[102:105], v232, s[0:1] offset:1280
	v_mfma_f32_16x16x32_bf16 v[34:37], v[170:173], v[110:113], v[34:37]
	s_waitcnt vmcnt(8)
	ds_write_b128 v2, v[62:65] offset:57344
	v_mfma_f32_16x16x32_bf16 v[46:49], v[174:177], v[110:113], v[46:49]
	v_mfma_f32_16x16x32_bf16 v[58:61], v[178:181], v[110:113], v[58:61]
	v_mfma_f32_16x16x32_bf16 v[18:21], v[182:185], v[110:113], v[18:21]
	global_load_dwordx4 v[62:65], v233, s[0:1] offset:1280
	v_mfma_f32_16x16x32_bf16 v[38:41], v[170:173], v[146:149], v[38:41]
	s_waitcnt vmcnt(8)
	ds_write_b128 v2, v[98:101] offset:61440
	v_mfma_f32_16x16x32_bf16 v[50:53], v[174:177], v[146:149], v[50:53]
	v_mfma_f32_16x16x32_bf16 v[54:57], v[178:181], v[146:149], v[54:57]
	v_mfma_f32_16x16x32_bf16 v[22:25], v[182:185], v[146:149], v[22:25]
	s_setprio 0
	s_waitcnt lgkmcnt(0)
	s_barrier
	ds_read_b128 v[98:101], v6 offset:32768
	ds_read_b128 v[110:113], v6 offset:34816
	ds_read_b128 v[114:117], v7 offset:49152
	ds_read_b128 v[126:129], v7 offset:51200
	ds_read_b128 v[146:149], v6 offset:36864
	ds_read_b128 v[150:153], v6 offset:38912
	ds_read_b128 v[154:157], v7 offset:53248
	ds_read_b128 v[158:161], v7 offset:55296
	s_setprio 2
	s_waitcnt lgkmcnt(5)
	v_mfma_f32_16x16x32_bf16 v[26:29], v[114:117], v[98:101], v[26:29]
	global_load_dwordx4 v[166:169], v8, s[36:37] offset:1408
	s_waitcnt lgkmcnt(0)
	v_mfma_f32_16x16x32_bf16 v[10:13], v[158:161], v[98:101], v[10:13]
	s_waitcnt vmcnt(8)
	ds_write_b128 v2, v[162:165]
	v_mfma_f32_16x16x32_bf16 v[86:89], v[126:129], v[98:101], v[86:89]
	ds_read_b128 v[162:165], v4 offset:32768
	v_mfma_f32_16x16x32_bf16 v[94:97], v[154:157], v[98:101], v[94:97]
	ds_read_b128 v[170:173], v5 offset:49152
	global_load_dwordx4 v[98:101], v228, s[36:37] offset:1408
	v_mfma_f32_16x16x32_bf16 v[30:33], v[114:117], v[110:113], v[30:33]
	s_waitcnt vmcnt(8)
	ds_write_b128 v2, v[82:85] offset:4096
	v_mfma_f32_16x16x32_bf16 v[42:45], v[126:129], v[110:113], v[42:45]
	ds_read_b128 v[82:85], v4 offset:34816
	v_mfma_f32_16x16x32_bf16 v[14:17], v[158:161], v[110:113], v[14:17]
	ds_read_b128 v[174:177], v5 offset:51200
	v_mfma_f32_16x16x32_bf16 v[90:93], v[154:157], v[110:113], v[90:93]
	global_load_dwordx4 v[110:113], v229, s[36:37] offset:1408
	v_mfma_f32_16x16x32_bf16 v[34:37], v[114:117], v[146:149], v[34:37]
	s_waitcnt vmcnt(8)
; template <int MODE>
; __device__ __forceinline__ void gemm_tile(const Params& P, int tm, int tn, unsigned char* smem) {
;     ...
; #pragma unroll
;         for (int i = 0; i < 4; ++i) { fa[i] = *(const bf16x8*)(sA + arow_off + i * 2048 + ch0); fb[i] = *(const bf16x8*)(sB + brow_off + i * 2048 + ch0); }
;         __builtin_amdgcn_sched_barrier(0);
;         __builtin_amdgcn_s_setprio(2);
;         if (wr_ok) *(uint4*)(nA + soff0) = ra0;
;         if (ld_ok) ra0 = *(const uint4*)(Ab + (aoff + 0u * LDA + koa));
;         ga[0] = *(const bf16x8*)(sA + arow_off + 0 * 2048 + ch1); gb[0] = *(const bf16x8*)(sB + brow_off + 0 * 2048 + ch1);
;         __builtin_amdgcn_sched_barrier(0);
; #pragma unroll
;         for (int j = 0; j < 4; ++j) acc[0][j] = __builtin_amdgcn_mfma_f32_16x16x32_bf16(fb[j], fa[0], acc[0][j], 0, 0, 0);
;         __builtin_amdgcn_sched_barrier(0);
;         if (wr_ok) *(uint4*)(nA + soff0 + 4096) = ra1;
;         if (ld_ok) ra1 = *(const uint4*)(Ab + (aoff + 32u * LDA + koa));
;         ga[1] = *(const bf16x8*)(sA + arow_off + 1 * 2048 + ch1); gb[1] = *(const bf16x8*)(sB + brow_off + 1 * 2048 + ch1);
;         __builtin_amdgcn_sched_barrier(0);
; #pragma unroll
;         for (int j = 0; j < 4; ++j) acc[1][j] = __builtin_amdgcn_mfma_f32_16x16x32_bf16(fb[j], fa[1], acc[1][j], 0, 0, 0);
;         __builtin_amdgcn_sched_barrier(0);
;         if (wr_ok) *(uint4*)(nA + soff0 + 8192) = ra2;
;         if (ld_ok) ra2 = *(const uint4*)(Ab + (aoff + 64u * LDA + koa));
;         ga[2] = *(const bf16x8*)(sA + arow_off + 2 * 2048 + ch1); gb[2] = *(const bf16x8*)(sB + brow_off + 2 * 2048 + ch1);
;         __builtin_amdgcn_sched_barrier(0);
; #pragma unroll
;         for (int j = 0; j < 4; ++j) acc[2][j] = __builtin_amdgcn_mfma_f32_16x16x32_bf16(fb[j], fa[2], acc[2][j], 0, 0, 0);
;         __builtin_amdgcn_sched_barrier(0);
;         if (wr_ok) *(uint4*)(nA + soff0 + 12288) = ra3;
;         if (ld_ok) ra3 = *(const uint4*)(Ab + (aoff + 96u * LDA + koa));
;         ga[3] = *(const bf16x8*)(sA + arow_off + 3 * 2048 + ch1); gb[3] = *(const bf16x8*)(sB + brow_off + 3 * 2048 + ch1);
;         __builtin_amdgcn_sched_barrier(0);
; #pragma unroll
;         for (int j = 0; j < 4; ++j) acc[3][j] = __builtin_amdgcn_mfma_f32_16x16x32_bf16(fb[j], fa[3], acc[3][j], 0, 0, 0);
;         __builtin_amdgcn_sched_barrier(0);
;         if (wr_ok) *(uint4*)(nB + soff0) = rb0;
	ds_write_b128 v2, v[106:109] offset:8192
	v_mfma_f32_16x16x32_bf16 v[46:49], v[126:129], v[146:149], v[46:49]
	ds_read_b128 v[106:109], v4 offset:36864
	v_mfma_f32_16x16x32_bf16 v[58:61], v[154:157], v[146:149], v[58:61]
	ds_read_b128 v[178:181], v5 offset:53248
	v_mfma_f32_16x16x32_bf16 v[18:21], v[158:161], v[146:149], v[18:21]
	global_load_dwordx4 v[146:149], v230, s[36:37] offset:1408
	v_mfma_f32_16x16x32_bf16 v[38:41], v[114:117], v[150:153], v[38:41]
	s_waitcnt vmcnt(8)
	ds_write_b128 v2, v[132:135] offset:12288
	v_mfma_f32_16x16x32_bf16 v[50:53], v[126:129], v[150:153], v[50:53]
	ds_read_b128 v[132:135], v4 offset:38912
	v_mfma_f32_16x16x32_bf16 v[54:57], v[154:157], v[150:153], v[54:57]
	ds_read_b128 v[182:185], v5 offset:55296
	v_mfma_f32_16x16x32_bf16 v[22:25], v[158:161], v[150:153], v[22:25]
	s_waitcnt lgkmcnt(9)
	v_mfma_f32_16x16x32_bf16 v[26:29], v[170:173], v[162:165], v[26:29]
	global_load_dwordx4 v[114:117], v3, s[0:1] offset:1408
	s_waitcnt lgkmcnt(0)
	v_mfma_f32_16x16x32_bf16 v[10:13], v[182:185], v[162:165], v[10:13]
	s_waitcnt vmcnt(8)
	ds_write_b128 v2, v[122:125] offset:16384
	v_mfma_f32_16x16x32_bf16 v[86:89], v[174:177], v[162:165], v[86:89]
	v_mfma_f32_16x16x32_bf16 v[94:97], v[178:181], v[162:165], v[94:97]
	global_load_dwordx4 v[122:125], v231, s[0:1] offset:1408
	v_mfma_f32_16x16x32_bf16 v[30:33], v[170:173], v[82:85], v[30:33]
	s_waitcnt vmcnt(8)
	ds_write_b128 v2, v[118:121] offset:20480
	v_mfma_f32_16x16x32_bf16 v[42:45], v[174:177], v[82:85], v[42:45]
	v_mfma_f32_16x16x32_bf16 v[14:17], v[182:185], v[82:85], v[14:17]
	v_mfma_f32_16x16x32_bf16 v[90:93], v[178:181], v[82:85], v[90:93]
	global_load_dwordx4 v[82:85], v232, s[0:1] offset:1408
	v_mfma_f32_16x16x32_bf16 v[34:37], v[170:173], v[106:109], v[34:37]
	s_waitcnt vmcnt(8)
	ds_write_b128 v2, v[102:105] offset:24576
	v_mfma_f32_16x16x32_bf16 v[46:49], v[174:177], v[106:109], v[46:49]
	v_mfma_f32_16x16x32_bf16 v[58:61], v[178:181], v[106:109], v[58:61]
	v_mfma_f32_16x16x32_bf16 v[18:21], v[182:185], v[106:109], v[18:21]
	global_load_dwordx4 v[102:105], v233, s[0:1] offset:1408
	v_mfma_f32_16x16x32_bf16 v[38:41], v[170:173], v[132:135], v[38:41]
	s_waitcnt vmcnt(8)
	ds_write_b128 v2, v[62:65] offset:28672
	v_mfma_f32_16x16x32_bf16 v[50:53], v[174:177], v[132:135], v[50:53]
	v_mfma_f32_16x16x32_bf16 v[54:57], v[178:181], v[132:135], v[54:57]
	v_mfma_f32_16x16x32_bf16 v[22:25], v[182:185], v[132:135], v[22:25]
	s_setprio 0
	s_waitcnt lgkmcnt(0)
	s_barrier
	ds_read_b128 v[62:65], v6
	ds_read_b128 v[106:109], v6 offset:2048
	ds_read_b128 v[118:121], v7 offset:16384
	ds_read_b128 v[126:129], v7 offset:18432
	ds_read_b128 v[132:135], v6 offset:4096
	ds_read_b128 v[150:153], v6 offset:6144
	ds_read_b128 v[154:157], v7 offset:20480
	ds_read_b128 v[158:161], v7 offset:22528
	s_setprio 2
	s_waitcnt lgkmcnt(5)
	v_mfma_f32_16x16x32_bf16 v[26:29], v[118:121], v[62:65], v[26:29]
	global_load_dwordx4 v[162:165], v8, s[36:37] offset:1536
	s_waitcnt lgkmcnt(0)
	v_mfma_f32_16x16x32_bf16 v[10:13], v[158:161], v[62:65], v[10:13]
	s_waitcnt vmcnt(8)
	ds_write_b128 v2, v[166:169] offset:32768
	v_mfma_f32_16x16x32_bf16 v[86:89], v[126:129], v[62:65], v[86:89]
	ds_read_b128 v[166:169], v4
	v_mfma_f32_16x16x32_bf16 v[94:97], v[154:157], v[62:65], v[94:97]
	ds_read_b128 v[170:173], v5 offset:16384
	global_load_dwordx4 v[62:65], v228, s[36:37] offset:1536
	v_mfma_f32_16x16x32_bf16 v[30:33], v[118:121], v[106:109], v[30:33]
	s_waitcnt vmcnt(8)
	ds_write_b128 v2, v[98:101] offset:36864
	v_mfma_f32_16x16x32_bf16 v[42:45], v[126:129], v[106:109], v[42:45]
	ds_read_b128 v[98:101], v4 offset:2048
	v_mfma_f32_16x16x32_bf16 v[14:17], v[158:161], v[106:109], v[14:17]
	ds_read_b128 v[174:177], v5 offset:18432
	v_mfma_f32_16x16x32_bf16 v[90:93], v[154:157], v[106:109], v[90:93]
	global_load_dwordx4 v[106:109], v229, s[36:37] offset:1536
	v_mfma_f32_16x16x32_bf16 v[34:37], v[118:121], v[132:135], v[34:37]
	s_waitcnt vmcnt(8)
	ds_write_b128 v2, v[110:113] offset:40960
	v_mfma_f32_16x16x32_bf16 v[46:49], v[126:129], v[132:135], v[46:49]
	ds_read_b128 v[110:113], v4 offset:4096
	v_mfma_f32_16x16x32_bf16 v[58:61], v[154:157], v[132:135], v[58:61]
	ds_read_b128 v[178:181], v5 offset:20480
	v_mfma_f32_16x16x32_bf16 v[18:21], v[158:161], v[132:135], v[18:21]
	global_load_dwordx4 v[132:135], v230, s[36:37] offset:1536
	v_mfma_f32_16x16x32_bf16 v[38:41], v[118:121], v[150:153], v[38:41]
	s_waitcnt vmcnt(8)
	ds_write_b128 v2, v[146:149] offset:45056
	v_mfma_f32_16x16x32_bf16 v[50:53], v[126:129], v[150:153], v[50:53]
	ds_read_b128 v[146:149], v4 offset:6144
	v_mfma_f32_16x16x32_bf16 v[54:57], v[154:157], v[150:153], v[54:57]
	ds_read_b128 v[182:185], v5 offset:22528
	v_mfma_f32_16x16x32_bf16 v[22:25], v[158:161], v[150:153], v[22:25]
	s_waitcnt lgkmcnt(9)
	v_mfma_f32_16x16x32_bf16 v[26:29], v[170:173], v[166:169], v[26:29]
	global_load_dwordx4 v[118:121], v3, s[0:1] offset:1536
	s_waitcnt lgkmcnt(0)
	v_mfma_f32_16x16x32_bf16 v[10:13], v[182:185], v[166:169], v[10:13]
	s_waitcnt vmcnt(8)
	ds_write_b128 v2, v[114:117] offset:49152
	v_mfma_f32_16x16x32_bf16 v[86:89], v[174:177], v[166:169], v[86:89]
	v_mfma_f32_16x16x32_bf16 v[94:97], v[178:181], v[166:169], v[94:97]
	global_load_dwordx4 v[114:117], v231, s[0:1] offset:1536
	v_mfma_f32_16x16x32_bf16 v[30:33], v[170:173], v[98:101], v[30:33]
	s_waitcnt vmcnt(8)
	ds_write_b128 v2, v[122:125] offset:53248
	v_mfma_f32_16x16x32_bf16 v[42:45], v[174:177], v[98:101], v[42:45]
	v_mfma_f32_16x16x32_bf16 v[14:17], v[182:185], v[98:101], v[14:17]
	v_mfma_f32_16x16x32_bf16 v[90:93], v[178:181], v[98:101], v[90:93]
	global_load_dwordx4 v[98:101], v232, s[0:1] offset:1536
	v_mfma_f32_16x16x32_bf16 v[34:37], v[170:173], v[110:113], v[34:37]
	s_waitcnt vmcnt(8)
	ds_write_b128 v2, v[82:85] offset:57344
	v_mfma_f32_16x16x32_bf16 v[46:49], v[174:177], v[110:113], v[46:49]
	v_mfma_f32_16x16x32_bf16 v[58:61], v[178:181], v[110:113], v[58:61]
	v_mfma_f32_16x16x32_bf16 v[18:21], v[182:185], v[110:113], v[18:21]
	global_load_dwordx4 v[82:85], v233, s[0:1] offset:1536
	v_mfma_f32_16x16x32_bf16 v[38:41], v[170:173], v[146:149], v[38:41]
	s_waitcnt vmcnt(8)
	ds_write_b128 v2, v[102:105] offset:61440
	v_mfma_f32_16x16x32_bf16 v[50:53], v[174:177], v[146:149], v[50:53]
	v_mfma_f32_16x16x32_bf16 v[54:57], v[178:181], v[146:149], v[54:57]
	v_mfma_f32_16x16x32_bf16 v[22:25], v[182:185], v[146:149], v[22:25]
	s_setprio 0
	s_waitcnt lgkmcnt(0)
	s_barrier
; template <int MODE>
; __device__ __forceinline__ void gemm_tile(const Params& P, int tm, int tn, unsigned char* smem) {
;     ...
; #pragma unroll
;         for (int i = 0; i < 4; ++i) { fa[i] = *(const bf16x8*)(sA + arow_off + i * 2048 + ch0); fb[i] = *(const bf16x8*)(sB + brow_off + i * 2048 + ch0); }
;         __builtin_amdgcn_sched_barrier(0);
;         __builtin_amdgcn_s_setprio(2);
;         if (wr_ok) *(uint4*)(nA + soff0) = ra0;
;         if (ld_ok) ra0 = *(const uint4*)(Ab + (aoff + 0u * LDA + koa));
;         ga[0] = *(const bf16x8*)(sA + arow_off + 0 * 2048 + ch1); gb[0] = *(const bf16x8*)(sB + brow_off + 0 * 2048 + ch1);
;         __builtin_amdgcn_sched_barrier(0);
; #pragma unroll
;         for (int j = 0; j < 4; ++j) acc[0][j] = __builtin_amdgcn_mfma_f32_16x16x32_bf16(fb[j], fa[0], acc[0][j], 0, 0, 0);
;         __builtin_amdgcn_sched_barrier(0);
;         if (wr_ok) *(uint4*)(nA + soff0 + 4096) = ra1;
;         if (ld_ok) ra1 = *(const uint4*)(Ab + (aoff + 32u * LDA + koa));
;         ga[1] = *(const bf16x8*)(sA + arow_off + 1 * 2048 + ch1); gb[1] = *(const bf16x8*)(sB + brow_off + 1 * 2048 + ch1);
;         __builtin_amdgcn_sched_barrier(0);
; #pragma unroll
;         for (int j = 0; j < 4; ++j) acc[1][j] = __builtin_amdgcn_mfma_f32_16x16x32_bf16(fb[j], fa[1], acc[1][j], 0, 0, 0);
;         __builtin_amdgcn_sched_barrier(0);
;         if (wr_ok) *(uint4*)(nA + soff0 + 8192) = ra2;
;         if (ld_ok) ra2 = *(const uint4*)(Ab + (aoff + 64u * LDA + koa));
;         ga[2] = *(const bf16x8*)(sA + arow_off + 2 * 2048 + ch1); gb[2] = *(const bf16x8*)(sB + brow_off + 2 * 2048 + ch1);
;         __builtin_amdgcn_sched_barrier(0);
; #pragma unroll
;         for (int j = 0; j < 4; ++j) acc[2][j] = __builtin_amdgcn_mfma_f32_16x16x32_bf16(fb[j], fa[2], acc[2][j], 0, 0, 0);
;         __builtin_amdgcn_sched_barrier(0);
;         if (wr_ok) *(uint4*)(nA + soff0 + 12288) = ra3;
;         if (ld_ok) ra3 = *(const uint4*)(Ab + (aoff + 96u * LDA + koa));
;         ga[3] = *(const bf16x8*)(sA + arow_off + 3 * 2048 + ch1); gb[3] = *(const bf16x8*)(sB + brow_off + 3 * 2048 + ch1);
;         __builtin_amdgcn_sched_barrier(0);
; #pragma unroll
;         for (int j = 0; j < 4; ++j) acc[3][j] = __builtin_amdgcn_mfma_f32_16x16x32_bf16(fb[j], fa[3], acc[3][j], 0, 0, 0);
;         __builtin_amdgcn_sched_barrier(0);
;         if (wr_ok) *(uint4*)(nB + soff0) = rb0;
	ds_read_b128 v[102:105], v6 offset:32768
	ds_read_b128 v[110:113], v6 offset:34816
	ds_read_b128 v[122:125], v7 offset:49152
	ds_read_b128 v[126:129], v7 offset:51200
	ds_read_b128 v[146:149], v6 offset:36864
	ds_read_b128 v[150:153], v6 offset:38912
	ds_read_b128 v[154:157], v7 offset:53248
	ds_read_b128 v[158:161], v7 offset:55296
	s_setprio 2
	s_waitcnt lgkmcnt(5)
	v_mfma_f32_16x16x32_bf16 v[26:29], v[122:125], v[102:105], v[26:29]
	global_load_dwordx4 v[166:169], v8, s[36:37] offset:1664
	s_waitcnt lgkmcnt(0)
	v_mfma_f32_16x16x32_bf16 v[10:13], v[158:161], v[102:105], v[10:13]
	s_waitcnt vmcnt(8)
	ds_write_b128 v2, v[162:165]
	v_mfma_f32_16x16x32_bf16 v[86:89], v[126:129], v[102:105], v[86:89]
	ds_read_b128 v[162:165], v4 offset:32768
	v_mfma_f32_16x16x32_bf16 v[94:97], v[154:157], v[102:105], v[94:97]
	ds_read_b128 v[170:173], v5 offset:49152
	global_load_dwordx4 v[102:105], v228, s[36:37] offset:1664
	v_mfma_f32_16x16x32_bf16 v[30:33], v[122:125], v[110:113], v[30:33]
	s_waitcnt vmcnt(8)
	ds_write_b128 v2, v[62:65] offset:4096
	v_mfma_f32_16x16x32_bf16 v[42:45], v[126:129], v[110:113], v[42:45]
	ds_read_b128 v[62:65], v4 offset:34816
	v_mfma_f32_16x16x32_bf16 v[14:17], v[158:161], v[110:113], v[14:17]
	ds_read_b128 v[174:177], v5 offset:51200
	v_mfma_f32_16x16x32_bf16 v[90:93], v[154:157], v[110:113], v[90:93]
	global_load_dwordx4 v[110:113], v229, s[36:37] offset:1664
	v_mfma_f32_16x16x32_bf16 v[34:37], v[122:125], v[146:149], v[34:37]
	s_waitcnt vmcnt(8)
	ds_write_b128 v2, v[106:109] offset:8192
	v_mfma_f32_16x16x32_bf16 v[46:49], v[126:129], v[146:149], v[46:49]
	ds_read_b128 v[106:109], v4 offset:36864
	v_mfma_f32_16x16x32_bf16 v[58:61], v[154:157], v[146:149], v[58:61]
	ds_read_b128 v[178:181], v5 offset:53248
	v_mfma_f32_16x16x32_bf16 v[18:21], v[158:161], v[146:149], v[18:21]
	global_load_dwordx4 v[146:149], v230, s[36:37] offset:1664
	v_mfma_f32_16x16x32_bf16 v[38:41], v[122:125], v[150:153], v[38:41]
	s_waitcnt vmcnt(8)
	ds_write_b128 v2, v[132:135] offset:12288
	v_mfma_f32_16x16x32_bf16 v[50:53], v[126:129], v[150:153], v[50:53]
	ds_read_b128 v[132:135], v4 offset:38912
	v_mfma_f32_16x16x32_bf16 v[54:57], v[154:157], v[150:153], v[54:57]
	ds_read_b128 v[182:185], v5 offset:55296
	v_mfma_f32_16x16x32_bf16 v[22:25], v[158:161], v[150:153], v[22:25]
	s_waitcnt lgkmcnt(9)
	v_mfma_f32_16x16x32_bf16 v[26:29], v[170:173], v[162:165], v[26:29]
	global_load_dwordx4 v[122:125], v3, s[0:1] offset:1664
	s_waitcnt lgkmcnt(0)
	v_mfma_f32_16x16x32_bf16 v[10:13], v[182:185], v[162:165], v[10:13]
	s_waitcnt vmcnt(8)
	ds_write_b128 v2, v[118:121] offset:16384
	v_mfma_f32_16x16x32_bf16 v[86:89], v[174:177], v[162:165], v[86:89]
	v_mfma_f32_16x16x32_bf16 v[94:97], v[178:181], v[162:165], v[94:97]
	global_load_dwordx4 v[118:121], v231, s[0:1] offset:1664
	v_mfma_f32_16x16x32_bf16 v[30:33], v[170:173], v[62:65], v[30:33]
	s_waitcnt vmcnt(8)
	ds_write_b128 v2, v[114:117] offset:20480
	v_mfma_f32_16x16x32_bf16 v[42:45], v[174:177], v[62:65], v[42:45]
	v_mfma_f32_16x16x32_bf16 v[14:17], v[182:185], v[62:65], v[14:17]
	v_mfma_f32_16x16x32_bf16 v[90:93], v[178:181], v[62:65], v[90:93]
	global_load_dwordx4 v[62:65], v232, s[0:1] offset:1664
	v_mfma_f32_16x16x32_bf16 v[34:37], v[170:173], v[106:109], v[34:37]
	s_waitcnt vmcnt(8)
	ds_write_b128 v2, v[98:101] offset:24576
	v_mfma_f32_16x16x32_bf16 v[46:49], v[174:177], v[106:109], v[46:49]
	v_mfma_f32_16x16x32_bf16 v[58:61], v[178:181], v[106:109], v[58:61]
	v_mfma_f32_16x16x32_bf16 v[18:21], v[182:185], v[106:109], v[18:21]
	global_load_dwordx4 v[98:101], v233, s[0:1] offset:1664
	v_mfma_f32_16x16x32_bf16 v[38:41], v[170:173], v[132:135], v[38:41]
	s_waitcnt vmcnt(8)
	ds_write_b128 v2, v[82:85] offset:28672
	v_mfma_f32_16x16x32_bf16 v[50:53], v[174:177], v[132:135], v[50:53]
	v_mfma_f32_16x16x32_bf16 v[54:57], v[178:181], v[132:135], v[54:57]
	v_mfma_f32_16x16x32_bf16 v[22:25], v[182:185], v[132:135], v[22:25]
	s_setprio 0
	s_waitcnt lgkmcnt(0)
	s_barrier
	ds_read_b128 v[82:85], v6
	ds_read_b128 v[106:109], v6 offset:2048
	ds_read_b128 v[114:117], v7 offset:16384
	ds_read_b128 v[126:129], v7 offset:18432
	ds_read_b128 v[132:135], v6 offset:4096
	ds_read_b128 v[150:153], v6 offset:6144
	ds_read_b128 v[154:157], v7 offset:20480
	ds_read_b128 v[158:161], v7 offset:22528
	s_setprio 2
	s_waitcnt lgkmcnt(5)
	v_mfma_f32_16x16x32_bf16 v[26:29], v[114:117], v[82:85], v[26:29]
	global_load_dwordx4 v[162:165], v8, s[36:37] offset:1792
	s_waitcnt lgkmcnt(0)
	v_mfma_f32_16x16x32_bf16 v[10:13], v[158:161], v[82:85], v[10:13]
	s_waitcnt vmcnt(8)
	ds_write_b128 v2, v[166:169] offset:32768
	v_mfma_f32_16x16x32_bf16 v[86:89], v[126:129], v[82:85], v[86:89]
	ds_read_b128 v[166:169], v4
	v_mfma_f32_16x16x32_bf16 v[94:97], v[154:157], v[82:85], v[94:97]
	ds_read_b128 v[170:173], v5 offset:16384
	global_load_dwordx4 v[82:85], v228, s[36:37] offset:1792
	v_mfma_f32_16x16x32_bf16 v[30:33], v[114:117], v[106:109], v[30:33]
	s_waitcnt vmcnt(8)
	ds_write_b128 v2, v[102:105] offset:36864
	v_mfma_f32_16x16x32_bf16 v[42:45], v[126:129], v[106:109], v[42:45]
	ds_read_b128 v[102:105], v4 offset:2048
	v_mfma_f32_16x16x32_bf16 v[14:17], v[158:161], v[106:109], v[14:17]
	ds_read_b128 v[174:177], v5 offset:18432
	v_mfma_f32_16x16x32_bf16 v[90:93], v[154:157], v[106:109], v[90:93]
	global_load_dwordx4 v[106:109], v229, s[36:37] offset:1792
	v_mfma_f32_16x16x32_bf16 v[34:37], v[114:117], v[132:135], v[34:37]
	s_waitcnt vmcnt(8)
; template <int MODE>
; __device__ __forceinline__ void gemm_tile(const Params& P, int tm, int tn, unsigned char* smem) {
;     ...
; #pragma unroll
;         for (int i = 0; i < 4; ++i) { fa[i] = *(const bf16x8*)(sA + arow_off + i * 2048 + ch0); fb[i] = *(const bf16x8*)(sB + brow_off + i * 2048 + ch0); }
;         __builtin_amdgcn_sched_barrier(0);
;         __builtin_amdgcn_s_setprio(2);
;         if (wr_ok) *(uint4*)(nA + soff0) = ra0;
;         if (ld_ok) ra0 = *(const uint4*)(Ab + (aoff + 0u * LDA + koa));
;         ga[0] = *(const bf16x8*)(sA + arow_off + 0 * 2048 + ch1); gb[0] = *(const bf16x8*)(sB + brow_off + 0 * 2048 + ch1);
;         __builtin_amdgcn_sched_barrier(0);
; #pragma unroll
;         for (int j = 0; j < 4; ++j) acc[0][j] = __builtin_amdgcn_mfma_f32_16x16x32_bf16(fb[j], fa[0], acc[0][j], 0, 0, 0);
;         __builtin_amdgcn_sched_barrier(0);
;         if (wr_ok) *(uint4*)(nA + soff0 + 4096) = ra1;
;         if (ld_ok) ra1 = *(const uint4*)(Ab + (aoff + 32u * LDA + koa));
;         ga[1] = *(const bf16x8*)(sA + arow_off + 1 * 2048 + ch1); gb[1] = *(const bf16x8*)(sB + brow_off + 1 * 2048 + ch1);
;         __builtin_amdgcn_sched_barrier(0);
; #pragma unroll
;         for (int j = 0; j < 4; ++j) acc[1][j] = __builtin_amdgcn_mfma_f32_16x16x32_bf16(fb[j], fa[1], acc[1][j], 0, 0, 0);
;         __builtin_amdgcn_sched_barrier(0);
;         if (wr_ok) *(uint4*)(nA + soff0 + 8192) = ra2;
;         if (ld_ok) ra2 = *(const uint4*)(Ab + (aoff + 64u * LDA + koa));
;         ga[2] = *(const bf16x8*)(sA + arow_off + 2 * 2048 + ch1); gb[2] = *(const bf16x8*)(sB + brow_off + 2 * 2048 + ch1);
;         __builtin_amdgcn_sched_barrier(0);
; #pragma unroll
;         for (int j = 0; j < 4; ++j) acc[2][j] = __builtin_amdgcn_mfma_f32_16x16x32_bf16(fb[j], fa[2], acc[2][j], 0, 0, 0);
;         __builtin_amdgcn_sched_barrier(0);
;         if (wr_ok) *(uint4*)(nA + soff0 + 12288) = ra3;
;         if (ld_ok) ra3 = *(const uint4*)(Ab + (aoff + 96u * LDA + koa));
;         ga[3] = *(const bf16x8*)(sA + arow_off + 3 * 2048 + ch1); gb[3] = *(const bf16x8*)(sB + brow_off + 3 * 2048 + ch1);
;         __builtin_amdgcn_sched_barrier(0);
; #pragma unroll
;         for (int j = 0; j < 4; ++j) acc[3][j] = __builtin_amdgcn_mfma_f32_16x16x32_bf16(fb[j], fa[3], acc[3][j], 0, 0, 0);
;         __builtin_amdgcn_sched_barrier(0);
;         if (wr_ok) *(uint4*)(nB + soff0) = rb0;
	ds_write_b128 v2, v[110:113] offset:40960
	v_mfma_f32_16x16x32_bf16 v[46:49], v[126:129], v[132:135], v[46:49]
	ds_read_b128 v[110:113], v4 offset:4096
	v_mfma_f32_16x16x32_bf16 v[58:61], v[154:157], v[132:135], v[58:61]
	ds_read_b128 v[178:181], v5 offset:20480
	v_mfma_f32_16x16x32_bf16 v[18:21], v[158:161], v[132:135], v[18:21]
	global_load_dwordx4 v[132:135], v230, s[36:37] offset:1792
	v_mfma_f32_16x16x32_bf16 v[38:41], v[114:117], v[150:153], v[38:41]
	s_waitcnt vmcnt(8)
	ds_write_b128 v2, v[146:149] offset:45056
	v_mfma_f32_16x16x32_bf16 v[50:53], v[126:129], v[150:153], v[50:53]
	ds_read_b128 v[146:149], v4 offset:6144
	v_mfma_f32_16x16x32_bf16 v[54:57], v[154:157], v[150:153], v[54:57]
	ds_read_b128 v[182:185], v5 offset:22528
	v_mfma_f32_16x16x32_bf16 v[22:25], v[158:161], v[150:153], v[22:25]
	s_waitcnt lgkmcnt(9)
	v_mfma_f32_16x16x32_bf16 v[26:29], v[170:173], v[166:169], v[26:29]
	global_load_dwordx4 v[114:117], v3, s[0:1] offset:1792
	s_waitcnt lgkmcnt(0)
	v_mfma_f32_16x16x32_bf16 v[10:13], v[182:185], v[166:169], v[10:13]
	s_waitcnt vmcnt(8)
	ds_write_b128 v2, v[122:125] offset:49152
	v_mfma_f32_16x16x32_bf16 v[86:89], v[174:177], v[166:169], v[86:89]
	v_mfma_f32_16x16x32_bf16 v[94:97], v[178:181], v[166:169], v[94:97]
	global_load_dwordx4 v[122:125], v231, s[0:1] offset:1792
	v_mfma_f32_16x16x32_bf16 v[30:33], v[170:173], v[102:105], v[30:33]
	s_waitcnt vmcnt(8)
	ds_write_b128 v2, v[118:121] offset:53248
	v_mfma_f32_16x16x32_bf16 v[42:45], v[174:177], v[102:105], v[42:45]
	v_mfma_f32_16x16x32_bf16 v[14:17], v[182:185], v[102:105], v[14:17]
	v_mfma_f32_16x16x32_bf16 v[90:93], v[178:181], v[102:105], v[90:93]
	global_load_dwordx4 v[102:105], v232, s[0:1] offset:1792
	v_mfma_f32_16x16x32_bf16 v[34:37], v[170:173], v[110:113], v[34:37]
	s_waitcnt vmcnt(8)
	ds_write_b128 v2, v[62:65] offset:57344
	v_mfma_f32_16x16x32_bf16 v[46:49], v[174:177], v[110:113], v[46:49]
	v_mfma_f32_16x16x32_bf16 v[58:61], v[178:181], v[110:113], v[58:61]
	v_mfma_f32_16x16x32_bf16 v[18:21], v[182:185], v[110:113], v[18:21]
	global_load_dwordx4 v[62:65], v233, s[0:1] offset:1792
	v_mfma_f32_16x16x32_bf16 v[38:41], v[170:173], v[146:149], v[38:41]
	s_waitcnt vmcnt(8)
	ds_write_b128 v2, v[98:101] offset:61440
	v_mfma_f32_16x16x32_bf16 v[50:53], v[174:177], v[146:149], v[50:53]
	v_mfma_f32_16x16x32_bf16 v[54:57], v[178:181], v[146:149], v[54:57]
	v_mfma_f32_16x16x32_bf16 v[22:25], v[182:185], v[146:149], v[22:25]
	s_setprio 0
	s_waitcnt lgkmcnt(0)
	s_barrier
	ds_read_b128 v[98:101], v6 offset:32768
	ds_read_b128 v[110:113], v6 offset:34816
	ds_read_b128 v[118:121], v7 offset:49152
	ds_read_b128 v[126:129], v7 offset:51200
	ds_read_b128 v[146:149], v6 offset:36864
	ds_read_b128 v[150:153], v6 offset:38912
	ds_read_b128 v[154:157], v7 offset:53248
	ds_read_b128 v[158:161], v7 offset:55296
	s_setprio 2
	s_waitcnt lgkmcnt(5)
	v_mfma_f32_16x16x32_bf16 v[26:29], v[118:121], v[98:101], v[26:29]
	global_load_dwordx4 v[166:169], v8, s[36:37] offset:1920
	s_waitcnt lgkmcnt(0)
	v_mfma_f32_16x16x32_bf16 v[10:13], v[158:161], v[98:101], v[10:13]
	s_waitcnt vmcnt(8)
	ds_write_b128 v2, v[162:165]
	v_mfma_f32_16x16x32_bf16 v[86:89], v[126:129], v[98:101], v[86:89]
	ds_read_b128 v[162:165], v4 offset:32768
	v_mfma_f32_16x16x32_bf16 v[94:97], v[154:157], v[98:101], v[94:97]
	ds_read_b128 v[170:173], v5 offset:49152
	global_load_dwordx4 v[98:101], v228, s[36:37] offset:1920
	v_mfma_f32_16x16x32_bf16 v[30:33], v[118:121], v[110:113], v[30:33]
	s_waitcnt vmcnt(8)
	ds_write_b128 v2, v[82:85] offset:4096
	v_mfma_f32_16x16x32_bf16 v[42:45], v[126:129], v[110:113], v[42:45]
	ds_read_b128 v[82:85], v4 offset:34816
	v_mfma_f32_16x16x32_bf16 v[14:17], v[158:161], v[110:113], v[14:17]
	ds_read_b128 v[174:177], v5 offset:51200
	v_mfma_f32_16x16x32_bf16 v[90:93], v[154:157], v[110:113], v[90:93]
	global_load_dwordx4 v[110:113], v229, s[36:37] offset:1920
	v_mfma_f32_16x16x32_bf16 v[34:37], v[118:121], v[146:149], v[34:37]
	s_waitcnt vmcnt(8)
	ds_write_b128 v2, v[106:109] offset:8192
	v_mfma_f32_16x16x32_bf16 v[46:49], v[126:129], v[146:149], v[46:49]
	ds_read_b128 v[106:109], v4 offset:36864
	v_mfma_f32_16x16x32_bf16 v[58:61], v[154:157], v[146:149], v[58:61]
	ds_read_b128 v[178:181], v5 offset:53248
	v_mfma_f32_16x16x32_bf16 v[18:21], v[158:161], v[146:149], v[18:21]
	v_add_u32_e32 v8, 0x30780, v8
	global_load_dwordx4 v[146:149], v8, s[36:37]
	s_waitcnt vmcnt(8)
	ds_write_b128 v2, v[132:135] offset:12288
	ds_read_b128 v[132:135], v4 offset:38912
	ds_read_b128 v[182:185], v5 offset:55296
	v_mfma_f32_16x16x32_bf16 v[38:41], v[118:121], v[150:153], v[38:41]
	v_mfma_f32_16x16x32_bf16 v[50:53], v[126:129], v[150:153], v[50:53]
	v_mfma_f32_16x16x32_bf16 v[54:57], v[154:157], v[150:153], v[54:57]
	v_mfma_f32_16x16x32_bf16 v[22:25], v[158:161], v[150:153], v[22:25]
	s_waitcnt lgkmcnt(9)
	v_mfma_f32_16x16x32_bf16 v[26:29], v[170:173], v[162:165], v[26:29]
	global_load_dwordx4 v[118:121], v3, s[0:1] offset:1920
	s_waitcnt lgkmcnt(0)
	v_mfma_f32_16x16x32_bf16 v[8:11], v[182:185], v[162:165], v[10:13]
	s_waitcnt vmcnt(8)
	ds_write_b128 v2, v[114:117] offset:16384
	v_mfma_f32_16x16x32_bf16 v[86:89], v[174:177], v[162:165], v[86:89]
	v_mfma_f32_16x16x32_bf16 v[94:97], v[178:181], v[162:165], v[94:97]
	s_nop 0
	global_load_dwordx4 v[114:117], v231, s[0:1] offset:1920
	s_waitcnt vmcnt(8)
	ds_write_b128 v2, v[122:125] offset:20480
	v_mfma_f32_16x16x32_bf16 v[30:33], v[170:173], v[82:85], v[30:33]
	v_mfma_f32_16x16x32_bf16 v[42:45], v[174:177], v[82:85], v[42:45]
	v_mfma_f32_16x16x32_bf16 v[12:15], v[182:185], v[82:85], v[14:17]
	v_mfma_f32_16x16x32_bf16 v[90:93], v[178:181], v[82:85], v[90:93]
	s_nop 1
	global_load_dwordx4 v[82:85], v232, s[0:1] offset:1920
	s_waitcnt vmcnt(8)
	ds_write_b128 v2, v[102:105] offset:24576
	v_mfma_f32_16x16x32_bf16 v[34:37], v[170:173], v[106:109], v[34:37]
	v_mfma_f32_16x16x32_bf16 v[46:49], v[174:177], v[106:109], v[46:49]
	v_mfma_f32_16x16x32_bf16 v[58:61], v[178:181], v[106:109], v[58:61]
	v_mfma_f32_16x16x32_bf16 v[16:19], v[182:185], v[106:109], v[18:21]
	v_add_u32_e32 v3, 0x30780, v3
	global_load_dwordx4 v[102:105], v3, s[0:1]
	s_waitcnt vmcnt(8)
	ds_write_b128 v2, v[62:65] offset:28672
	v_mfma_f32_16x16x32_bf16 v[38:41], v[170:173], v[132:135], v[38:41]
	v_mfma_f32_16x16x32_bf16 v[50:53], v[174:177], v[132:135], v[50:53]
	v_mfma_f32_16x16x32_bf16 v[54:57], v[178:181], v[132:135], v[54:57]
	v_mfma_f32_16x16x32_bf16 v[20:23], v[182:185], v[132:135], v[22:25]
	s_setprio 0
	s_waitcnt lgkmcnt(0)
	s_barrier
; template <int MODE>
; __device__ __forceinline__ void gemm_tile(const Params& P, int tm, int tn, unsigned char* smem) {
;     ...
;     for (int kt = 0; kt < 16; ++kt) {
;         unsigned char* sA = (kt & 1) ? sA1 : sA0; unsigned char* sB = (kt & 1) ? sB1 : sB0;
;         unsigned char* nA = (kt & 1) ? sA0 : sA1; unsigned char* nB = (kt & 1) ? sB0 : sB1;
;         bf16x8 fa[4], fb[4], ga[4], gb[4];
;         const int ch0 = ((g ^ sw) << 4), ch1 = (((4 + g) ^ sw) << 4);
;         const unsigned ko = (unsigned)(kt + 2) * 128u;
;         const unsigned koa = ko + ((MODE == 2 && kt + 2 >= 8) ? (unsigned)(ZC_FQ - 512) * 2u : 0u);
;         const bool wr_ok = kt < 15, ld_ok = kt < 14;
; #pragma unroll
;         for (int i = 0; i < 4; ++i) { fa[i] = *(const bf16x8*)(sA + arow_off + i * 2048 + ch0); fb[i] = *(const bf16x8*)(sB + brow_off + i * 2048 + ch0); }
;         __builtin_amdgcn_sched_barrier(0);
;         __builtin_amdgcn_s_setprio(2);
;         if (wr_ok) *(uint4*)(nA + soff0) = ra0;
;         if (ld_ok) ra0 = *(const uint4*)(Ab + (aoff + 0u * LDA + koa));
;         ga[0] = *(const bf16x8*)(sA + arow_off + 0 * 2048 + ch1); gb[0] = *(const bf16x8*)(sB + brow_off + 0 * 2048 + ch1);
;         __builtin_amdgcn_sched_barrier(0);
; #pragma unroll
;         for (int j = 0; j < 4; ++j) acc[0][j] = __builtin_amdgcn_mfma_f32_16x16x32_bf16(fb[j], fa[0], acc[0][j], 0, 0, 0);
;         __builtin_amdgcn_sched_barrier(0);
;         if (wr_ok) *(uint4*)(nA + soff0 + 4096) = ra1;
;         if (ld_ok) ra1 = *(const uint4*)(Ab + (aoff + 32u * LDA + koa));
;         ga[1] = *(const bf16x8*)(sA + arow_off + 1 * 2048 + ch1); gb[1] = *(const bf16x8*)(sB + brow_off + 1 * 2048 + ch1);
;         __builtin_amdgcn_sched_barrier(0);
; #pragma unroll
;         for (int j = 0; j < 4; ++j) acc[1][j] = __builtin_amdgcn_mfma_f32_16x16x32_bf16(fb[j], fa[1], acc[1][j], 0, 0, 0);
;         __builtin_amdgcn_sched_barrier(0);
;         if (wr_ok) *(uint4*)(nA + soff0 + 8192) = ra2;
;         if (ld_ok) ra2 = *(const uint4*)(Ab + (aoff + 64u * LDA + koa));
;         ga[2] = *(const bf16x8*)(sA + arow_off + 2 * 2048 + ch1); gb[2] = *(const bf16x8*)(sB + brow_off + 2 * 2048 + ch1);
;         __builtin_amdgcn_sched_barrier(0);
; #pragma unroll
;         for (int j = 0; j < 4; ++j) acc[2][j] = __builtin_amdgcn_mfma_f32_16x16x32_bf16(fb[j], fa[2], acc[2][j], 0, 0, 0);
	ds_read_b128 v[62:65], v6
	ds_read_b128 v[106:109], v6 offset:2048
	ds_read_b128 v[122:125], v7 offset:16384
	ds_read_b128 v[126:129], v7 offset:18432
	ds_read_b128 v[132:135], v6 offset:4096
	ds_read_b128 v[150:153], v6 offset:6144
	ds_read_b128 v[154:157], v7 offset:20480
	ds_read_b128 v[158:161], v7 offset:22528
	s_setprio 2
	s_waitcnt lgkmcnt(5)
	v_mfma_f32_16x16x32_bf16 v[24:27], v[122:125], v[62:65], v[26:29]
	s_waitcnt lgkmcnt(0)
	v_mfma_f32_16x16x32_bf16 v[8:11], v[158:161], v[62:65], v[8:11]
	s_waitcnt vmcnt(7)
	ds_write_b128 v2, v[166:169] offset:32768
	v_mfma_f32_16x16x32_bf16 v[86:89], v[126:129], v[62:65], v[86:89]
	ds_read_b128 v[162:165], v4
	v_mfma_f32_16x16x32_bf16 v[94:97], v[154:157], v[62:65], v[94:97]
	ds_read_b128 v[166:169], v5 offset:16384
	v_mfma_f32_16x16x32_bf16 v[28:31], v[122:125], v[106:109], v[30:33]
	s_waitcnt vmcnt(6)
	ds_write_b128 v2, v[98:101] offset:36864
	v_mfma_f32_16x16x32_bf16 v[42:45], v[126:129], v[106:109], v[42:45]
	ds_read_b128 v[62:65], v4 offset:2048
	v_mfma_f32_16x16x32_bf16 v[12:15], v[158:161], v[106:109], v[12:15]
	ds_read_b128 v[98:101], v5 offset:18432
	v_mfma_f32_16x16x32_bf16 v[90:93], v[154:157], v[106:109], v[90:93]
	v_mfma_f32_16x16x32_bf16 v[32:35], v[122:125], v[132:135], v[34:37]
	s_waitcnt vmcnt(5)
	ds_write_b128 v2, v[110:113] offset:40960
	v_mfma_f32_16x16x32_bf16 v[46:49], v[126:129], v[132:135], v[46:49]
	ds_read_b128 v[106:109], v4 offset:4096
	v_mfma_f32_16x16x32_bf16 v[58:61], v[154:157], v[132:135], v[58:61]
	ds_read_b128 v[110:113], v5 offset:20480
	v_mfma_f32_16x16x32_bf16 v[16:19], v[158:161], v[132:135], v[16:19]
	v_mfma_f32_16x16x32_bf16 v[36:39], v[122:125], v[150:153], v[38:41]
	s_waitcnt vmcnt(4)
	ds_write_b128 v2, v[146:149] offset:45056
	v_mfma_f32_16x16x32_bf16 v[50:53], v[126:129], v[150:153], v[50:53]
	ds_read_b128 v[132:135], v4 offset:6144
	v_mfma_f32_16x16x32_bf16 v[54:57], v[154:157], v[150:153], v[54:57]
	ds_read_b128 v[146:149], v5 offset:22528
	v_mfma_f32_16x16x32_bf16 v[20:23], v[158:161], v[150:153], v[20:23]
	s_waitcnt lgkmcnt(9)
	v_mfma_f32_16x16x32_bf16 v[24:27], v[166:169], v[162:165], v[24:27]
	s_waitcnt lgkmcnt(0)
	v_mfma_f32_16x16x32_bf16 v[8:11], v[146:149], v[162:165], v[8:11]
	s_waitcnt vmcnt(3)
	ds_write_b128 v2, v[118:121] offset:49152
	v_mfma_f32_16x16x32_bf16 v[86:89], v[98:101], v[162:165], v[86:89]
	v_mfma_f32_16x16x32_bf16 v[94:97], v[110:113], v[162:165], v[94:97]
	v_mfma_f32_16x16x32_bf16 v[28:31], v[166:169], v[62:65], v[28:31]
	s_waitcnt vmcnt(2)
	ds_write_b128 v2, v[114:117] offset:53248
	v_mfma_f32_16x16x32_bf16 v[40:43], v[98:101], v[62:65], v[42:45]
	v_mfma_f32_16x16x32_bf16 v[12:15], v[146:149], v[62:65], v[12:15]
	v_mfma_f32_16x16x32_bf16 v[90:93], v[110:113], v[62:65], v[90:93]
	v_mfma_f32_16x16x32_bf16 v[32:35], v[166:169], v[106:109], v[32:35]
	s_waitcnt vmcnt(1)
	ds_write_b128 v2, v[82:85] offset:57344
	v_mfma_f32_16x16x32_bf16 v[44:47], v[98:101], v[106:109], v[46:49]
	v_mfma_f32_16x16x32_bf16 v[58:61], v[110:113], v[106:109], v[58:61]
	v_mfma_f32_16x16x32_bf16 v[16:19], v[146:149], v[106:109], v[16:19]
	v_mfma_f32_16x16x32_bf16 v[36:39], v[166:169], v[132:135], v[36:39]
	s_waitcnt vmcnt(0)
	ds_write_b128 v2, v[102:105] offset:61440
	v_mfma_f32_16x16x32_bf16 v[48:51], v[98:101], v[132:135], v[50:53]
	v_mfma_f32_16x16x32_bf16 v[52:55], v[110:113], v[132:135], v[54:57]
	v_mfma_f32_16x16x32_bf16 v[20:23], v[146:149], v[132:135], v[20:23]
	s_setprio 0
	s_waitcnt lgkmcnt(0)
	s_barrier
	ds_read_b128 v[62:65], v6 offset:32768
	ds_read_b128 v[82:85], v6 offset:34816
	ds_read_b128 v[98:101], v7 offset:49152
	ds_read_b128 v[102:105], v7 offset:51200
	ds_read_b128 v[106:109], v6 offset:36864
	ds_read_b128 v[110:113], v6 offset:38912
	ds_read_b128 v[114:117], v7 offset:53248
	ds_read_b128 v[118:121], v7 offset:55296
	s_setprio 2
	s_waitcnt lgkmcnt(5)
	v_mfma_f32_16x16x32_bf16 v[24:27], v[98:101], v[62:65], v[24:27]
	s_waitcnt lgkmcnt(0)
	v_mfma_f32_16x16x32_bf16 v[6:9], v[118:121], v[62:65], v[8:11]
	ds_read_b128 v[122:125], v4 offset:32768
	v_mfma_f32_16x16x32_bf16 v[86:89], v[102:105], v[62:65], v[86:89]
	ds_read_b128 v[126:129], v5 offset:49152
	v_mfma_f32_16x16x32_bf16 v[94:97], v[114:117], v[62:65], v[94:97]
	v_mfma_f32_16x16x32_bf16 v[28:31], v[98:101], v[82:85], v[28:31]
	ds_read_b128 v[132:135], v4 offset:34816
	v_mfma_f32_16x16x32_bf16 v[40:43], v[102:105], v[82:85], v[40:43]
	ds_read_b128 v[146:149], v5 offset:51200
	v_mfma_f32_16x16x32_bf16 v[10:13], v[118:121], v[82:85], v[12:15]
	v_mfma_f32_16x16x32_bf16 v[90:93], v[114:117], v[82:85], v[90:93]
	v_mfma_f32_16x16x32_bf16 v[14:17], v[118:121], v[106:109], v[16:19]
	ds_read_b128 v[82:85], v4 offset:36864
	v_mfma_f32_16x16x32_bf16 v[154:157], v[98:101], v[106:109], v[32:35]
	ds_read_b128 v[150:153], v5 offset:53248
	v_mfma_f32_16x16x32_bf16 v[158:161], v[102:105], v[106:109], v[44:47]
	v_mfma_f32_16x16x32_bf16 v[162:165], v[114:117], v[106:109], v[58:61]
	v_mfma_f32_16x16x32_bf16 v[98:101], v[98:101], v[110:113], v[36:39]
	ds_read_b128 v[106:109], v4 offset:38912
	v_mfma_f32_16x16x32_bf16 v[102:105], v[102:105], v[110:113], v[48:51]
	ds_read_b128 v[2:5], v5 offset:55296
	v_mfma_f32_16x16x32_bf16 v[114:117], v[114:117], v[110:113], v[52:55]
	v_mfma_f32_16x16x32_bf16 v[110:113], v[118:121], v[110:113], v[20:23]
	s_waitcnt lgkmcnt(6)
	v_mfma_f32_16x16x32_bf16 v[62:65], v[126:129], v[122:125], v[24:27]
	s_waitcnt lgkmcnt(4)
	v_mfma_f32_16x16x32_bf16 v[58:61], v[146:149], v[122:125], v[86:89]
	s_waitcnt lgkmcnt(2)
	v_mfma_f32_16x16x32_bf16 v[54:57], v[150:153], v[122:125], v[94:97]
	s_waitcnt lgkmcnt(0)
	v_mfma_f32_16x16x32_bf16 v[50:53], v[2:5], v[122:125], v[6:9]
	v_mfma_f32_16x16x32_bf16 v[46:49], v[126:129], v[132:135], v[28:31]
	v_mfma_f32_16x16x32_bf16 v[42:45], v[146:149], v[132:135], v[40:43]
	v_mfma_f32_16x16x32_bf16 v[38:41], v[150:153], v[132:135], v[90:93]
	v_mfma_f32_16x16x32_bf16 v[34:37], v[2:5], v[132:135], v[10:13]
	v_mfma_f32_16x16x32_bf16 v[30:33], v[126:129], v[82:85], v[154:157]
	v_mfma_f32_16x16x32_bf16 v[26:29], v[146:149], v[82:85], v[158:161]
	v_mfma_f32_16x16x32_bf16 v[22:25], v[150:153], v[82:85], v[162:165]
	v_mfma_f32_16x16x32_bf16 v[18:21], v[2:5], v[82:85], v[14:17]
	v_mfma_f32_16x16x32_bf16 v[14:17], v[126:129], v[106:109], v[98:101]
	v_mfma_f32_16x16x32_bf16 v[10:13], v[146:149], v[106:109], v[102:105]
	v_mfma_f32_16x16x32_bf16 v[6:9], v[150:153], v[106:109], v[114:117]
	v_mfma_f32_16x16x32_bf16 v[2:5], v[2:5], v[106:109], v[110:113]
	s_setprio 0
	s_and_b32 s0, s5, -8
	s_cmp_lg_u32 s0, 16
	s_barrier
; template <int MODE>
; __device__ __forceinline__ void gemm_tile(const Params& P, int tm, int tn, unsigned char* smem) {
;     ...
;         if (n0 >= ZC_FQ && n0 < ZC_FV) {
;             const bool isk = n0 >= ZC_FK;
;             const float* gain = isk ? P.f_k_norm : P.f_q_norm;
;             const float scl = isk ? 1.0f : 0.125f * LOG2E;
;             float gn[4][4];
; #pragma unroll
;             for (int j = 0; j < 4; ++j)
; #pragma unroll
;                 for (int r = 0; r < 4; ++r) gn[j][r] = gain[16 * j + 4 * g + r];
; #pragma unroll
;             for (int i = 0; i < 4; ++i) {
;                 float ss = 0.f;
; #pragma unroll
;                 for (int j = 0; j < 4; ++j)
; #pragma unroll
;                     for (int r = 0; r < 4; ++r) ss += acc[i][j][r] * acc[i][j][r];
;                 ss = x4_sum(ss);
;                 const float rstd = rsqrtf(ss * (1.0f / 64.0f) + EPS) * scl;
	s_cbranch_scc1 .LBB0_244
	v_mul_f32_e32 v68, v63, v63
	v_fmac_f32_e32 v68, v62, v62
	v_fmac_f32_e32 v68, v64, v64
	v_fmac_f32_e32 v68, v65, v65
	v_fmac_f32_e32 v68, v58, v58
	v_fmac_f32_e32 v68, v59, v59
	v_fmac_f32_e32 v68, v60, v60
	v_fmac_f32_e32 v68, v61, v61
	v_fmac_f32_e32 v68, v54, v54
	v_fmac_f32_e32 v68, v55, v55
	v_fmac_f32_e32 v68, v56, v56
	s_cmp_gt_u32 s5, 19
	v_fmac_f32_e32 v68, v57, v57
	v_pk_mul_f32 v[82:83], v[50:51], v[50:51]
	v_mov_b32_e32 v66, 0x3e38aa3b
	s_cselect_b64 s[0:1], -1, 0
	v_add_f32_e32 v68, v82, v68
	v_cndmask_b32_e64 v106, v66, 1.0, s[0:1]
	v_pk_mul_f32 v[66:67], v[52:53], v[52:53]
	v_add_f32_e32 v68, v83, v68
	v_add_f32_e32 v66, v66, v68
	v_add_f32_e32 v66, v67, v66
	v_mov_b32_e32 v67, v66
	s_nop 1
	v_permlane32_swap_b32_e32 v66, v67
	v_add_f32_e32 v67, v66, v67
	v_mul_f32_e32 v66, v47, v47
	v_fmac_f32_e32 v66, v46, v46
	v_fmac_f32_e32 v66, v48, v48
	v_fmac_f32_e32 v66, v49, v49
	v_fmac_f32_e32 v66, v42, v42
	v_fmac_f32_e32 v66, v43, v43
	v_fmac_f32_e32 v66, v44, v44
	v_fmac_f32_e32 v66, v45, v45
	v_fmac_f32_e32 v66, v38, v38
	v_fmac_f32_e32 v66, v39, v39
	v_fmac_f32_e32 v66, v40, v40
	v_fmac_f32_e32 v66, v41, v41
	v_pk_mul_f32 v[86:87], v[34:35], v[34:35]
	v_pk_mul_f32 v[84:85], v[36:37], v[36:37]
	v_add_f32_e32 v66, v86, v66
	v_add_f32_e32 v66, v87, v66
	v_add_f32_e32 v66, v84, v66
	v_add_f32_e32 v66, v85, v66
	v_mov_b32_e32 v68, v66
	s_nop 1
	v_permlane32_swap_b32_e32 v66, v68
	v_add_f32_e32 v66, v66, v68
	s_and_b64 s[0:1], s[0:1], exec
	v_mov_b32_e32 v83, v67
	v_mov_b32_e32 v82, v66
	s_nop 0
	v_permlane16_swap_b32_e32 v67, v83
	v_permlane16_swap_b32_e32 v66, v82
	s_mov_b32 s0, 0x358637bd
	v_pk_add_f32 v[82:83], v[66:67], v[82:83]
	s_mov_b32 s8, 0x3c800000
	v_mov_b64_e32 v[66:67], s[0:1]
	v_mul_f32_e32 v95, v31, v31
	v_pk_fma_f32 v[86:87], v[82:83], s[8:9], v[66:67] op_sel_hi:[1,0,0]
	s_mov_b32 s5, 0x800000
	v_fmac_f32_e32 v95, v30, v30
	v_mul_f32_e32 v68, 0x4b800000, v87
	v_cmp_gt_f32_e32 vcc, s5, v87
	v_fmac_f32_e32 v95, v32, v32
	v_fmac_f32_e32 v95, v33, v33
	v_cndmask_b32_e32 v68, v87, v68, vcc
	v_rsq_f32_e32 v68, v68
	v_mul_f32_e32 v70, 0x4b800000, v86
	v_cmp_gt_f32_e64 s[0:1], s5, v86
	v_fmac_f32_e32 v95, v26, v26
	v_fmac_f32_e32 v95, v27, v27
	v_cndmask_b32_e64 v70, v86, v70, s[0:1]
	v_rsq_f32_e32 v86, v70
	v_fmac_f32_e32 v95, v28, v28
	s_cselect_b32 s7, s41, s39
	s_cselect_b32 s6, s40, s38
	v_lshlrev_b32_e32 v94, 4, v81
	v_fmac_f32_e32 v95, v29, v29
	global_load_dwordx4 v[82:85], v94, s[6:7]
	v_mul_f32_e32 v70, 0x45800000, v68
	v_fmac_f32_e32 v95, v22, v22
	v_cndmask_b32_e32 v68, v68, v70, vcc
	v_fmac_f32_e32 v95, v23, v23
	v_mul_f32_e32 v70, v106, v68
	v_mul_f32_e32 v68, 0x45800000, v86
	v_fmac_f32_e32 v95, v24, v24
	v_cndmask_b32_e64 v68, v86, v68, s[0:1]
	global_load_dwordx4 v[86:89], v94, s[6:7] offset:64
	v_fmac_f32_e32 v95, v25, v25
	v_pk_mul_f32 v[92:93], v[18:19], v[18:19]
	v_pk_mul_f32 v[90:91], v[20:21], v[20:21]
	v_add_f32_e32 v92, v92, v95
	v_add_f32_e32 v92, v93, v92
	v_add_f32_e32 v90, v90, v92
	v_add_f32_e32 v95, v91, v90
	global_load_dwordx4 v[90:93], v94, s[6:7] offset:128
	v_mov_b32_e32 v96, v95
	s_nop 1
	v_permlane32_swap_b32_e32 v95, v96
	v_add_f32_e32 v99, v95, v96
	global_load_dwordx4 v[94:97], v94, s[6:7] offset:192
	v_mul_f32_e32 v98, v15, v15
	v_fmac_f32_e32 v98, v14, v14
	v_fmac_f32_e32 v98, v16, v16
	v_fmac_f32_e32 v98, v17, v17
	v_fmac_f32_e32 v98, v10, v10
	v_fmac_f32_e32 v98, v11, v11
	v_fmac_f32_e32 v98, v12, v12
	v_fmac_f32_e32 v98, v13, v13
	v_fmac_f32_e32 v98, v6, v6
	v_fmac_f32_e32 v98, v7, v7
	v_fmac_f32_e32 v98, v8, v8
	v_fmac_f32_e32 v98, v9, v9
	v_pk_mul_f32 v[104:105], v[2:3], v[2:3]
	v_pk_mul_f32 v[102:103], v[4:5], v[4:5]
	v_add_f32_e32 v98, v104, v98
	v_add_f32_e32 v98, v105, v98
	v_add_f32_e32 v98, v102, v98
	v_add_f32_e32 v98, v103, v98
	v_mov_b32_e32 v100, v98
	s_nop 1
	v_permlane32_swap_b32_e32 v98, v100
	v_add_f32_e32 v98, v98, v100
	v_mov_b32_e32 v101, v99
	v_mov_b32_e32 v100, v98
	s_nop 0
	v_permlane16_swap_b32_e32 v99, v101
	v_permlane16_swap_b32_e32 v98, v100
	v_pk_add_f32 v[98:99], v[98:99], v[100:101]
	v_mul_f32_e32 v68, v106, v68
	v_pk_fma_f32 v[66:67], v[98:99], s[8:9], v[66:67] op_sel_hi:[1,0,0]
	s_waitcnt vmcnt(3)
; template <int MODE>
; __device__ __forceinline__ void gemm_tile(const Params& P, int tm, int tn, unsigned char* smem) {
;     ...
; #pragma unroll
;                 for (int j = 0; j < 4; ++j)
; #pragma unroll
;                     for (int r = 0; r < 4; ++r) acc[i][j][r] *= rstd * gn[j][r];
;             }
	v_pk_mul_f32 v[100:101], v[82:83], v[70:71] op_sel_hi:[1,0]
	v_mul_f32_e32 v98, 0x4b800000, v67
	v_cmp_gt_f32_e32 vcc, s5, v67
	v_cmp_gt_f32_e64 s[0:1], s5, v66
	v_pk_mul_f32 v[62:63], v[62:63], v[100:101]
	v_cndmask_b32_e32 v67, v67, v98, vcc
	v_mul_f32_e32 v98, 0x4b800000, v66
	v_rsq_f32_e32 v67, v67
	v_cndmask_b32_e64 v66, v66, v98, s[0:1]
	v_rsq_f32_e32 v98, v66
	v_pk_mul_f32 v[100:101], v[82:83], v[68:69] op_sel_hi:[1,0]
	v_mul_f32_e32 v66, 0x45800000, v67
	v_cndmask_b32_e32 v66, v67, v66, vcc
	v_mul_f32_e32 v67, 0x45800000, v98
	v_cndmask_b32_e64 v67, v98, v67, s[0:1]
	v_mul_f32_e32 v66, v106, v66
	v_mul_f32_e32 v98, v106, v67
	v_pk_mul_f32 v[102:103], v[84:85], v[70:71] op_sel_hi:[1,0]
	v_pk_mul_f32 v[46:47], v[46:47], v[100:101]
	v_pk_mul_f32 v[100:101], v[82:83], v[66:67] op_sel_hi:[1,0]
	v_pk_mul_f32 v[82:83], v[82:83], v[98:99] op_sel_hi:[1,0]
	v_pk_mul_f32 v[64:65], v[64:65], v[102:103]
	v_pk_mul_f32 v[102:103], v[84:85], v[68:69] op_sel_hi:[1,0]
	v_pk_mul_f32 v[14:15], v[14:15], v[82:83]
	s_waitcnt vmcnt(2)
	v_pk_mul_f32 v[82:83], v[86:87], v[70:71] op_sel_hi:[1,0]
	v_pk_mul_f32 v[48:49], v[48:49], v[102:103]
	v_pk_mul_f32 v[102:103], v[84:85], v[66:67] op_sel_hi:[1,0]
	v_pk_mul_f32 v[84:85], v[84:85], v[98:99] op_sel_hi:[1,0]
	v_pk_mul_f32 v[58:59], v[58:59], v[82:83]
	v_pk_mul_f32 v[82:83], v[86:87], v[68:69] op_sel_hi:[1,0]
	v_pk_mul_f32 v[16:17], v[16:17], v[84:85]
	v_pk_mul_f32 v[84:85], v[88:89], v[70:71] op_sel_hi:[1,0]
	v_pk_mul_f32 v[42:43], v[42:43], v[82:83]
	v_pk_mul_f32 v[82:83], v[86:87], v[66:67] op_sel_hi:[1,0]
	v_pk_mul_f32 v[60:61], v[60:61], v[84:85]
	v_pk_mul_f32 v[84:85], v[88:89], v[68:69] op_sel_hi:[1,0]
	v_pk_mul_f32 v[26:27], v[26:27], v[82:83]
	v_pk_mul_f32 v[82:83], v[86:87], v[98:99] op_sel_hi:[1,0]
	v_pk_mul_f32 v[44:45], v[44:45], v[84:85]
	v_pk_mul_f32 v[84:85], v[88:89], v[66:67] op_sel_hi:[1,0]
	v_pk_mul_f32 v[10:11], v[10:11], v[82:83]
	s_waitcnt vmcnt(1)
	v_pk_mul_f32 v[82:83], v[90:91], v[70:71] op_sel_hi:[1,0]
	v_pk_mul_f32 v[28:29], v[28:29], v[84:85]
	v_pk_mul_f32 v[84:85], v[88:89], v[98:99] op_sel_hi:[1,0]
	v_pk_mul_f32 v[54:55], v[54:55], v[82:83]
	v_pk_mul_f32 v[82:83], v[90:91], v[68:69] op_sel_hi:[1,0]
	v_pk_mul_f32 v[12:13], v[12:13], v[84:85]
	v_pk_mul_f32 v[84:85], v[92:93], v[70:71] op_sel_hi:[1,0]
	v_pk_mul_f32 v[38:39], v[38:39], v[82:83]
	v_pk_mul_f32 v[82:83], v[90:91], v[66:67] op_sel_hi:[1,0]
	v_pk_mul_f32 v[56:57], v[56:57], v[84:85]
	v_pk_mul_f32 v[84:85], v[92:93], v[68:69] op_sel_hi:[1,0]
	v_pk_mul_f32 v[22:23], v[22:23], v[82:83]
	v_pk_mul_f32 v[82:83], v[90:91], v[98:99] op_sel_hi:[1,0]
	v_pk_mul_f32 v[40:41], v[40:41], v[84:85]
	v_pk_mul_f32 v[84:85], v[92:93], v[66:67] op_sel_hi:[1,0]
	v_pk_mul_f32 v[6:7], v[6:7], v[82:83]
	s_waitcnt vmcnt(0)
	v_pk_mul_f32 v[82:83], v[94:95], v[70:71] op_sel_hi:[1,0]
	v_pk_mul_f32 v[24:25], v[24:25], v[84:85]
	v_pk_mul_f32 v[84:85], v[92:93], v[98:99] op_sel_hi:[1,0]
	v_pk_mul_f32 v[50:51], v[50:51], v[82:83]
	v_pk_mul_f32 v[82:83], v[94:95], v[68:69] op_sel_hi:[1,0]
	v_pk_mul_f32 v[8:9], v[8:9], v[84:85]
	v_pk_mul_f32 v[84:85], v[96:97], v[70:71] op_sel_hi:[1,0]
	v_pk_mul_f32 v[34:35], v[34:35], v[82:83]
	v_pk_mul_f32 v[82:83], v[94:95], v[66:67] op_sel_hi:[1,0]
	v_pk_mul_f32 v[66:67], v[96:97], v[66:67] op_sel_hi:[1,0]
	v_pk_mul_f32 v[52:53], v[52:53], v[84:85]
	v_pk_mul_f32 v[84:85], v[96:97], v[68:69] op_sel_hi:[1,0]
	v_pk_mul_f32 v[20:21], v[20:21], v[66:67]
	v_pk_mul_f32 v[18:19], v[18:19], v[82:83]
	v_pk_mul_f32 v[66:67], v[94:95], v[98:99] op_sel_hi:[1,0]
	v_pk_mul_f32 v[82:83], v[96:97], v[98:99] op_sel_hi:[1,0]
	v_pk_mul_f32 v[32:33], v[32:33], v[102:103]
	v_pk_mul_f32 v[30:31], v[30:31], v[100:101]
	v_pk_mul_f32 v[36:37], v[36:37], v[84:85]
	v_pk_mul_f32 v[4:5], v[4:5], v[82:83]
	v_pk_mul_f32 v[2:3], v[2:3], v[66:67]

; template <int MODE>
; __device__ __forceinline__ void gemm_tile(const Params& P, int tm, int tn, unsigned char* smem) {
;     ...
;         aoff = (unsigned)ar * LDA + (unsigned)sc * 16u;
;         boff = (unsigned)(n0 + srow) * 2048u + (unsigned)sc * 16u;
;         soff0 = srow * 128 + ((sc ^ (srow & 7)) << 4);
;     }
;     const unsigned char* Ab = (const unsigned char*)A; const unsigned char* Bb = (const unsigned char*)Bt;
;     float4 ssp0, ssp1, ssp2, ssp3;
;     if (MODE == 3) {
;         const float* ssq = (const float*)(P.ws + WS_SSQ) + (size_t)(m0 + wr * 64 + lr) * 16 + 4 * g;
;         ssp0 = *(const float4*)(ssq); ssp1 = *(const float4*)(ssq + 16 * 16); ssp2 = *(const float4*)(ssq + 32 * 16); ssp3 = *(const float4*)(ssq + 48 * 16);
;     }
;     f32x4 acc[4][4];
; #pragma unroll
;     for (int i = 0; i < 4; ++i)
; #pragma unroll
;         for (int j = 0; j < 4; ++j) acc[i][j] = (f32x4){0.f, 0.f, 0.f, 0.f};
;     uint4 ra0, ra1, ra2, ra3, rb0, rb1, rb2, rb3;
;     ...
;     unsigned char* sA0 = smem; unsigned char* sB0 = smem + 16384; unsigned char* sA1 = smem + 32768; unsigned char* sB1 = smem + 49152;
;     G_LOAD(0)
;     G_WRITE(sA0, sB0)
;     __syncthreads();
;     const int arow_off = (wr * 64 + lr) * 128, brow_off = (wc * 64 + lr) * 128, sw = lr & 7;
;     G_LOAD(1)
;     for (int kt = 0; kt < 16; ++kt) {
;         unsigned char* sA = (kt & 1) ? sA1 : sA0; unsigned char* sB = (kt & 1) ? sB1 : sB0;
;         unsigned char* nA = (kt & 1) ? sA0 : sA1; unsigned char* nB = (kt & 1) ? sB0 : sB1;
;         bf16x8 fa[4], fb[4], ga[4], gb[4];
;         const int ch0 = ((g ^ sw) << 4), ch1 = (((4 + g) ^ sw) << 4);
;         const unsigned ko = (unsigned)(kt + 2) * 128u;
;         const unsigned koa = ko + ((MODE == 2 && kt + 2 >= 8) ? (unsigned)(ZC_FQ - 512) * 2u : 0u);
;         const bool wr_ok = kt < 15, ld_ok = kt < 14;
; #pragma unroll
;         for (int i = 0; i < 4; ++i) { fa[i] = *(const bf16x8*)(sA + arow_off + i * 2048 + ch0); fb[i] = *(const bf16x8*)(sB + brow_off + i * 2048 + ch0); }
;         __builtin_amdgcn_sched_barrier(0);
;         __builtin_amdgcn_s_setprio(2);
;         if (wr_ok) *(uint4*)(nA + soff0) = ra0;
;         if (ld_ok) ra0 = *(const uint4*)(Ab + (aoff + 0u * LDA + koa));
;         ga[0] = *(const bf16x8*)(sA + arow_off + 0 * 2048 + ch1); gb[0] = *(const bf16x8*)(sB + brow_off + 0 * 2048 + ch1);
.LBB0_1263:
	s_lshr_b32 s0, s14, 4
	s_and_b32 s0, s0, 0x1fffff8
	s_and_b32 s1, s14, 7
	s_or_b32 s0, s0, s1
	v_mov_b32_e32 v88, v0
	s_bfe_u32 s2, s14, 0x40003
	s_lshl_b32 s23, s0, 7
	v_ashrrev_i32_e32 v6, 3, v88
	v_lshlrev_b32_e32 v3, 4, v88
	v_add_u32_e32 v2, s23, v6
	v_and_b32_e32 v3, 0x70, v3
	s_lshl_b32 s0, s2, 18
	v_lshl_add_u32 v4, v6, 11, s0
	v_lshl_or_b32 v24, v2, 11, v3
	v_or_b32_e32 v18, v4, v3
	v_add_u32_e32 v2, 0x10000, v24
	v_add_u32_e32 v3, 0x20000, v24
	global_load_dwordx4 v[20:23], v2, s[36:37]
	global_load_dwordx4 v[26:29], v3, s[36:37]
	v_add_u32_e32 v2, 0x20000, v18
	v_add_u32_e32 v3, 0x30000, v18
	global_load_dwordx4 v[30:33], v2, s[6:7]
	global_load_dwordx4 v[34:37], v3, s[6:7]
	v_add_u32_e32 v2, 0x30000, v24
	v_add_u32_e32 v3, 0x10000, v18
	global_load_dwordx4 v[38:41], v2, s[36:37]
	global_load_dwordx4 v[42:45], v3, s[6:7]
	global_load_dwordx4 v[46:49], v24, s[36:37]
	global_load_dwordx4 v[50:53], v18, s[6:7]
	v_ashrrev_i32_e32 v2, 1, v88
	v_and_b32_e32 v25, 0xffffffc0, v2
	v_and_b32_e32 v90, 15, v88
	v_add_u32_e32 v2, s23, v25
	v_or_b32_e32 v84, v2, v90
	v_ashrrev_i32_e32 v85, 31, v84
	v_xor_b32_e32 v7, v6, v88
	v_bfe_u32 v89, v88, 4, 2
	v_lshlrev_b64 v[2:3], 6, v[84:85]
	v_lshlrev_b32_e32 v6, 7, v6
	v_lshlrev_b32_e32 v7, 4, v7
	v_lshlrev_b32_e32 v82, 4, v89
	v_lshl_add_u64 v[2:3], s[4:5], 0, v[2:3]
	v_and_or_b32 v6, v7, s15, v6
	v_lshl_add_u64 v[54:55], v[2:3], 0, v[82:83]
	v_add_u32_e32 v19, 0, v6
	v_or_b32_e32 v62, 0x80, v24
	global_load_dwordx4 v[10:13], v[54:55], off
	global_load_dwordx4 v[2:5], v[54:55], off offset:3072
	v_or_b32_e32 v58, 0x80, v18
	v_add_u32_e32 v59, 0x10080, v18
	v_add_u32_e32 v60, 0x20080, v18
	v_add_u32_e32 v61, 0x30080, v18
	v_add_u32_e32 v63, 0x10080, v24
	v_add_u32_e32 v64, 0x20080, v24
	v_add_u32_e32 v65, 0x30080, v24
	global_load_dwordx4 v[14:17], v[54:55], off offset:1024
	global_load_dwordx4 v[6:9], v[54:55], off offset:2048
	v_or_b32_e32 v82, v25, v90
	v_and_b32_e32 v25, 7, v88
	v_bfe_u32 v91, v88, 6, 1
	v_lshl_add_u32 v104, v82, 7, 0
	s_waitcnt vmcnt(9)
	ds_write_b128 v19, v[30:33] offset:24576
	s_waitcnt vmcnt(8)
	ds_write_b128 v19, v[34:37] offset:28672
	ds_write_b128 v19, v[20:23] offset:4096
	ds_write_b128 v19, v[26:29] offset:8192
	s_waitcnt vmcnt(7)
	ds_write_b128 v19, v[38:41] offset:12288
	s_waitcnt vmcnt(6)
	ds_write_b128 v19, v[42:45] offset:20480
	s_waitcnt vmcnt(5)
	ds_write_b128 v19, v[46:49]
	s_waitcnt vmcnt(4)
	ds_write_b128 v19, v[50:53] offset:16384
	s_waitcnt lgkmcnt(0)
	s_barrier
	global_load_dwordx4 v[26:29], v62, s[36:37]
	global_load_dwordx4 v[30:33], v63, s[36:37]
	global_load_dwordx4 v[34:37], v64, s[36:37]
	global_load_dwordx4 v[38:41], v65, s[36:37]
	global_load_dwordx4 v[42:45], v58, s[6:7]
	global_load_dwordx4 v[46:49], v59, s[6:7]
	global_load_dwordx4 v[50:53], v60, s[6:7]
	global_load_dwordx4 v[54:57], v61, s[6:7]
	v_lshrrev_b32_e32 v20, 4, v88
	v_lshlrev_b32_e32 v21, 7, v90
	v_bitop3_b32 v20, v20, v25, 3 bitop3:0x6c
	v_lshl_or_b32 v21, v91, 13, v21
	v_lshlrev_b32_e32 v20, 4, v20
	v_add_u32_e32 v22, v104, v20
	v_add_u32_e32 v21, 0, v21
	v_add_u32_e32 v23, v21, v20
	ds_read_b128 v[58:61], v22
	ds_read_b128 v[62:65], v22 offset:2048
	ds_read_b128 v[66:69], v23 offset:16384
	ds_read_b128 v[70:73], v23 offset:18432
	ds_read_b128 v[74:77], v22 offset:4096
	ds_read_b128 v[78:81], v22 offset:6144
	ds_read_b128 v[92:95], v23 offset:20480
	ds_read_b128 v[96:99], v23 offset:22528
	v_bitop3_b32 v20, v89, v25, 4 bitop3:0x36
	v_lshlrev_b32_e32 v25, 4, v20
	s_setprio 2
	global_load_dwordx4 v[100:103], v24, s[36:37] offset:256
	s_waitcnt vmcnt(8)
	ds_write_b128 v19, v[26:29] offset:32768
	v_add_u32_e32 v20, v104, v25
	v_add_u32_e32 v21, v21, v25
	ds_read_b128 v[26:29], v20
	ds_read_b128 v[104:107], v21 offset:16384
	s_waitcnt lgkmcnt(8)
	v_mfma_f32_16x16x32_bf16 v[108:111], v[66:69], v[58:61], 0
	s_waitcnt lgkmcnt(7)
	v_mfma_f32_16x16x32_bf16 v[112:115], v[70:73], v[58:61], 0
	s_waitcnt lgkmcnt(4)
	v_mfma_f32_16x16x32_bf16 v[116:119], v[92:95], v[58:61], 0
	s_waitcnt lgkmcnt(3)
	v_mfma_f32_16x16x32_bf16 v[58:61], v[96:99], v[58:61], 0
	v_add_u32_e32 v245, 0x10000, v24
	global_load_dwordx4 v[120:123], v245, s[36:37] offset:256
	s_waitcnt vmcnt(8)
	ds_write_b128 v19, v[30:33] offset:36864
	ds_read_b128 v[30:33], v20 offset:2048
	ds_read_b128 v[124:127], v21 offset:18432
	v_mfma_f32_16x16x32_bf16 v[132:135], v[66:69], v[62:65], 0
	v_mfma_f32_16x16x32_bf16 v[136:139], v[70:73], v[62:65], 0
	v_mfma_f32_16x16x32_bf16 v[140:143], v[92:95], v[62:65], 0
	v_mfma_f32_16x16x32_bf16 v[62:65], v[96:99], v[62:65], 0
	v_add_u32_e32 v246, 0x20000, v24
	global_load_dwordx4 v[144:147], v246, s[36:37] offset:256
	s_waitcnt vmcnt(8)
	ds_write_b128 v19, v[34:37] offset:40960
	ds_read_b128 v[34:37], v20 offset:4096
	ds_read_b128 v[148:151], v21 offset:20480
	v_mfma_f32_16x16x32_bf16 v[152:155], v[66:69], v[74:77], 0
	v_mfma_f32_16x16x32_bf16 v[156:159], v[70:73], v[74:77], 0
	v_mfma_f32_16x16x32_bf16 v[160:163], v[92:95], v[74:77], 0
	v_mfma_f32_16x16x32_bf16 v[74:77], v[96:99], v[74:77], 0
	v_add_u32_e32 v247, 0x30000, v24
	global_load_dwordx4 v[164:167], v247, s[36:37] offset:256
	s_waitcnt vmcnt(8)
	ds_write_b128 v19, v[38:41] offset:45056
	ds_read_b128 v[38:41], v20 offset:6144
	ds_read_b128 v[168:171], v21 offset:22528
	v_mfma_f32_16x16x32_bf16 v[66:69], v[66:69], v[78:81], 0
	v_mfma_f32_16x16x32_bf16 v[70:73], v[70:73], v[78:81], 0
	v_mfma_f32_16x16x32_bf16 v[92:95], v[92:95], v[78:81], 0
	v_mfma_f32_16x16x32_bf16 v[78:81], v[96:99], v[78:81], 0
	global_load_dwordx4 v[96:99], v18, s[6:7] offset:256
	s_waitcnt vmcnt(8)
	ds_write_b128 v19, v[42:45] offset:49152
	s_waitcnt lgkmcnt(10)
; template <int MODE>
; __device__ __forceinline__ void gemm_tile(const Params& P, int tm, int tn, unsigned char* smem) {
;     ...
; #pragma unroll
;         for (int i = 0; i < 4; ++i) { fa[i] = *(const bf16x8*)(sA + arow_off + i * 2048 + ch0); fb[i] = *(const bf16x8*)(sB + brow_off + i * 2048 + ch0); }
;         __builtin_amdgcn_sched_barrier(0);
;         __builtin_amdgcn_s_setprio(2);
;         if (wr_ok) *(uint4*)(nA + soff0) = ra0;
;         if (ld_ok) ra0 = *(const uint4*)(Ab + (aoff + 0u * LDA + koa));
;         ga[0] = *(const bf16x8*)(sA + arow_off + 0 * 2048 + ch1); gb[0] = *(const bf16x8*)(sB + brow_off + 0 * 2048 + ch1);
;         __builtin_amdgcn_sched_barrier(0);
; #pragma unroll
;         for (int j = 0; j < 4; ++j) acc[0][j] = __builtin_amdgcn_mfma_f32_16x16x32_bf16(fb[j], fa[0], acc[0][j], 0, 0, 0);
;         __builtin_amdgcn_sched_barrier(0);
;         if (wr_ok) *(uint4*)(nA + soff0 + 4096) = ra1;
;         if (ld_ok) ra1 = *(const uint4*)(Ab + (aoff + 32u * LDA + koa));
;         ga[1] = *(const bf16x8*)(sA + arow_off + 1 * 2048 + ch1); gb[1] = *(const bf16x8*)(sB + brow_off + 1 * 2048 + ch1);
;         __builtin_amdgcn_sched_barrier(0);
; #pragma unroll
;         for (int j = 0; j < 4; ++j) acc[1][j] = __builtin_amdgcn_mfma_f32_16x16x32_bf16(fb[j], fa[1], acc[1][j], 0, 0, 0);
;         __builtin_amdgcn_sched_barrier(0);
;         if (wr_ok) *(uint4*)(nA + soff0 + 8192) = ra2;
;         if (ld_ok) ra2 = *(const uint4*)(Ab + (aoff + 64u * LDA + koa));
;         ga[2] = *(const bf16x8*)(sA + arow_off + 2 * 2048 + ch1); gb[2] = *(const bf16x8*)(sB + brow_off + 2 * 2048 + ch1);
;         __builtin_amdgcn_sched_barrier(0);
; #pragma unroll
;         for (int j = 0; j < 4; ++j) acc[2][j] = __builtin_amdgcn_mfma_f32_16x16x32_bf16(fb[j], fa[2], acc[2][j], 0, 0, 0);
;         __builtin_amdgcn_sched_barrier(0);
;         if (wr_ok) *(uint4*)(nA + soff0 + 12288) = ra3;
;         if (ld_ok) ra3 = *(const uint4*)(Ab + (aoff + 96u * LDA + koa));
;         ga[3] = *(const bf16x8*)(sA + arow_off + 3 * 2048 + ch1); gb[3] = *(const bf16x8*)(sB + brow_off + 3 * 2048 + ch1);
;         __builtin_amdgcn_sched_barrier(0);
; #pragma unroll
;         for (int j = 0; j < 4; ++j) acc[3][j] = __builtin_amdgcn_mfma_f32_16x16x32_bf16(fb[j], fa[3], acc[3][j], 0, 0, 0);
;         __builtin_amdgcn_sched_barrier(0);
;         if (wr_ok) *(uint4*)(nB + soff0) = rb0;
	v_mfma_f32_16x16x32_bf16 v[42:45], v[104:107], v[26:29], v[108:111]
	s_waitcnt lgkmcnt(7)
	v_mfma_f32_16x16x32_bf16 v[108:111], v[124:127], v[26:29], v[112:115]
	s_waitcnt lgkmcnt(4)
	v_mfma_f32_16x16x32_bf16 v[112:115], v[148:151], v[26:29], v[116:119]
	s_waitcnt lgkmcnt(1)
	v_mfma_f32_16x16x32_bf16 v[26:29], v[168:171], v[26:29], v[58:61]
	v_add_u32_e32 v248, 0x10000, v18
	global_load_dwordx4 v[58:61], v248, s[6:7] offset:256
	s_waitcnt vmcnt(8)
	ds_write_b128 v19, v[46:49] offset:53248
	v_mfma_f32_16x16x32_bf16 v[46:49], v[104:107], v[30:33], v[132:135]
	v_mfma_f32_16x16x32_bf16 v[116:119], v[124:127], v[30:33], v[136:139]
	v_mfma_f32_16x16x32_bf16 v[132:135], v[148:151], v[30:33], v[140:143]
	v_mfma_f32_16x16x32_bf16 v[30:33], v[168:171], v[30:33], v[62:65]
	v_add_u32_e32 v249, 0x20000, v18
	global_load_dwordx4 v[62:65], v249, s[6:7] offset:256
	s_waitcnt vmcnt(8)
	ds_write_b128 v19, v[50:53] offset:57344
	v_mfma_f32_16x16x32_bf16 v[50:53], v[104:107], v[34:37], v[152:155]
	v_mfma_f32_16x16x32_bf16 v[136:139], v[124:127], v[34:37], v[156:159]
	v_mfma_f32_16x16x32_bf16 v[140:143], v[148:151], v[34:37], v[160:163]
	v_mfma_f32_16x16x32_bf16 v[34:37], v[168:171], v[34:37], v[74:77]
	v_add_u32_e32 v250, 0x30000, v18
	global_load_dwordx4 v[74:77], v250, s[6:7] offset:256
	s_waitcnt vmcnt(8)
	ds_write_b128 v19, v[54:57] offset:61440
	v_mfma_f32_16x16x32_bf16 v[54:57], v[104:107], v[38:41], v[66:69]
	v_mfma_f32_16x16x32_bf16 v[66:69], v[124:127], v[38:41], v[70:73]
	v_mfma_f32_16x16x32_bf16 v[70:73], v[148:151], v[38:41], v[92:95]
	v_mfma_f32_16x16x32_bf16 v[38:41], v[168:171], v[38:41], v[78:81]
	s_setprio 0
	s_waitcnt lgkmcnt(0)
	s_barrier
	ds_read_b128 v[78:81], v22 offset:32768
	ds_read_b128 v[92:95], v22 offset:34816
	ds_read_b128 v[104:107], v23 offset:49152
	ds_read_b128 v[124:127], v23 offset:51200
	ds_read_b128 v[148:151], v22 offset:36864
	ds_read_b128 v[152:155], v22 offset:38912
	ds_read_b128 v[156:159], v23 offset:53248
	ds_read_b128 v[160:163], v23 offset:55296
	s_setprio 2
	s_waitcnt lgkmcnt(5)
	v_mfma_f32_16x16x32_bf16 v[42:45], v[104:107], v[78:81], v[42:45]
	global_load_dwordx4 v[168:171], v24, s[36:37] offset:384
	s_waitcnt lgkmcnt(0)
	v_mfma_f32_16x16x32_bf16 v[26:29], v[160:163], v[78:81], v[26:29]
	s_waitcnt vmcnt(8)
	ds_write_b128 v19, v[100:103]
	v_mfma_f32_16x16x32_bf16 v[108:111], v[124:127], v[78:81], v[108:111]
	ds_read_b128 v[100:103], v20 offset:32768
	v_mfma_f32_16x16x32_bf16 v[112:115], v[156:159], v[78:81], v[112:115]
	ds_read_b128 v[172:175], v21 offset:49152
	global_load_dwordx4 v[78:81], v245, s[36:37] offset:384
	v_mfma_f32_16x16x32_bf16 v[46:49], v[104:107], v[92:95], v[46:49]
	s_waitcnt vmcnt(8)
	ds_write_b128 v19, v[120:123] offset:4096
	v_mfma_f32_16x16x32_bf16 v[30:33], v[160:163], v[92:95], v[30:33]
	ds_read_b128 v[120:123], v20 offset:34816
	v_mfma_f32_16x16x32_bf16 v[116:119], v[124:127], v[92:95], v[116:119]
	ds_read_b128 v[176:179], v21 offset:51200
	v_mfma_f32_16x16x32_bf16 v[132:135], v[156:159], v[92:95], v[132:135]
	global_load_dwordx4 v[92:95], v246, s[36:37] offset:384
	v_mfma_f32_16x16x32_bf16 v[50:53], v[104:107], v[148:151], v[50:53]
	s_waitcnt vmcnt(8)
	ds_write_b128 v19, v[144:147] offset:8192
	v_mfma_f32_16x16x32_bf16 v[34:37], v[160:163], v[148:151], v[34:37]
	ds_read_b128 v[144:147], v20 offset:36864
	v_mfma_f32_16x16x32_bf16 v[136:139], v[124:127], v[148:151], v[136:139]
	ds_read_b128 v[180:183], v21 offset:53248
	v_mfma_f32_16x16x32_bf16 v[140:143], v[156:159], v[148:151], v[140:143]
	global_load_dwordx4 v[148:151], v247, s[36:37] offset:384
	v_mfma_f32_16x16x32_bf16 v[54:57], v[104:107], v[152:155], v[54:57]
	s_waitcnt vmcnt(8)
	ds_write_b128 v19, v[164:167] offset:12288
	v_mfma_f32_16x16x32_bf16 v[66:69], v[124:127], v[152:155], v[66:69]
	ds_read_b128 v[164:167], v20 offset:38912
	v_mfma_f32_16x16x32_bf16 v[70:73], v[156:159], v[152:155], v[70:73]
	ds_read_b128 v[184:187], v21 offset:55296
	v_mfma_f32_16x16x32_bf16 v[38:41], v[160:163], v[152:155], v[38:41]
	global_load_dwordx4 v[104:107], v18, s[6:7] offset:384
	s_waitcnt vmcnt(8)
	ds_write_b128 v19, v[96:99] offset:16384
	s_waitcnt lgkmcnt(10)
	v_mfma_f32_16x16x32_bf16 v[42:45], v[172:175], v[100:103], v[42:45]
	s_waitcnt lgkmcnt(1)
	v_mfma_f32_16x16x32_bf16 v[26:29], v[184:187], v[100:103], v[26:29]
	v_mfma_f32_16x16x32_bf16 v[96:99], v[176:179], v[100:103], v[108:111]
	v_mfma_f32_16x16x32_bf16 v[108:111], v[180:183], v[100:103], v[112:115]
	global_load_dwordx4 v[100:103], v248, s[6:7] offset:384
	s_waitcnt vmcnt(8)
	ds_write_b128 v19, v[58:61] offset:20480
	v_mfma_f32_16x16x32_bf16 v[46:49], v[172:175], v[120:123], v[46:49]
	v_mfma_f32_16x16x32_bf16 v[58:61], v[176:179], v[120:123], v[116:119]
	v_mfma_f32_16x16x32_bf16 v[30:33], v[184:187], v[120:123], v[30:33]
	v_mfma_f32_16x16x32_bf16 v[112:115], v[180:183], v[120:123], v[132:135]
	global_load_dwordx4 v[116:119], v249, s[6:7] offset:384
	s_waitcnt vmcnt(8)
	ds_write_b128 v19, v[62:65] offset:24576
	v_mfma_f32_16x16x32_bf16 v[50:53], v[172:175], v[144:147], v[50:53]
	v_mfma_f32_16x16x32_bf16 v[62:65], v[176:179], v[144:147], v[136:139]
	v_mfma_f32_16x16x32_bf16 v[34:37], v[184:187], v[144:147], v[34:37]
	v_mfma_f32_16x16x32_bf16 v[120:123], v[180:183], v[144:147], v[140:143]
	global_load_dwordx4 v[124:127], v250, s[6:7] offset:384
	v_mfma_f32_16x16x32_bf16 v[54:57], v[172:175], v[164:167], v[54:57]
	s_waitcnt vmcnt(8)
	ds_write_b128 v19, v[74:77] offset:28672
	v_mfma_f32_16x16x32_bf16 v[66:69], v[176:179], v[164:167], v[66:69]
	v_mfma_f32_16x16x32_bf16 v[70:73], v[180:183], v[164:167], v[70:73]
	v_mfma_f32_16x16x32_bf16 v[38:41], v[184:187], v[164:167], v[38:41]
	s_setprio 0
	s_waitcnt lgkmcnt(0)
	s_barrier
; template <int MODE>
; __device__ __forceinline__ void gemm_tile(const Params& P, int tm, int tn, unsigned char* smem) {
;     ...
; #pragma unroll
;         for (int i = 0; i < 4; ++i) { fa[i] = *(const bf16x8*)(sA + arow_off + i * 2048 + ch0); fb[i] = *(const bf16x8*)(sB + brow_off + i * 2048 + ch0); }
;         __builtin_amdgcn_sched_barrier(0);
;         __builtin_amdgcn_s_setprio(2);
;         if (wr_ok) *(uint4*)(nA + soff0) = ra0;
;         if (ld_ok) ra0 = *(const uint4*)(Ab + (aoff + 0u * LDA + koa));
;         ga[0] = *(const bf16x8*)(sA + arow_off + 0 * 2048 + ch1); gb[0] = *(const bf16x8*)(sB + brow_off + 0 * 2048 + ch1);
;         __builtin_amdgcn_sched_barrier(0);
; #pragma unroll
;         for (int j = 0; j < 4; ++j) acc[0][j] = __builtin_amdgcn_mfma_f32_16x16x32_bf16(fb[j], fa[0], acc[0][j], 0, 0, 0);
;         __builtin_amdgcn_sched_barrier(0);
;         if (wr_ok) *(uint4*)(nA + soff0 + 4096) = ra1;
;         if (ld_ok) ra1 = *(const uint4*)(Ab + (aoff + 32u * LDA + koa));
;         ga[1] = *(const bf16x8*)(sA + arow_off + 1 * 2048 + ch1); gb[1] = *(const bf16x8*)(sB + brow_off + 1 * 2048 + ch1);
;         __builtin_amdgcn_sched_barrier(0);
; #pragma unroll
;         for (int j = 0; j < 4; ++j) acc[1][j] = __builtin_amdgcn_mfma_f32_16x16x32_bf16(fb[j], fa[1], acc[1][j], 0, 0, 0);
;         __builtin_amdgcn_sched_barrier(0);
;         if (wr_ok) *(uint4*)(nA + soff0 + 8192) = ra2;
;         if (ld_ok) ra2 = *(const uint4*)(Ab + (aoff + 64u * LDA + koa));
;         ga[2] = *(const bf16x8*)(sA + arow_off + 2 * 2048 + ch1); gb[2] = *(const bf16x8*)(sB + brow_off + 2 * 2048 + ch1);
;         __builtin_amdgcn_sched_barrier(0);
; #pragma unroll
;         for (int j = 0; j < 4; ++j) acc[2][j] = __builtin_amdgcn_mfma_f32_16x16x32_bf16(fb[j], fa[2], acc[2][j], 0, 0, 0);
;         __builtin_amdgcn_sched_barrier(0);
;         if (wr_ok) *(uint4*)(nA + soff0 + 12288) = ra3;
;         if (ld_ok) ra3 = *(const uint4*)(Ab + (aoff + 96u * LDA + koa));
;         ga[3] = *(const bf16x8*)(sA + arow_off + 3 * 2048 + ch1); gb[3] = *(const bf16x8*)(sB + brow_off + 3 * 2048 + ch1);
;         __builtin_amdgcn_sched_barrier(0);
; #pragma unroll
;         for (int j = 0; j < 4; ++j) acc[3][j] = __builtin_amdgcn_mfma_f32_16x16x32_bf16(fb[j], fa[3], acc[3][j], 0, 0, 0);
;         __builtin_amdgcn_sched_barrier(0);
;         if (wr_ok) *(uint4*)(nB + soff0) = rb0;
	ds_read_b128 v[74:77], v22
	ds_read_b128 v[132:135], v22 offset:2048
	ds_read_b128 v[136:139], v23 offset:16384
	ds_read_b128 v[140:143], v23 offset:18432
	ds_read_b128 v[144:147], v22 offset:4096
	ds_read_b128 v[152:155], v22 offset:6144
	ds_read_b128 v[156:159], v23 offset:20480
	ds_read_b128 v[160:163], v23 offset:22528
	s_setprio 2
	s_waitcnt lgkmcnt(5)
	v_mfma_f32_16x16x32_bf16 v[42:45], v[136:139], v[74:77], v[42:45]
	global_load_dwordx4 v[164:167], v24, s[36:37] offset:512
	s_waitcnt lgkmcnt(0)
	v_mfma_f32_16x16x32_bf16 v[26:29], v[160:163], v[74:77], v[26:29]
	s_waitcnt vmcnt(8)
	ds_write_b128 v19, v[168:171] offset:32768
	v_mfma_f32_16x16x32_bf16 v[96:99], v[140:143], v[74:77], v[96:99]
	ds_read_b128 v[168:171], v20
	v_mfma_f32_16x16x32_bf16 v[108:111], v[156:159], v[74:77], v[108:111]
	ds_read_b128 v[172:175], v21 offset:16384
	global_load_dwordx4 v[74:77], v245, s[36:37] offset:512
	v_mfma_f32_16x16x32_bf16 v[46:49], v[136:139], v[132:135], v[46:49]
	s_waitcnt vmcnt(8)
	ds_write_b128 v19, v[78:81] offset:36864
	v_mfma_f32_16x16x32_bf16 v[58:61], v[140:143], v[132:135], v[58:61]
	ds_read_b128 v[78:81], v20 offset:2048
	v_mfma_f32_16x16x32_bf16 v[30:33], v[160:163], v[132:135], v[30:33]
	ds_read_b128 v[176:179], v21 offset:18432
	v_mfma_f32_16x16x32_bf16 v[112:115], v[156:159], v[132:135], v[112:115]
	global_load_dwordx4 v[132:135], v246, s[36:37] offset:512
	v_mfma_f32_16x16x32_bf16 v[50:53], v[136:139], v[144:147], v[50:53]
	s_waitcnt vmcnt(8)
	ds_write_b128 v19, v[92:95] offset:40960
	v_mfma_f32_16x16x32_bf16 v[62:65], v[140:143], v[144:147], v[62:65]
	ds_read_b128 v[92:95], v20 offset:4096
	v_mfma_f32_16x16x32_bf16 v[34:37], v[160:163], v[144:147], v[34:37]
	ds_read_b128 v[180:183], v21 offset:20480
	v_mfma_f32_16x16x32_bf16 v[120:123], v[156:159], v[144:147], v[120:123]
	global_load_dwordx4 v[144:147], v247, s[36:37] offset:512
	v_mfma_f32_16x16x32_bf16 v[54:57], v[136:139], v[152:155], v[54:57]
	s_waitcnt vmcnt(8)
	ds_write_b128 v19, v[148:151] offset:45056
	v_mfma_f32_16x16x32_bf16 v[66:69], v[140:143], v[152:155], v[66:69]
	ds_read_b128 v[148:151], v20 offset:6144
	v_mfma_f32_16x16x32_bf16 v[70:73], v[156:159], v[152:155], v[70:73]
	ds_read_b128 v[184:187], v21 offset:22528
	v_mfma_f32_16x16x32_bf16 v[38:41], v[160:163], v[152:155], v[38:41]
	global_load_dwordx4 v[136:139], v18, s[6:7] offset:512
	s_waitcnt vmcnt(8)
	ds_write_b128 v19, v[104:107] offset:49152
	s_waitcnt lgkmcnt(10)
	v_mfma_f32_16x16x32_bf16 v[42:45], v[172:175], v[168:171], v[42:45]
	s_waitcnt lgkmcnt(1)
	v_mfma_f32_16x16x32_bf16 v[26:29], v[184:187], v[168:171], v[26:29]
	v_mfma_f32_16x16x32_bf16 v[96:99], v[176:179], v[168:171], v[96:99]
	v_mfma_f32_16x16x32_bf16 v[104:107], v[180:183], v[168:171], v[108:111]
	global_load_dwordx4 v[108:111], v248, s[6:7] offset:512
	s_waitcnt vmcnt(8)
	ds_write_b128 v19, v[100:103] offset:53248
	v_mfma_f32_16x16x32_bf16 v[46:49], v[172:175], v[78:81], v[46:49]
	v_mfma_f32_16x16x32_bf16 v[58:61], v[176:179], v[78:81], v[58:61]
	v_mfma_f32_16x16x32_bf16 v[30:33], v[184:187], v[78:81], v[30:33]
	v_mfma_f32_16x16x32_bf16 v[100:103], v[180:183], v[78:81], v[112:115]
	global_load_dwordx4 v[78:81], v249, s[6:7] offset:512
	v_mfma_f32_16x16x32_bf16 v[50:53], v[172:175], v[92:95], v[50:53]
	s_waitcnt vmcnt(8)
	ds_write_b128 v19, v[116:119] offset:57344
	v_mfma_f32_16x16x32_bf16 v[62:65], v[176:179], v[92:95], v[62:65]
	v_mfma_f32_16x16x32_bf16 v[34:37], v[184:187], v[92:95], v[34:37]
	v_mfma_f32_16x16x32_bf16 v[112:115], v[180:183], v[92:95], v[120:123]
	global_load_dwordx4 v[92:95], v250, s[6:7] offset:512
	v_mfma_f32_16x16x32_bf16 v[54:57], v[172:175], v[148:151], v[54:57]
	s_waitcnt vmcnt(8)
	ds_write_b128 v19, v[124:127] offset:61440
	v_mfma_f32_16x16x32_bf16 v[66:69], v[176:179], v[148:151], v[66:69]
	v_mfma_f32_16x16x32_bf16 v[70:73], v[180:183], v[148:151], v[70:73]
	v_mfma_f32_16x16x32_bf16 v[38:41], v[184:187], v[148:151], v[38:41]
	s_setprio 0
	s_waitcnt lgkmcnt(0)
	s_barrier
	ds_read_b128 v[116:119], v22 offset:32768
	ds_read_b128 v[120:123], v22 offset:34816
	ds_read_b128 v[124:127], v23 offset:49152
	ds_read_b128 v[140:143], v23 offset:51200
	ds_read_b128 v[148:151], v22 offset:36864
	ds_read_b128 v[152:155], v22 offset:38912
	ds_read_b128 v[156:159], v23 offset:53248
	ds_read_b128 v[160:163], v23 offset:55296
	s_setprio 2
	s_waitcnt lgkmcnt(5)
	v_mfma_f32_16x16x32_bf16 v[42:45], v[124:127], v[116:119], v[42:45]
	global_load_dwordx4 v[168:171], v24, s[36:37] offset:640
	s_waitcnt lgkmcnt(0)
	v_mfma_f32_16x16x32_bf16 v[26:29], v[160:163], v[116:119], v[26:29]
	s_waitcnt vmcnt(8)
	ds_write_b128 v19, v[164:167]
	v_mfma_f32_16x16x32_bf16 v[96:99], v[140:143], v[116:119], v[96:99]
	ds_read_b128 v[164:167], v20 offset:32768
	v_mfma_f32_16x16x32_bf16 v[104:107], v[156:159], v[116:119], v[104:107]
	ds_read_b128 v[172:175], v21 offset:49152
	global_load_dwordx4 v[116:119], v245, s[36:37] offset:640
	v_mfma_f32_16x16x32_bf16 v[46:49], v[124:127], v[120:123], v[46:49]
	s_waitcnt vmcnt(8)
	ds_write_b128 v19, v[74:77] offset:4096
	v_mfma_f32_16x16x32_bf16 v[58:61], v[140:143], v[120:123], v[58:61]
	ds_read_b128 v[74:77], v20 offset:34816
	v_mfma_f32_16x16x32_bf16 v[30:33], v[160:163], v[120:123], v[30:33]
	ds_read_b128 v[176:179], v21 offset:51200
	v_mfma_f32_16x16x32_bf16 v[100:103], v[156:159], v[120:123], v[100:103]
	global_load_dwordx4 v[120:123], v246, s[36:37] offset:640
	v_mfma_f32_16x16x32_bf16 v[50:53], v[124:127], v[148:151], v[50:53]
	s_waitcnt vmcnt(8)
; template <int MODE>
; __device__ __forceinline__ void gemm_tile(const Params& P, int tm, int tn, unsigned char* smem) {
;     ...
; #pragma unroll
;         for (int i = 0; i < 4; ++i) { fa[i] = *(const bf16x8*)(sA + arow_off + i * 2048 + ch0); fb[i] = *(const bf16x8*)(sB + brow_off + i * 2048 + ch0); }
;         __builtin_amdgcn_sched_barrier(0);
;         __builtin_amdgcn_s_setprio(2);
;         if (wr_ok) *(uint4*)(nA + soff0) = ra0;
;         if (ld_ok) ra0 = *(const uint4*)(Ab + (aoff + 0u * LDA + koa));
;         ga[0] = *(const bf16x8*)(sA + arow_off + 0 * 2048 + ch1); gb[0] = *(const bf16x8*)(sB + brow_off + 0 * 2048 + ch1);
;         __builtin_amdgcn_sched_barrier(0);
; #pragma unroll
;         for (int j = 0; j < 4; ++j) acc[0][j] = __builtin_amdgcn_mfma_f32_16x16x32_bf16(fb[j], fa[0], acc[0][j], 0, 0, 0);
;         __builtin_amdgcn_sched_barrier(0);
;         if (wr_ok) *(uint4*)(nA + soff0 + 4096) = ra1;
;         if (ld_ok) ra1 = *(const uint4*)(Ab + (aoff + 32u * LDA + koa));
;         ga[1] = *(const bf16x8*)(sA + arow_off + 1 * 2048 + ch1); gb[1] = *(const bf16x8*)(sB + brow_off + 1 * 2048 + ch1);
;         __builtin_amdgcn_sched_barrier(0);
; #pragma unroll
;         for (int j = 0; j < 4; ++j) acc[1][j] = __builtin_amdgcn_mfma_f32_16x16x32_bf16(fb[j], fa[1], acc[1][j], 0, 0, 0);
;         __builtin_amdgcn_sched_barrier(0);
;         if (wr_ok) *(uint4*)(nA + soff0 + 8192) = ra2;
;         if (ld_ok) ra2 = *(const uint4*)(Ab + (aoff + 64u * LDA + koa));
;         ga[2] = *(const bf16x8*)(sA + arow_off + 2 * 2048 + ch1); gb[2] = *(const bf16x8*)(sB + brow_off + 2 * 2048 + ch1);
;         __builtin_amdgcn_sched_barrier(0);
; #pragma unroll
;         for (int j = 0; j < 4; ++j) acc[2][j] = __builtin_amdgcn_mfma_f32_16x16x32_bf16(fb[j], fa[2], acc[2][j], 0, 0, 0);
;         __builtin_amdgcn_sched_barrier(0);
;         if (wr_ok) *(uint4*)(nA + soff0 + 12288) = ra3;
;         if (ld_ok) ra3 = *(const uint4*)(Ab + (aoff + 96u * LDA + koa));
;         ga[3] = *(const bf16x8*)(sA + arow_off + 3 * 2048 + ch1); gb[3] = *(const bf16x8*)(sB + brow_off + 3 * 2048 + ch1);
;         __builtin_amdgcn_sched_barrier(0);
; #pragma unroll
;         for (int j = 0; j < 4; ++j) acc[3][j] = __builtin_amdgcn_mfma_f32_16x16x32_bf16(fb[j], fa[3], acc[3][j], 0, 0, 0);
;         __builtin_amdgcn_sched_barrier(0);
;         if (wr_ok) *(uint4*)(nB + soff0) = rb0;
	ds_write_b128 v19, v[132:135] offset:8192
	v_mfma_f32_16x16x32_bf16 v[62:65], v[140:143], v[148:151], v[62:65]
	ds_read_b128 v[132:135], v20 offset:36864
	v_mfma_f32_16x16x32_bf16 v[34:37], v[160:163], v[148:151], v[34:37]
	ds_read_b128 v[180:183], v21 offset:53248
	v_mfma_f32_16x16x32_bf16 v[112:115], v[156:159], v[148:151], v[112:115]
	global_load_dwordx4 v[148:151], v247, s[36:37] offset:640
	v_mfma_f32_16x16x32_bf16 v[54:57], v[124:127], v[152:155], v[54:57]
	s_waitcnt vmcnt(8)
	ds_write_b128 v19, v[144:147] offset:12288
	v_mfma_f32_16x16x32_bf16 v[66:69], v[140:143], v[152:155], v[66:69]
	ds_read_b128 v[144:147], v20 offset:38912
	v_mfma_f32_16x16x32_bf16 v[70:73], v[156:159], v[152:155], v[70:73]
	ds_read_b128 v[184:187], v21 offset:55296
	v_mfma_f32_16x16x32_bf16 v[38:41], v[160:163], v[152:155], v[38:41]
	s_waitcnt lgkmcnt(9)
	v_mfma_f32_16x16x32_bf16 v[42:45], v[172:175], v[164:167], v[42:45]
	global_load_dwordx4 v[124:127], v18, s[6:7] offset:640
	s_waitcnt lgkmcnt(0)
	v_mfma_f32_16x16x32_bf16 v[26:29], v[184:187], v[164:167], v[26:29]
	s_waitcnt vmcnt(8)
	ds_write_b128 v19, v[136:139] offset:16384
	v_mfma_f32_16x16x32_bf16 v[96:99], v[176:179], v[164:167], v[96:99]
	v_mfma_f32_16x16x32_bf16 v[104:107], v[180:183], v[164:167], v[104:107]
	global_load_dwordx4 v[136:139], v248, s[6:7] offset:640
	v_mfma_f32_16x16x32_bf16 v[46:49], v[172:175], v[74:77], v[46:49]
	s_waitcnt vmcnt(8)
	ds_write_b128 v19, v[108:111] offset:20480
	v_mfma_f32_16x16x32_bf16 v[58:61], v[176:179], v[74:77], v[58:61]
	v_mfma_f32_16x16x32_bf16 v[30:33], v[184:187], v[74:77], v[30:33]
	v_mfma_f32_16x16x32_bf16 v[100:103], v[180:183], v[74:77], v[100:103]
	global_load_dwordx4 v[74:77], v249, s[6:7] offset:640
	s_waitcnt vmcnt(8)
	ds_write_b128 v19, v[78:81] offset:24576
	v_mfma_f32_16x16x32_bf16 v[50:53], v[172:175], v[132:135], v[50:53]
	v_mfma_f32_16x16x32_bf16 v[62:65], v[176:179], v[132:135], v[62:65]
	v_mfma_f32_16x16x32_bf16 v[78:81], v[180:183], v[132:135], v[112:115]
	v_mfma_f32_16x16x32_bf16 v[34:37], v[184:187], v[132:135], v[34:37]
	global_load_dwordx4 v[108:111], v250, s[6:7] offset:640
	v_mfma_f32_16x16x32_bf16 v[54:57], v[172:175], v[144:147], v[54:57]
	s_waitcnt vmcnt(8)
	ds_write_b128 v19, v[92:95] offset:28672
	v_mfma_f32_16x16x32_bf16 v[66:69], v[176:179], v[144:147], v[66:69]
	v_mfma_f32_16x16x32_bf16 v[70:73], v[180:183], v[144:147], v[70:73]
	v_mfma_f32_16x16x32_bf16 v[38:41], v[184:187], v[144:147], v[38:41]
	s_setprio 0
	s_waitcnt lgkmcnt(0)
	s_barrier
	ds_read_b128 v[92:95], v22
	ds_read_b128 v[112:115], v22 offset:2048
	ds_read_b128 v[132:135], v23 offset:16384
	ds_read_b128 v[140:143], v23 offset:18432
	ds_read_b128 v[144:147], v22 offset:4096
	ds_read_b128 v[152:155], v22 offset:6144
	ds_read_b128 v[156:159], v23 offset:20480
	ds_read_b128 v[160:163], v23 offset:22528
	s_setprio 2
	s_waitcnt lgkmcnt(5)
	v_mfma_f32_16x16x32_bf16 v[42:45], v[132:135], v[92:95], v[42:45]
	global_load_dwordx4 v[164:167], v24, s[36:37] offset:768
	s_waitcnt lgkmcnt(0)
	v_mfma_f32_16x16x32_bf16 v[26:29], v[160:163], v[92:95], v[26:29]
	s_waitcnt vmcnt(8)
	ds_write_b128 v19, v[168:171] offset:32768
	v_mfma_f32_16x16x32_bf16 v[96:99], v[140:143], v[92:95], v[96:99]
	ds_read_b128 v[168:171], v20
	v_mfma_f32_16x16x32_bf16 v[104:107], v[156:159], v[92:95], v[104:107]
	ds_read_b128 v[172:175], v21 offset:16384
	global_load_dwordx4 v[92:95], v245, s[36:37] offset:768
	v_mfma_f32_16x16x32_bf16 v[46:49], v[132:135], v[112:115], v[46:49]
	s_waitcnt vmcnt(8)
	ds_write_b128 v19, v[116:119] offset:36864
	v_mfma_f32_16x16x32_bf16 v[58:61], v[140:143], v[112:115], v[58:61]
	ds_read_b128 v[116:119], v20 offset:2048
	v_mfma_f32_16x16x32_bf16 v[30:33], v[160:163], v[112:115], v[30:33]
	ds_read_b128 v[176:179], v21 offset:18432
	v_mfma_f32_16x16x32_bf16 v[100:103], v[156:159], v[112:115], v[100:103]
	global_load_dwordx4 v[112:115], v246, s[36:37] offset:768
	v_mfma_f32_16x16x32_bf16 v[50:53], v[132:135], v[144:147], v[50:53]
	s_waitcnt vmcnt(8)
	ds_write_b128 v19, v[120:123] offset:40960
	v_mfma_f32_16x16x32_bf16 v[62:65], v[140:143], v[144:147], v[62:65]
	ds_read_b128 v[120:123], v20 offset:4096
	v_mfma_f32_16x16x32_bf16 v[78:81], v[156:159], v[144:147], v[78:81]
	ds_read_b128 v[180:183], v21 offset:20480
	v_mfma_f32_16x16x32_bf16 v[34:37], v[160:163], v[144:147], v[34:37]
	global_load_dwordx4 v[144:147], v247, s[36:37] offset:768
	v_mfma_f32_16x16x32_bf16 v[54:57], v[132:135], v[152:155], v[54:57]
	s_waitcnt vmcnt(8)
	ds_write_b128 v19, v[148:151] offset:45056
	v_mfma_f32_16x16x32_bf16 v[66:69], v[140:143], v[152:155], v[66:69]
	ds_read_b128 v[148:151], v20 offset:6144
	v_mfma_f32_16x16x32_bf16 v[70:73], v[156:159], v[152:155], v[70:73]
	ds_read_b128 v[184:187], v21 offset:22528
	v_mfma_f32_16x16x32_bf16 v[38:41], v[160:163], v[152:155], v[38:41]
	s_waitcnt lgkmcnt(9)
	v_mfma_f32_16x16x32_bf16 v[42:45], v[172:175], v[168:171], v[42:45]
	global_load_dwordx4 v[132:135], v18, s[6:7] offset:768
	s_waitcnt lgkmcnt(0)
	v_mfma_f32_16x16x32_bf16 v[26:29], v[184:187], v[168:171], v[26:29]
	s_waitcnt vmcnt(8)
	ds_write_b128 v19, v[124:127] offset:49152
	v_mfma_f32_16x16x32_bf16 v[96:99], v[176:179], v[168:171], v[96:99]
	v_mfma_f32_16x16x32_bf16 v[104:107], v[180:183], v[168:171], v[104:107]
	global_load_dwordx4 v[124:127], v248, s[6:7] offset:768
	v_mfma_f32_16x16x32_bf16 v[46:49], v[172:175], v[116:119], v[46:49]
	s_waitcnt vmcnt(8)
	ds_write_b128 v19, v[136:139] offset:53248
	v_mfma_f32_16x16x32_bf16 v[58:61], v[176:179], v[116:119], v[58:61]
	v_mfma_f32_16x16x32_bf16 v[30:33], v[184:187], v[116:119], v[30:33]
	v_mfma_f32_16x16x32_bf16 v[100:103], v[180:183], v[116:119], v[100:103]
	global_load_dwordx4 v[116:119], v249, s[6:7] offset:768
	s_waitcnt vmcnt(8)
	ds_write_b128 v19, v[74:77] offset:57344
	v_mfma_f32_16x16x32_bf16 v[50:53], v[172:175], v[120:123], v[50:53]
	v_mfma_f32_16x16x32_bf16 v[62:65], v[176:179], v[120:123], v[62:65]
	v_mfma_f32_16x16x32_bf16 v[74:77], v[180:183], v[120:123], v[78:81]
	v_mfma_f32_16x16x32_bf16 v[34:37], v[184:187], v[120:123], v[34:37]
	global_load_dwordx4 v[78:81], v250, s[6:7] offset:768
	v_mfma_f32_16x16x32_bf16 v[54:57], v[172:175], v[148:151], v[54:57]
	s_waitcnt vmcnt(8)
	ds_write_b128 v19, v[108:111] offset:61440
	v_mfma_f32_16x16x32_bf16 v[66:69], v[176:179], v[148:151], v[66:69]
	v_mfma_f32_16x16x32_bf16 v[70:73], v[180:183], v[148:151], v[70:73]
	v_mfma_f32_16x16x32_bf16 v[38:41], v[184:187], v[148:151], v[38:41]
	s_setprio 0
	s_waitcnt lgkmcnt(0)
	s_barrier
; template <int MODE>
; __device__ __forceinline__ void gemm_tile(const Params& P, int tm, int tn, unsigned char* smem) {
;     ...
; #pragma unroll
;         for (int i = 0; i < 4; ++i) { fa[i] = *(const bf16x8*)(sA + arow_off + i * 2048 + ch0); fb[i] = *(const bf16x8*)(sB + brow_off + i * 2048 + ch0); }
;         __builtin_amdgcn_sched_barrier(0);
;         __builtin_amdgcn_s_setprio(2);
;         if (wr_ok) *(uint4*)(nA + soff0) = ra0;
;         if (ld_ok) ra0 = *(const uint4*)(Ab + (aoff + 0u * LDA + koa));
;         ga[0] = *(const bf16x8*)(sA + arow_off + 0 * 2048 + ch1); gb[0] = *(const bf16x8*)(sB + brow_off + 0 * 2048 + ch1);
;         __builtin_amdgcn_sched_barrier(0);
; #pragma unroll
;         for (int j = 0; j < 4; ++j) acc[0][j] = __builtin_amdgcn_mfma_f32_16x16x32_bf16(fb[j], fa[0], acc[0][j], 0, 0, 0);
;         __builtin_amdgcn_sched_barrier(0);
;         if (wr_ok) *(uint4*)(nA + soff0 + 4096) = ra1;
;         if (ld_ok) ra1 = *(const uint4*)(Ab + (aoff + 32u * LDA + koa));
;         ga[1] = *(const bf16x8*)(sA + arow_off + 1 * 2048 + ch1); gb[1] = *(const bf16x8*)(sB + brow_off + 1 * 2048 + ch1);
;         __builtin_amdgcn_sched_barrier(0);
; #pragma unroll
;         for (int j = 0; j < 4; ++j) acc[1][j] = __builtin_amdgcn_mfma_f32_16x16x32_bf16(fb[j], fa[1], acc[1][j], 0, 0, 0);
;         __builtin_amdgcn_sched_barrier(0);
;         if (wr_ok) *(uint4*)(nA + soff0 + 8192) = ra2;
;         if (ld_ok) ra2 = *(const uint4*)(Ab + (aoff + 64u * LDA + koa));
;         ga[2] = *(const bf16x8*)(sA + arow_off + 2 * 2048 + ch1); gb[2] = *(const bf16x8*)(sB + brow_off + 2 * 2048 + ch1);
;         __builtin_amdgcn_sched_barrier(0);
; #pragma unroll
;         for (int j = 0; j < 4; ++j) acc[2][j] = __builtin_amdgcn_mfma_f32_16x16x32_bf16(fb[j], fa[2], acc[2][j], 0, 0, 0);
;         __builtin_amdgcn_sched_barrier(0);
;         if (wr_ok) *(uint4*)(nA + soff0 + 12288) = ra3;
;         if (ld_ok) ra3 = *(const uint4*)(Ab + (aoff + 96u * LDA + koa));
;         ga[3] = *(const bf16x8*)(sA + arow_off + 3 * 2048 + ch1); gb[3] = *(const bf16x8*)(sB + brow_off + 3 * 2048 + ch1);
;         __builtin_amdgcn_sched_barrier(0);
; #pragma unroll
;         for (int j = 0; j < 4; ++j) acc[3][j] = __builtin_amdgcn_mfma_f32_16x16x32_bf16(fb[j], fa[3], acc[3][j], 0, 0, 0);
;         __builtin_amdgcn_sched_barrier(0);
;         if (wr_ok) *(uint4*)(nB + soff0) = rb0;
	ds_read_b128 v[108:111], v22 offset:32768
	ds_read_b128 v[120:123], v22 offset:34816
	ds_read_b128 v[136:139], v23 offset:49152
	ds_read_b128 v[140:143], v23 offset:51200
	ds_read_b128 v[148:151], v22 offset:36864
	ds_read_b128 v[152:155], v22 offset:38912
	ds_read_b128 v[156:159], v23 offset:53248
	ds_read_b128 v[160:163], v23 offset:55296
	s_setprio 2
	s_waitcnt lgkmcnt(5)
	v_mfma_f32_16x16x32_bf16 v[42:45], v[136:139], v[108:111], v[42:45]
	global_load_dwordx4 v[168:171], v24, s[36:37] offset:896
	s_waitcnt lgkmcnt(0)
	v_mfma_f32_16x16x32_bf16 v[26:29], v[160:163], v[108:111], v[26:29]
	s_waitcnt vmcnt(8)
	ds_write_b128 v19, v[164:167]
	v_mfma_f32_16x16x32_bf16 v[96:99], v[140:143], v[108:111], v[96:99]
	ds_read_b128 v[164:167], v20 offset:32768
	v_mfma_f32_16x16x32_bf16 v[104:107], v[156:159], v[108:111], v[104:107]
	ds_read_b128 v[172:175], v21 offset:49152
	global_load_dwordx4 v[108:111], v245, s[36:37] offset:896
	v_mfma_f32_16x16x32_bf16 v[46:49], v[136:139], v[120:123], v[46:49]
	s_waitcnt vmcnt(8)
	ds_write_b128 v19, v[92:95] offset:4096
	v_mfma_f32_16x16x32_bf16 v[58:61], v[140:143], v[120:123], v[58:61]
	ds_read_b128 v[92:95], v20 offset:34816
	v_mfma_f32_16x16x32_bf16 v[30:33], v[160:163], v[120:123], v[30:33]
	ds_read_b128 v[176:179], v21 offset:51200
	v_mfma_f32_16x16x32_bf16 v[100:103], v[156:159], v[120:123], v[100:103]
	global_load_dwordx4 v[120:123], v246, s[36:37] offset:896
	v_mfma_f32_16x16x32_bf16 v[50:53], v[136:139], v[148:151], v[50:53]
	s_waitcnt vmcnt(8)
	ds_write_b128 v19, v[112:115] offset:8192
	v_mfma_f32_16x16x32_bf16 v[62:65], v[140:143], v[148:151], v[62:65]
	ds_read_b128 v[112:115], v20 offset:36864
	v_mfma_f32_16x16x32_bf16 v[74:77], v[156:159], v[148:151], v[74:77]
	ds_read_b128 v[180:183], v21 offset:53248
	v_mfma_f32_16x16x32_bf16 v[34:37], v[160:163], v[148:151], v[34:37]
	global_load_dwordx4 v[148:151], v247, s[36:37] offset:896
	v_mfma_f32_16x16x32_bf16 v[54:57], v[136:139], v[152:155], v[54:57]
	s_waitcnt vmcnt(8)
	ds_write_b128 v19, v[144:147] offset:12288
	v_mfma_f32_16x16x32_bf16 v[66:69], v[140:143], v[152:155], v[66:69]
	ds_read_b128 v[144:147], v20 offset:38912
	v_mfma_f32_16x16x32_bf16 v[70:73], v[156:159], v[152:155], v[70:73]
	ds_read_b128 v[184:187], v21 offset:55296
	v_mfma_f32_16x16x32_bf16 v[38:41], v[160:163], v[152:155], v[38:41]
	s_waitcnt lgkmcnt(9)
	v_mfma_f32_16x16x32_bf16 v[42:45], v[172:175], v[164:167], v[42:45]
	global_load_dwordx4 v[136:139], v18, s[6:7] offset:896
	s_waitcnt lgkmcnt(0)
	v_mfma_f32_16x16x32_bf16 v[26:29], v[184:187], v[164:167], v[26:29]
	s_waitcnt vmcnt(8)
	ds_write_b128 v19, v[132:135] offset:16384
	v_mfma_f32_16x16x32_bf16 v[96:99], v[176:179], v[164:167], v[96:99]
	v_mfma_f32_16x16x32_bf16 v[104:107], v[180:183], v[164:167], v[104:107]
	global_load_dwordx4 v[132:135], v248, s[6:7] offset:896
	v_mfma_f32_16x16x32_bf16 v[46:49], v[172:175], v[92:95], v[46:49]
	s_waitcnt vmcnt(8)
	ds_write_b128 v19, v[124:127] offset:20480
	v_mfma_f32_16x16x32_bf16 v[58:61], v[176:179], v[92:95], v[58:61]
	v_mfma_f32_16x16x32_bf16 v[30:33], v[184:187], v[92:95], v[30:33]
	v_mfma_f32_16x16x32_bf16 v[100:103], v[180:183], v[92:95], v[100:103]
	global_load_dwordx4 v[92:95], v249, s[6:7] offset:896
	v_mfma_f32_16x16x32_bf16 v[50:53], v[172:175], v[112:115], v[50:53]
	s_waitcnt vmcnt(8)
	ds_write_b128 v19, v[116:119] offset:24576
	v_mfma_f32_16x16x32_bf16 v[62:65], v[176:179], v[112:115], v[62:65]
	v_mfma_f32_16x16x32_bf16 v[74:77], v[180:183], v[112:115], v[74:77]
	v_mfma_f32_16x16x32_bf16 v[34:37], v[184:187], v[112:115], v[34:37]
	global_load_dwordx4 v[112:115], v250, s[6:7] offset:896
	v_mfma_f32_16x16x32_bf16 v[54:57], v[172:175], v[144:147], v[54:57]
	s_waitcnt vmcnt(8)
	ds_write_b128 v19, v[78:81] offset:28672
	v_mfma_f32_16x16x32_bf16 v[66:69], v[176:179], v[144:147], v[66:69]
	v_mfma_f32_16x16x32_bf16 v[70:73], v[180:183], v[144:147], v[70:73]
	v_mfma_f32_16x16x32_bf16 v[38:41], v[184:187], v[144:147], v[38:41]
	s_setprio 0
	s_waitcnt lgkmcnt(0)
	s_barrier
	ds_read_b128 v[78:81], v22
	ds_read_b128 v[116:119], v22 offset:2048
	ds_read_b128 v[124:127], v23 offset:16384
	ds_read_b128 v[140:143], v23 offset:18432
	ds_read_b128 v[144:147], v22 offset:4096
	ds_read_b128 v[152:155], v22 offset:6144
	ds_read_b128 v[156:159], v23 offset:20480
	ds_read_b128 v[160:163], v23 offset:22528
	s_setprio 2
	s_waitcnt lgkmcnt(5)
	v_mfma_f32_16x16x32_bf16 v[42:45], v[124:127], v[78:81], v[42:45]
	global_load_dwordx4 v[164:167], v24, s[36:37] offset:1024
	s_waitcnt lgkmcnt(0)
	v_mfma_f32_16x16x32_bf16 v[26:29], v[160:163], v[78:81], v[26:29]
	s_waitcnt vmcnt(8)
	ds_write_b128 v19, v[168:171] offset:32768
	v_mfma_f32_16x16x32_bf16 v[96:99], v[140:143], v[78:81], v[96:99]
	ds_read_b128 v[168:171], v20
	v_mfma_f32_16x16x32_bf16 v[104:107], v[156:159], v[78:81], v[104:107]
	ds_read_b128 v[172:175], v21 offset:16384
	global_load_dwordx4 v[78:81], v245, s[36:37] offset:1024
	v_mfma_f32_16x16x32_bf16 v[46:49], v[124:127], v[116:119], v[46:49]
	s_waitcnt vmcnt(8)
	ds_write_b128 v19, v[108:111] offset:36864
	v_mfma_f32_16x16x32_bf16 v[58:61], v[140:143], v[116:119], v[58:61]
	ds_read_b128 v[108:111], v20 offset:2048
	v_mfma_f32_16x16x32_bf16 v[30:33], v[160:163], v[116:119], v[30:33]
	ds_read_b128 v[176:179], v21 offset:18432
	v_mfma_f32_16x16x32_bf16 v[100:103], v[156:159], v[116:119], v[100:103]
	global_load_dwordx4 v[116:119], v246, s[36:37] offset:1024
	v_mfma_f32_16x16x32_bf16 v[50:53], v[124:127], v[144:147], v[50:53]
	s_waitcnt vmcnt(8)
; template <int MODE>
; __device__ __forceinline__ void gemm_tile(const Params& P, int tm, int tn, unsigned char* smem) {
;     ...
; #pragma unroll
;         for (int i = 0; i < 4; ++i) { fa[i] = *(const bf16x8*)(sA + arow_off + i * 2048 + ch0); fb[i] = *(const bf16x8*)(sB + brow_off + i * 2048 + ch0); }
;         __builtin_amdgcn_sched_barrier(0);
;         __builtin_amdgcn_s_setprio(2);
;         if (wr_ok) *(uint4*)(nA + soff0) = ra0;
;         if (ld_ok) ra0 = *(const uint4*)(Ab + (aoff + 0u * LDA + koa));
;         ga[0] = *(const bf16x8*)(sA + arow_off + 0 * 2048 + ch1); gb[0] = *(const bf16x8*)(sB + brow_off + 0 * 2048 + ch1);
;         __builtin_amdgcn_sched_barrier(0);
; #pragma unroll
;         for (int j = 0; j < 4; ++j) acc[0][j] = __builtin_amdgcn_mfma_f32_16x16x32_bf16(fb[j], fa[0], acc[0][j], 0, 0, 0);
;         __builtin_amdgcn_sched_barrier(0);
;         if (wr_ok) *(uint4*)(nA + soff0 + 4096) = ra1;
;         if (ld_ok) ra1 = *(const uint4*)(Ab + (aoff + 32u * LDA + koa));
;         ga[1] = *(const bf16x8*)(sA + arow_off + 1 * 2048 + ch1); gb[1] = *(const bf16x8*)(sB + brow_off + 1 * 2048 + ch1);
;         __builtin_amdgcn_sched_barrier(0);
; #pragma unroll
;         for (int j = 0; j < 4; ++j) acc[1][j] = __builtin_amdgcn_mfma_f32_16x16x32_bf16(fb[j], fa[1], acc[1][j], 0, 0, 0);
;         __builtin_amdgcn_sched_barrier(0);
;         if (wr_ok) *(uint4*)(nA + soff0 + 8192) = ra2;
;         if (ld_ok) ra2 = *(const uint4*)(Ab + (aoff + 64u * LDA + koa));
;         ga[2] = *(const bf16x8*)(sA + arow_off + 2 * 2048 + ch1); gb[2] = *(const bf16x8*)(sB + brow_off + 2 * 2048 + ch1);
;         __builtin_amdgcn_sched_barrier(0);
; #pragma unroll
;         for (int j = 0; j < 4; ++j) acc[2][j] = __builtin_amdgcn_mfma_f32_16x16x32_bf16(fb[j], fa[2], acc[2][j], 0, 0, 0);
;         __builtin_amdgcn_sched_barrier(0);
;         if (wr_ok) *(uint4*)(nA + soff0 + 12288) = ra3;
;         if (ld_ok) ra3 = *(const uint4*)(Ab + (aoff + 96u * LDA + koa));
;         ga[3] = *(const bf16x8*)(sA + arow_off + 3 * 2048 + ch1); gb[3] = *(const bf16x8*)(sB + brow_off + 3 * 2048 + ch1);
;         __builtin_amdgcn_sched_barrier(0);
; #pragma unroll
;         for (int j = 0; j < 4; ++j) acc[3][j] = __builtin_amdgcn_mfma_f32_16x16x32_bf16(fb[j], fa[3], acc[3][j], 0, 0, 0);
;         __builtin_amdgcn_sched_barrier(0);
;         if (wr_ok) *(uint4*)(nB + soff0) = rb0;
	ds_write_b128 v19, v[120:123] offset:40960
	v_mfma_f32_16x16x32_bf16 v[62:65], v[140:143], v[144:147], v[62:65]
	ds_read_b128 v[120:123], v20 offset:4096
	v_mfma_f32_16x16x32_bf16 v[74:77], v[156:159], v[144:147], v[74:77]
	ds_read_b128 v[180:183], v21 offset:20480
	v_mfma_f32_16x16x32_bf16 v[34:37], v[160:163], v[144:147], v[34:37]
	global_load_dwordx4 v[144:147], v247, s[36:37] offset:1024
	v_mfma_f32_16x16x32_bf16 v[54:57], v[124:127], v[152:155], v[54:57]
	s_waitcnt vmcnt(8)
	ds_write_b128 v19, v[148:151] offset:45056
	v_mfma_f32_16x16x32_bf16 v[66:69], v[140:143], v[152:155], v[66:69]
	ds_read_b128 v[148:151], v20 offset:6144
	v_mfma_f32_16x16x32_bf16 v[70:73], v[156:159], v[152:155], v[70:73]
	ds_read_b128 v[184:187], v21 offset:22528
	v_mfma_f32_16x16x32_bf16 v[38:41], v[160:163], v[152:155], v[38:41]
	s_waitcnt lgkmcnt(9)
	v_mfma_f32_16x16x32_bf16 v[42:45], v[172:175], v[168:171], v[42:45]
	global_load_dwordx4 v[124:127], v18, s[6:7] offset:1024
	s_waitcnt lgkmcnt(0)
	v_mfma_f32_16x16x32_bf16 v[26:29], v[184:187], v[168:171], v[26:29]
	s_waitcnt vmcnt(8)
	ds_write_b128 v19, v[136:139] offset:49152
	v_mfma_f32_16x16x32_bf16 v[96:99], v[176:179], v[168:171], v[96:99]
	v_mfma_f32_16x16x32_bf16 v[104:107], v[180:183], v[168:171], v[104:107]
	global_load_dwordx4 v[136:139], v248, s[6:7] offset:1024
	v_mfma_f32_16x16x32_bf16 v[46:49], v[172:175], v[108:111], v[46:49]
	s_waitcnt vmcnt(8)
	ds_write_b128 v19, v[132:135] offset:53248
	v_mfma_f32_16x16x32_bf16 v[58:61], v[176:179], v[108:111], v[58:61]
	v_mfma_f32_16x16x32_bf16 v[30:33], v[184:187], v[108:111], v[30:33]
	v_mfma_f32_16x16x32_bf16 v[100:103], v[180:183], v[108:111], v[100:103]
	global_load_dwordx4 v[108:111], v249, s[6:7] offset:1024
	v_mfma_f32_16x16x32_bf16 v[50:53], v[172:175], v[120:123], v[50:53]
	s_waitcnt vmcnt(8)
	ds_write_b128 v19, v[92:95] offset:57344
	v_mfma_f32_16x16x32_bf16 v[62:65], v[176:179], v[120:123], v[62:65]
	v_mfma_f32_16x16x32_bf16 v[74:77], v[180:183], v[120:123], v[74:77]
	v_mfma_f32_16x16x32_bf16 v[34:37], v[184:187], v[120:123], v[34:37]
	global_load_dwordx4 v[92:95], v250, s[6:7] offset:1024
	v_mfma_f32_16x16x32_bf16 v[54:57], v[172:175], v[148:151], v[54:57]
	s_waitcnt vmcnt(8)
	ds_write_b128 v19, v[112:115] offset:61440
	v_mfma_f32_16x16x32_bf16 v[66:69], v[176:179], v[148:151], v[66:69]
	v_mfma_f32_16x16x32_bf16 v[70:73], v[180:183], v[148:151], v[70:73]
	v_mfma_f32_16x16x32_bf16 v[38:41], v[184:187], v[148:151], v[38:41]
	s_setprio 0
	s_waitcnt lgkmcnt(0)
	s_barrier
	ds_read_b128 v[112:115], v22 offset:32768
	ds_read_b128 v[120:123], v22 offset:34816
	ds_read_b128 v[132:135], v23 offset:49152
	ds_read_b128 v[140:143], v23 offset:51200
	ds_read_b128 v[148:151], v22 offset:36864
	ds_read_b128 v[152:155], v22 offset:38912
	ds_read_b128 v[156:159], v23 offset:53248
	ds_read_b128 v[160:163], v23 offset:55296
	s_setprio 2
	s_waitcnt lgkmcnt(5)
	v_mfma_f32_16x16x32_bf16 v[42:45], v[132:135], v[112:115], v[42:45]
	global_load_dwordx4 v[168:171], v24, s[36:37] offset:1152
	s_waitcnt lgkmcnt(0)
	v_mfma_f32_16x16x32_bf16 v[26:29], v[160:163], v[112:115], v[26:29]
	s_waitcnt vmcnt(8)
	ds_write_b128 v19, v[164:167]
	v_mfma_f32_16x16x32_bf16 v[96:99], v[140:143], v[112:115], v[96:99]
	ds_read_b128 v[164:167], v20 offset:32768
	v_mfma_f32_16x16x32_bf16 v[104:107], v[156:159], v[112:115], v[104:107]
	ds_read_b128 v[172:175], v21 offset:49152
	global_load_dwordx4 v[112:115], v245, s[36:37] offset:1152
	v_mfma_f32_16x16x32_bf16 v[46:49], v[132:135], v[120:123], v[46:49]
	s_waitcnt vmcnt(8)
	ds_write_b128 v19, v[78:81] offset:4096
	v_mfma_f32_16x16x32_bf16 v[58:61], v[140:143], v[120:123], v[58:61]
	ds_read_b128 v[78:81], v20 offset:34816
	v_mfma_f32_16x16x32_bf16 v[30:33], v[160:163], v[120:123], v[30:33]
	ds_read_b128 v[176:179], v21 offset:51200
	v_mfma_f32_16x16x32_bf16 v[100:103], v[156:159], v[120:123], v[100:103]
	global_load_dwordx4 v[120:123], v246, s[36:37] offset:1152
	v_mfma_f32_16x16x32_bf16 v[50:53], v[132:135], v[148:151], v[50:53]
	s_waitcnt vmcnt(8)
	ds_write_b128 v19, v[116:119] offset:8192
	v_mfma_f32_16x16x32_bf16 v[62:65], v[140:143], v[148:151], v[62:65]
	ds_read_b128 v[116:119], v20 offset:36864
	v_mfma_f32_16x16x32_bf16 v[74:77], v[156:159], v[148:151], v[74:77]
	ds_read_b128 v[180:183], v21 offset:53248
	v_mfma_f32_16x16x32_bf16 v[34:37], v[160:163], v[148:151], v[34:37]
	global_load_dwordx4 v[148:151], v247, s[36:37] offset:1152
	v_mfma_f32_16x16x32_bf16 v[54:57], v[132:135], v[152:155], v[54:57]
	s_waitcnt vmcnt(8)
	ds_write_b128 v19, v[144:147] offset:12288
	v_mfma_f32_16x16x32_bf16 v[66:69], v[140:143], v[152:155], v[66:69]
	ds_read_b128 v[144:147], v20 offset:38912
	v_mfma_f32_16x16x32_bf16 v[70:73], v[156:159], v[152:155], v[70:73]
	ds_read_b128 v[184:187], v21 offset:55296
	v_mfma_f32_16x16x32_bf16 v[38:41], v[160:163], v[152:155], v[38:41]
	s_waitcnt lgkmcnt(9)
	v_mfma_f32_16x16x32_bf16 v[42:45], v[172:175], v[164:167], v[42:45]
	global_load_dwordx4 v[132:135], v18, s[6:7] offset:1152
	s_waitcnt lgkmcnt(0)
	v_mfma_f32_16x16x32_bf16 v[26:29], v[184:187], v[164:167], v[26:29]
	s_waitcnt vmcnt(8)
	ds_write_b128 v19, v[124:127] offset:16384
	v_mfma_f32_16x16x32_bf16 v[96:99], v[176:179], v[164:167], v[96:99]
	v_mfma_f32_16x16x32_bf16 v[104:107], v[180:183], v[164:167], v[104:107]
	global_load_dwordx4 v[124:127], v248, s[6:7] offset:1152
	v_mfma_f32_16x16x32_bf16 v[46:49], v[172:175], v[78:81], v[46:49]
	s_waitcnt vmcnt(8)
	ds_write_b128 v19, v[136:139] offset:20480
	v_mfma_f32_16x16x32_bf16 v[58:61], v[176:179], v[78:81], v[58:61]
	v_mfma_f32_16x16x32_bf16 v[30:33], v[184:187], v[78:81], v[30:33]
	v_mfma_f32_16x16x32_bf16 v[100:103], v[180:183], v[78:81], v[100:103]
	global_load_dwordx4 v[78:81], v249, s[6:7] offset:1152
	v_mfma_f32_16x16x32_bf16 v[50:53], v[172:175], v[116:119], v[50:53]
	s_waitcnt vmcnt(8)
	ds_write_b128 v19, v[108:111] offset:24576
	v_mfma_f32_16x16x32_bf16 v[62:65], v[176:179], v[116:119], v[62:65]
	v_mfma_f32_16x16x32_bf16 v[74:77], v[180:183], v[116:119], v[74:77]
	v_mfma_f32_16x16x32_bf16 v[34:37], v[184:187], v[116:119], v[34:37]
	global_load_dwordx4 v[108:111], v250, s[6:7] offset:1152
	v_mfma_f32_16x16x32_bf16 v[54:57], v[172:175], v[144:147], v[54:57]
	s_waitcnt vmcnt(8)
	ds_write_b128 v19, v[92:95] offset:28672
	v_mfma_f32_16x16x32_bf16 v[66:69], v[176:179], v[144:147], v[66:69]
	v_mfma_f32_16x16x32_bf16 v[70:73], v[180:183], v[144:147], v[70:73]
	v_mfma_f32_16x16x32_bf16 v[38:41], v[184:187], v[144:147], v[38:41]
	s_setprio 0
	s_waitcnt lgkmcnt(0)
	s_barrier
; template <int MODE>
; __device__ __forceinline__ void gemm_tile(const Params& P, int tm, int tn, unsigned char* smem) {
;     ...
; #pragma unroll
;         for (int i = 0; i < 4; ++i) { fa[i] = *(const bf16x8*)(sA + arow_off + i * 2048 + ch0); fb[i] = *(const bf16x8*)(sB + brow_off + i * 2048 + ch0); }
;         __builtin_amdgcn_sched_barrier(0);
;         __builtin_amdgcn_s_setprio(2);
;         if (wr_ok) *(uint4*)(nA + soff0) = ra0;
;         if (ld_ok) ra0 = *(const uint4*)(Ab + (aoff + 0u * LDA + koa));
;         ga[0] = *(const bf16x8*)(sA + arow_off + 0 * 2048 + ch1); gb[0] = *(const bf16x8*)(sB + brow_off + 0 * 2048 + ch1);
;         __builtin_amdgcn_sched_barrier(0);
; #pragma unroll
;         for (int j = 0; j < 4; ++j) acc[0][j] = __builtin_amdgcn_mfma_f32_16x16x32_bf16(fb[j], fa[0], acc[0][j], 0, 0, 0);
;         __builtin_amdgcn_sched_barrier(0);
;         if (wr_ok) *(uint4*)(nA + soff0 + 4096) = ra1;
;         if (ld_ok) ra1 = *(const uint4*)(Ab + (aoff + 32u * LDA + koa));
;         ga[1] = *(const bf16x8*)(sA + arow_off + 1 * 2048 + ch1); gb[1] = *(const bf16x8*)(sB + brow_off + 1 * 2048 + ch1);
;         __builtin_amdgcn_sched_barrier(0);
; #pragma unroll
;         for (int j = 0; j < 4; ++j) acc[1][j] = __builtin_amdgcn_mfma_f32_16x16x32_bf16(fb[j], fa[1], acc[1][j], 0, 0, 0);
;         __builtin_amdgcn_sched_barrier(0);
;         if (wr_ok) *(uint4*)(nA + soff0 + 8192) = ra2;
;         if (ld_ok) ra2 = *(const uint4*)(Ab + (aoff + 64u * LDA + koa));
;         ga[2] = *(const bf16x8*)(sA + arow_off + 2 * 2048 + ch1); gb[2] = *(const bf16x8*)(sB + brow_off + 2 * 2048 + ch1);
;         __builtin_amdgcn_sched_barrier(0);
; #pragma unroll
;         for (int j = 0; j < 4; ++j) acc[2][j] = __builtin_amdgcn_mfma_f32_16x16x32_bf16(fb[j], fa[2], acc[2][j], 0, 0, 0);
;         __builtin_amdgcn_sched_barrier(0);
;         if (wr_ok) *(uint4*)(nA + soff0 + 12288) = ra3;
;         if (ld_ok) ra3 = *(const uint4*)(Ab + (aoff + 96u * LDA + koa));
;         ga[3] = *(const bf16x8*)(sA + arow_off + 3 * 2048 + ch1); gb[3] = *(const bf16x8*)(sB + brow_off + 3 * 2048 + ch1);
;         __builtin_amdgcn_sched_barrier(0);
; #pragma unroll
;         for (int j = 0; j < 4; ++j) acc[3][j] = __builtin_amdgcn_mfma_f32_16x16x32_bf16(fb[j], fa[3], acc[3][j], 0, 0, 0);
;         __builtin_amdgcn_sched_barrier(0);
;         if (wr_ok) *(uint4*)(nB + soff0) = rb0;
	ds_read_b128 v[92:95], v22
	ds_read_b128 v[116:119], v22 offset:2048
	ds_read_b128 v[136:139], v23 offset:16384
	ds_read_b128 v[140:143], v23 offset:18432
	ds_read_b128 v[144:147], v22 offset:4096
	ds_read_b128 v[152:155], v22 offset:6144
	ds_read_b128 v[156:159], v23 offset:20480
	ds_read_b128 v[160:163], v23 offset:22528
	s_setprio 2
	s_waitcnt lgkmcnt(5)
	v_mfma_f32_16x16x32_bf16 v[42:45], v[136:139], v[92:95], v[42:45]
	global_load_dwordx4 v[164:167], v24, s[36:37] offset:1280
	s_waitcnt lgkmcnt(0)
	v_mfma_f32_16x16x32_bf16 v[26:29], v[160:163], v[92:95], v[26:29]
	s_waitcnt vmcnt(8)
	ds_write_b128 v19, v[168:171] offset:32768
	v_mfma_f32_16x16x32_bf16 v[96:99], v[140:143], v[92:95], v[96:99]
	ds_read_b128 v[168:171], v20
	v_mfma_f32_16x16x32_bf16 v[104:107], v[156:159], v[92:95], v[104:107]
	ds_read_b128 v[172:175], v21 offset:16384
	global_load_dwordx4 v[92:95], v245, s[36:37] offset:1280
	v_mfma_f32_16x16x32_bf16 v[46:49], v[136:139], v[116:119], v[46:49]
	s_waitcnt vmcnt(8)
	ds_write_b128 v19, v[112:115] offset:36864
	v_mfma_f32_16x16x32_bf16 v[58:61], v[140:143], v[116:119], v[58:61]
	ds_read_b128 v[112:115], v20 offset:2048
	v_mfma_f32_16x16x32_bf16 v[30:33], v[160:163], v[116:119], v[30:33]
	ds_read_b128 v[176:179], v21 offset:18432
	v_mfma_f32_16x16x32_bf16 v[100:103], v[156:159], v[116:119], v[100:103]
	global_load_dwordx4 v[116:119], v246, s[36:37] offset:1280
	v_mfma_f32_16x16x32_bf16 v[50:53], v[136:139], v[144:147], v[50:53]
	s_waitcnt vmcnt(8)
	ds_write_b128 v19, v[120:123] offset:40960
	v_mfma_f32_16x16x32_bf16 v[62:65], v[140:143], v[144:147], v[62:65]
	ds_read_b128 v[120:123], v20 offset:4096
	v_mfma_f32_16x16x32_bf16 v[74:77], v[156:159], v[144:147], v[74:77]
	ds_read_b128 v[180:183], v21 offset:20480
	v_mfma_f32_16x16x32_bf16 v[34:37], v[160:163], v[144:147], v[34:37]
	global_load_dwordx4 v[144:147], v247, s[36:37] offset:1280
	v_mfma_f32_16x16x32_bf16 v[54:57], v[136:139], v[152:155], v[54:57]
	s_waitcnt vmcnt(8)
	ds_write_b128 v19, v[148:151] offset:45056
	v_mfma_f32_16x16x32_bf16 v[66:69], v[140:143], v[152:155], v[66:69]
	ds_read_b128 v[148:151], v20 offset:6144
	v_mfma_f32_16x16x32_bf16 v[70:73], v[156:159], v[152:155], v[70:73]
	ds_read_b128 v[184:187], v21 offset:22528
	v_mfma_f32_16x16x32_bf16 v[38:41], v[160:163], v[152:155], v[38:41]
	s_waitcnt lgkmcnt(9)
	v_mfma_f32_16x16x32_bf16 v[42:45], v[172:175], v[168:171], v[42:45]
	global_load_dwordx4 v[136:139], v18, s[6:7] offset:1280
	s_waitcnt lgkmcnt(0)
	v_mfma_f32_16x16x32_bf16 v[26:29], v[184:187], v[168:171], v[26:29]
	s_waitcnt vmcnt(8)
	ds_write_b128 v19, v[132:135] offset:49152
	v_mfma_f32_16x16x32_bf16 v[96:99], v[176:179], v[168:171], v[96:99]
	v_mfma_f32_16x16x32_bf16 v[104:107], v[180:183], v[168:171], v[104:107]
	global_load_dwordx4 v[132:135], v248, s[6:7] offset:1280
	v_mfma_f32_16x16x32_bf16 v[46:49], v[172:175], v[112:115], v[46:49]
	s_waitcnt vmcnt(8)
	ds_write_b128 v19, v[124:127] offset:53248
	v_mfma_f32_16x16x32_bf16 v[58:61], v[176:179], v[112:115], v[58:61]
	v_mfma_f32_16x16x32_bf16 v[30:33], v[184:187], v[112:115], v[30:33]
	v_mfma_f32_16x16x32_bf16 v[100:103], v[180:183], v[112:115], v[100:103]
	global_load_dwordx4 v[112:115], v249, s[6:7] offset:1280
	v_mfma_f32_16x16x32_bf16 v[50:53], v[172:175], v[120:123], v[50:53]
	s_waitcnt vmcnt(8)
	ds_write_b128 v19, v[78:81] offset:57344
	v_mfma_f32_16x16x32_bf16 v[62:65], v[176:179], v[120:123], v[62:65]
	v_mfma_f32_16x16x32_bf16 v[74:77], v[180:183], v[120:123], v[74:77]
	v_mfma_f32_16x16x32_bf16 v[34:37], v[184:187], v[120:123], v[34:37]
	global_load_dwordx4 v[78:81], v250, s[6:7] offset:1280
	v_mfma_f32_16x16x32_bf16 v[54:57], v[172:175], v[148:151], v[54:57]
	s_waitcnt vmcnt(8)
	ds_write_b128 v19, v[108:111] offset:61440
	v_mfma_f32_16x16x32_bf16 v[66:69], v[176:179], v[148:151], v[66:69]
	v_mfma_f32_16x16x32_bf16 v[70:73], v[180:183], v[148:151], v[70:73]
	v_mfma_f32_16x16x32_bf16 v[38:41], v[184:187], v[148:151], v[38:41]
	s_setprio 0
	s_waitcnt lgkmcnt(0)
	s_barrier
	ds_read_b128 v[108:111], v22 offset:32768
	ds_read_b128 v[120:123], v22 offset:34816
	ds_read_b128 v[124:127], v23 offset:49152
	ds_read_b128 v[140:143], v23 offset:51200
	ds_read_b128 v[148:151], v22 offset:36864
	ds_read_b128 v[152:155], v22 offset:38912
	ds_read_b128 v[156:159], v23 offset:53248
	ds_read_b128 v[160:163], v23 offset:55296
	s_setprio 2
	s_waitcnt lgkmcnt(5)
	v_mfma_f32_16x16x32_bf16 v[42:45], v[124:127], v[108:111], v[42:45]
	global_load_dwordx4 v[168:171], v24, s[36:37] offset:1408
	s_waitcnt lgkmcnt(0)
	v_mfma_f32_16x16x32_bf16 v[26:29], v[160:163], v[108:111], v[26:29]
	s_waitcnt vmcnt(8)
	ds_write_b128 v19, v[164:167]
	v_mfma_f32_16x16x32_bf16 v[96:99], v[140:143], v[108:111], v[96:99]
	ds_read_b128 v[164:167], v20 offset:32768
	v_mfma_f32_16x16x32_bf16 v[104:107], v[156:159], v[108:111], v[104:107]
	ds_read_b128 v[172:175], v21 offset:49152
	global_load_dwordx4 v[108:111], v245, s[36:37] offset:1408
	v_mfma_f32_16x16x32_bf16 v[46:49], v[124:127], v[120:123], v[46:49]
	s_waitcnt vmcnt(8)
	ds_write_b128 v19, v[92:95] offset:4096
	v_mfma_f32_16x16x32_bf16 v[58:61], v[140:143], v[120:123], v[58:61]
	ds_read_b128 v[92:95], v20 offset:34816
	v_mfma_f32_16x16x32_bf16 v[30:33], v[160:163], v[120:123], v[30:33]
	ds_read_b128 v[176:179], v21 offset:51200
	v_mfma_f32_16x16x32_bf16 v[100:103], v[156:159], v[120:123], v[100:103]
	global_load_dwordx4 v[120:123], v246, s[36:37] offset:1408
	v_mfma_f32_16x16x32_bf16 v[50:53], v[124:127], v[148:151], v[50:53]
	s_waitcnt vmcnt(8)
; template <int MODE>
; __device__ __forceinline__ void gemm_tile(const Params& P, int tm, int tn, unsigned char* smem) {
;     ...
; #pragma unroll
;         for (int i = 0; i < 4; ++i) { fa[i] = *(const bf16x8*)(sA + arow_off + i * 2048 + ch0); fb[i] = *(const bf16x8*)(sB + brow_off + i * 2048 + ch0); }
;         __builtin_amdgcn_sched_barrier(0);
;         __builtin_amdgcn_s_setprio(2);
;         if (wr_ok) *(uint4*)(nA + soff0) = ra0;
;         if (ld_ok) ra0 = *(const uint4*)(Ab + (aoff + 0u * LDA + koa));
;         ga[0] = *(const bf16x8*)(sA + arow_off + 0 * 2048 + ch1); gb[0] = *(const bf16x8*)(sB + brow_off + 0 * 2048 + ch1);
;         __builtin_amdgcn_sched_barrier(0);
; #pragma unroll
;         for (int j = 0; j < 4; ++j) acc[0][j] = __builtin_amdgcn_mfma_f32_16x16x32_bf16(fb[j], fa[0], acc[0][j], 0, 0, 0);
;         __builtin_amdgcn_sched_barrier(0);
;         if (wr_ok) *(uint4*)(nA + soff0 + 4096) = ra1;
;         if (ld_ok) ra1 = *(const uint4*)(Ab + (aoff + 32u * LDA + koa));
;         ga[1] = *(const bf16x8*)(sA + arow_off + 1 * 2048 + ch1); gb[1] = *(const bf16x8*)(sB + brow_off + 1 * 2048 + ch1);
;         __builtin_amdgcn_sched_barrier(0);
; #pragma unroll
;         for (int j = 0; j < 4; ++j) acc[1][j] = __builtin_amdgcn_mfma_f32_16x16x32_bf16(fb[j], fa[1], acc[1][j], 0, 0, 0);
;         __builtin_amdgcn_sched_barrier(0);
;         if (wr_ok) *(uint4*)(nA + soff0 + 8192) = ra2;
;         if (ld_ok) ra2 = *(const uint4*)(Ab + (aoff + 64u * LDA + koa));
;         ga[2] = *(const bf16x8*)(sA + arow_off + 2 * 2048 + ch1); gb[2] = *(const bf16x8*)(sB + brow_off + 2 * 2048 + ch1);
;         __builtin_amdgcn_sched_barrier(0);
; #pragma unroll
;         for (int j = 0; j < 4; ++j) acc[2][j] = __builtin_amdgcn_mfma_f32_16x16x32_bf16(fb[j], fa[2], acc[2][j], 0, 0, 0);
;         __builtin_amdgcn_sched_barrier(0);
;         if (wr_ok) *(uint4*)(nA + soff0 + 12288) = ra3;
;         if (ld_ok) ra3 = *(const uint4*)(Ab + (aoff + 96u * LDA + koa));
;         ga[3] = *(const bf16x8*)(sA + arow_off + 3 * 2048 + ch1); gb[3] = *(const bf16x8*)(sB + brow_off + 3 * 2048 + ch1);
;         __builtin_amdgcn_sched_barrier(0);
; #pragma unroll
;         for (int j = 0; j < 4; ++j) acc[3][j] = __builtin_amdgcn_mfma_f32_16x16x32_bf16(fb[j], fa[3], acc[3][j], 0, 0, 0);
;         __builtin_amdgcn_sched_barrier(0);
;         if (wr_ok) *(uint4*)(nB + soff0) = rb0;
	ds_write_b128 v19, v[116:119] offset:8192
	v_mfma_f32_16x16x32_bf16 v[62:65], v[140:143], v[148:151], v[62:65]
	ds_read_b128 v[116:119], v20 offset:36864
	v_mfma_f32_16x16x32_bf16 v[74:77], v[156:159], v[148:151], v[74:77]
	ds_read_b128 v[180:183], v21 offset:53248
	v_mfma_f32_16x16x32_bf16 v[34:37], v[160:163], v[148:151], v[34:37]
	global_load_dwordx4 v[148:151], v247, s[36:37] offset:1408
	v_mfma_f32_16x16x32_bf16 v[54:57], v[124:127], v[152:155], v[54:57]
	s_waitcnt vmcnt(8)
	ds_write_b128 v19, v[144:147] offset:12288
	v_mfma_f32_16x16x32_bf16 v[66:69], v[140:143], v[152:155], v[66:69]
	ds_read_b128 v[144:147], v20 offset:38912
	v_mfma_f32_16x16x32_bf16 v[70:73], v[156:159], v[152:155], v[70:73]
	ds_read_b128 v[184:187], v21 offset:55296
	v_mfma_f32_16x16x32_bf16 v[38:41], v[160:163], v[152:155], v[38:41]
	s_waitcnt lgkmcnt(9)
	v_mfma_f32_16x16x32_bf16 v[42:45], v[172:175], v[164:167], v[42:45]
	global_load_dwordx4 v[124:127], v18, s[6:7] offset:1408
	s_waitcnt lgkmcnt(0)
	v_mfma_f32_16x16x32_bf16 v[26:29], v[184:187], v[164:167], v[26:29]
	s_waitcnt vmcnt(8)
	ds_write_b128 v19, v[136:139] offset:16384
	v_mfma_f32_16x16x32_bf16 v[96:99], v[176:179], v[164:167], v[96:99]
	v_mfma_f32_16x16x32_bf16 v[104:107], v[180:183], v[164:167], v[104:107]
	global_load_dwordx4 v[136:139], v248, s[6:7] offset:1408
	v_mfma_f32_16x16x32_bf16 v[46:49], v[172:175], v[92:95], v[46:49]
	s_waitcnt vmcnt(8)
	ds_write_b128 v19, v[132:135] offset:20480
	v_mfma_f32_16x16x32_bf16 v[58:61], v[176:179], v[92:95], v[58:61]
	v_mfma_f32_16x16x32_bf16 v[30:33], v[184:187], v[92:95], v[30:33]
	v_mfma_f32_16x16x32_bf16 v[100:103], v[180:183], v[92:95], v[100:103]
	global_load_dwordx4 v[92:95], v249, s[6:7] offset:1408
	v_mfma_f32_16x16x32_bf16 v[50:53], v[172:175], v[116:119], v[50:53]
	s_waitcnt vmcnt(8)
	ds_write_b128 v19, v[112:115] offset:24576
	v_mfma_f32_16x16x32_bf16 v[62:65], v[176:179], v[116:119], v[62:65]
	v_mfma_f32_16x16x32_bf16 v[74:77], v[180:183], v[116:119], v[74:77]
	v_mfma_f32_16x16x32_bf16 v[34:37], v[184:187], v[116:119], v[34:37]
	global_load_dwordx4 v[112:115], v250, s[6:7] offset:1408
	v_mfma_f32_16x16x32_bf16 v[54:57], v[172:175], v[144:147], v[54:57]
	s_waitcnt vmcnt(8)
	ds_write_b128 v19, v[78:81] offset:28672
	v_mfma_f32_16x16x32_bf16 v[66:69], v[176:179], v[144:147], v[66:69]
	v_mfma_f32_16x16x32_bf16 v[70:73], v[180:183], v[144:147], v[70:73]
	v_mfma_f32_16x16x32_bf16 v[38:41], v[184:187], v[144:147], v[38:41]
	s_setprio 0
	s_waitcnt lgkmcnt(0)
	s_barrier
	ds_read_b128 v[78:81], v22
	ds_read_b128 v[116:119], v22 offset:2048
	ds_read_b128 v[132:135], v23 offset:16384
	ds_read_b128 v[140:143], v23 offset:18432
	ds_read_b128 v[144:147], v22 offset:4096
	ds_read_b128 v[152:155], v22 offset:6144
	ds_read_b128 v[156:159], v23 offset:20480
	ds_read_b128 v[160:163], v23 offset:22528
	s_setprio 2
	s_waitcnt lgkmcnt(5)
	v_mfma_f32_16x16x32_bf16 v[42:45], v[132:135], v[78:81], v[42:45]
	global_load_dwordx4 v[164:167], v24, s[36:37] offset:1536
	s_waitcnt lgkmcnt(0)
	v_mfma_f32_16x16x32_bf16 v[26:29], v[160:163], v[78:81], v[26:29]
	s_waitcnt vmcnt(8)
	ds_write_b128 v19, v[168:171] offset:32768
	v_mfma_f32_16x16x32_bf16 v[96:99], v[140:143], v[78:81], v[96:99]
	ds_read_b128 v[168:171], v20
	v_mfma_f32_16x16x32_bf16 v[104:107], v[156:159], v[78:81], v[104:107]
	ds_read_b128 v[172:175], v21 offset:16384
	global_load_dwordx4 v[78:81], v245, s[36:37] offset:1536
	v_mfma_f32_16x16x32_bf16 v[46:49], v[132:135], v[116:119], v[46:49]
	s_waitcnt vmcnt(8)
	ds_write_b128 v19, v[108:111] offset:36864
	v_mfma_f32_16x16x32_bf16 v[58:61], v[140:143], v[116:119], v[58:61]
	ds_read_b128 v[108:111], v20 offset:2048
	v_mfma_f32_16x16x32_bf16 v[30:33], v[160:163], v[116:119], v[30:33]
	ds_read_b128 v[176:179], v21 offset:18432
	v_mfma_f32_16x16x32_bf16 v[100:103], v[156:159], v[116:119], v[100:103]
	global_load_dwordx4 v[116:119], v246, s[36:37] offset:1536
	v_mfma_f32_16x16x32_bf16 v[50:53], v[132:135], v[144:147], v[50:53]
	s_waitcnt vmcnt(8)
	ds_write_b128 v19, v[120:123] offset:40960
	v_mfma_f32_16x16x32_bf16 v[62:65], v[140:143], v[144:147], v[62:65]
	ds_read_b128 v[120:123], v20 offset:4096
	v_mfma_f32_16x16x32_bf16 v[74:77], v[156:159], v[144:147], v[74:77]
	ds_read_b128 v[180:183], v21 offset:20480
	v_mfma_f32_16x16x32_bf16 v[34:37], v[160:163], v[144:147], v[34:37]
	global_load_dwordx4 v[144:147], v247, s[36:37] offset:1536
	v_mfma_f32_16x16x32_bf16 v[54:57], v[132:135], v[152:155], v[54:57]
	s_waitcnt vmcnt(8)
	ds_write_b128 v19, v[148:151] offset:45056
	v_mfma_f32_16x16x32_bf16 v[66:69], v[140:143], v[152:155], v[66:69]
	ds_read_b128 v[148:151], v20 offset:6144
	v_mfma_f32_16x16x32_bf16 v[70:73], v[156:159], v[152:155], v[70:73]
	ds_read_b128 v[184:187], v21 offset:22528
	v_mfma_f32_16x16x32_bf16 v[38:41], v[160:163], v[152:155], v[38:41]
	s_waitcnt lgkmcnt(9)
	v_mfma_f32_16x16x32_bf16 v[42:45], v[172:175], v[168:171], v[42:45]
	global_load_dwordx4 v[132:135], v18, s[6:7] offset:1536
	s_waitcnt lgkmcnt(0)
	v_mfma_f32_16x16x32_bf16 v[26:29], v[184:187], v[168:171], v[26:29]
	s_waitcnt vmcnt(8)
	ds_write_b128 v19, v[124:127] offset:49152
	v_mfma_f32_16x16x32_bf16 v[96:99], v[176:179], v[168:171], v[96:99]
	v_mfma_f32_16x16x32_bf16 v[104:107], v[180:183], v[168:171], v[104:107]
	global_load_dwordx4 v[124:127], v248, s[6:7] offset:1536
	v_mfma_f32_16x16x32_bf16 v[46:49], v[172:175], v[108:111], v[46:49]
	s_waitcnt vmcnt(8)
	ds_write_b128 v19, v[136:139] offset:53248
	v_mfma_f32_16x16x32_bf16 v[58:61], v[176:179], v[108:111], v[58:61]
	v_mfma_f32_16x16x32_bf16 v[30:33], v[184:187], v[108:111], v[30:33]
	v_mfma_f32_16x16x32_bf16 v[100:103], v[180:183], v[108:111], v[100:103]
	global_load_dwordx4 v[108:111], v249, s[6:7] offset:1536
	v_mfma_f32_16x16x32_bf16 v[50:53], v[172:175], v[120:123], v[50:53]
	s_waitcnt vmcnt(8)
	ds_write_b128 v19, v[92:95] offset:57344
	v_mfma_f32_16x16x32_bf16 v[62:65], v[176:179], v[120:123], v[62:65]
	v_mfma_f32_16x16x32_bf16 v[74:77], v[180:183], v[120:123], v[74:77]
	v_mfma_f32_16x16x32_bf16 v[34:37], v[184:187], v[120:123], v[34:37]
	global_load_dwordx4 v[92:95], v250, s[6:7] offset:1536
	v_mfma_f32_16x16x32_bf16 v[54:57], v[172:175], v[148:151], v[54:57]
	s_waitcnt vmcnt(8)
	ds_write_b128 v19, v[112:115] offset:61440
	v_mfma_f32_16x16x32_bf16 v[66:69], v[176:179], v[148:151], v[66:69]
	v_mfma_f32_16x16x32_bf16 v[70:73], v[180:183], v[148:151], v[70:73]
	v_mfma_f32_16x16x32_bf16 v[38:41], v[184:187], v[148:151], v[38:41]
	s_setprio 0
	s_waitcnt lgkmcnt(0)
	s_barrier
; template <int MODE>
; __device__ __forceinline__ void gemm_tile(const Params& P, int tm, int tn, unsigned char* smem) {
;     ...
; #pragma unroll
;         for (int i = 0; i < 4; ++i) { fa[i] = *(const bf16x8*)(sA + arow_off + i * 2048 + ch0); fb[i] = *(const bf16x8*)(sB + brow_off + i * 2048 + ch0); }
;         __builtin_amdgcn_sched_barrier(0);
;         __builtin_amdgcn_s_setprio(2);
;         if (wr_ok) *(uint4*)(nA + soff0) = ra0;
;         if (ld_ok) ra0 = *(const uint4*)(Ab + (aoff + 0u * LDA + koa));
;         ga[0] = *(const bf16x8*)(sA + arow_off + 0 * 2048 + ch1); gb[0] = *(const bf16x8*)(sB + brow_off + 0 * 2048 + ch1);
;         __builtin_amdgcn_sched_barrier(0);
; #pragma unroll
;         for (int j = 0; j < 4; ++j) acc[0][j] = __builtin_amdgcn_mfma_f32_16x16x32_bf16(fb[j], fa[0], acc[0][j], 0, 0, 0);
;         __builtin_amdgcn_sched_barrier(0);
;         if (wr_ok) *(uint4*)(nA + soff0 + 4096) = ra1;
;         if (ld_ok) ra1 = *(const uint4*)(Ab + (aoff + 32u * LDA + koa));
;         ga[1] = *(const bf16x8*)(sA + arow_off + 1 * 2048 + ch1); gb[1] = *(const bf16x8*)(sB + brow_off + 1 * 2048 + ch1);
;         __builtin_amdgcn_sched_barrier(0);
; #pragma unroll
;         for (int j = 0; j < 4; ++j) acc[1][j] = __builtin_amdgcn_mfma_f32_16x16x32_bf16(fb[j], fa[1], acc[1][j], 0, 0, 0);
;         __builtin_amdgcn_sched_barrier(0);
;         if (wr_ok) *(uint4*)(nA + soff0 + 8192) = ra2;
;         if (ld_ok) ra2 = *(const uint4*)(Ab + (aoff + 64u * LDA + koa));
;         ga[2] = *(const bf16x8*)(sA + arow_off + 2 * 2048 + ch1); gb[2] = *(const bf16x8*)(sB + brow_off + 2 * 2048 + ch1);
;         __builtin_amdgcn_sched_barrier(0);
; #pragma unroll
;         for (int j = 0; j < 4; ++j) acc[2][j] = __builtin_amdgcn_mfma_f32_16x16x32_bf16(fb[j], fa[2], acc[2][j], 0, 0, 0);
;         __builtin_amdgcn_sched_barrier(0);
;         if (wr_ok) *(uint4*)(nA + soff0 + 12288) = ra3;
;         if (ld_ok) ra3 = *(const uint4*)(Ab + (aoff + 96u * LDA + koa));
;         ga[3] = *(const bf16x8*)(sA + arow_off + 3 * 2048 + ch1); gb[3] = *(const bf16x8*)(sB + brow_off + 3 * 2048 + ch1);
;         __builtin_amdgcn_sched_barrier(0);
; #pragma unroll
;         for (int j = 0; j < 4; ++j) acc[3][j] = __builtin_amdgcn_mfma_f32_16x16x32_bf16(fb[j], fa[3], acc[3][j], 0, 0, 0);
;         __builtin_amdgcn_sched_barrier(0);
;         if (wr_ok) *(uint4*)(nB + soff0) = rb0;
	ds_read_b128 v[112:115], v22 offset:32768
	ds_read_b128 v[120:123], v22 offset:34816
	ds_read_b128 v[136:139], v23 offset:49152
	ds_read_b128 v[140:143], v23 offset:51200
	ds_read_b128 v[148:151], v22 offset:36864
	ds_read_b128 v[152:155], v22 offset:38912
	ds_read_b128 v[156:159], v23 offset:53248
	ds_read_b128 v[160:163], v23 offset:55296
	s_setprio 2
	s_waitcnt lgkmcnt(5)
	v_mfma_f32_16x16x32_bf16 v[42:45], v[136:139], v[112:115], v[42:45]
	global_load_dwordx4 v[168:171], v24, s[36:37] offset:1664
	s_waitcnt lgkmcnt(0)
	v_mfma_f32_16x16x32_bf16 v[26:29], v[160:163], v[112:115], v[26:29]
	s_waitcnt vmcnt(8)
	ds_write_b128 v19, v[164:167]
	v_mfma_f32_16x16x32_bf16 v[96:99], v[140:143], v[112:115], v[96:99]
	ds_read_b128 v[164:167], v20 offset:32768
	v_mfma_f32_16x16x32_bf16 v[104:107], v[156:159], v[112:115], v[104:107]
	ds_read_b128 v[172:175], v21 offset:49152
	global_load_dwordx4 v[112:115], v245, s[36:37] offset:1664
	v_mfma_f32_16x16x32_bf16 v[46:49], v[136:139], v[120:123], v[46:49]
	s_waitcnt vmcnt(8)
	ds_write_b128 v19, v[78:81] offset:4096
	v_mfma_f32_16x16x32_bf16 v[58:61], v[140:143], v[120:123], v[58:61]
	ds_read_b128 v[78:81], v20 offset:34816
	v_mfma_f32_16x16x32_bf16 v[30:33], v[160:163], v[120:123], v[30:33]
	ds_read_b128 v[176:179], v21 offset:51200
	v_mfma_f32_16x16x32_bf16 v[100:103], v[156:159], v[120:123], v[100:103]
	global_load_dwordx4 v[120:123], v246, s[36:37] offset:1664
	v_mfma_f32_16x16x32_bf16 v[50:53], v[136:139], v[148:151], v[50:53]
	s_waitcnt vmcnt(8)
	ds_write_b128 v19, v[116:119] offset:8192
	v_mfma_f32_16x16x32_bf16 v[62:65], v[140:143], v[148:151], v[62:65]
	ds_read_b128 v[116:119], v20 offset:36864
	v_mfma_f32_16x16x32_bf16 v[74:77], v[156:159], v[148:151], v[74:77]
	ds_read_b128 v[180:183], v21 offset:53248
	v_mfma_f32_16x16x32_bf16 v[34:37], v[160:163], v[148:151], v[34:37]
	global_load_dwordx4 v[148:151], v247, s[36:37] offset:1664
	v_mfma_f32_16x16x32_bf16 v[54:57], v[136:139], v[152:155], v[54:57]
	s_waitcnt vmcnt(8)
	ds_write_b128 v19, v[144:147] offset:12288
	v_mfma_f32_16x16x32_bf16 v[66:69], v[140:143], v[152:155], v[66:69]
	ds_read_b128 v[144:147], v20 offset:38912
	v_mfma_f32_16x16x32_bf16 v[70:73], v[156:159], v[152:155], v[70:73]
	ds_read_b128 v[184:187], v21 offset:55296
	v_mfma_f32_16x16x32_bf16 v[38:41], v[160:163], v[152:155], v[38:41]
	s_waitcnt lgkmcnt(9)
	v_mfma_f32_16x16x32_bf16 v[42:45], v[172:175], v[164:167], v[42:45]
	global_load_dwordx4 v[136:139], v18, s[6:7] offset:1664
	s_waitcnt lgkmcnt(0)
	v_mfma_f32_16x16x32_bf16 v[26:29], v[184:187], v[164:167], v[26:29]
	s_waitcnt vmcnt(8)
	ds_write_b128 v19, v[132:135] offset:16384
	v_mfma_f32_16x16x32_bf16 v[96:99], v[176:179], v[164:167], v[96:99]
	v_mfma_f32_16x16x32_bf16 v[104:107], v[180:183], v[164:167], v[104:107]
	global_load_dwordx4 v[132:135], v248, s[6:7] offset:1664
	v_mfma_f32_16x16x32_bf16 v[46:49], v[172:175], v[78:81], v[46:49]
	s_waitcnt vmcnt(8)
	ds_write_b128 v19, v[124:127] offset:20480
	v_mfma_f32_16x16x32_bf16 v[58:61], v[176:179], v[78:81], v[58:61]
	v_mfma_f32_16x16x32_bf16 v[30:33], v[184:187], v[78:81], v[30:33]
	v_mfma_f32_16x16x32_bf16 v[100:103], v[180:183], v[78:81], v[100:103]
	global_load_dwordx4 v[78:81], v249, s[6:7] offset:1664
	v_mfma_f32_16x16x32_bf16 v[50:53], v[172:175], v[116:119], v[50:53]
	s_waitcnt vmcnt(8)
	ds_write_b128 v19, v[108:111] offset:24576
	v_mfma_f32_16x16x32_bf16 v[62:65], v[176:179], v[116:119], v[62:65]
	v_mfma_f32_16x16x32_bf16 v[74:77], v[180:183], v[116:119], v[74:77]
	v_mfma_f32_16x16x32_bf16 v[34:37], v[184:187], v[116:119], v[34:37]
	global_load_dwordx4 v[108:111], v250, s[6:7] offset:1664
	v_mfma_f32_16x16x32_bf16 v[54:57], v[172:175], v[144:147], v[54:57]
	s_waitcnt vmcnt(8)
	ds_write_b128 v19, v[92:95] offset:28672
	v_mfma_f32_16x16x32_bf16 v[66:69], v[176:179], v[144:147], v[66:69]
	v_mfma_f32_16x16x32_bf16 v[70:73], v[180:183], v[144:147], v[70:73]
	v_mfma_f32_16x16x32_bf16 v[38:41], v[184:187], v[144:147], v[38:41]
	s_setprio 0
	s_waitcnt lgkmcnt(0)
	s_barrier
	ds_read_b128 v[92:95], v22
	ds_read_b128 v[116:119], v22 offset:2048
	ds_read_b128 v[124:127], v23 offset:16384
	ds_read_b128 v[140:143], v23 offset:18432
	ds_read_b128 v[144:147], v22 offset:4096
	ds_read_b128 v[152:155], v22 offset:6144
	ds_read_b128 v[156:159], v23 offset:20480
	ds_read_b128 v[160:163], v23 offset:22528
	s_setprio 2
	s_waitcnt lgkmcnt(5)
	v_mfma_f32_16x16x32_bf16 v[42:45], v[124:127], v[92:95], v[42:45]
	global_load_dwordx4 v[164:167], v24, s[36:37] offset:1792
	s_waitcnt lgkmcnt(0)
	v_mfma_f32_16x16x32_bf16 v[26:29], v[160:163], v[92:95], v[26:29]
	s_waitcnt vmcnt(8)
	ds_write_b128 v19, v[168:171] offset:32768
	v_mfma_f32_16x16x32_bf16 v[96:99], v[140:143], v[92:95], v[96:99]
	ds_read_b128 v[168:171], v20
	v_mfma_f32_16x16x32_bf16 v[104:107], v[156:159], v[92:95], v[104:107]
	ds_read_b128 v[172:175], v21 offset:16384
	global_load_dwordx4 v[92:95], v245, s[36:37] offset:1792
	v_mfma_f32_16x16x32_bf16 v[46:49], v[124:127], v[116:119], v[46:49]
	s_waitcnt vmcnt(8)
	ds_write_b128 v19, v[112:115] offset:36864
	v_mfma_f32_16x16x32_bf16 v[58:61], v[140:143], v[116:119], v[58:61]
	ds_read_b128 v[112:115], v20 offset:2048
	v_mfma_f32_16x16x32_bf16 v[30:33], v[160:163], v[116:119], v[30:33]
	ds_read_b128 v[176:179], v21 offset:18432
	v_mfma_f32_16x16x32_bf16 v[100:103], v[156:159], v[116:119], v[100:103]
	global_load_dwordx4 v[116:119], v246, s[36:37] offset:1792
	v_mfma_f32_16x16x32_bf16 v[50:53], v[124:127], v[144:147], v[50:53]
	s_waitcnt vmcnt(8)
; template <int MODE>
; __device__ __forceinline__ void gemm_tile(const Params& P, int tm, int tn, unsigned char* smem) {
;     ...
; #pragma unroll
;         for (int i = 0; i < 4; ++i) { fa[i] = *(const bf16x8*)(sA + arow_off + i * 2048 + ch0); fb[i] = *(const bf16x8*)(sB + brow_off + i * 2048 + ch0); }
;         __builtin_amdgcn_sched_barrier(0);
;         __builtin_amdgcn_s_setprio(2);
;         if (wr_ok) *(uint4*)(nA + soff0) = ra0;
;         if (ld_ok) ra0 = *(const uint4*)(Ab + (aoff + 0u * LDA + koa));
;         ga[0] = *(const bf16x8*)(sA + arow_off + 0 * 2048 + ch1); gb[0] = *(const bf16x8*)(sB + brow_off + 0 * 2048 + ch1);
;         __builtin_amdgcn_sched_barrier(0);
; #pragma unroll
;         for (int j = 0; j < 4; ++j) acc[0][j] = __builtin_amdgcn_mfma_f32_16x16x32_bf16(fb[j], fa[0], acc[0][j], 0, 0, 0);
;         __builtin_amdgcn_sched_barrier(0);
;         if (wr_ok) *(uint4*)(nA + soff0 + 4096) = ra1;
;         if (ld_ok) ra1 = *(const uint4*)(Ab + (aoff + 32u * LDA + koa));
;         ga[1] = *(const bf16x8*)(sA + arow_off + 1 * 2048 + ch1); gb[1] = *(const bf16x8*)(sB + brow_off + 1 * 2048 + ch1);
;         __builtin_amdgcn_sched_barrier(0);
; #pragma unroll
;         for (int j = 0; j < 4; ++j) acc[1][j] = __builtin_amdgcn_mfma_f32_16x16x32_bf16(fb[j], fa[1], acc[1][j], 0, 0, 0);
;         __builtin_amdgcn_sched_barrier(0);
;         if (wr_ok) *(uint4*)(nA + soff0 + 8192) = ra2;
;         if (ld_ok) ra2 = *(const uint4*)(Ab + (aoff + 64u * LDA + koa));
;         ga[2] = *(const bf16x8*)(sA + arow_off + 2 * 2048 + ch1); gb[2] = *(const bf16x8*)(sB + brow_off + 2 * 2048 + ch1);
;         __builtin_amdgcn_sched_barrier(0);
; #pragma unroll
;         for (int j = 0; j < 4; ++j) acc[2][j] = __builtin_amdgcn_mfma_f32_16x16x32_bf16(fb[j], fa[2], acc[2][j], 0, 0, 0);
;         __builtin_amdgcn_sched_barrier(0);
;         if (wr_ok) *(uint4*)(nA + soff0 + 12288) = ra3;
;         if (ld_ok) ra3 = *(const uint4*)(Ab + (aoff + 96u * LDA + koa));
;         ga[3] = *(const bf16x8*)(sA + arow_off + 3 * 2048 + ch1); gb[3] = *(const bf16x8*)(sB + brow_off + 3 * 2048 + ch1);
;         __builtin_amdgcn_sched_barrier(0);
; #pragma unroll
;         for (int j = 0; j < 4; ++j) acc[3][j] = __builtin_amdgcn_mfma_f32_16x16x32_bf16(fb[j], fa[3], acc[3][j], 0, 0, 0);
;         __builtin_amdgcn_sched_barrier(0);
;         if (wr_ok) *(uint4*)(nB + soff0) = rb0;
	ds_write_b128 v19, v[120:123] offset:40960
	v_mfma_f32_16x16x32_bf16 v[62:65], v[140:143], v[144:147], v[62:65]
	ds_read_b128 v[120:123], v20 offset:4096
	v_mfma_f32_16x16x32_bf16 v[74:77], v[156:159], v[144:147], v[74:77]
	ds_read_b128 v[180:183], v21 offset:20480
	v_mfma_f32_16x16x32_bf16 v[34:37], v[160:163], v[144:147], v[34:37]
	global_load_dwordx4 v[144:147], v247, s[36:37] offset:1792
	v_mfma_f32_16x16x32_bf16 v[54:57], v[124:127], v[152:155], v[54:57]
	s_waitcnt vmcnt(8)
	ds_write_b128 v19, v[148:151] offset:45056
	v_mfma_f32_16x16x32_bf16 v[66:69], v[140:143], v[152:155], v[66:69]
	ds_read_b128 v[148:151], v20 offset:6144
	v_mfma_f32_16x16x32_bf16 v[70:73], v[156:159], v[152:155], v[70:73]
	ds_read_b128 v[184:187], v21 offset:22528
	v_mfma_f32_16x16x32_bf16 v[38:41], v[160:163], v[152:155], v[38:41]
	s_waitcnt lgkmcnt(9)
	v_mfma_f32_16x16x32_bf16 v[42:45], v[172:175], v[168:171], v[42:45]
	global_load_dwordx4 v[124:127], v18, s[6:7] offset:1792
	s_waitcnt lgkmcnt(0)
	v_mfma_f32_16x16x32_bf16 v[26:29], v[184:187], v[168:171], v[26:29]
	s_waitcnt vmcnt(8)
	ds_write_b128 v19, v[136:139] offset:49152
	v_mfma_f32_16x16x32_bf16 v[96:99], v[176:179], v[168:171], v[96:99]
	v_mfma_f32_16x16x32_bf16 v[104:107], v[180:183], v[168:171], v[104:107]
	global_load_dwordx4 v[136:139], v248, s[6:7] offset:1792
	v_mfma_f32_16x16x32_bf16 v[46:49], v[172:175], v[112:115], v[46:49]
	s_waitcnt vmcnt(8)
	ds_write_b128 v19, v[132:135] offset:53248
	v_mfma_f32_16x16x32_bf16 v[58:61], v[176:179], v[112:115], v[58:61]
	v_mfma_f32_16x16x32_bf16 v[30:33], v[184:187], v[112:115], v[30:33]
	v_mfma_f32_16x16x32_bf16 v[100:103], v[180:183], v[112:115], v[100:103]
	global_load_dwordx4 v[112:115], v249, s[6:7] offset:1792
	v_mfma_f32_16x16x32_bf16 v[50:53], v[172:175], v[120:123], v[50:53]
	s_waitcnt vmcnt(8)
	ds_write_b128 v19, v[78:81] offset:57344
	v_mfma_f32_16x16x32_bf16 v[62:65], v[176:179], v[120:123], v[62:65]
	v_mfma_f32_16x16x32_bf16 v[74:77], v[180:183], v[120:123], v[74:77]
	v_mfma_f32_16x16x32_bf16 v[34:37], v[184:187], v[120:123], v[34:37]
	global_load_dwordx4 v[78:81], v250, s[6:7] offset:1792
	v_mfma_f32_16x16x32_bf16 v[54:57], v[172:175], v[148:151], v[54:57]
	s_waitcnt vmcnt(8)
	ds_write_b128 v19, v[108:111] offset:61440
	v_mfma_f32_16x16x32_bf16 v[66:69], v[176:179], v[148:151], v[66:69]
	v_mfma_f32_16x16x32_bf16 v[70:73], v[180:183], v[148:151], v[70:73]
	v_mfma_f32_16x16x32_bf16 v[38:41], v[184:187], v[148:151], v[38:41]
	s_setprio 0
	s_waitcnt lgkmcnt(0)
	s_barrier
	ds_read_b128 v[108:111], v22 offset:32768
	ds_read_b128 v[120:123], v22 offset:34816
	ds_read_b128 v[132:135], v23 offset:49152
	ds_read_b128 v[140:143], v23 offset:51200
	ds_read_b128 v[148:151], v22 offset:36864
	ds_read_b128 v[152:155], v22 offset:38912
	ds_read_b128 v[156:159], v23 offset:53248
	ds_read_b128 v[160:163], v23 offset:55296
	s_setprio 2
	s_waitcnt lgkmcnt(5)
	v_mfma_f32_16x16x32_bf16 v[42:45], v[132:135], v[108:111], v[42:45]
	global_load_dwordx4 v[168:171], v24, s[36:37] offset:1920
	s_waitcnt lgkmcnt(0)
	v_mfma_f32_16x16x32_bf16 v[26:29], v[160:163], v[108:111], v[26:29]
	s_waitcnt vmcnt(8)
	ds_write_b128 v19, v[164:167]
	v_mfma_f32_16x16x32_bf16 v[96:99], v[140:143], v[108:111], v[96:99]
	ds_read_b128 v[164:167], v20 offset:32768
	v_mfma_f32_16x16x32_bf16 v[104:107], v[156:159], v[108:111], v[104:107]
	ds_read_b128 v[172:175], v21 offset:49152
	global_load_dwordx4 v[108:111], v245, s[36:37] offset:1920
	v_mfma_f32_16x16x32_bf16 v[46:49], v[132:135], v[120:123], v[46:49]
	s_waitcnt vmcnt(8)
	ds_write_b128 v19, v[92:95] offset:4096
	v_mfma_f32_16x16x32_bf16 v[58:61], v[140:143], v[120:123], v[58:61]
	ds_read_b128 v[92:95], v20 offset:34816
	v_mfma_f32_16x16x32_bf16 v[30:33], v[160:163], v[120:123], v[30:33]
	ds_read_b128 v[176:179], v21 offset:51200
	v_mfma_f32_16x16x32_bf16 v[100:103], v[156:159], v[120:123], v[100:103]
	global_load_dwordx4 v[120:123], v246, s[36:37] offset:1920
	v_mfma_f32_16x16x32_bf16 v[50:53], v[132:135], v[148:151], v[50:53]
	s_waitcnt vmcnt(8)
	ds_write_b128 v19, v[116:119] offset:8192
	v_mfma_f32_16x16x32_bf16 v[62:65], v[140:143], v[148:151], v[62:65]
	ds_read_b128 v[116:119], v20 offset:36864
	v_mfma_f32_16x16x32_bf16 v[74:77], v[156:159], v[148:151], v[74:77]
	ds_read_b128 v[180:183], v21 offset:53248
	v_mfma_f32_16x16x32_bf16 v[34:37], v[160:163], v[148:151], v[34:37]
	v_add_u32_e32 v24, 0x30780, v24
	global_load_dwordx4 v[148:151], v24, s[36:37]
	s_waitcnt vmcnt(8)
	ds_write_b128 v19, v[144:147] offset:12288
	ds_read_b128 v[144:147], v20 offset:38912
	ds_read_b128 v[184:187], v21 offset:55296
	v_mfma_f32_16x16x32_bf16 v[54:57], v[132:135], v[152:155], v[54:57]
	v_mfma_f32_16x16x32_bf16 v[66:69], v[140:143], v[152:155], v[66:69]
	v_mfma_f32_16x16x32_bf16 v[70:73], v[156:159], v[152:155], v[70:73]
	v_mfma_f32_16x16x32_bf16 v[38:41], v[160:163], v[152:155], v[38:41]
	s_waitcnt lgkmcnt(9)
	v_mfma_f32_16x16x32_bf16 v[42:45], v[172:175], v[164:167], v[42:45]
	global_load_dwordx4 v[132:135], v18, s[6:7] offset:1920
	s_waitcnt lgkmcnt(0)
	v_mfma_f32_16x16x32_bf16 v[24:27], v[184:187], v[164:167], v[26:29]
	s_waitcnt vmcnt(8)
	ds_write_b128 v19, v[124:127] offset:16384
	v_mfma_f32_16x16x32_bf16 v[96:99], v[176:179], v[164:167], v[96:99]
	v_mfma_f32_16x16x32_bf16 v[104:107], v[180:183], v[164:167], v[104:107]
	s_nop 0
	global_load_dwordx4 v[124:127], v248, s[6:7] offset:1920
	s_waitcnt vmcnt(8)
	ds_write_b128 v19, v[136:139] offset:20480
	v_mfma_f32_16x16x32_bf16 v[46:49], v[172:175], v[92:95], v[46:49]
	v_mfma_f32_16x16x32_bf16 v[58:61], v[176:179], v[92:95], v[58:61]
	v_mfma_f32_16x16x32_bf16 v[28:31], v[184:187], v[92:95], v[30:33]
	v_mfma_f32_16x16x32_bf16 v[100:103], v[180:183], v[92:95], v[100:103]
	s_nop 1
	global_load_dwordx4 v[92:95], v249, s[6:7] offset:1920
	s_waitcnt vmcnt(8)
	ds_write_b128 v19, v[112:115] offset:24576
	v_mfma_f32_16x16x32_bf16 v[50:53], v[172:175], v[116:119], v[50:53]
	v_mfma_f32_16x16x32_bf16 v[62:65], v[176:179], v[116:119], v[62:65]
	v_mfma_f32_16x16x32_bf16 v[74:77], v[180:183], v[116:119], v[74:77]
	v_mfma_f32_16x16x32_bf16 v[32:35], v[184:187], v[116:119], v[34:37]
	v_add_u32_e32 v18, 0x30780, v18
	global_load_dwordx4 v[112:115], v18, s[6:7]
	s_waitcnt vmcnt(8)
	ds_write_b128 v19, v[78:81] offset:28672
	v_mfma_f32_16x16x32_bf16 v[54:57], v[172:175], v[144:147], v[54:57]
	v_mfma_f32_16x16x32_bf16 v[66:69], v[176:179], v[144:147], v[66:69]
	v_mfma_f32_16x16x32_bf16 v[70:73], v[180:183], v[144:147], v[70:73]
	v_mfma_f32_16x16x32_bf16 v[36:39], v[184:187], v[144:147], v[38:41]
	s_setprio 0
	s_waitcnt lgkmcnt(0)
	s_barrier
; template <int MODE>
; __device__ __forceinline__ void gemm_tile(const Params& P, int tm, int tn, unsigned char* smem) {
;     ...
; #pragma unroll
;         for (int i = 0; i < 4; ++i) { fa[i] = *(const bf16x8*)(sA + arow_off + i * 2048 + ch0); fb[i] = *(const bf16x8*)(sB + brow_off + i * 2048 + ch0); }
;         __builtin_amdgcn_sched_barrier(0);
;         __builtin_amdgcn_s_setprio(2);
;         if (wr_ok) *(uint4*)(nA + soff0) = ra0;
;         if (ld_ok) ra0 = *(const uint4*)(Ab + (aoff + 0u * LDA + koa));
;         ga[0] = *(const bf16x8*)(sA + arow_off + 0 * 2048 + ch1); gb[0] = *(const bf16x8*)(sB + brow_off + 0 * 2048 + ch1);
;         __builtin_amdgcn_sched_barrier(0);
; #pragma unroll
;         for (int j = 0; j < 4; ++j) acc[0][j] = __builtin_amdgcn_mfma_f32_16x16x32_bf16(fb[j], fa[0], acc[0][j], 0, 0, 0);
;         __builtin_amdgcn_sched_barrier(0);
;         if (wr_ok) *(uint4*)(nA + soff0 + 4096) = ra1;
;         if (ld_ok) ra1 = *(const uint4*)(Ab + (aoff + 32u * LDA + koa));
;         ga[1] = *(const bf16x8*)(sA + arow_off + 1 * 2048 + ch1); gb[1] = *(const bf16x8*)(sB + brow_off + 1 * 2048 + ch1);
;         __builtin_amdgcn_sched_barrier(0);
; #pragma unroll
;         for (int j = 0; j < 4; ++j) acc[1][j] = __builtin_amdgcn_mfma_f32_16x16x32_bf16(fb[j], fa[1], acc[1][j], 0, 0, 0);
;         __builtin_amdgcn_sched_barrier(0);
;         if (wr_ok) *(uint4*)(nA + soff0 + 8192) = ra2;
;         if (ld_ok) ra2 = *(const uint4*)(Ab + (aoff + 64u * LDA + koa));
;         ga[2] = *(const bf16x8*)(sA + arow_off + 2 * 2048 + ch1); gb[2] = *(const bf16x8*)(sB + brow_off + 2 * 2048 + ch1);
;         __builtin_amdgcn_sched_barrier(0);
; #pragma unroll
;         for (int j = 0; j < 4; ++j) acc[2][j] = __builtin_amdgcn_mfma_f32_16x16x32_bf16(fb[j], fa[2], acc[2][j], 0, 0, 0);
;         __builtin_amdgcn_sched_barrier(0);
;         if (wr_ok) *(uint4*)(nA + soff0 + 12288) = ra3;
;         if (ld_ok) ra3 = *(const uint4*)(Ab + (aoff + 96u * LDA + koa));
;         ga[3] = *(const bf16x8*)(sA + arow_off + 3 * 2048 + ch1); gb[3] = *(const bf16x8*)(sB + brow_off + 3 * 2048 + ch1);
;         __builtin_amdgcn_sched_barrier(0);
; #pragma unroll
;         for (int j = 0; j < 4; ++j) acc[3][j] = __builtin_amdgcn_mfma_f32_16x16x32_bf16(fb[j], fa[3], acc[3][j], 0, 0, 0);
;         __builtin_amdgcn_sched_barrier(0);
;         if (wr_ok) *(uint4*)(nB + soff0) = rb0;
	ds_read_b128 v[78:81], v22
	ds_read_b128 v[116:119], v22 offset:2048
	ds_read_b128 v[136:139], v23 offset:16384
	ds_read_b128 v[140:143], v23 offset:18432
	ds_read_b128 v[144:147], v22 offset:4096
	ds_read_b128 v[152:155], v22 offset:6144
	ds_read_b128 v[156:159], v23 offset:20480
	ds_read_b128 v[160:163], v23 offset:22528
	s_setprio 2
	s_waitcnt lgkmcnt(5)
	v_mfma_f32_16x16x32_bf16 v[40:43], v[136:139], v[78:81], v[42:45]
	s_waitcnt lgkmcnt(0)
	v_mfma_f32_16x16x32_bf16 v[24:27], v[160:163], v[78:81], v[24:27]
	s_waitcnt vmcnt(7)
	ds_write_b128 v19, v[168:171] offset:32768
	v_mfma_f32_16x16x32_bf16 v[96:99], v[140:143], v[78:81], v[96:99]
	ds_read_b128 v[164:167], v20
	v_mfma_f32_16x16x32_bf16 v[104:107], v[156:159], v[78:81], v[104:107]
	ds_read_b128 v[168:171], v21 offset:16384
	v_mfma_f32_16x16x32_bf16 v[44:47], v[136:139], v[116:119], v[46:49]
	s_waitcnt vmcnt(6)
	ds_write_b128 v19, v[108:111] offset:36864
	v_mfma_f32_16x16x32_bf16 v[58:61], v[140:143], v[116:119], v[58:61]
	ds_read_b128 v[78:81], v20 offset:2048
	v_mfma_f32_16x16x32_bf16 v[28:31], v[160:163], v[116:119], v[28:31]
	ds_read_b128 v[108:111], v21 offset:18432
	v_mfma_f32_16x16x32_bf16 v[100:103], v[156:159], v[116:119], v[100:103]
	v_mfma_f32_16x16x32_bf16 v[48:51], v[136:139], v[144:147], v[50:53]
	s_waitcnt vmcnt(5)
	ds_write_b128 v19, v[120:123] offset:40960
	v_mfma_f32_16x16x32_bf16 v[62:65], v[140:143], v[144:147], v[62:65]
	ds_read_b128 v[116:119], v20 offset:4096
	v_mfma_f32_16x16x32_bf16 v[74:77], v[156:159], v[144:147], v[74:77]
	ds_read_b128 v[120:123], v21 offset:20480
	v_mfma_f32_16x16x32_bf16 v[32:35], v[160:163], v[144:147], v[32:35]
	v_mfma_f32_16x16x32_bf16 v[52:55], v[136:139], v[152:155], v[54:57]
	s_waitcnt vmcnt(4)
	ds_write_b128 v19, v[148:151] offset:45056
	v_mfma_f32_16x16x32_bf16 v[66:69], v[140:143], v[152:155], v[66:69]
	ds_read_b128 v[144:147], v20 offset:6144
	v_mfma_f32_16x16x32_bf16 v[70:73], v[156:159], v[152:155], v[70:73]
	ds_read_b128 v[148:151], v21 offset:22528
	v_mfma_f32_16x16x32_bf16 v[36:39], v[160:163], v[152:155], v[36:39]
	s_waitcnt lgkmcnt(9)
	v_mfma_f32_16x16x32_bf16 v[40:43], v[168:171], v[164:167], v[40:43]
	s_waitcnt lgkmcnt(0)
	v_mfma_f32_16x16x32_bf16 v[24:27], v[148:151], v[164:167], v[24:27]
	s_waitcnt vmcnt(3)
	ds_write_b128 v19, v[132:135] offset:49152
	v_mfma_f32_16x16x32_bf16 v[96:99], v[108:111], v[164:167], v[96:99]
	v_mfma_f32_16x16x32_bf16 v[104:107], v[120:123], v[164:167], v[104:107]
	v_mfma_f32_16x16x32_bf16 v[44:47], v[168:171], v[78:81], v[44:47]
	s_waitcnt vmcnt(2)
	ds_write_b128 v19, v[124:127] offset:53248
	v_mfma_f32_16x16x32_bf16 v[56:59], v[108:111], v[78:81], v[58:61]
	v_mfma_f32_16x16x32_bf16 v[28:31], v[148:151], v[78:81], v[28:31]
	v_mfma_f32_16x16x32_bf16 v[100:103], v[120:123], v[78:81], v[100:103]
	v_mfma_f32_16x16x32_bf16 v[48:51], v[168:171], v[116:119], v[48:51]
	s_waitcnt vmcnt(1)
	ds_write_b128 v19, v[92:95] offset:57344
	v_mfma_f32_16x16x32_bf16 v[60:63], v[108:111], v[116:119], v[62:65]
	v_mfma_f32_16x16x32_bf16 v[74:77], v[120:123], v[116:119], v[74:77]
	v_mfma_f32_16x16x32_bf16 v[32:35], v[148:151], v[116:119], v[32:35]
	v_mfma_f32_16x16x32_bf16 v[52:55], v[168:171], v[144:147], v[52:55]
	s_waitcnt vmcnt(0)
	ds_write_b128 v19, v[112:115] offset:61440
	v_mfma_f32_16x16x32_bf16 v[64:67], v[108:111], v[144:147], v[66:69]
	v_mfma_f32_16x16x32_bf16 v[68:71], v[120:123], v[144:147], v[70:73]
	v_mfma_f32_16x16x32_bf16 v[36:39], v[148:151], v[144:147], v[36:39]
	s_setprio 0
	s_waitcnt lgkmcnt(0)
	s_barrier
; template <int MODE>
; __device__ __forceinline__ void gemm_tile(const Params& P, int tm, int tn, unsigned char* smem) {
;     ...
; #pragma unroll
;         for (int i = 0; i < 4; ++i) { fa[i] = *(const bf16x8*)(sA + arow_off + i * 2048 + ch0); fb[i] = *(const bf16x8*)(sB + brow_off + i * 2048 + ch0); }
;         __builtin_amdgcn_sched_barrier(0);
;         __builtin_amdgcn_s_setprio(2);
;         if (wr_ok) *(uint4*)(nA + soff0) = ra0;
;         if (ld_ok) ra0 = *(const uint4*)(Ab + (aoff + 0u * LDA + koa));
;         ga[0] = *(const bf16x8*)(sA + arow_off + 0 * 2048 + ch1); gb[0] = *(const bf16x8*)(sB + brow_off + 0 * 2048 + ch1);
;         __builtin_amdgcn_sched_barrier(0);
; #pragma unroll
;         for (int j = 0; j < 4; ++j) acc[0][j] = __builtin_amdgcn_mfma_f32_16x16x32_bf16(fb[j], fa[0], acc[0][j], 0, 0, 0);
;         __builtin_amdgcn_sched_barrier(0);
;         if (wr_ok) *(uint4*)(nA + soff0 + 4096) = ra1;
;         if (ld_ok) ra1 = *(const uint4*)(Ab + (aoff + 32u * LDA + koa));
;         ga[1] = *(const bf16x8*)(sA + arow_off + 1 * 2048 + ch1); gb[1] = *(const bf16x8*)(sB + brow_off + 1 * 2048 + ch1);
;         __builtin_amdgcn_sched_barrier(0);
; #pragma unroll
;         for (int j = 0; j < 4; ++j) acc[1][j] = __builtin_amdgcn_mfma_f32_16x16x32_bf16(fb[j], fa[1], acc[1][j], 0, 0, 0);
;         __builtin_amdgcn_sched_barrier(0);
;         if (wr_ok) *(uint4*)(nA + soff0 + 8192) = ra2;
;         if (ld_ok) ra2 = *(const uint4*)(Ab + (aoff + 64u * LDA + koa));
;         ga[2] = *(const bf16x8*)(sA + arow_off + 2 * 2048 + ch1); gb[2] = *(const bf16x8*)(sB + brow_off + 2 * 2048 + ch1);
;         __builtin_amdgcn_sched_barrier(0);
; #pragma unroll
;         for (int j = 0; j < 4; ++j) acc[2][j] = __builtin_amdgcn_mfma_f32_16x16x32_bf16(fb[j], fa[2], acc[2][j], 0, 0, 0);
;         __builtin_amdgcn_sched_barrier(0);
;         if (wr_ok) *(uint4*)(nA + soff0 + 12288) = ra3;
;         if (ld_ok) ra3 = *(const uint4*)(Ab + (aoff + 96u * LDA + koa));
;         ga[3] = *(const bf16x8*)(sA + arow_off + 3 * 2048 + ch1); gb[3] = *(const bf16x8*)(sB + brow_off + 3 * 2048 + ch1);
;         __builtin_amdgcn_sched_barrier(0);
; #pragma unroll
;         for (int j = 0; j < 4; ++j) acc[3][j] = __builtin_amdgcn_mfma_f32_16x16x32_bf16(fb[j], fa[3], acc[3][j], 0, 0, 0);
;         __builtin_amdgcn_sched_barrier(0);
;         if (wr_ok) *(uint4*)(nB + soff0) = rb0;
	ds_read_b128 v[78:81], v22 offset:32768
	ds_read_b128 v[92:95], v22 offset:34816
	ds_read_b128 v[108:111], v23 offset:49152
	ds_read_b128 v[112:115], v23 offset:51200
	ds_read_b128 v[116:119], v22 offset:36864
	ds_read_b128 v[120:123], v22 offset:38912
	ds_read_b128 v[124:127], v23 offset:53248
	ds_read_b128 v[132:135], v23 offset:55296
	s_setprio 2
	s_waitcnt lgkmcnt(5)
	v_mfma_f32_16x16x32_bf16 v[40:43], v[108:111], v[78:81], v[40:43]
	s_waitcnt lgkmcnt(0)
	v_mfma_f32_16x16x32_bf16 v[22:25], v[132:135], v[78:81], v[24:27]
	ds_read_b128 v[136:139], v20 offset:32768
	v_mfma_f32_16x16x32_bf16 v[96:99], v[112:115], v[78:81], v[96:99]
	ds_read_b128 v[140:143], v21 offset:49152
	v_mfma_f32_16x16x32_bf16 v[104:107], v[124:127], v[78:81], v[104:107]
	v_mfma_f32_16x16x32_bf16 v[44:47], v[108:111], v[92:95], v[44:47]
	ds_read_b128 v[144:147], v20 offset:34816
	v_mfma_f32_16x16x32_bf16 v[56:59], v[112:115], v[92:95], v[56:59]
	ds_read_b128 v[148:151], v21 offset:51200
	v_mfma_f32_16x16x32_bf16 v[26:29], v[132:135], v[92:95], v[28:31]
	v_mfma_f32_16x16x32_bf16 v[100:103], v[124:127], v[92:95], v[100:103]
	v_mfma_f32_16x16x32_bf16 v[30:33], v[132:135], v[116:119], v[32:35]
	ds_read_b128 v[92:95], v20 offset:36864
	v_mfma_f32_16x16x32_bf16 v[156:159], v[108:111], v[116:119], v[48:51]
	ds_read_b128 v[152:155], v21 offset:53248
	v_mfma_f32_16x16x32_bf16 v[160:163], v[112:115], v[116:119], v[60:63]
	v_mfma_f32_16x16x32_bf16 v[164:167], v[124:127], v[116:119], v[74:77]
	v_mfma_f32_16x16x32_bf16 v[108:111], v[108:111], v[120:123], v[52:55]
	ds_read_b128 v[116:119], v20 offset:38912
	v_mfma_f32_16x16x32_bf16 v[112:115], v[112:115], v[120:123], v[64:67]
	ds_read_b128 v[18:21], v21 offset:55296
	v_mfma_f32_16x16x32_bf16 v[124:127], v[124:127], v[120:123], v[68:71]
	v_mfma_f32_16x16x32_bf16 v[120:123], v[132:135], v[120:123], v[36:39]
	s_waitcnt lgkmcnt(6)
	v_mfma_f32_16x16x32_bf16 v[78:81], v[140:143], v[136:139], v[40:43]
	s_waitcnt lgkmcnt(4)
	v_mfma_f32_16x16x32_bf16 v[74:77], v[148:151], v[136:139], v[96:99]
	s_waitcnt lgkmcnt(2)
	v_mfma_f32_16x16x32_bf16 v[70:73], v[152:155], v[136:139], v[104:107]
	s_waitcnt lgkmcnt(0)
	v_mfma_f32_16x16x32_bf16 v[66:69], v[18:21], v[136:139], v[22:25]
	v_mfma_f32_16x16x32_bf16 v[62:65], v[140:143], v[144:147], v[44:47]
	v_mfma_f32_16x16x32_bf16 v[58:61], v[148:151], v[144:147], v[56:59]
	v_mfma_f32_16x16x32_bf16 v[54:57], v[152:155], v[144:147], v[100:103]
	v_mfma_f32_16x16x32_bf16 v[50:53], v[18:21], v[144:147], v[26:29]
	v_mfma_f32_16x16x32_bf16 v[46:49], v[140:143], v[92:95], v[156:159]
	v_mfma_f32_16x16x32_bf16 v[42:45], v[148:151], v[92:95], v[160:163]
	v_mfma_f32_16x16x32_bf16 v[38:41], v[152:155], v[92:95], v[164:167]
	v_mfma_f32_16x16x32_bf16 v[34:37], v[18:21], v[92:95], v[30:33]
	v_mfma_f32_16x16x32_bf16 v[30:33], v[140:143], v[116:119], v[108:111]
	v_mfma_f32_16x16x32_bf16 v[26:29], v[148:151], v[116:119], v[112:115]
	v_mfma_f32_16x16x32_bf16 v[22:25], v[152:155], v[116:119], v[124:127]
	v_mfma_f32_16x16x32_bf16 v[18:21], v[18:21], v[116:119], v[120:123]
	s_setprio 0
	v_add_f32_e32 v10, v10, v11
	v_add_f32_e32 v11, v12, v13
	v_add_f32_e32 v10, v10, v11
	v_mov_b32_e32 v11, v10
	s_nop 1
	v_permlane32_swap_b32_e32 v10, v11
	v_add_f32_e32 v10, v10, v11
	v_mov_b32_e32 v11, v10
	s_nop 1
	v_permlane16_swap_b32_e32 v10, v11
	v_add_f32_e32 v10, v10, v11
	v_fmamk_f32 v10, v10, 0x3a800000, v86
	v_mul_f32_e32 v11, 0x4b800000, v10
	v_cmp_gt_f32_e64 s[0:1], s19, v10
	v_lshl_add_u64 v[84:85], v[84:85], 2, s[8:9]
	s_nop 0
	v_cndmask_b32_e64 v10, v10, v11, s[0:1]
	v_rsq_f32_e32 v10, v10
	v_or3_b32 v11, v91, s2, v89
	v_cmp_eq_u32_e32 vcc, 0, v11
	s_barrier
	v_mul_f32_e32 v11, 0x45800000, v10
	v_cndmask_b32_e64 v12, v10, v11, s[0:1]
	s_and_saveexec_b64 s[0:1], vcc
	s_cbranch_execz .LBB0_1265
	global_store_dword v[84:85], v12, off
